# removed per-phase s_setprio flips from GEMM loops (MFMA blocks re-aligned to 8 bytes)
# speedup vs baseline: 1.0321x; 1.0005x over previous
.LBB0_245:
	ds_read_b128 v[150:153], v147
	ds_read_b128 v[154:157], v147 offset:1024
	ds_read_b128 v[158:161], v147 offset:2048
	ds_read_b128 v[162:165], v147 offset:3072
	ds_read_b128 v[166:169], v148
	ds_read_b128 v[170:173], v148 offset:1024
	ds_read_b128 v[174:177], v148 offset:2048
	ds_read_b128 v[178:181], v148 offset:3072
	s_add_u32 s28, s40, 0xfffc0080
	s_addc_u32 s29, s41, -1
	s_cmp_eq_u32 s77, 12
	s_cselect_b32 s47, s19, s29
	s_cselect_b32 s46, s65, s28
	s_cselect_b32 s43, s15, s76
	s_cselect_b32 s42, s66, s67
	v_lshl_add_u64 v[186:187], s[40:41], 0, v[136:137]
	s_add_i32 m0, s35, 0xc000
	ds_read_b128 v[182:185], v149
	ds_read_b128 v[190:193], v149 offset:1024
	ds_read_b128 v[194:197], v149 offset:2048
	ds_read_b128 v[198:201], v149 offset:3072
	ds_read_b128 v[202:205], v149 offset:4096
	ds_read_b128 v[206:209], v149 offset:5120
	ds_read_b128 v[210:213], v149 offset:6144
	ds_read_b128 v[214:217], v149 offset:7168
	global_load_lds_dwordx4 v[186:187], off
	v_lshl_add_u64 v[186:187], s[40:41], 0, v[138:139]
	s_add_i32 m0, s35, 0xe000
	s_nop 0
	global_load_lds_dwordx4 v[186:187], off
	s_waitcnt vmcnt(8)
	s_waitcnt lgkmcnt(0)
	s_nop 0
	s_barrier
	s_waitcnt lgkmcnt(0)
	v_mfma_f32_16x16x32_bf16 v[124:127], v[150:153], v[182:185], v[124:127]
	v_mfma_f32_16x16x32_bf16 v[116:119], v[158:161], v[182:185], v[116:119]
	v_mfma_f32_16x16x32_bf16 v[108:111], v[150:153], v[194:197], v[108:111]
	v_mfma_f32_16x16x32_bf16 v[100:103], v[158:161], v[194:197], v[100:103]
	v_mfma_f32_16x16x32_bf16 v[92:95], v[150:153], v[202:205], v[92:95]
	v_mfma_f32_16x16x32_bf16 v[84:87], v[158:161], v[202:205], v[84:87]
	v_mfma_f32_16x16x32_bf16 v[76:79], v[150:153], v[210:213], v[76:79]
	v_mfma_f32_16x16x32_bf16 v[68:71], v[158:161], v[210:213], v[68:71]
	v_mfma_f32_16x16x32_bf16 v[124:127], v[154:157], v[190:193], v[124:127]
	v_mfma_f32_16x16x32_bf16 v[116:119], v[162:165], v[190:193], v[116:119]
	v_mfma_f32_16x16x32_bf16 v[108:111], v[154:157], v[198:201], v[108:111]
	v_mfma_f32_16x16x32_bf16 v[100:103], v[162:165], v[198:201], v[100:103]
	v_mfma_f32_16x16x32_bf16 v[92:95], v[154:157], v[206:209], v[92:95]
	v_mfma_f32_16x16x32_bf16 v[84:87], v[162:165], v[206:209], v[84:87]
	v_mfma_f32_16x16x32_bf16 v[76:79], v[154:157], v[214:217], v[76:79]
	v_mfma_f32_16x16x32_bf16 v[68:71], v[162:165], v[214:217], v[68:71]
	v_mfma_f32_16x16x32_bf16 v[120:123], v[166:169], v[182:185], v[120:123]
	v_mfma_f32_16x16x32_bf16 v[112:115], v[174:177], v[182:185], v[112:115]
	v_mfma_f32_16x16x32_bf16 v[104:107], v[166:169], v[194:197], v[104:107]
	v_mfma_f32_16x16x32_bf16 v[96:99], v[174:177], v[194:197], v[96:99]
	v_mfma_f32_16x16x32_bf16 v[88:91], v[166:169], v[202:205], v[88:91]
	v_mfma_f32_16x16x32_bf16 v[80:83], v[174:177], v[202:205], v[80:83]
	v_mfma_f32_16x16x32_bf16 v[72:75], v[166:169], v[210:213], v[72:75]
	v_mfma_f32_16x16x32_bf16 v[64:67], v[174:177], v[210:213], v[64:67]
	v_mfma_f32_16x16x32_bf16 v[120:123], v[170:173], v[190:193], v[120:123]
	v_mfma_f32_16x16x32_bf16 v[112:115], v[178:181], v[190:193], v[112:115]
	v_mfma_f32_16x16x32_bf16 v[104:107], v[170:173], v[198:201], v[104:107]
	v_mfma_f32_16x16x32_bf16 v[96:99], v[178:181], v[198:201], v[96:99]
	v_mfma_f32_16x16x32_bf16 v[88:91], v[170:173], v[206:209], v[88:91]
	v_mfma_f32_16x16x32_bf16 v[80:83], v[178:181], v[206:209], v[80:83]
	v_mfma_f32_16x16x32_bf16 v[72:75], v[170:173], v[214:217], v[72:75]
	v_mfma_f32_16x16x32_bf16 v[64:67], v[178:181], v[214:217], v[64:67]
	s_barrier
	s_add_i32 s28, s61, s12
	v_lshl_add_u64 v[186:187], s[42:43], 0, v[132:133]
	s_mov_b32 m0, s28
	ds_read_b128 v[182:185], v149 offset:16384
	ds_read_b128 v[190:193], v149 offset:17408
	ds_read_b128 v[194:197], v149 offset:18432
	ds_read_b128 v[198:201], v149 offset:19456
	ds_read_b128 v[202:205], v149 offset:20480
	ds_read_b128 v[206:209], v149 offset:21504
	ds_read_b128 v[210:213], v149 offset:22528
	ds_read_b128 v[214:217], v149 offset:23552
	global_load_lds_dwordx4 v[186:187], off
	s_add_i32 m0, s28, 0x2000
	s_add_u32 s28, s42, 0x40000
	v_lshl_add_u64 v[218:219], s[42:43], 0, v[128:129]
	s_addc_u32 s29, s43, 0
	s_add_i32 s33, s62, s12
	global_load_lds_dwordx4 v[218:219], off
	v_lshl_add_u64 v[220:221], s[28:29], 0, v[132:133]
	s_mov_b32 m0, s33
	v_lshl_add_u64 v[222:223], s[46:47], 0, v[130:131]
	global_load_lds_dwordx4 v[220:221], off
	v_lshl_add_u64 v[220:221], s[28:29], 0, v[128:129]
	s_add_i32 m0, s33, 0x2000
	s_nop 0
	global_load_lds_dwordx4 v[220:221], off
	v_lshl_add_u64 v[220:221], s[46:47], 0, v[134:135]
	s_mov_b32 m0, s35
	s_nop 0
	global_load_lds_dwordx4 v[220:221], off
	s_mov_b32 m0, s39
	s_nop 0
	global_load_lds_dwordx4 v[222:223], off
	s_waitcnt vmcnt(8)
	s_waitcnt lgkmcnt(0)
	s_nop 0
	s_barrier
	s_waitcnt lgkmcnt(0)
	v_mfma_f32_16x16x32_bf16 v[60:63], v[150:153], v[182:185], v[60:63]
	v_mfma_f32_16x16x32_bf16 v[52:55], v[158:161], v[182:185], v[52:55]
	v_mfma_f32_16x16x32_bf16 v[44:47], v[150:153], v[194:197], v[44:47]
	v_mfma_f32_16x16x32_bf16 v[36:39], v[158:161], v[194:197], v[36:39]
	v_mfma_f32_16x16x32_bf16 v[28:31], v[150:153], v[202:205], v[28:31]
	v_mfma_f32_16x16x32_bf16 v[20:23], v[158:161], v[202:205], v[20:23]
	v_mfma_f32_16x16x32_bf16 v[12:15], v[150:153], v[210:213], v[12:15]
	v_mfma_f32_16x16x32_bf16 v[4:7], v[158:161], v[210:213], v[4:7]
	v_mfma_f32_16x16x32_bf16 v[60:63], v[154:157], v[190:193], v[60:63]
	v_mfma_f32_16x16x32_bf16 v[52:55], v[162:165], v[190:193], v[52:55]
	v_mfma_f32_16x16x32_bf16 v[44:47], v[154:157], v[198:201], v[44:47]
	v_mfma_f32_16x16x32_bf16 v[36:39], v[162:165], v[198:201], v[36:39]
	v_mfma_f32_16x16x32_bf16 v[28:31], v[154:157], v[206:209], v[28:31]
	v_mfma_f32_16x16x32_bf16 v[20:23], v[162:165], v[206:209], v[20:23]
	v_mfma_f32_16x16x32_bf16 v[12:15], v[154:157], v[214:217], v[12:15]
	v_mfma_f32_16x16x32_bf16 v[4:7], v[162:165], v[214:217], v[4:7]
	v_mfma_f32_16x16x32_bf16 v[56:59], v[166:169], v[182:185], v[56:59]
	v_mfma_f32_16x16x32_bf16 v[48:51], v[174:177], v[182:185], v[48:51]
	v_mfma_f32_16x16x32_bf16 v[40:43], v[166:169], v[194:197], v[40:43]
	v_mfma_f32_16x16x32_bf16 v[32:35], v[174:177], v[194:197], v[32:35]
	v_mfma_f32_16x16x32_bf16 v[24:27], v[166:169], v[202:205], v[24:27]
	v_mfma_f32_16x16x32_bf16 v[16:19], v[174:177], v[202:205], v[16:19]
	v_mfma_f32_16x16x32_bf16 v[8:11], v[166:169], v[210:213], v[8:11]
	v_mfma_f32_16x16x32_bf16 v[0:3], v[174:177], v[210:213], v[0:3]
	v_mfma_f32_16x16x32_bf16 v[56:59], v[170:173], v[190:193], v[56:59]
	v_mfma_f32_16x16x32_bf16 v[48:51], v[178:181], v[190:193], v[48:51]
	v_mfma_f32_16x16x32_bf16 v[40:43], v[170:173], v[198:201], v[40:43]
	v_mfma_f32_16x16x32_bf16 v[32:35], v[178:181], v[198:201], v[32:35]
	v_mfma_f32_16x16x32_bf16 v[24:27], v[170:173], v[206:209], v[24:27]
	v_mfma_f32_16x16x32_bf16 v[16:19], v[178:181], v[206:209], v[16:19]
	v_mfma_f32_16x16x32_bf16 v[8:11], v[170:173], v[214:217], v[8:11]
	v_mfma_f32_16x16x32_bf16 v[0:3], v[178:181], v[214:217], v[0:3]
	s_barrier
	s_add_i32 s33, 0, 0x18000
	s_add_i32 s56, 0, 0x1c000
	v_add_u32_e32 v162, s33, v145
	v_add_u32_e32 v178, s56, v145
	ds_read_b128 v[150:153], v162
	ds_read_b128 v[154:157], v162 offset:1024
	ds_read_b128 v[158:161], v162 offset:2048
	ds_read_b128 v[162:165], v162 offset:3072
	ds_read_b128 v[166:169], v178
	ds_read_b128 v[170:173], v178 offset:1024
	ds_read_b128 v[174:177], v178 offset:2048
	ds_read_b128 v[178:181], v178 offset:3072
	s_add_u32 s28, s46, 0x40000
	s_addc_u32 s29, s47, 0
	s_mov_b32 m0, s50
	v_lshl_add_u64 v[224:225], s[28:29], 0, v[134:135]
	ds_read_b128 v[182:185], v149 offset:32768
	ds_read_b128 v[190:193], v149 offset:33792
	ds_read_b128 v[194:197], v149 offset:34816
	ds_read_b128 v[198:201], v149 offset:35840
	ds_read_b128 v[202:205], v149 offset:36864
	ds_read_b128 v[206:209], v149 offset:37888
	ds_read_b128 v[210:213], v149 offset:38912
	ds_read_b128 v[214:217], v149 offset:39936
	global_load_lds_dwordx4 v[224:225], off
	v_lshl_add_u64 v[224:225], s[28:29], 0, v[130:131]
	s_mov_b32 m0, s51
	s_nop 0
	global_load_lds_dwordx4 v[224:225], off
	s_waitcnt vmcnt(8)
	s_waitcnt lgkmcnt(0)
	s_nop 0
	s_barrier
	s_waitcnt lgkmcnt(0)
	v_mfma_f32_16x16x32_bf16 v[124:127], v[150:153], v[182:185], v[124:127]
	v_mfma_f32_16x16x32_bf16 v[116:119], v[158:161], v[182:185], v[116:119]
	v_mfma_f32_16x16x32_bf16 v[108:111], v[150:153], v[194:197], v[108:111]
	v_mfma_f32_16x16x32_bf16 v[100:103], v[158:161], v[194:197], v[100:103]
	v_mfma_f32_16x16x32_bf16 v[92:95], v[150:153], v[202:205], v[92:95]
	v_mfma_f32_16x16x32_bf16 v[84:87], v[158:161], v[202:205], v[84:87]
	v_mfma_f32_16x16x32_bf16 v[76:79], v[150:153], v[210:213], v[76:79]
	v_mfma_f32_16x16x32_bf16 v[68:71], v[158:161], v[210:213], v[68:71]
	v_mfma_f32_16x16x32_bf16 v[124:127], v[154:157], v[190:193], v[124:127]
	v_mfma_f32_16x16x32_bf16 v[116:119], v[162:165], v[190:193], v[116:119]
	v_mfma_f32_16x16x32_bf16 v[108:111], v[154:157], v[198:201], v[108:111]
	v_mfma_f32_16x16x32_bf16 v[100:103], v[162:165], v[198:201], v[100:103]
	v_mfma_f32_16x16x32_bf16 v[92:95], v[154:157], v[206:209], v[92:95]
	v_mfma_f32_16x16x32_bf16 v[84:87], v[162:165], v[206:209], v[84:87]
	v_mfma_f32_16x16x32_bf16 v[76:79], v[154:157], v[214:217], v[76:79]
	v_mfma_f32_16x16x32_bf16 v[68:71], v[162:165], v[214:217], v[68:71]
	v_mfma_f32_16x16x32_bf16 v[120:123], v[166:169], v[182:185], v[120:123]
	v_mfma_f32_16x16x32_bf16 v[112:115], v[174:177], v[182:185], v[112:115]
	v_mfma_f32_16x16x32_bf16 v[104:107], v[166:169], v[194:197], v[104:107]
	v_mfma_f32_16x16x32_bf16 v[96:99], v[174:177], v[194:197], v[96:99]
	v_mfma_f32_16x16x32_bf16 v[88:91], v[166:169], v[202:205], v[88:91]
	v_mfma_f32_16x16x32_bf16 v[80:83], v[174:177], v[202:205], v[80:83]
	v_mfma_f32_16x16x32_bf16 v[72:75], v[166:169], v[210:213], v[72:75]
	v_mfma_f32_16x16x32_bf16 v[64:67], v[174:177], v[210:213], v[64:67]
	v_mfma_f32_16x16x32_bf16 v[120:123], v[170:173], v[190:193], v[120:123]
	v_mfma_f32_16x16x32_bf16 v[112:115], v[178:181], v[190:193], v[112:115]
	v_mfma_f32_16x16x32_bf16 v[104:107], v[170:173], v[198:201], v[104:107]
	v_mfma_f32_16x16x32_bf16 v[96:99], v[178:181], v[198:201], v[96:99]
	v_mfma_f32_16x16x32_bf16 v[88:91], v[170:173], v[206:209], v[88:91]
	v_mfma_f32_16x16x32_bf16 v[80:83], v[178:181], v[206:209], v[80:83]
	v_mfma_f32_16x16x32_bf16 v[72:75], v[170:173], v[214:217], v[72:75]
	v_mfma_f32_16x16x32_bf16 v[64:67], v[178:181], v[214:217], v[64:67]
	s_barrier
	s_add_i32 s28, s33, s12
	v_lshl_add_u64 v[186:187], v[186:187], 0, s[6:7]
	s_mov_b32 m0, s28
	ds_read_b128 v[182:185], v149 offset:49152
	ds_read_b128 v[190:193], v149 offset:50176
	ds_read_b128 v[194:197], v149 offset:51200
	ds_read_b128 v[198:201], v149 offset:52224
	ds_read_b128 v[202:205], v149 offset:53248
	ds_read_b128 v[206:209], v149 offset:54272
	ds_read_b128 v[210:213], v149 offset:55296
	ds_read_b128 v[214:217], v149 offset:56320
	global_load_lds_dwordx4 v[186:187], off
	s_add_i32 m0, s28, 0x2000
	s_add_u32 s28, s42, 0x40080
	v_lshl_add_u64 v[186:187], v[218:219], 0, s[6:7]
	s_addc_u32 s29, s43, 0
	s_add_i32 s33, s56, s12
	global_load_lds_dwordx4 v[186:187], off
	v_lshl_add_u64 v[186:187], s[28:29], 0, v[132:133]
	s_mov_b32 m0, s33
	s_nop 0
	global_load_lds_dwordx4 v[186:187], off
	v_lshl_add_u64 v[186:187], s[28:29], 0, v[128:129]
	s_add_i32 m0, s33, 0x2000
	s_nop 0
	global_load_lds_dwordx4 v[186:187], off
	v_lshl_add_u64 v[186:187], v[220:221], 0, s[6:7]
	s_mov_b32 m0, s53
	s_nop 0
	global_load_lds_dwordx4 v[186:187], off
	v_lshl_add_u64 v[186:187], v[222:223], 0, s[6:7]
	s_mov_b32 m0, s54
	s_nop 0
	global_load_lds_dwordx4 v[186:187], off
	s_waitcnt vmcnt(8)
	s_waitcnt lgkmcnt(0)
	s_barrier
	s_waitcnt lgkmcnt(0)
	v_mfma_f32_16x16x32_bf16 v[60:63], v[150:153], v[182:185], v[60:63]
	v_mfma_f32_16x16x32_bf16 v[52:55], v[158:161], v[182:185], v[52:55]
	v_mfma_f32_16x16x32_bf16 v[44:47], v[150:153], v[194:197], v[44:47]
	v_mfma_f32_16x16x32_bf16 v[36:39], v[158:161], v[194:197], v[36:39]
	v_mfma_f32_16x16x32_bf16 v[28:31], v[150:153], v[202:205], v[28:31]
	v_mfma_f32_16x16x32_bf16 v[20:23], v[158:161], v[202:205], v[20:23]
	v_mfma_f32_16x16x32_bf16 v[12:15], v[150:153], v[210:213], v[12:15]
	v_mfma_f32_16x16x32_bf16 v[4:7], v[158:161], v[210:213], v[4:7]
	v_mfma_f32_16x16x32_bf16 v[60:63], v[154:157], v[190:193], v[60:63]
	v_mfma_f32_16x16x32_bf16 v[52:55], v[162:165], v[190:193], v[52:55]
	v_mfma_f32_16x16x32_bf16 v[44:47], v[154:157], v[198:201], v[44:47]
	v_mfma_f32_16x16x32_bf16 v[36:39], v[162:165], v[198:201], v[36:39]
	v_mfma_f32_16x16x32_bf16 v[28:31], v[154:157], v[206:209], v[28:31]
	v_mfma_f32_16x16x32_bf16 v[20:23], v[162:165], v[206:209], v[20:23]
	v_mfma_f32_16x16x32_bf16 v[12:15], v[154:157], v[214:217], v[12:15]
	v_mfma_f32_16x16x32_bf16 v[4:7], v[162:165], v[214:217], v[4:7]
	v_mfma_f32_16x16x32_bf16 v[56:59], v[166:169], v[182:185], v[56:59]
	v_mfma_f32_16x16x32_bf16 v[48:51], v[174:177], v[182:185], v[48:51]
	v_mfma_f32_16x16x32_bf16 v[40:43], v[166:169], v[194:197], v[40:43]
	v_mfma_f32_16x16x32_bf16 v[32:35], v[174:177], v[194:197], v[32:35]
	v_mfma_f32_16x16x32_bf16 v[24:27], v[166:169], v[202:205], v[24:27]
	v_mfma_f32_16x16x32_bf16 v[16:19], v[174:177], v[202:205], v[16:19]
	v_mfma_f32_16x16x32_bf16 v[8:11], v[166:169], v[210:213], v[8:11]
	v_mfma_f32_16x16x32_bf16 v[0:3], v[174:177], v[210:213], v[0:3]
	v_mfma_f32_16x16x32_bf16 v[56:59], v[170:173], v[190:193], v[56:59]
	v_mfma_f32_16x16x32_bf16 v[48:51], v[178:181], v[190:193], v[48:51]
	v_mfma_f32_16x16x32_bf16 v[40:43], v[170:173], v[198:201], v[40:43]
	v_mfma_f32_16x16x32_bf16 v[32:35], v[178:181], v[198:201], v[32:35]
	v_mfma_f32_16x16x32_bf16 v[24:27], v[170:173], v[206:209], v[24:27]
	v_mfma_f32_16x16x32_bf16 v[16:19], v[178:181], v[206:209], v[16:19]
	v_mfma_f32_16x16x32_bf16 v[8:11], v[170:173], v[214:217], v[8:11]
	v_mfma_f32_16x16x32_bf16 v[0:3], v[178:181], v[214:217], v[0:3]
	s_barrier
	s_add_i32 s77, s77, 2
	s_add_u32 s40, s40, 0x100
	s_addc_u32 s41, s41, 0
	s_add_u32 s67, s67, 0x100
	s_addc_u32 s76, s76, 0
	s_cmp_gt_u32 s77, 13
	s_cbranch_scc0 .LBB0_245
	s_and_b64 vcc, exec, s[8:9]
	s_cbranch_vccz .LBB0_248
	s_barrier

.LBB0_325:
	ds_read_b128 v[152:155], v149
	ds_read_b128 v[156:159], v149 offset:1024
	ds_read_b128 v[160:163], v149 offset:2048
	ds_read_b128 v[164:167], v149 offset:3072
	ds_read_b128 v[168:171], v150
	ds_read_b128 v[172:175], v150 offset:1024
	ds_read_b128 v[176:179], v150 offset:2048
	ds_read_b128 v[180:183], v150 offset:3072
	s_add_u32 s50, s46, 0x10000
	s_addc_u32 s51, s47, 0
	s_cmp_eq_u32 s91, 40
	s_cselect_b32 s55, s5, s51
	s_cselect_b32 s54, s4, s50
	s_cselect_b32 s53, s43, s90
	s_cselect_b32 s52, s42, s89
	v_lshl_add_u64 v[144:145], s[46:47], 0, v[136:137]
	s_add_i32 m0, s35, 0xc000
	ds_read_b128 v[184:187], v151
	ds_read_b128 v[190:193], v151 offset:1024
	ds_read_b128 v[194:197], v151 offset:2048
	ds_read_b128 v[198:201], v151 offset:3072
	ds_read_b128 v[202:205], v151 offset:4096
	ds_read_b128 v[206:209], v151 offset:5120
	ds_read_b128 v[210:213], v151 offset:6144
	ds_read_b128 v[214:217], v151 offset:7168
	global_load_lds_dwordx4 v[144:145], off
	v_lshl_add_u64 v[144:145], s[46:47], 0, v[138:139]
	s_add_i32 m0, s35, 0xe000
	s_nop 0
	global_load_lds_dwordx4 v[144:145], off
	s_waitcnt vmcnt(8)
	s_waitcnt lgkmcnt(0)
	s_barrier
	s_waitcnt lgkmcnt(0)
	v_mfma_f32_16x16x32_bf16 v[124:127], v[152:155], v[184:187], v[124:127]
	v_mfma_f32_16x16x32_bf16 v[120:123], v[160:163], v[184:187], v[120:123]
	v_mfma_f32_16x16x32_bf16 v[116:119], v[152:155], v[194:197], v[116:119]
	v_mfma_f32_16x16x32_bf16 v[108:111], v[160:163], v[194:197], v[108:111]
	v_mfma_f32_16x16x32_bf16 v[100:103], v[152:155], v[202:205], v[100:103]
	v_mfma_f32_16x16x32_bf16 v[92:95], v[160:163], v[202:205], v[92:95]
	v_mfma_f32_16x16x32_bf16 v[84:87], v[152:155], v[210:213], v[84:87]
	v_mfma_f32_16x16x32_bf16 v[76:79], v[160:163], v[210:213], v[76:79]
	v_mfma_f32_16x16x32_bf16 v[124:127], v[156:159], v[190:193], v[124:127]
	v_mfma_f32_16x16x32_bf16 v[120:123], v[164:167], v[190:193], v[120:123]
	v_mfma_f32_16x16x32_bf16 v[116:119], v[156:159], v[198:201], v[116:119]
	v_mfma_f32_16x16x32_bf16 v[108:111], v[164:167], v[198:201], v[108:111]
	v_mfma_f32_16x16x32_bf16 v[100:103], v[156:159], v[206:209], v[100:103]
	v_mfma_f32_16x16x32_bf16 v[92:95], v[164:167], v[206:209], v[92:95]
	v_mfma_f32_16x16x32_bf16 v[84:87], v[156:159], v[214:217], v[84:87]
	v_mfma_f32_16x16x32_bf16 v[76:79], v[164:167], v[214:217], v[76:79]
	v_mfma_f32_16x16x32_bf16 v[112:115], v[168:171], v[184:187], v[112:115]
	v_mfma_f32_16x16x32_bf16 v[104:107], v[176:179], v[184:187], v[104:107]
	v_mfma_f32_16x16x32_bf16 v[96:99], v[168:171], v[194:197], v[96:99]
	v_mfma_f32_16x16x32_bf16 v[88:91], v[176:179], v[194:197], v[88:91]
	v_mfma_f32_16x16x32_bf16 v[80:83], v[168:171], v[202:205], v[80:83]
	v_mfma_f32_16x16x32_bf16 v[72:75], v[176:179], v[202:205], v[72:75]
	v_mfma_f32_16x16x32_bf16 v[68:71], v[168:171], v[210:213], v[68:71]
	v_mfma_f32_16x16x32_bf16 v[64:67], v[176:179], v[210:213], v[64:67]
	v_mfma_f32_16x16x32_bf16 v[112:115], v[172:175], v[190:193], v[112:115]
	v_mfma_f32_16x16x32_bf16 v[104:107], v[180:183], v[190:193], v[104:107]
	v_mfma_f32_16x16x32_bf16 v[96:99], v[172:175], v[198:201], v[96:99]
	v_mfma_f32_16x16x32_bf16 v[88:91], v[180:183], v[198:201], v[88:91]
	v_mfma_f32_16x16x32_bf16 v[80:83], v[172:175], v[206:209], v[80:83]
	v_mfma_f32_16x16x32_bf16 v[72:75], v[180:183], v[206:209], v[72:75]
	v_mfma_f32_16x16x32_bf16 v[68:71], v[172:175], v[214:217], v[68:71]
	v_mfma_f32_16x16x32_bf16 v[64:67], v[180:183], v[214:217], v[64:67]
	s_barrier
	s_add_i32 s28, s76, s34
	v_lshl_add_u64 v[144:145], s[52:53], 0, v[130:131]
	s_mov_b32 m0, s28
	ds_read_b128 v[184:187], v151 offset:16384
	ds_read_b128 v[190:193], v151 offset:17408
	ds_read_b128 v[194:197], v151 offset:18432
	ds_read_b128 v[198:201], v151 offset:19456
	ds_read_b128 v[202:205], v151 offset:20480
	ds_read_b128 v[206:209], v151 offset:21504
	ds_read_b128 v[210:213], v151 offset:22528
	ds_read_b128 v[214:217], v151 offset:23552
	global_load_lds_dwordx4 v[144:145], off
	s_add_i32 m0, s28, 0x2000
	s_add_u32 s28, s52, 0xb0000
	v_lshl_add_u64 v[218:219], s[52:53], 0, v[134:135]
	s_addc_u32 s29, s53, 0
	s_add_i32 s33, s77, s34
	global_load_lds_dwordx4 v[218:219], off
	v_lshl_add_u64 v[220:221], s[28:29], 0, v[130:131]
	s_mov_b32 m0, s33
	v_lshl_add_u64 v[222:223], s[54:55], 0, v[132:133]
	global_load_lds_dwordx4 v[220:221], off
	v_lshl_add_u64 v[220:221], s[28:29], 0, v[134:135]
	s_add_i32 m0, s33, 0x2000
	s_nop 0
	global_load_lds_dwordx4 v[220:221], off
	v_lshl_add_u64 v[220:221], s[54:55], 0, v[128:129]
	s_mov_b32 m0, s35
	s_nop 0
	global_load_lds_dwordx4 v[220:221], off
	s_mov_b32 m0, s60
	s_nop 0
	global_load_lds_dwordx4 v[222:223], off
	s_waitcnt vmcnt(8)
	s_waitcnt lgkmcnt(0)
	s_nop 0
	s_barrier
	s_waitcnt lgkmcnt(0)
	v_mfma_f32_16x16x32_bf16 v[60:63], v[152:155], v[184:187], v[60:63]
	v_mfma_f32_16x16x32_bf16 v[56:59], v[160:163], v[184:187], v[56:59]
	v_mfma_f32_16x16x32_bf16 v[52:55], v[152:155], v[194:197], v[52:55]
	v_mfma_f32_16x16x32_bf16 v[44:47], v[160:163], v[194:197], v[44:47]
	v_mfma_f32_16x16x32_bf16 v[36:39], v[152:155], v[202:205], v[36:39]
	v_mfma_f32_16x16x32_bf16 v[28:31], v[160:163], v[202:205], v[28:31]
	v_mfma_f32_16x16x32_bf16 v[20:23], v[152:155], v[210:213], v[20:23]
	v_mfma_f32_16x16x32_bf16 v[12:15], v[160:163], v[210:213], v[12:15]
	v_mfma_f32_16x16x32_bf16 v[60:63], v[156:159], v[190:193], v[60:63]
	v_mfma_f32_16x16x32_bf16 v[56:59], v[164:167], v[190:193], v[56:59]
	v_mfma_f32_16x16x32_bf16 v[52:55], v[156:159], v[198:201], v[52:55]
	v_mfma_f32_16x16x32_bf16 v[44:47], v[164:167], v[198:201], v[44:47]
	v_mfma_f32_16x16x32_bf16 v[36:39], v[156:159], v[206:209], v[36:39]
	v_mfma_f32_16x16x32_bf16 v[28:31], v[164:167], v[206:209], v[28:31]
	v_mfma_f32_16x16x32_bf16 v[20:23], v[156:159], v[214:217], v[20:23]
	v_mfma_f32_16x16x32_bf16 v[12:15], v[164:167], v[214:217], v[12:15]
	v_mfma_f32_16x16x32_bf16 v[48:51], v[168:171], v[184:187], v[48:51]
	v_mfma_f32_16x16x32_bf16 v[40:43], v[176:179], v[184:187], v[40:43]
	v_mfma_f32_16x16x32_bf16 v[32:35], v[168:171], v[194:197], v[32:35]
	v_mfma_f32_16x16x32_bf16 v[24:27], v[176:179], v[194:197], v[24:27]
	v_mfma_f32_16x16x32_bf16 v[16:19], v[168:171], v[202:205], v[16:19]
	v_mfma_f32_16x16x32_bf16 v[8:11], v[176:179], v[202:205], v[8:11]
	v_mfma_f32_16x16x32_bf16 v[4:7], v[168:171], v[210:213], v[4:7]
	v_mfma_f32_16x16x32_bf16 v[0:3], v[176:179], v[210:213], v[0:3]
	v_mfma_f32_16x16x32_bf16 v[48:51], v[172:175], v[190:193], v[48:51]
	v_mfma_f32_16x16x32_bf16 v[40:43], v[180:183], v[190:193], v[40:43]
	v_mfma_f32_16x16x32_bf16 v[32:35], v[172:175], v[198:201], v[32:35]
	v_mfma_f32_16x16x32_bf16 v[24:27], v[180:183], v[198:201], v[24:27]
	v_mfma_f32_16x16x32_bf16 v[16:19], v[172:175], v[206:209], v[16:19]
	v_mfma_f32_16x16x32_bf16 v[8:11], v[180:183], v[206:209], v[8:11]
	v_mfma_f32_16x16x32_bf16 v[4:7], v[172:175], v[214:217], v[4:7]
	v_mfma_f32_16x16x32_bf16 v[0:3], v[180:183], v[214:217], v[0:3]
	s_barrier
	s_add_i32 s33, 0, 0x18000
	s_add_i32 s46, 0, 0x1c000
	v_add_u32_e32 v164, s33, v147
	v_add_u32_e32 v180, s46, v147
	ds_read_b128 v[152:155], v164
	ds_read_b128 v[156:159], v164 offset:1024
	ds_read_b128 v[160:163], v164 offset:2048
	ds_read_b128 v[164:167], v164 offset:3072
	ds_read_b128 v[168:171], v180
	ds_read_b128 v[172:175], v180 offset:1024
	ds_read_b128 v[176:179], v180 offset:2048
	ds_read_b128 v[180:183], v180 offset:3072
	s_add_u32 s28, s54, 0x4000
	s_addc_u32 s29, s55, 0
	s_mov_b32 m0, s61
	v_lshl_add_u64 v[224:225], s[28:29], 0, v[128:129]
	ds_read_b128 v[184:187], v151 offset:32768
	ds_read_b128 v[190:193], v151 offset:33792
	ds_read_b128 v[194:197], v151 offset:34816
	ds_read_b128 v[198:201], v151 offset:35840
	ds_read_b128 v[202:205], v151 offset:36864
	ds_read_b128 v[206:209], v151 offset:37888
	ds_read_b128 v[210:213], v151 offset:38912
	ds_read_b128 v[214:217], v151 offset:39936
	global_load_lds_dwordx4 v[224:225], off
	v_lshl_add_u64 v[224:225], s[28:29], 0, v[132:133]
	s_mov_b32 m0, s62
	s_nop 0
	global_load_lds_dwordx4 v[224:225], off
	s_waitcnt vmcnt(8)
	s_waitcnt lgkmcnt(0)
	s_nop 0
	s_barrier
	s_waitcnt lgkmcnt(0)
	v_mfma_f32_16x16x32_bf16 v[124:127], v[152:155], v[184:187], v[124:127]
	v_mfma_f32_16x16x32_bf16 v[120:123], v[160:163], v[184:187], v[120:123]
	v_mfma_f32_16x16x32_bf16 v[116:119], v[152:155], v[194:197], v[116:119]
	v_mfma_f32_16x16x32_bf16 v[108:111], v[160:163], v[194:197], v[108:111]
	v_mfma_f32_16x16x32_bf16 v[100:103], v[152:155], v[202:205], v[100:103]
	v_mfma_f32_16x16x32_bf16 v[92:95], v[160:163], v[202:205], v[92:95]
	v_mfma_f32_16x16x32_bf16 v[84:87], v[152:155], v[210:213], v[84:87]
	v_mfma_f32_16x16x32_bf16 v[76:79], v[160:163], v[210:213], v[76:79]
	v_mfma_f32_16x16x32_bf16 v[124:127], v[156:159], v[190:193], v[124:127]
	v_mfma_f32_16x16x32_bf16 v[120:123], v[164:167], v[190:193], v[120:123]
	v_mfma_f32_16x16x32_bf16 v[116:119], v[156:159], v[198:201], v[116:119]
	v_mfma_f32_16x16x32_bf16 v[108:111], v[164:167], v[198:201], v[108:111]
	v_mfma_f32_16x16x32_bf16 v[100:103], v[156:159], v[206:209], v[100:103]
	v_mfma_f32_16x16x32_bf16 v[92:95], v[164:167], v[206:209], v[92:95]
	v_mfma_f32_16x16x32_bf16 v[84:87], v[156:159], v[214:217], v[84:87]
	v_mfma_f32_16x16x32_bf16 v[76:79], v[164:167], v[214:217], v[76:79]
	v_mfma_f32_16x16x32_bf16 v[112:115], v[168:171], v[184:187], v[112:115]
	v_mfma_f32_16x16x32_bf16 v[104:107], v[176:179], v[184:187], v[104:107]
	v_mfma_f32_16x16x32_bf16 v[96:99], v[168:171], v[194:197], v[96:99]
	v_mfma_f32_16x16x32_bf16 v[88:91], v[176:179], v[194:197], v[88:91]
	v_mfma_f32_16x16x32_bf16 v[80:83], v[168:171], v[202:205], v[80:83]
	v_mfma_f32_16x16x32_bf16 v[72:75], v[176:179], v[202:205], v[72:75]
	v_mfma_f32_16x16x32_bf16 v[68:71], v[168:171], v[210:213], v[68:71]
	v_mfma_f32_16x16x32_bf16 v[64:67], v[176:179], v[210:213], v[64:67]
	v_mfma_f32_16x16x32_bf16 v[112:115], v[172:175], v[190:193], v[112:115]
	v_mfma_f32_16x16x32_bf16 v[104:107], v[180:183], v[190:193], v[104:107]
	v_mfma_f32_16x16x32_bf16 v[96:99], v[172:175], v[198:201], v[96:99]
	v_mfma_f32_16x16x32_bf16 v[88:91], v[180:183], v[198:201], v[88:91]
	v_mfma_f32_16x16x32_bf16 v[80:83], v[172:175], v[206:209], v[80:83]
	v_mfma_f32_16x16x32_bf16 v[72:75], v[180:183], v[206:209], v[72:75]
	v_mfma_f32_16x16x32_bf16 v[68:71], v[172:175], v[214:217], v[68:71]
	v_mfma_f32_16x16x32_bf16 v[64:67], v[180:183], v[214:217], v[64:67]
	s_barrier
	s_add_i32 s28, s33, s34
	v_lshl_add_u64 v[144:145], v[144:145], 0, s[8:9]
	s_mov_b32 m0, s28
	ds_read_b128 v[184:187], v151 offset:49152
	ds_read_b128 v[190:193], v151 offset:50176
	ds_read_b128 v[194:197], v151 offset:51200
	ds_read_b128 v[198:201], v151 offset:52224
	ds_read_b128 v[202:205], v151 offset:53248
	ds_read_b128 v[206:209], v151 offset:54272
	ds_read_b128 v[210:213], v151 offset:55296
	ds_read_b128 v[214:217], v151 offset:56320
	global_load_lds_dwordx4 v[144:145], off
	s_add_i32 m0, s28, 0x2000
	s_add_u32 s28, s52, 0xb0080
	v_lshl_add_u64 v[144:145], v[218:219], 0, s[8:9]
	s_addc_u32 s29, s53, 0
	s_add_i32 s33, s46, s34
	global_load_lds_dwordx4 v[144:145], off
	v_lshl_add_u64 v[144:145], s[28:29], 0, v[130:131]
	s_mov_b32 m0, s33
	s_nop 0
	global_load_lds_dwordx4 v[144:145], off
	v_lshl_add_u64 v[144:145], s[28:29], 0, v[134:135]
	s_add_i32 m0, s33, 0x2000
	s_nop 0
	global_load_lds_dwordx4 v[144:145], off
	v_lshl_add_u64 v[144:145], v[220:221], 0, s[92:93]
	s_mov_b32 m0, s64
	s_nop 0
	global_load_lds_dwordx4 v[144:145], off
	v_lshl_add_u64 v[144:145], v[222:223], 0, s[92:93]
	s_mov_b32 m0, s65
	s_nop 0
	global_load_lds_dwordx4 v[144:145], off
	s_waitcnt vmcnt(8)
	s_waitcnt lgkmcnt(0)
	s_barrier
	s_waitcnt lgkmcnt(0)
	v_mfma_f32_16x16x32_bf16 v[60:63], v[152:155], v[184:187], v[60:63]
	v_mfma_f32_16x16x32_bf16 v[56:59], v[160:163], v[184:187], v[56:59]
	v_mfma_f32_16x16x32_bf16 v[52:55], v[152:155], v[194:197], v[52:55]
	v_mfma_f32_16x16x32_bf16 v[44:47], v[160:163], v[194:197], v[44:47]
	v_mfma_f32_16x16x32_bf16 v[36:39], v[152:155], v[202:205], v[36:39]
	v_mfma_f32_16x16x32_bf16 v[28:31], v[160:163], v[202:205], v[28:31]
	v_mfma_f32_16x16x32_bf16 v[20:23], v[152:155], v[210:213], v[20:23]
	v_mfma_f32_16x16x32_bf16 v[12:15], v[160:163], v[210:213], v[12:15]
	v_mfma_f32_16x16x32_bf16 v[60:63], v[156:159], v[190:193], v[60:63]
	v_mfma_f32_16x16x32_bf16 v[56:59], v[164:167], v[190:193], v[56:59]
	v_mfma_f32_16x16x32_bf16 v[52:55], v[156:159], v[198:201], v[52:55]
	v_mfma_f32_16x16x32_bf16 v[44:47], v[164:167], v[198:201], v[44:47]
	v_mfma_f32_16x16x32_bf16 v[36:39], v[156:159], v[206:209], v[36:39]
	v_mfma_f32_16x16x32_bf16 v[28:31], v[164:167], v[206:209], v[28:31]
	v_mfma_f32_16x16x32_bf16 v[20:23], v[156:159], v[214:217], v[20:23]
	v_mfma_f32_16x16x32_bf16 v[12:15], v[164:167], v[214:217], v[12:15]
	v_mfma_f32_16x16x32_bf16 v[48:51], v[168:171], v[184:187], v[48:51]
	v_mfma_f32_16x16x32_bf16 v[40:43], v[176:179], v[184:187], v[40:43]
	v_mfma_f32_16x16x32_bf16 v[32:35], v[168:171], v[194:197], v[32:35]
	v_mfma_f32_16x16x32_bf16 v[24:27], v[176:179], v[194:197], v[24:27]
	v_mfma_f32_16x16x32_bf16 v[16:19], v[168:171], v[202:205], v[16:19]
	v_mfma_f32_16x16x32_bf16 v[8:11], v[176:179], v[202:205], v[8:11]
	v_mfma_f32_16x16x32_bf16 v[4:7], v[168:171], v[210:213], v[4:7]
	v_mfma_f32_16x16x32_bf16 v[0:3], v[176:179], v[210:213], v[0:3]
	v_mfma_f32_16x16x32_bf16 v[48:51], v[172:175], v[190:193], v[48:51]
	v_mfma_f32_16x16x32_bf16 v[40:43], v[180:183], v[190:193], v[40:43]
	v_mfma_f32_16x16x32_bf16 v[32:35], v[172:175], v[198:201], v[32:35]
	v_mfma_f32_16x16x32_bf16 v[24:27], v[180:183], v[198:201], v[24:27]
	v_mfma_f32_16x16x32_bf16 v[16:19], v[172:175], v[206:209], v[16:19]
	v_mfma_f32_16x16x32_bf16 v[8:11], v[180:183], v[206:209], v[8:11]
	v_mfma_f32_16x16x32_bf16 v[4:7], v[172:175], v[214:217], v[4:7]
	v_mfma_f32_16x16x32_bf16 v[0:3], v[180:183], v[214:217], v[0:3]
	s_barrier
	s_add_i32 s91, s91, 2
	s_add_u32 s89, s89, 0x100
	s_addc_u32 s90, s90, 0
	s_cmp_gt_u32 s91, 41
	s_mov_b64 s[46:47], s[50:51]
	s_cbranch_scc0 .LBB0_325
	s_and_b64 vcc, exec, s[10:11]
	s_cbranch_vccz .LBB0_328
	s_barrier

.LBB0_562:
	ds_read_b128 v[40:43], v187
	ds_read_b128 v[44:47], v187 offset:1024
	ds_read_b128 v[56:59], v187 offset:2048
	ds_read_b128 v[60:63], v187 offset:3072
	ds_read_b128 v[168:171], v190
	ds_read_b128 v[172:175], v190 offset:1024
	ds_read_b128 v[192:195], v190 offset:2048
	ds_read_b128 v[196:199], v190 offset:3072
	s_add_u32 s28, s8, 0xfffc0080
	s_addc_u32 s29, s9, -1
	s_cmp_eq_u32 s66, 12
	s_cselect_b32 s63, s7, s29
	s_cselect_b32 s62, s10, s28
	s_cselect_b32 s61, s47, s65
	s_cselect_b32 s60, s51, s64
	v_lshl_add_u64 v[232:233], s[8:9], 0, v[160:161]
	s_add_i32 m0, s82, 0xc000
	ds_read_b128 v[200:203], v191
	ds_read_b128 v[204:207], v191 offset:1024
	ds_read_b128 v[208:211], v191 offset:2048
	ds_read_b128 v[212:215], v191 offset:3072
	ds_read_b128 v[216:219], v191 offset:4096
	ds_read_b128 v[220:223], v191 offset:5120
	ds_read_b128 v[224:227], v191 offset:6144
	ds_read_b128 v[228:231], v191 offset:7168
	global_load_lds_dwordx4 v[232:233], off
	v_lshl_add_u64 v[232:233], s[8:9], 0, v[162:163]
	s_add_i32 m0, s82, 0xe000
	s_nop 0
	global_load_lds_dwordx4 v[232:233], off
	s_waitcnt vmcnt(8)
	s_waitcnt lgkmcnt(0)
	s_nop 0
	s_barrier
	s_waitcnt lgkmcnt(0)
	v_mfma_f32_16x16x32_bf16 v[140:143], v[40:43], v[200:203], v[140:143]
	v_mfma_f32_16x16x32_bf16 v[136:139], v[56:59], v[200:203], v[136:139]
	v_mfma_f32_16x16x32_bf16 v[124:127], v[40:43], v[208:211], v[124:127]
	v_mfma_f32_16x16x32_bf16 v[120:123], v[56:59], v[208:211], v[120:123]
	v_mfma_f32_16x16x32_bf16 v[108:111], v[40:43], v[216:219], v[108:111]
	v_mfma_f32_16x16x32_bf16 v[104:107], v[56:59], v[216:219], v[104:107]
	v_mfma_f32_16x16x32_bf16 v[92:95], v[40:43], v[224:227], v[92:95]
	v_mfma_f32_16x16x32_bf16 v[88:91], v[56:59], v[224:227], v[88:91]
	v_mfma_f32_16x16x32_bf16 v[140:143], v[44:47], v[204:207], v[140:143]
	v_mfma_f32_16x16x32_bf16 v[136:139], v[60:63], v[204:207], v[136:139]
	v_mfma_f32_16x16x32_bf16 v[124:127], v[44:47], v[212:215], v[124:127]
	v_mfma_f32_16x16x32_bf16 v[120:123], v[60:63], v[212:215], v[120:123]
	v_mfma_f32_16x16x32_bf16 v[108:111], v[44:47], v[220:223], v[108:111]
	v_mfma_f32_16x16x32_bf16 v[104:107], v[60:63], v[220:223], v[104:107]
	v_mfma_f32_16x16x32_bf16 v[92:95], v[44:47], v[228:231], v[92:95]
	v_mfma_f32_16x16x32_bf16 v[88:91], v[60:63], v[228:231], v[88:91]
	v_mfma_f32_16x16x32_bf16 v[132:135], v[168:171], v[200:203], v[132:135]
	v_mfma_f32_16x16x32_bf16 v[128:131], v[192:195], v[200:203], v[128:131]
	v_mfma_f32_16x16x32_bf16 v[116:119], v[168:171], v[208:211], v[116:119]
	v_mfma_f32_16x16x32_bf16 v[112:115], v[192:195], v[208:211], v[112:115]
	v_mfma_f32_16x16x32_bf16 v[100:103], v[168:171], v[216:219], v[100:103]
	v_mfma_f32_16x16x32_bf16 v[96:99], v[192:195], v[216:219], v[96:99]
	v_mfma_f32_16x16x32_bf16 v[84:87], v[168:171], v[224:227], v[84:87]
	v_mfma_f32_16x16x32_bf16 v[80:83], v[192:195], v[224:227], v[80:83]
	v_mfma_f32_16x16x32_bf16 v[132:135], v[172:175], v[204:207], v[132:135]
	v_mfma_f32_16x16x32_bf16 v[128:131], v[196:199], v[204:207], v[128:131]
	v_mfma_f32_16x16x32_bf16 v[116:119], v[172:175], v[212:215], v[116:119]
	v_mfma_f32_16x16x32_bf16 v[112:115], v[196:199], v[212:215], v[112:115]
	v_mfma_f32_16x16x32_bf16 v[100:103], v[172:175], v[220:223], v[100:103]
	v_mfma_f32_16x16x32_bf16 v[96:99], v[196:199], v[220:223], v[96:99]
	v_mfma_f32_16x16x32_bf16 v[84:87], v[172:175], v[228:231], v[84:87]
	v_mfma_f32_16x16x32_bf16 v[80:83], v[196:199], v[228:231], v[80:83]
	s_barrier
	s_add_i32 s28, s13, s41
	v_lshl_add_u64 v[232:233], s[60:61], 0, v[146:147]
	s_mov_b32 m0, s28
	ds_read_b128 v[200:203], v191 offset:16384
	ds_read_b128 v[204:207], v191 offset:17408
	ds_read_b128 v[208:211], v191 offset:18432
	ds_read_b128 v[212:215], v191 offset:19456
	ds_read_b128 v[216:219], v191 offset:20480
	ds_read_b128 v[220:223], v191 offset:21504
	ds_read_b128 v[224:227], v191 offset:22528
	ds_read_b128 v[228:231], v191 offset:23552
	global_load_lds_dwordx4 v[232:233], off
	s_add_i32 m0, s28, 0x2000
	s_add_u32 s28, s60, 0x40000
	v_lshl_add_u64 v[234:235], s[60:61], 0, v[150:151]
	s_addc_u32 s29, s61, 0
	s_add_i32 s33, s34, s41
	global_load_lds_dwordx4 v[234:235], off
	v_lshl_add_u64 v[236:237], s[28:29], 0, v[146:147]
	s_mov_b32 m0, s33
	v_lshl_add_u64 v[238:239], s[62:63], 0, v[148:149]
	global_load_lds_dwordx4 v[236:237], off
	v_lshl_add_u64 v[236:237], s[28:29], 0, v[150:151]
	s_add_i32 m0, s33, 0x2000
	s_nop 0
	global_load_lds_dwordx4 v[236:237], off
	v_lshl_add_u64 v[236:237], s[62:63], 0, v[144:145]
	s_mov_b32 m0, s82
	s_nop 0
	global_load_lds_dwordx4 v[236:237], off
	s_mov_b32 m0, s83
	s_nop 0
	global_load_lds_dwordx4 v[238:239], off
	s_waitcnt vmcnt(8)
	s_waitcnt lgkmcnt(0)
	s_nop 0
	s_barrier
	s_waitcnt lgkmcnt(0)
	v_mfma_f32_16x16x32_bf16 v[76:79], v[40:43], v[200:203], v[76:79]
	v_mfma_f32_16x16x32_bf16 v[72:75], v[56:59], v[200:203], v[72:75]
	v_mfma_f32_16x16x32_bf16 v[52:55], v[40:43], v[208:211], v[52:55]
	v_mfma_f32_16x16x32_bf16 v[48:51], v[56:59], v[208:211], v[48:51]
	v_mfma_f32_16x16x32_bf16 v[28:31], v[40:43], v[216:219], v[28:31]
	v_mfma_f32_16x16x32_bf16 v[24:27], v[56:59], v[216:219], v[24:27]
	v_mfma_f32_16x16x32_bf16 v[12:15], v[40:43], v[224:227], v[12:15]
	v_mfma_f32_16x16x32_bf16 v[8:11], v[56:59], v[224:227], v[8:11]
	v_mfma_f32_16x16x32_bf16 v[76:79], v[44:47], v[204:207], v[76:79]
	v_mfma_f32_16x16x32_bf16 v[72:75], v[60:63], v[204:207], v[72:75]
	v_mfma_f32_16x16x32_bf16 v[52:55], v[44:47], v[212:215], v[52:55]
	v_mfma_f32_16x16x32_bf16 v[48:51], v[60:63], v[212:215], v[48:51]
	v_mfma_f32_16x16x32_bf16 v[28:31], v[44:47], v[220:223], v[28:31]
	v_mfma_f32_16x16x32_bf16 v[24:27], v[60:63], v[220:223], v[24:27]
	v_mfma_f32_16x16x32_bf16 v[12:15], v[44:47], v[228:231], v[12:15]
	v_mfma_f32_16x16x32_bf16 v[8:11], v[60:63], v[228:231], v[8:11]
	v_mfma_f32_16x16x32_bf16 v[36:39], v[168:171], v[208:211], v[36:39]
	v_mfma_f32_16x16x32_bf16 v[32:35], v[192:195], v[208:211], v[32:35]
	v_mfma_f32_16x16x32_bf16 v[20:23], v[168:171], v[216:219], v[20:23]
	v_mfma_f32_16x16x32_bf16 v[16:19], v[192:195], v[216:219], v[16:19]
	v_mfma_f32_16x16x32_bf16 v[4:7], v[168:171], v[224:227], v[4:7]
	v_mfma_f32_16x16x32_bf16 v[0:3], v[192:195], v[224:227], v[0:3]
	v_mfma_f32_16x16x32_bf16 v[40:43], v[168:171], v[200:203], v[68:71]
	v_mfma_f32_16x16x32_bf16 v[44:47], v[192:195], v[200:203], v[64:67]
	v_mfma_f32_16x16x32_bf16 v[36:39], v[172:175], v[212:215], v[36:39]
	v_mfma_f32_16x16x32_bf16 v[32:35], v[196:199], v[212:215], v[32:35]
	v_mfma_f32_16x16x32_bf16 v[20:23], v[172:175], v[220:223], v[20:23]
	v_mfma_f32_16x16x32_bf16 v[16:19], v[196:199], v[220:223], v[16:19]
	v_mfma_f32_16x16x32_bf16 v[4:7], v[172:175], v[228:231], v[4:7]
	v_mfma_f32_16x16x32_bf16 v[0:3], v[196:199], v[228:231], v[0:3]
	v_mfma_f32_16x16x32_bf16 v[40:43], v[172:175], v[204:207], v[40:43]
	v_mfma_f32_16x16x32_bf16 v[44:47], v[196:199], v[204:207], v[44:47]
	s_barrier
	s_add_i32 s33, 0, 0x18000
	s_add_i32 s56, 0, 0x1c000
	v_add_u32_e32 v68, s33, v176
	v_add_u32_e32 v152, s56, v176
	ds_read_b128 v[56:59], v68
	ds_read_b128 v[60:63], v68 offset:1024
	ds_read_b128 v[64:67], v68 offset:2048
	ds_read_b128 v[68:71], v68 offset:3072
	ds_read_b128 v[168:171], v152
	ds_read_b128 v[172:175], v152 offset:1024
	ds_read_b128 v[192:195], v152 offset:2048
	ds_read_b128 v[196:199], v152 offset:3072
	s_add_u32 s28, s62, 0x40000
	s_addc_u32 s29, s63, 0
	s_mov_b32 m0, s92
	v_lshl_add_u64 v[240:241], s[28:29], 0, v[144:145]
	ds_read_b128 v[200:203], v191 offset:32768
	ds_read_b128 v[204:207], v191 offset:33792
	ds_read_b128 v[208:211], v191 offset:34816
	ds_read_b128 v[212:215], v191 offset:35840
	ds_read_b128 v[216:219], v191 offset:36864
	ds_read_b128 v[220:223], v191 offset:37888
	ds_read_b128 v[224:227], v191 offset:38912
	ds_read_b128 v[228:231], v191 offset:39936
	global_load_lds_dwordx4 v[240:241], off
	v_lshl_add_u64 v[240:241], s[28:29], 0, v[148:149]
	s_mov_b32 m0, s93
	s_nop 0
	global_load_lds_dwordx4 v[240:241], off
	s_waitcnt vmcnt(8)
	s_waitcnt lgkmcnt(0)
	s_nop 0
	s_barrier
	s_waitcnt lgkmcnt(0)
	v_mfma_f32_16x16x32_bf16 v[140:143], v[56:59], v[200:203], v[140:143]
	v_mfma_f32_16x16x32_bf16 v[136:139], v[64:67], v[200:203], v[136:139]
	v_mfma_f32_16x16x32_bf16 v[124:127], v[56:59], v[208:211], v[124:127]
	v_mfma_f32_16x16x32_bf16 v[120:123], v[64:67], v[208:211], v[120:123]
	v_mfma_f32_16x16x32_bf16 v[108:111], v[56:59], v[216:219], v[108:111]
	v_mfma_f32_16x16x32_bf16 v[104:107], v[64:67], v[216:219], v[104:107]
	v_mfma_f32_16x16x32_bf16 v[92:95], v[56:59], v[224:227], v[92:95]
	v_mfma_f32_16x16x32_bf16 v[88:91], v[64:67], v[224:227], v[88:91]
	v_mfma_f32_16x16x32_bf16 v[140:143], v[60:63], v[204:207], v[140:143]
	v_mfma_f32_16x16x32_bf16 v[136:139], v[68:71], v[204:207], v[136:139]
	v_mfma_f32_16x16x32_bf16 v[124:127], v[60:63], v[212:215], v[124:127]
	v_mfma_f32_16x16x32_bf16 v[120:123], v[68:71], v[212:215], v[120:123]
	v_mfma_f32_16x16x32_bf16 v[108:111], v[60:63], v[220:223], v[108:111]
	v_mfma_f32_16x16x32_bf16 v[104:107], v[68:71], v[220:223], v[104:107]
	v_mfma_f32_16x16x32_bf16 v[92:95], v[60:63], v[228:231], v[92:95]
	v_mfma_f32_16x16x32_bf16 v[88:91], v[68:71], v[228:231], v[88:91]
	v_mfma_f32_16x16x32_bf16 v[132:135], v[168:171], v[200:203], v[132:135]
	v_mfma_f32_16x16x32_bf16 v[128:131], v[192:195], v[200:203], v[128:131]
	v_mfma_f32_16x16x32_bf16 v[116:119], v[168:171], v[208:211], v[116:119]
	v_mfma_f32_16x16x32_bf16 v[112:115], v[192:195], v[208:211], v[112:115]
	v_mfma_f32_16x16x32_bf16 v[100:103], v[168:171], v[216:219], v[100:103]
	v_mfma_f32_16x16x32_bf16 v[96:99], v[192:195], v[216:219], v[96:99]
	v_mfma_f32_16x16x32_bf16 v[84:87], v[168:171], v[224:227], v[84:87]
	v_mfma_f32_16x16x32_bf16 v[80:83], v[192:195], v[224:227], v[80:83]
	v_mfma_f32_16x16x32_bf16 v[132:135], v[172:175], v[204:207], v[132:135]
	v_mfma_f32_16x16x32_bf16 v[128:131], v[196:199], v[204:207], v[128:131]
	v_mfma_f32_16x16x32_bf16 v[116:119], v[172:175], v[212:215], v[116:119]
	v_mfma_f32_16x16x32_bf16 v[112:115], v[196:199], v[212:215], v[112:115]
	v_mfma_f32_16x16x32_bf16 v[100:103], v[172:175], v[220:223], v[100:103]
	v_mfma_f32_16x16x32_bf16 v[96:99], v[196:199], v[220:223], v[96:99]
	v_mfma_f32_16x16x32_bf16 v[84:87], v[172:175], v[228:231], v[84:87]
	v_mfma_f32_16x16x32_bf16 v[80:83], v[196:199], v[228:231], v[80:83]
	s_barrier
	s_add_i32 s28, s33, s41
	v_lshl_add_u64 v[232:233], v[232:233], 0, s[16:17]
	s_mov_b32 m0, s28
	ds_read_b128 v[200:203], v191 offset:49152
	ds_read_b128 v[204:207], v191 offset:50176
	ds_read_b128 v[208:211], v191 offset:51200
	ds_read_b128 v[212:215], v191 offset:52224
	ds_read_b128 v[216:219], v191 offset:53248
	ds_read_b128 v[220:223], v191 offset:54272
	ds_read_b128 v[224:227], v191 offset:55296
	ds_read_b128 v[228:231], v191 offset:56320
	global_load_lds_dwordx4 v[232:233], off
	s_add_i32 m0, s28, 0x2000
	s_add_u32 s28, s60, 0x40080
	v_lshl_add_u64 v[232:233], v[234:235], 0, s[16:17]
	s_addc_u32 s29, s61, 0
	s_add_i32 s33, s56, s41
	global_load_lds_dwordx4 v[232:233], off
	v_lshl_add_u64 v[232:233], s[28:29], 0, v[146:147]
	s_mov_b32 m0, s33
	s_nop 0
	global_load_lds_dwordx4 v[232:233], off
	v_lshl_add_u64 v[232:233], s[28:29], 0, v[150:151]
	s_add_i32 m0, s33, 0x2000
	s_nop 0
	global_load_lds_dwordx4 v[232:233], off
	v_lshl_add_u64 v[232:233], v[236:237], 0, s[16:17]
	s_mov_b32 m0, s3
	s_nop 0
	global_load_lds_dwordx4 v[232:233], off
	v_lshl_add_u64 v[232:233], v[238:239], 0, s[16:17]
	s_mov_b32 m0, s78
	s_nop 0
	global_load_lds_dwordx4 v[232:233], off
	s_waitcnt vmcnt(8)
	s_waitcnt lgkmcnt(0)
	s_barrier
	s_waitcnt lgkmcnt(0)
	v_mfma_f32_16x16x32_bf16 v[76:79], v[56:59], v[200:203], v[76:79]
	v_mfma_f32_16x16x32_bf16 v[72:75], v[64:67], v[200:203], v[72:75]
	v_mfma_f32_16x16x32_bf16 v[52:55], v[56:59], v[208:211], v[52:55]
	v_mfma_f32_16x16x32_bf16 v[48:51], v[64:67], v[208:211], v[48:51]
	v_mfma_f32_16x16x32_bf16 v[28:31], v[56:59], v[216:219], v[28:31]
	v_mfma_f32_16x16x32_bf16 v[24:27], v[64:67], v[216:219], v[24:27]
	v_mfma_f32_16x16x32_bf16 v[12:15], v[56:59], v[224:227], v[12:15]
	v_mfma_f32_16x16x32_bf16 v[8:11], v[64:67], v[224:227], v[8:11]
	v_mfma_f32_16x16x32_bf16 v[76:79], v[60:63], v[204:207], v[76:79]
	v_mfma_f32_16x16x32_bf16 v[72:75], v[68:71], v[204:207], v[72:75]
	v_mfma_f32_16x16x32_bf16 v[52:55], v[60:63], v[212:215], v[52:55]
	v_mfma_f32_16x16x32_bf16 v[48:51], v[68:71], v[212:215], v[48:51]
	v_mfma_f32_16x16x32_bf16 v[28:31], v[60:63], v[220:223], v[28:31]
	v_mfma_f32_16x16x32_bf16 v[24:27], v[68:71], v[220:223], v[24:27]
	v_mfma_f32_16x16x32_bf16 v[12:15], v[60:63], v[228:231], v[12:15]
	v_mfma_f32_16x16x32_bf16 v[8:11], v[68:71], v[228:231], v[8:11]
	v_mfma_f32_16x16x32_bf16 v[40:43], v[168:171], v[200:203], v[40:43]
	v_mfma_f32_16x16x32_bf16 v[68:71], v[172:175], v[204:207], v[40:43]
	v_mfma_f32_16x16x32_bf16 v[40:43], v[192:195], v[200:203], v[44:47]
	v_mfma_f32_16x16x32_bf16 v[36:39], v[168:171], v[208:211], v[36:39]
	v_mfma_f32_16x16x32_bf16 v[32:35], v[192:195], v[208:211], v[32:35]
	v_mfma_f32_16x16x32_bf16 v[20:23], v[168:171], v[216:219], v[20:23]
	v_mfma_f32_16x16x32_bf16 v[16:19], v[192:195], v[216:219], v[16:19]
	v_mfma_f32_16x16x32_bf16 v[4:7], v[168:171], v[224:227], v[4:7]
	v_mfma_f32_16x16x32_bf16 v[0:3], v[192:195], v[224:227], v[0:3]
	v_mfma_f32_16x16x32_bf16 v[64:67], v[196:199], v[204:207], v[40:43]
	v_mfma_f32_16x16x32_bf16 v[36:39], v[172:175], v[212:215], v[36:39]
	v_mfma_f32_16x16x32_bf16 v[32:35], v[196:199], v[212:215], v[32:35]
	v_mfma_f32_16x16x32_bf16 v[20:23], v[172:175], v[220:223], v[20:23]
	v_mfma_f32_16x16x32_bf16 v[16:19], v[196:199], v[220:223], v[16:19]
	v_mfma_f32_16x16x32_bf16 v[4:7], v[172:175], v[228:231], v[4:7]
	v_mfma_f32_16x16x32_bf16 v[0:3], v[196:199], v[228:231], v[0:3]
	s_barrier
	s_add_i32 s66, s66, 2
	s_add_u32 s8, s8, 0x100
	s_addc_u32 s9, s9, 0
	s_add_u32 s64, s64, 0x100
	s_addc_u32 s65, s65, 0
	s_cmp_gt_u32 s66, 13
	s_cbranch_scc0 .LBB0_562
	s_and_b64 vcc, exec, s[18:19]
	s_cbranch_vccz .LBB0_565
	s_barrier

.LBB0_859:
	s_add_u32 s16, s10, s14
	ds_read_b128 v[82:85], v79
	ds_read_b128 v[86:89], v79 offset:1024
	ds_read_b128 v[90:93], v79 offset:2048
	ds_read_b128 v[94:97], v79 offset:3072
	s_addc_u32 s17, s11, s15
	s_add_u32 s16, s16, 0xb000100
	s_addc_u32 s17, s17, 0
	s_add_u32 s28, s63, s14
	s_addc_u32 s29, s64, s15
	s_cmpk_eq_i32 s14, 0x300
	s_cselect_b32 s19, s7, s17
	s_cselect_b32 s18, s6, s16
	s_cselect_b32 s17, s5, s29
	s_cselect_b32 s16, s4, s28
	s_mov_b32 m0, s66
	v_lshl_add_u64 v[130:131], v[72:73], 0, s[14:15]
	ds_read_b128 v[98:101], v80
	ds_read_b128 v[102:105], v80 offset:1024
	ds_read_b128 v[106:109], v80 offset:2048
	ds_read_b128 v[110:113], v80 offset:3072
	ds_read_b128 v[114:117], v80 offset:4096
	ds_read_b128 v[118:121], v80 offset:5120
	ds_read_b128 v[122:125], v80 offset:6144
	ds_read_b128 v[126:129], v80 offset:7168
	global_load_lds_dwordx4 v[130:131], off
	v_lshl_add_u64 v[130:131], v[74:75], 0, s[14:15]
	s_mov_b32 m0, s67
	s_nop 0
	global_load_lds_dwordx4 v[130:131], off
	s_waitcnt vmcnt(8)
	s_waitcnt lgkmcnt(0)
	s_barrier
	s_waitcnt lgkmcnt(0)
	v_mfma_f32_16x16x32_bf16 v[60:63], v[82:85], v[98:101], v[60:63]
	v_mfma_f32_16x16x32_bf16 v[56:59], v[90:93], v[98:101], v[56:59]
	v_mfma_f32_16x16x32_bf16 v[52:55], v[82:85], v[106:109], v[52:55]
	v_mfma_f32_16x16x32_bf16 v[48:51], v[90:93], v[106:109], v[48:51]
	v_mfma_f32_16x16x32_bf16 v[44:47], v[82:85], v[114:117], v[44:47]
	v_mfma_f32_16x16x32_bf16 v[40:43], v[90:93], v[114:117], v[40:43]
	v_mfma_f32_16x16x32_bf16 v[36:39], v[82:85], v[122:125], v[36:39]
	v_mfma_f32_16x16x32_bf16 v[32:35], v[90:93], v[122:125], v[32:35]
	v_mfma_f32_16x16x32_bf16 v[60:63], v[86:89], v[102:105], v[60:63]
	v_mfma_f32_16x16x32_bf16 v[56:59], v[94:97], v[102:105], v[56:59]
	v_mfma_f32_16x16x32_bf16 v[52:55], v[86:89], v[110:113], v[52:55]
	v_mfma_f32_16x16x32_bf16 v[48:51], v[94:97], v[110:113], v[48:51]
	v_mfma_f32_16x16x32_bf16 v[44:47], v[86:89], v[118:121], v[44:47]
	v_mfma_f32_16x16x32_bf16 v[40:43], v[94:97], v[118:121], v[40:43]
	v_mfma_f32_16x16x32_bf16 v[36:39], v[86:89], v[126:129], v[36:39]
	v_mfma_f32_16x16x32_bf16 v[32:35], v[94:97], v[126:129], v[32:35]
	s_barrier
	s_mov_b32 m0, s76
	v_lshl_add_u64 v[130:131], s[16:17], 0, v[68:69]
	s_add_u32 s28, s16, 0x20000
	ds_read_b128 v[98:101], v80 offset:16384
	ds_read_b128 v[102:105], v80 offset:17408
	ds_read_b128 v[106:109], v80 offset:18432
	ds_read_b128 v[110:113], v80 offset:19456
	ds_read_b128 v[114:117], v80 offset:20480
	ds_read_b128 v[118:121], v80 offset:21504
	ds_read_b128 v[122:125], v80 offset:22528
	ds_read_b128 v[126:129], v80 offset:23552
	global_load_lds_dwordx4 v[130:131], off
	v_lshl_add_u64 v[132:133], s[16:17], 0, v[64:65]
	s_mov_b32 m0, s77
	s_addc_u32 s29, s17, 0
	global_load_lds_dwordx4 v[132:133], off
	v_lshl_add_u64 v[134:135], s[28:29], 0, v[68:69]
	s_mov_b32 m0, s35
	v_lshl_add_u64 v[136:137], s[18:19], 0, v[66:67]
	global_load_lds_dwordx4 v[134:135], off
	v_lshl_add_u64 v[134:135], s[28:29], 0, v[64:65]
	s_mov_b32 m0, s46
	s_nop 0
	global_load_lds_dwordx4 v[134:135], off
	v_lshl_add_u64 v[134:135], s[18:19], 0, v[70:71]
	s_mov_b32 m0, s1
	s_nop 0
	global_load_lds_dwordx4 v[134:135], off
	s_mov_b32 m0, s51
	s_nop 0
	global_load_lds_dwordx4 v[136:137], off
	s_waitcnt vmcnt(8)
	s_waitcnt lgkmcnt(0)
	s_nop 0
	s_barrier
	s_waitcnt lgkmcnt(0)
	v_mfma_f32_16x16x32_bf16 v[28:31], v[82:85], v[98:101], v[28:31]
	v_mfma_f32_16x16x32_bf16 v[24:27], v[90:93], v[98:101], v[24:27]
	v_mfma_f32_16x16x32_bf16 v[20:23], v[82:85], v[106:109], v[20:23]
	v_mfma_f32_16x16x32_bf16 v[16:19], v[90:93], v[106:109], v[16:19]
	v_mfma_f32_16x16x32_bf16 v[12:15], v[82:85], v[114:117], v[12:15]
	v_mfma_f32_16x16x32_bf16 v[8:11], v[90:93], v[114:117], v[8:11]
	v_mfma_f32_16x16x32_bf16 v[4:7], v[82:85], v[122:125], v[4:7]
	v_mfma_f32_16x16x32_bf16 v[0:3], v[90:93], v[122:125], v[0:3]
	v_mfma_f32_16x16x32_bf16 v[28:31], v[86:89], v[102:105], v[28:31]
	v_mfma_f32_16x16x32_bf16 v[24:27], v[94:97], v[102:105], v[24:27]
	v_mfma_f32_16x16x32_bf16 v[20:23], v[86:89], v[110:113], v[20:23]
	v_mfma_f32_16x16x32_bf16 v[16:19], v[94:97], v[110:113], v[16:19]
	v_mfma_f32_16x16x32_bf16 v[12:15], v[86:89], v[118:121], v[12:15]
	v_mfma_f32_16x16x32_bf16 v[8:11], v[94:97], v[118:121], v[8:11]
	v_mfma_f32_16x16x32_bf16 v[4:7], v[86:89], v[126:129], v[4:7]
	v_mfma_f32_16x16x32_bf16 v[0:3], v[94:97], v[126:129], v[0:3]
	s_barrier
	ds_read_b128 v[82:85], v81
	ds_read_b128 v[86:89], v81 offset:1024
	ds_read_b128 v[90:93], v81 offset:2048
	ds_read_b128 v[94:97], v81 offset:3072
	s_add_u32 s18, s18, 0x28000
	s_addc_u32 s19, s19, 0
	s_mov_b32 m0, s52
	v_lshl_add_u64 v[138:139], s[18:19], 0, v[70:71]
	ds_read_b128 v[98:101], v80 offset:32768
	ds_read_b128 v[102:105], v80 offset:33792
	ds_read_b128 v[106:109], v80 offset:34816
	ds_read_b128 v[110:113], v80 offset:35840
	ds_read_b128 v[114:117], v80 offset:36864
	ds_read_b128 v[118:121], v80 offset:37888
	ds_read_b128 v[122:125], v80 offset:38912
	ds_read_b128 v[126:129], v80 offset:39936
	global_load_lds_dwordx4 v[138:139], off
	v_lshl_add_u64 v[138:139], s[18:19], 0, v[66:67]
	s_mov_b32 m0, s53
	s_nop 0
	global_load_lds_dwordx4 v[138:139], off
	s_waitcnt vmcnt(8)
	s_waitcnt lgkmcnt(0)
	s_nop 0
	s_barrier
	s_waitcnt lgkmcnt(0)
	v_mfma_f32_16x16x32_bf16 v[60:63], v[82:85], v[98:101], v[60:63]
	v_mfma_f32_16x16x32_bf16 v[56:59], v[90:93], v[98:101], v[56:59]
	v_mfma_f32_16x16x32_bf16 v[52:55], v[82:85], v[106:109], v[52:55]
	v_mfma_f32_16x16x32_bf16 v[48:51], v[90:93], v[106:109], v[48:51]
	v_mfma_f32_16x16x32_bf16 v[44:47], v[82:85], v[114:117], v[44:47]
	v_mfma_f32_16x16x32_bf16 v[40:43], v[90:93], v[114:117], v[40:43]
	v_mfma_f32_16x16x32_bf16 v[36:39], v[82:85], v[122:125], v[36:39]
	v_mfma_f32_16x16x32_bf16 v[32:35], v[90:93], v[122:125], v[32:35]
	v_mfma_f32_16x16x32_bf16 v[60:63], v[86:89], v[102:105], v[60:63]
	v_mfma_f32_16x16x32_bf16 v[56:59], v[94:97], v[102:105], v[56:59]
	v_mfma_f32_16x16x32_bf16 v[52:55], v[86:89], v[110:113], v[52:55]
	v_mfma_f32_16x16x32_bf16 v[48:51], v[94:97], v[110:113], v[48:51]
	v_mfma_f32_16x16x32_bf16 v[44:47], v[86:89], v[118:121], v[44:47]
	v_mfma_f32_16x16x32_bf16 v[40:43], v[94:97], v[118:121], v[40:43]
	v_mfma_f32_16x16x32_bf16 v[36:39], v[86:89], v[126:129], v[36:39]
	v_mfma_f32_16x16x32_bf16 v[32:35], v[94:97], v[126:129], v[32:35]
	s_barrier
	s_mov_b32 m0, s78
	v_lshl_add_u64 v[130:131], v[130:131], 0, s[8:9]
	s_add_u32 s16, s16, 0x20080
	ds_read_b128 v[98:101], v80 offset:49152
	ds_read_b128 v[102:105], v80 offset:50176
	ds_read_b128 v[106:109], v80 offset:51200
	ds_read_b128 v[110:113], v80 offset:52224
	ds_read_b128 v[114:117], v80 offset:53248
	ds_read_b128 v[118:121], v80 offset:54272
	ds_read_b128 v[122:125], v80 offset:55296
	ds_read_b128 v[126:129], v80 offset:56320
	global_load_lds_dwordx4 v[130:131], off
	v_lshl_add_u64 v[130:131], v[132:133], 0, s[8:9]
	s_mov_b32 m0, s79
	s_addc_u32 s17, s17, 0
	global_load_lds_dwordx4 v[130:131], off
	v_lshl_add_u64 v[130:131], s[16:17], 0, v[68:69]
	s_mov_b32 m0, s61
	s_nop 0
	global_load_lds_dwordx4 v[130:131], off
	v_lshl_add_u64 v[130:131], s[16:17], 0, v[64:65]
	s_mov_b32 m0, s62
	s_nop 0
	global_load_lds_dwordx4 v[130:131], off
	v_lshl_add_u64 v[130:131], v[134:135], 0, s[8:9]
	s_mov_b32 m0, s55
	s_nop 0
	global_load_lds_dwordx4 v[130:131], off
	v_lshl_add_u64 v[130:131], v[136:137], 0, s[8:9]
	s_mov_b32 m0, s60
	s_nop 0
	global_load_lds_dwordx4 v[130:131], off
	s_waitcnt vmcnt(8)
	s_waitcnt lgkmcnt(0)
	s_barrier
	s_waitcnt lgkmcnt(0)
	v_mfma_f32_16x16x32_bf16 v[28:31], v[82:85], v[98:101], v[28:31]
	v_mfma_f32_16x16x32_bf16 v[24:27], v[90:93], v[98:101], v[24:27]
	v_mfma_f32_16x16x32_bf16 v[20:23], v[82:85], v[106:109], v[20:23]
	v_mfma_f32_16x16x32_bf16 v[16:19], v[90:93], v[106:109], v[16:19]
	v_mfma_f32_16x16x32_bf16 v[12:15], v[82:85], v[114:117], v[12:15]
	v_mfma_f32_16x16x32_bf16 v[8:11], v[90:93], v[114:117], v[8:11]
	v_mfma_f32_16x16x32_bf16 v[4:7], v[82:85], v[122:125], v[4:7]
	v_mfma_f32_16x16x32_bf16 v[0:3], v[90:93], v[122:125], v[0:3]
	v_mfma_f32_16x16x32_bf16 v[28:31], v[86:89], v[102:105], v[28:31]
	v_mfma_f32_16x16x32_bf16 v[24:27], v[94:97], v[102:105], v[24:27]
	v_mfma_f32_16x16x32_bf16 v[20:23], v[86:89], v[110:113], v[20:23]
	v_mfma_f32_16x16x32_bf16 v[16:19], v[94:97], v[110:113], v[16:19]
	v_mfma_f32_16x16x32_bf16 v[12:15], v[86:89], v[118:121], v[12:15]
	v_mfma_f32_16x16x32_bf16 v[8:11], v[94:97], v[118:121], v[8:11]
	v_mfma_f32_16x16x32_bf16 v[4:7], v[86:89], v[126:129], v[4:7]
	v_mfma_f32_16x16x32_bf16 v[0:3], v[94:97], v[126:129], v[0:3]
	s_barrier
	s_add_i32 s65, s65, 2
	s_add_u32 s14, s14, 0x100
	s_addc_u32 s15, s15, 0
	s_cmp_lt_u32 s65, 6
	s_cbranch_scc1 .LBB0_859
	s_waitcnt vmcnt(0)
	s_cmpk_gt_u32 s13, 0xff
	s_cbranch_scc1 .LBB0_862
	s_barrier

.LBB0_871:
	s_add_u32 s33, s42, s52
	s_addc_u32 s56, s43, s53
	s_add_u32 s54, s33, 0x100
	s_addc_u32 s55, s56, 0
	s_and_b64 s[28:29], s[50:51], exec
	s_cselect_b32 s55, s81, s55
	s_cselect_b32 s54, s82, s54
	s_add_u32 s28, s18, s52
	s_addc_u32 s29, s19, s53
	s_add_u32 s52, s28, 0x100
	s_addc_u32 s53, s29, 0
	s_and_b64 s[28:29], s[50:51], exec
	s_cselect_b32 s61, s83, s53
	s_cselect_b32 s60, s84, s52
	s_add_u32 s64, s33, 0x20080
	ds_read_b128 v[128:131], v192
	ds_read_b128 v[132:135], v192 offset:1024
	ds_read_b128 v[136:139], v192 offset:2048
	ds_read_b128 v[140:143], v192 offset:3072
	ds_read_b128 v[144:147], v193
	ds_read_b128 v[148:151], v193 offset:1024
	ds_read_b128 v[152:155], v193 offset:2048
	ds_read_b128 v[156:159], v193 offset:3072
	s_addc_u32 s65, s56, 0
	s_add_i32 s97, s77, s13
	s_add_i32 s29, s1, 0xe000
	s_add_i32 s28, s97, 0x2000
	s_add_u32 s62, s60, 0x20000
	s_addc_u32 s63, s61, 0
	s_add_i32 vcc_hi, s78, s13
	s_add_i32 vcc_lo, vcc_hi, 0x2000
	s_add_i32 s96, 0, 0x18000
	s_add_i32 s95, 0, 0x1c000
	s_add_u32 s52, s54, 0x20000
	s_addc_u32 s53, s55, 0
	s_add_i32 s94, s96, s13
	s_add_i32 s92, s94, 0x2000
	s_add_u32 s50, s60, 0x20080
	s_addc_u32 s51, s61, 0
	s_add_i32 s93, s95, s13
	s_add_i32 s85, s93, 0x2000
	s_mov_b32 m0, s79
	v_lshl_add_u64 v[186:187], s[64:65], 0, v[166:167]
	ds_read_b128 v[196:199], v194
	ds_read_b128 v[200:203], v194 offset:1024
	ds_read_b128 v[204:207], v194 offset:2048
	ds_read_b128 v[208:211], v194 offset:3072
	ds_read_b128 v[212:215], v194 offset:4096
	ds_read_b128 v[216:219], v194 offset:5120
	ds_read_b128 v[220:223], v194 offset:6144
	ds_read_b128 v[224:227], v194 offset:7168
	global_load_lds_dwordx4 v[186:187], off
	v_lshl_add_u64 v[186:187], s[64:65], 0, v[162:163]
	s_mov_b32 m0, s29
	s_nop 0
	global_load_lds_dwordx4 v[186:187], off
	s_waitcnt vmcnt(8)
	s_waitcnt lgkmcnt(0)
	s_nop 0
	s_barrier
	s_waitcnt lgkmcnt(0)
	v_mfma_f32_16x16x32_bf16 v[124:127], v[128:131], v[196:199], v[124:127]
	v_mfma_f32_16x16x32_bf16 v[120:123], v[136:139], v[196:199], v[120:123]
	v_mfma_f32_16x16x32_bf16 v[116:119], v[128:131], v[204:207], v[116:119]
	v_mfma_f32_16x16x32_bf16 v[112:115], v[136:139], v[204:207], v[112:115]
	v_mfma_f32_16x16x32_bf16 v[108:111], v[128:131], v[212:215], v[108:111]
	v_mfma_f32_16x16x32_bf16 v[96:99], v[136:139], v[212:215], v[96:99]
	v_mfma_f32_16x16x32_bf16 v[76:79], v[128:131], v[220:223], v[76:79]
	v_mfma_f32_16x16x32_bf16 v[72:75], v[136:139], v[220:223], v[72:75]
	v_mfma_f32_16x16x32_bf16 v[124:127], v[132:135], v[200:203], v[124:127]
	v_mfma_f32_16x16x32_bf16 v[120:123], v[140:143], v[200:203], v[120:123]
	v_mfma_f32_16x16x32_bf16 v[116:119], v[132:135], v[208:211], v[116:119]
	v_mfma_f32_16x16x32_bf16 v[112:115], v[140:143], v[208:211], v[112:115]
	v_mfma_f32_16x16x32_bf16 v[108:111], v[132:135], v[216:219], v[108:111]
	v_mfma_f32_16x16x32_bf16 v[96:99], v[140:143], v[216:219], v[96:99]
	v_mfma_f32_16x16x32_bf16 v[76:79], v[132:135], v[224:227], v[76:79]
	v_mfma_f32_16x16x32_bf16 v[72:75], v[140:143], v[224:227], v[72:75]
	v_mfma_f32_16x16x32_bf16 v[104:107], v[144:147], v[196:199], v[104:107]
	v_mfma_f32_16x16x32_bf16 v[100:103], v[152:155], v[196:199], v[100:103]
	v_mfma_f32_16x16x32_bf16 v[92:95], v[144:147], v[204:207], v[92:95]
	v_mfma_f32_16x16x32_bf16 v[88:91], v[152:155], v[204:207], v[88:91]
	v_mfma_f32_16x16x32_bf16 v[84:87], v[144:147], v[212:215], v[84:87]
	v_mfma_f32_16x16x32_bf16 v[80:83], v[152:155], v[212:215], v[80:83]
	v_mfma_f32_16x16x32_bf16 v[68:71], v[144:147], v[220:223], v[68:71]
	v_mfma_f32_16x16x32_bf16 v[64:67], v[152:155], v[220:223], v[64:67]
	v_mfma_f32_16x16x32_bf16 v[104:107], v[148:151], v[200:203], v[104:107]
	v_mfma_f32_16x16x32_bf16 v[100:103], v[156:159], v[200:203], v[100:103]
	v_mfma_f32_16x16x32_bf16 v[92:95], v[148:151], v[208:211], v[92:95]
	v_mfma_f32_16x16x32_bf16 v[88:91], v[156:159], v[208:211], v[88:91]
	v_mfma_f32_16x16x32_bf16 v[84:87], v[148:151], v[216:219], v[84:87]
	v_mfma_f32_16x16x32_bf16 v[80:83], v[156:159], v[216:219], v[80:83]
	v_mfma_f32_16x16x32_bf16 v[68:71], v[148:151], v[224:227], v[68:71]
	v_mfma_f32_16x16x32_bf16 v[64:67], v[156:159], v[224:227], v[64:67]
	s_barrier
	s_mov_b32 m0, s97
	v_lshl_add_u64 v[186:187], s[60:61], 0, v[164:165]
	ds_read_b128 v[196:199], v194 offset:16384
	ds_read_b128 v[200:203], v194 offset:17408
	ds_read_b128 v[204:207], v194 offset:18432
	ds_read_b128 v[208:211], v194 offset:19456
	ds_read_b128 v[212:215], v194 offset:20480
	ds_read_b128 v[216:219], v194 offset:21504
	ds_read_b128 v[220:223], v194 offset:22528
	ds_read_b128 v[224:227], v194 offset:23552
	global_load_lds_dwordx4 v[186:187], off
	v_lshl_add_u64 v[228:229], s[60:61], 0, v[160:161]
	s_mov_b32 m0, s28
	v_lshl_add_u64 v[230:231], s[62:63], 0, v[164:165]
	global_load_lds_dwordx4 v[228:229], off
	s_mov_b32 m0, vcc_hi
	v_lshl_add_u64 v[232:233], s[54:55], 0, v[162:163]
	global_load_lds_dwordx4 v[230:231], off
	v_lshl_add_u64 v[230:231], s[62:63], 0, v[160:161]
	s_mov_b32 m0, vcc_lo
	s_nop 0
	global_load_lds_dwordx4 v[230:231], off
	v_lshl_add_u64 v[230:231], s[54:55], 0, v[166:167]
	s_mov_b32 m0, s1
	s_nop 0
	global_load_lds_dwordx4 v[230:231], off
	s_mov_b32 m0, s34
	s_nop 0
	global_load_lds_dwordx4 v[232:233], off
	s_waitcnt vmcnt(8)
	s_waitcnt lgkmcnt(0)
	s_barrier
	s_waitcnt lgkmcnt(0)
	v_mfma_f32_16x16x32_bf16 v[60:63], v[128:131], v[196:199], v[60:63]
	v_mfma_f32_16x16x32_bf16 v[56:59], v[136:139], v[196:199], v[56:59]
	v_mfma_f32_16x16x32_bf16 v[48:51], v[128:131], v[204:207], v[48:51]
	v_mfma_f32_16x16x32_bf16 v[40:43], v[136:139], v[204:207], v[40:43]
	v_mfma_f32_16x16x32_bf16 v[32:35], v[128:131], v[212:215], v[32:35]
	v_mfma_f32_16x16x32_bf16 v[24:27], v[136:139], v[212:215], v[24:27]
	v_mfma_f32_16x16x32_bf16 v[16:19], v[128:131], v[220:223], v[16:19]
	v_mfma_f32_16x16x32_bf16 v[8:11], v[136:139], v[220:223], v[8:11]
	v_mfma_f32_16x16x32_bf16 v[60:63], v[132:135], v[200:203], v[60:63]
	v_mfma_f32_16x16x32_bf16 v[56:59], v[140:143], v[200:203], v[56:59]
	v_mfma_f32_16x16x32_bf16 v[48:51], v[132:135], v[208:211], v[48:51]
	v_mfma_f32_16x16x32_bf16 v[40:43], v[140:143], v[208:211], v[40:43]
	v_mfma_f32_16x16x32_bf16 v[32:35], v[132:135], v[216:219], v[32:35]
	v_mfma_f32_16x16x32_bf16 v[24:27], v[140:143], v[216:219], v[24:27]
	v_mfma_f32_16x16x32_bf16 v[16:19], v[132:135], v[224:227], v[16:19]
	v_mfma_f32_16x16x32_bf16 v[8:11], v[140:143], v[224:227], v[8:11]
	v_mfma_f32_16x16x32_bf16 v[52:55], v[144:147], v[196:199], v[52:55]
	v_mfma_f32_16x16x32_bf16 v[44:47], v[152:155], v[196:199], v[44:47]
	v_mfma_f32_16x16x32_bf16 v[36:39], v[144:147], v[204:207], v[36:39]
	v_mfma_f32_16x16x32_bf16 v[28:31], v[152:155], v[204:207], v[28:31]
	v_mfma_f32_16x16x32_bf16 v[20:23], v[144:147], v[212:215], v[20:23]
	v_mfma_f32_16x16x32_bf16 v[12:15], v[152:155], v[212:215], v[12:15]
	v_mfma_f32_16x16x32_bf16 v[4:7], v[144:147], v[220:223], v[4:7]
	v_mfma_f32_16x16x32_bf16 v[0:3], v[152:155], v[220:223], v[0:3]
	v_mfma_f32_16x16x32_bf16 v[52:55], v[148:151], v[200:203], v[52:55]
	v_mfma_f32_16x16x32_bf16 v[44:47], v[156:159], v[200:203], v[44:47]
	v_mfma_f32_16x16x32_bf16 v[36:39], v[148:151], v[208:211], v[36:39]
	v_mfma_f32_16x16x32_bf16 v[28:31], v[156:159], v[208:211], v[28:31]
	v_mfma_f32_16x16x32_bf16 v[20:23], v[148:151], v[216:219], v[20:23]
	v_mfma_f32_16x16x32_bf16 v[12:15], v[156:159], v[216:219], v[12:15]
	v_mfma_f32_16x16x32_bf16 v[4:7], v[148:151], v[224:227], v[4:7]
	v_mfma_f32_16x16x32_bf16 v[0:3], v[156:159], v[224:227], v[0:3]
	s_barrier
	v_add_u32_e32 v140, s96, v190
	v_add_u32_e32 v156, s95, v190
	ds_read_b128 v[128:131], v140
	ds_read_b128 v[132:135], v140 offset:1024
	ds_read_b128 v[136:139], v140 offset:2048
	ds_read_b128 v[140:143], v140 offset:3072
	ds_read_b128 v[144:147], v156
	ds_read_b128 v[148:151], v156 offset:1024
	ds_read_b128 v[152:155], v156 offset:2048
	ds_read_b128 v[156:159], v156 offset:3072
	s_mov_b32 m0, s35
	v_lshl_add_u64 v[234:235], s[52:53], 0, v[166:167]
	ds_read_b128 v[196:199], v194 offset:32768
	ds_read_b128 v[200:203], v194 offset:33792
	ds_read_b128 v[204:207], v194 offset:34816
	ds_read_b128 v[208:211], v194 offset:35840
	ds_read_b128 v[212:215], v194 offset:36864
	ds_read_b128 v[216:219], v194 offset:37888
	ds_read_b128 v[220:223], v194 offset:38912
	ds_read_b128 v[224:227], v194 offset:39936
	global_load_lds_dwordx4 v[234:235], off
	v_lshl_add_u64 v[234:235], s[52:53], 0, v[162:163]
	s_mov_b32 m0, s66
	s_nop 0
	global_load_lds_dwordx4 v[234:235], off
	s_waitcnt vmcnt(8)
	s_waitcnt lgkmcnt(0)
	s_barrier
	s_waitcnt lgkmcnt(0)
	v_mfma_f32_16x16x32_bf16 v[124:127], v[128:131], v[196:199], v[124:127]
	v_mfma_f32_16x16x32_bf16 v[120:123], v[136:139], v[196:199], v[120:123]
	v_mfma_f32_16x16x32_bf16 v[116:119], v[128:131], v[204:207], v[116:119]
	v_mfma_f32_16x16x32_bf16 v[112:115], v[136:139], v[204:207], v[112:115]
	v_mfma_f32_16x16x32_bf16 v[108:111], v[128:131], v[212:215], v[108:111]
	v_mfma_f32_16x16x32_bf16 v[96:99], v[136:139], v[212:215], v[96:99]
	v_mfma_f32_16x16x32_bf16 v[76:79], v[128:131], v[220:223], v[76:79]
	v_mfma_f32_16x16x32_bf16 v[72:75], v[136:139], v[220:223], v[72:75]
	v_mfma_f32_16x16x32_bf16 v[124:127], v[132:135], v[200:203], v[124:127]
	v_mfma_f32_16x16x32_bf16 v[120:123], v[140:143], v[200:203], v[120:123]
	v_mfma_f32_16x16x32_bf16 v[116:119], v[132:135], v[208:211], v[116:119]
	v_mfma_f32_16x16x32_bf16 v[112:115], v[140:143], v[208:211], v[112:115]
	v_mfma_f32_16x16x32_bf16 v[108:111], v[132:135], v[216:219], v[108:111]
	v_mfma_f32_16x16x32_bf16 v[96:99], v[140:143], v[216:219], v[96:99]
	v_mfma_f32_16x16x32_bf16 v[76:79], v[132:135], v[224:227], v[76:79]
	v_mfma_f32_16x16x32_bf16 v[72:75], v[140:143], v[224:227], v[72:75]
	v_mfma_f32_16x16x32_bf16 v[104:107], v[144:147], v[196:199], v[104:107]
	v_mfma_f32_16x16x32_bf16 v[100:103], v[152:155], v[196:199], v[100:103]
	v_mfma_f32_16x16x32_bf16 v[92:95], v[144:147], v[204:207], v[92:95]
	v_mfma_f32_16x16x32_bf16 v[88:91], v[152:155], v[204:207], v[88:91]
	v_mfma_f32_16x16x32_bf16 v[84:87], v[144:147], v[212:215], v[84:87]
	v_mfma_f32_16x16x32_bf16 v[80:83], v[152:155], v[212:215], v[80:83]
	v_mfma_f32_16x16x32_bf16 v[68:71], v[144:147], v[220:223], v[68:71]
	v_mfma_f32_16x16x32_bf16 v[64:67], v[152:155], v[220:223], v[64:67]
	v_mfma_f32_16x16x32_bf16 v[104:107], v[148:151], v[200:203], v[104:107]
	v_mfma_f32_16x16x32_bf16 v[100:103], v[156:159], v[200:203], v[100:103]
	v_mfma_f32_16x16x32_bf16 v[92:95], v[148:151], v[208:211], v[92:95]
	v_mfma_f32_16x16x32_bf16 v[88:91], v[156:159], v[208:211], v[88:91]
	v_mfma_f32_16x16x32_bf16 v[84:87], v[148:151], v[216:219], v[84:87]
	v_mfma_f32_16x16x32_bf16 v[80:83], v[156:159], v[216:219], v[80:83]
	v_mfma_f32_16x16x32_bf16 v[68:71], v[148:151], v[224:227], v[68:71]
	v_mfma_f32_16x16x32_bf16 v[64:67], v[156:159], v[224:227], v[64:67]
	s_barrier
	s_mov_b32 m0, s94
	v_lshl_add_u64 v[186:187], v[186:187], 0, s[6:7]
	ds_read_b128 v[196:199], v194 offset:49152
	ds_read_b128 v[200:203], v194 offset:50176
	ds_read_b128 v[204:207], v194 offset:51200
	ds_read_b128 v[208:211], v194 offset:52224
	ds_read_b128 v[212:215], v194 offset:53248
	ds_read_b128 v[216:219], v194 offset:54272
	ds_read_b128 v[220:223], v194 offset:55296
	ds_read_b128 v[224:227], v194 offset:56320
	global_load_lds_dwordx4 v[186:187], off
	v_lshl_add_u64 v[186:187], v[228:229], 0, s[6:7]
	s_mov_b32 m0, s92
	s_nop 0
	global_load_lds_dwordx4 v[186:187], off
	v_lshl_add_u64 v[186:187], s[50:51], 0, v[164:165]
	s_mov_b32 m0, s93
	s_nop 0
	global_load_lds_dwordx4 v[186:187], off
	v_lshl_add_u64 v[186:187], s[50:51], 0, v[160:161]
	s_mov_b32 m0, s85
	s_nop 0
	global_load_lds_dwordx4 v[186:187], off
	v_lshl_add_u64 v[186:187], v[230:231], 0, s[6:7]
	s_mov_b32 m0, s67
	s_nop 0
	global_load_lds_dwordx4 v[186:187], off
	v_lshl_add_u64 v[186:187], v[232:233], 0, s[6:7]
	s_mov_b32 m0, s76
	s_nop 0
	global_load_lds_dwordx4 v[186:187], off
	s_waitcnt vmcnt(8)
	s_waitcnt lgkmcnt(0)
	s_barrier
	s_waitcnt lgkmcnt(0)
	v_mfma_f32_16x16x32_bf16 v[60:63], v[128:131], v[196:199], v[60:63]
	v_mfma_f32_16x16x32_bf16 v[56:59], v[136:139], v[196:199], v[56:59]
	v_mfma_f32_16x16x32_bf16 v[48:51], v[128:131], v[204:207], v[48:51]
	v_mfma_f32_16x16x32_bf16 v[40:43], v[136:139], v[204:207], v[40:43]
	v_mfma_f32_16x16x32_bf16 v[32:35], v[128:131], v[212:215], v[32:35]
	v_mfma_f32_16x16x32_bf16 v[24:27], v[136:139], v[212:215], v[24:27]
	v_mfma_f32_16x16x32_bf16 v[16:19], v[128:131], v[220:223], v[16:19]
	v_mfma_f32_16x16x32_bf16 v[8:11], v[136:139], v[220:223], v[8:11]
	v_mfma_f32_16x16x32_bf16 v[60:63], v[132:135], v[200:203], v[60:63]
	v_mfma_f32_16x16x32_bf16 v[56:59], v[140:143], v[200:203], v[56:59]
	v_mfma_f32_16x16x32_bf16 v[48:51], v[132:135], v[208:211], v[48:51]
	v_mfma_f32_16x16x32_bf16 v[40:43], v[140:143], v[208:211], v[40:43]
	v_mfma_f32_16x16x32_bf16 v[32:35], v[132:135], v[216:219], v[32:35]
	v_mfma_f32_16x16x32_bf16 v[24:27], v[140:143], v[216:219], v[24:27]
	v_mfma_f32_16x16x32_bf16 v[16:19], v[132:135], v[224:227], v[16:19]
	v_mfma_f32_16x16x32_bf16 v[8:11], v[140:143], v[224:227], v[8:11]
	v_mfma_f32_16x16x32_bf16 v[52:55], v[144:147], v[196:199], v[52:55]
	v_mfma_f32_16x16x32_bf16 v[44:47], v[152:155], v[196:199], v[44:47]
	v_mfma_f32_16x16x32_bf16 v[36:39], v[144:147], v[204:207], v[36:39]
	v_mfma_f32_16x16x32_bf16 v[28:31], v[152:155], v[204:207], v[28:31]
	v_mfma_f32_16x16x32_bf16 v[20:23], v[144:147], v[212:215], v[20:23]
	v_mfma_f32_16x16x32_bf16 v[12:15], v[152:155], v[212:215], v[12:15]
	v_mfma_f32_16x16x32_bf16 v[4:7], v[144:147], v[220:223], v[4:7]
	v_mfma_f32_16x16x32_bf16 v[0:3], v[152:155], v[220:223], v[0:3]
	v_mfma_f32_16x16x32_bf16 v[52:55], v[148:151], v[200:203], v[52:55]
	v_mfma_f32_16x16x32_bf16 v[44:47], v[156:159], v[200:203], v[44:47]
	v_mfma_f32_16x16x32_bf16 v[36:39], v[148:151], v[208:211], v[36:39]
	v_mfma_f32_16x16x32_bf16 v[28:31], v[156:159], v[208:211], v[28:31]
	v_mfma_f32_16x16x32_bf16 v[20:23], v[148:151], v[216:219], v[20:23]
	v_mfma_f32_16x16x32_bf16 v[12:15], v[156:159], v[216:219], v[12:15]
	v_mfma_f32_16x16x32_bf16 v[4:7], v[148:151], v[224:227], v[4:7]
	v_mfma_f32_16x16x32_bf16 v[0:3], v[156:159], v[224:227], v[0:3]
	s_barrier
	s_mov_b64 s[50:51], -1
	s_andn2_b64 vcc, exec, s[46:47]
	s_mov_b64 s[46:47], 0
	s_mov_b64 s[52:53], 0x100
	s_cbranch_vccz .LBB0_871
	v_or_b32_e32 v168, s80, v191
	v_readlane_b32 s48, v242, 16
	v_lshlrev_b64 v[136:137], 2, v[168:169]
	v_readlane_b32 s52, v242, 20
	v_readlane_b32 s53, v242, 21
	v_readlane_b32 s54, v242, 22
	v_readlane_b32 s55, v242, 23
	v_lshl_add_u64 v[128:129], s[52:53], 0, v[136:137]
	global_load_dwordx4 v[148:151], v[128:129], off
	global_load_dwordx4 v[144:147], v[128:129], off offset:16
	global_load_dwordx4 v[132:135], v[128:129], off offset:512
	s_nop 0
	global_load_dwordx4 v[128:131], v[128:129], off offset:528
	v_lshl_add_u64 v[136:137], s[54:55], 0, v[136:137]
	global_load_dwordx4 v[156:159], v[136:137], off
	global_load_dwordx4 v[152:155], v[136:137], off offset:16
	global_load_dwordx4 v[140:143], v[136:137], off offset:512
	s_nop 0
	global_load_dwordx4 v[136:139], v[136:137], off offset:528
	v_lshlrev_b64 v[186:187], 1, v[168:169]
	v_lshl_add_u64 v[196:197], v[170:171], 0, v[186:187]
	v_lshl_add_u64 v[198:199], v[172:173], 0, v[186:187]
	v_lshl_add_u64 v[200:201], v[174:175], 0, v[186:187]
	s_movk_i32 s80, 0x100
	s_and_b64 vcc, exec, s[14:15]
	s_mov_b64 s[18:19], s[10:11]
	s_mov_b64 s[42:43], s[16:17]
	v_readlane_b32 s49, v242, 17
	v_readlane_b32 s50, v242, 18
	v_readlane_b32 s51, v242, 19
	v_readlane_b32 s56, v242, 24
	v_readlane_b32 s57, v242, 25
	v_readlane_b32 s58, v242, 26
	v_readlane_b32 s59, v242, 27
	v_readlane_b32 s60, v242, 28
	v_readlane_b32 s61, v242, 29
	v_readlane_b32 s62, v242, 30
	v_readlane_b32 s63, v242, 31
	s_waitcnt vmcnt(0)
	v_pk_add_f32 v[126:127], v[126:127], v[150:151]
	v_pk_add_f32 v[124:125], v[124:125], v[148:149]
	v_pk_add_f32 v[122:123], v[122:123], v[146:147]
	v_pk_add_f32 v[120:121], v[120:121], v[144:145]
	v_pk_add_f32 v[82:83], v[82:83], v[130:131]
	v_pk_add_f32 v[80:81], v[80:81], v[128:129]
	v_pk_add_f32 v[106:107], v[106:107], v[134:135]
	v_pk_add_f32 v[104:105], v[104:105], v[132:133]
	v_pk_add_f32 v[102:103], v[102:103], v[130:131]
	v_pk_add_f32 v[100:101], v[100:101], v[128:129]
	v_pk_mul_f32 v[126:127], v[158:159], v[126:127]
	v_pk_mul_f32 v[124:125], v[156:157], v[124:125]
	v_pk_mul_f32 v[122:123], v[154:155], v[122:123]
	v_pk_mul_f32 v[120:121], v[152:153], v[120:121]
	v_pk_mul_f32 v[202:203], v[138:139], v[82:83]
	v_pk_mul_f32 v[204:205], v[136:137], v[80:81]
	v_cvt_pk_bf16_f32 v80, v124, v125
	v_cvt_pk_bf16_f32 v81, v126, v127
	v_cvt_pk_bf16_f32 v82, v120, v121
	v_cvt_pk_bf16_f32 v83, v122, v123
	v_pk_add_f32 v[118:119], v[118:119], v[150:151]
	v_pk_add_f32 v[116:117], v[116:117], v[148:149]
	v_pk_add_f32 v[114:115], v[114:115], v[146:147]
	v_pk_add_f32 v[112:113], v[112:113], v[144:145]
	v_pk_mul_f32 v[106:107], v[142:143], v[106:107]
	v_pk_mul_f32 v[104:105], v[140:141], v[104:105]
	v_pk_mul_f32 v[102:103], v[138:139], v[102:103]
	v_pk_mul_f32 v[100:101], v[136:137], v[100:101]
	global_store_dwordx4 v[196:197], v[80:83], off
	v_pk_add_f32 v[94:95], v[94:95], v[134:135]
	v_pk_add_f32 v[92:93], v[92:93], v[132:133]
	v_cvt_pk_bf16_f32 v80, v104, v105
	v_cvt_pk_bf16_f32 v81, v106, v107
	v_cvt_pk_bf16_f32 v82, v100, v101
	v_cvt_pk_bf16_f32 v83, v102, v103
	v_pk_add_f32 v[90:91], v[90:91], v[130:131]
	v_pk_add_f32 v[88:89], v[88:89], v[128:129]
	v_pk_mul_f32 v[118:119], v[158:159], v[118:119]
	v_pk_mul_f32 v[116:117], v[156:157], v[116:117]
	v_pk_mul_f32 v[114:115], v[154:155], v[114:115]
	v_pk_mul_f32 v[112:113], v[152:153], v[112:113]
	global_store_dwordx4 v[196:197], v[80:83], off offset:256
	v_pk_add_f32 v[110:111], v[110:111], v[150:151]
	v_pk_add_f32 v[108:109], v[108:109], v[148:149]
	v_cvt_pk_bf16_f32 v80, v116, v117
	v_cvt_pk_bf16_f32 v81, v118, v119
	v_cvt_pk_bf16_f32 v82, v112, v113
	v_cvt_pk_bf16_f32 v83, v114, v115
	v_pk_add_f32 v[98:99], v[98:99], v[146:147]
	v_pk_add_f32 v[96:97], v[96:97], v[144:145]
	v_pk_mul_f32 v[94:95], v[142:143], v[94:95]
	v_pk_mul_f32 v[92:93], v[140:141], v[92:93]
	v_pk_mul_f32 v[90:91], v[138:139], v[90:91]
	v_pk_mul_f32 v[88:89], v[136:137], v[88:89]
	global_store_dwordx4 v[198:199], v[80:83], off
	v_pk_add_f32 v[86:87], v[86:87], v[134:135]
	v_pk_add_f32 v[84:85], v[84:85], v[132:133]
	v_cvt_pk_bf16_f32 v80, v92, v93
	v_cvt_pk_bf16_f32 v81, v94, v95
	v_cvt_pk_bf16_f32 v82, v88, v89
	v_cvt_pk_bf16_f32 v83, v90, v91
	v_pk_mul_f32 v[110:111], v[158:159], v[110:111]
	v_pk_mul_f32 v[108:109], v[156:157], v[108:109]
	v_pk_mul_f32 v[98:99], v[154:155], v[98:99]
	v_pk_mul_f32 v[96:97], v[152:153], v[96:97]
	global_store_dwordx4 v[198:199], v[80:83], off offset:256
	v_pk_mul_f32 v[86:87], v[142:143], v[86:87]
	v_pk_mul_f32 v[84:85], v[140:141], v[84:85]
	v_cvt_pk_bf16_f32 v80, v108, v109
	v_cvt_pk_bf16_f32 v81, v110, v111
	v_cvt_pk_bf16_f32 v82, v96, v97
	v_cvt_pk_bf16_f32 v83, v98, v99
	global_store_dwordx4 v[200:201], v[80:83], off
	v_pk_add_f32 v[78:79], v[78:79], v[150:151]
	v_pk_add_f32 v[76:77], v[76:77], v[148:149]
	v_cvt_pk_bf16_f32 v80, v84, v85
	v_cvt_pk_bf16_f32 v81, v86, v87
	v_cvt_pk_bf16_f32 v82, v204, v205
	v_cvt_pk_bf16_f32 v83, v202, v203
	v_pk_add_f32 v[74:75], v[74:75], v[146:147]
	v_pk_add_f32 v[72:73], v[72:73], v[144:145]
	global_store_dwordx4 v[200:201], v[80:83], off offset:256
	v_pk_mul_f32 v[78:79], v[158:159], v[78:79]
	v_pk_mul_f32 v[76:77], v[156:157], v[76:77]
	v_lshl_add_u64 v[80:81], v[176:177], 0, v[186:187]
	v_pk_mul_f32 v[82:83], v[154:155], v[74:75]
	v_pk_mul_f32 v[74:75], v[152:153], v[72:73]
	v_cvt_pk_bf16_f32 v72, v76, v77
	v_cvt_pk_bf16_f32 v73, v78, v79
	v_pk_add_f32 v[66:67], v[66:67], v[130:131]
	v_pk_add_f32 v[64:65], v[64:65], v[128:129]
	v_cvt_pk_bf16_f32 v74, v74, v75
	v_cvt_pk_bf16_f32 v75, v82, v83
	global_store_dwordx4 v[80:81], v[72:75], off
	v_pk_add_f32 v[70:71], v[70:71], v[134:135]
	v_pk_add_f32 v[68:69], v[68:69], v[132:133]
	v_pk_mul_f32 v[72:73], v[138:139], v[66:67]
	v_pk_mul_f32 v[66:67], v[136:137], v[64:65]
	v_pk_mul_f32 v[70:71], v[142:143], v[70:71]
	v_pk_mul_f32 v[68:69], v[140:141], v[68:69]
	v_pk_add_f32 v[62:63], v[62:63], v[150:151]
	v_cvt_pk_bf16_f32 v64, v68, v69
	v_cvt_pk_bf16_f32 v65, v70, v71
	v_cvt_pk_bf16_f32 v66, v66, v67
	v_cvt_pk_bf16_f32 v67, v72, v73
	v_pk_add_f32 v[60:61], v[60:61], v[148:149]
	v_pk_add_f32 v[58:59], v[58:59], v[146:147]
	v_pk_add_f32 v[56:57], v[56:57], v[144:145]
	global_store_dwordx4 v[80:81], v[64:67], off offset:256
	v_pk_mul_f32 v[62:63], v[158:159], v[62:63]
	v_pk_mul_f32 v[60:61], v[156:157], v[60:61]
	v_lshl_add_u64 v[64:65], v[178:179], 0, v[186:187]
	v_pk_mul_f32 v[66:67], v[154:155], v[58:59]
	v_pk_mul_f32 v[58:59], v[152:153], v[56:57]
	v_cvt_pk_bf16_f32 v56, v60, v61
	v_cvt_pk_bf16_f32 v57, v62, v63
	v_pk_add_f32 v[46:47], v[46:47], v[130:131]
	v_pk_add_f32 v[44:45], v[44:45], v[128:129]
	v_cvt_pk_bf16_f32 v58, v58, v59
	v_cvt_pk_bf16_f32 v59, v66, v67
	global_store_dwordx4 v[64:65], v[56:59], off
	v_pk_add_f32 v[54:55], v[54:55], v[134:135]
	v_pk_add_f32 v[52:53], v[52:53], v[132:133]
	v_pk_mul_f32 v[56:57], v[138:139], v[46:47]
	v_pk_mul_f32 v[46:47], v[136:137], v[44:45]
	v_pk_mul_f32 v[54:55], v[142:143], v[54:55]
	v_pk_mul_f32 v[52:53], v[140:141], v[52:53]
	v_pk_add_f32 v[48:49], v[48:49], v[148:149]
	v_cvt_pk_bf16_f32 v44, v52, v53
	v_cvt_pk_bf16_f32 v45, v54, v55
	v_cvt_pk_bf16_f32 v46, v46, v47
	v_cvt_pk_bf16_f32 v47, v56, v57
	global_store_dwordx4 v[64:65], v[44:47], off offset:256
	v_pk_add_f32 v[42:43], v[42:43], v[146:147]
	v_pk_add_f32 v[40:41], v[40:41], v[144:145]
	v_pk_add_f32 v[46:47], v[50:51], v[150:151]
	v_lshl_add_u64 v[44:45], v[180:181], 0, v[186:187]
	v_pk_mul_f32 v[46:47], v[158:159], v[46:47]
	v_pk_mul_f32 v[48:49], v[156:157], v[48:49]
	v_pk_mul_f32 v[50:51], v[154:155], v[42:43]
	v_pk_mul_f32 v[42:43], v[152:153], v[40:41]
	v_cvt_pk_bf16_f32 v40, v48, v49
	v_cvt_pk_bf16_f32 v41, v46, v47
	v_pk_add_f32 v[30:31], v[30:31], v[130:131]
	v_pk_add_f32 v[28:29], v[28:29], v[128:129]
	v_cvt_pk_bf16_f32 v42, v42, v43
	v_cvt_pk_bf16_f32 v43, v50, v51
	global_store_dwordx4 v[44:45], v[40:43], off
	v_pk_add_f32 v[38:39], v[38:39], v[134:135]
	v_pk_add_f32 v[36:37], v[36:37], v[132:133]
	v_pk_mul_f32 v[40:41], v[138:139], v[30:31]
	v_pk_mul_f32 v[30:31], v[136:137], v[28:29]
	v_pk_mul_f32 v[38:39], v[142:143], v[38:39]
	v_pk_mul_f32 v[36:37], v[140:141], v[36:37]
	v_pk_add_f32 v[32:33], v[32:33], v[148:149]
	v_cvt_pk_bf16_f32 v28, v36, v37
	v_cvt_pk_bf16_f32 v29, v38, v39
	v_cvt_pk_bf16_f32 v30, v30, v31
	v_cvt_pk_bf16_f32 v31, v40, v41
	global_store_dwordx4 v[44:45], v[28:31], off offset:256
	v_pk_add_f32 v[26:27], v[26:27], v[146:147]
	v_pk_add_f32 v[24:25], v[24:25], v[144:145]
	v_pk_add_f32 v[30:31], v[34:35], v[150:151]
	v_lshl_add_u64 v[28:29], v[182:183], 0, v[186:187]
	v_pk_mul_f32 v[30:31], v[158:159], v[30:31]
	v_pk_mul_f32 v[32:33], v[156:157], v[32:33]
	v_pk_mul_f32 v[34:35], v[154:155], v[26:27]
	v_pk_mul_f32 v[26:27], v[152:153], v[24:25]
	v_cvt_pk_bf16_f32 v24, v32, v33
	v_cvt_pk_bf16_f32 v25, v30, v31
	v_pk_add_f32 v[14:15], v[14:15], v[130:131]
	v_pk_add_f32 v[12:13], v[12:13], v[128:129]
	v_cvt_pk_bf16_f32 v26, v26, v27
	v_cvt_pk_bf16_f32 v27, v34, v35
	global_store_dwordx4 v[28:29], v[24:27], off
	v_pk_add_f32 v[22:23], v[22:23], v[134:135]
	v_pk_add_f32 v[20:21], v[20:21], v[132:133]
	v_pk_mul_f32 v[24:25], v[138:139], v[14:15]
	v_pk_mul_f32 v[14:15], v[136:137], v[12:13]
	v_pk_mul_f32 v[22:23], v[142:143], v[22:23]
	v_pk_mul_f32 v[20:21], v[140:141], v[20:21]
	v_pk_add_f32 v[16:17], v[16:17], v[148:149]
	v_cvt_pk_bf16_f32 v12, v20, v21
	v_cvt_pk_bf16_f32 v13, v22, v23
	v_cvt_pk_bf16_f32 v14, v14, v15
	v_cvt_pk_bf16_f32 v15, v24, v25
	global_store_dwordx4 v[28:29], v[12:15], off offset:256
	v_pk_add_f32 v[10:11], v[10:11], v[146:147]
	v_pk_add_f32 v[8:9], v[8:9], v[144:145]
	v_pk_add_f32 v[14:15], v[18:19], v[150:151]
	v_lshl_add_u64 v[12:13], v[184:185], 0, v[186:187]
	v_pk_mul_f32 v[14:15], v[158:159], v[14:15]
	v_pk_mul_f32 v[16:17], v[156:157], v[16:17]
	v_pk_mul_f32 v[18:19], v[154:155], v[10:11]
	v_pk_mul_f32 v[10:11], v[152:153], v[8:9]
	v_cvt_pk_bf16_f32 v8, v16, v17
	v_cvt_pk_bf16_f32 v9, v14, v15
	v_pk_add_f32 v[2:3], v[2:3], v[130:131]
	v_pk_add_f32 v[0:1], v[0:1], v[128:129]
	v_cvt_pk_bf16_f32 v10, v10, v11
	v_cvt_pk_bf16_f32 v11, v18, v19
	global_store_dwordx4 v[12:13], v[8:11], off
	v_pk_add_f32 v[6:7], v[6:7], v[134:135]
	v_pk_add_f32 v[4:5], v[4:5], v[132:133]
	v_pk_mul_f32 v[8:9], v[138:139], v[2:3]
	v_pk_mul_f32 v[2:3], v[136:137], v[0:1]
	v_pk_mul_f32 v[6:7], v[142:143], v[6:7]
	v_pk_mul_f32 v[4:5], v[140:141], v[4:5]
	s_nop 0
	v_cvt_pk_bf16_f32 v0, v4, v5
	v_cvt_pk_bf16_f32 v1, v6, v7
	v_cvt_pk_bf16_f32 v2, v2, v3
	v_cvt_pk_bf16_f32 v3, v8, v9
	global_store_dwordx4 v[12:13], v[0:3], off offset:256
	s_cbranch_vccz .LBB0_870
	s_waitcnt vmcnt(0)
	s_cmpk_gt_u32 s12, 0xff
	s_cbranch_scc1 .LBB0_875
	s_barrier

.LBB0_932:
	ds_read_b128 v[148:151], v131
	ds_read_b128 v[152:155], v131 offset:1024
	ds_read_b128 v[156:159], v131 offset:2048
	ds_read_b128 v[160:163], v131 offset:3072
	ds_read_b128 v[164:167], v136
	ds_read_b128 v[168:171], v136 offset:1024
	ds_read_b128 v[172:175], v136 offset:2048
	ds_read_b128 v[176:179], v136 offset:3072
	s_add_u32 s18, s14, s16
	s_addc_u32 s19, s15, s17
	s_add_u32 s18, s18, 0xb000100
	s_addc_u32 s19, s19, 0
	s_add_u32 s28, s27, s16
	s_addc_u32 s29, s52, s17
	s_cmpk_eq_i32 s16, 0x400
	s_cselect_b32 s41, s7, s19
	s_cselect_b32 s40, s6, s18
	s_cselect_b32 s19, s1, s29
	s_cselect_b32 s18, s0, s28
	s_mov_b32 m0, s54
	v_lshl_add_u64 v[214:215], v[120:121], 0, s[16:17]
	ds_read_b128 v[180:183], v137
	ds_read_b128 v[184:187], v137 offset:1024
	ds_read_b128 v[190:193], v137 offset:2048
	ds_read_b128 v[194:197], v137 offset:3072
	ds_read_b128 v[198:201], v137 offset:4096
	ds_read_b128 v[202:205], v137 offset:5120
	ds_read_b128 v[206:209], v137 offset:6144
	ds_read_b128 v[210:213], v137 offset:7168
	global_load_lds_dwordx4 v[214:215], off
	v_lshl_add_u64 v[214:215], v[122:123], 0, s[16:17]
	s_mov_b32 m0, s55
	s_nop 0
	global_load_lds_dwordx4 v[214:215], off
	s_waitcnt vmcnt(8)
	s_waitcnt lgkmcnt(0)
	s_barrier
	s_waitcnt lgkmcnt(0)
	v_mfma_f32_16x16x32_bf16 v[144:147], v[148:151], v[180:183], v[144:147]
	v_mfma_f32_16x16x32_bf16 v[140:143], v[156:159], v[180:183], v[140:143]
	v_mfma_f32_16x16x32_bf16 v[132:135], v[148:151], v[190:193], v[132:135]
	v_mfma_f32_16x16x32_bf16 v[124:127], v[156:159], v[190:193], v[124:127]
	v_mfma_f32_16x16x32_bf16 v[116:119], v[148:151], v[198:201], v[116:119]
	v_mfma_f32_16x16x32_bf16 v[112:115], v[156:159], v[198:201], v[112:115]
	v_mfma_f32_16x16x32_bf16 v[100:103], v[148:151], v[206:209], v[100:103]
	v_mfma_f32_16x16x32_bf16 v[96:99], v[156:159], v[206:209], v[96:99]
	v_mfma_f32_16x16x32_bf16 v[144:147], v[152:155], v[184:187], v[144:147]
	v_mfma_f32_16x16x32_bf16 v[140:143], v[160:163], v[184:187], v[140:143]
	v_mfma_f32_16x16x32_bf16 v[132:135], v[152:155], v[194:197], v[132:135]
	v_mfma_f32_16x16x32_bf16 v[124:127], v[160:163], v[194:197], v[124:127]
	v_mfma_f32_16x16x32_bf16 v[116:119], v[152:155], v[202:205], v[116:119]
	v_mfma_f32_16x16x32_bf16 v[112:115], v[160:163], v[202:205], v[112:115]
	v_mfma_f32_16x16x32_bf16 v[100:103], v[152:155], v[210:213], v[100:103]
	v_mfma_f32_16x16x32_bf16 v[96:99], v[160:163], v[210:213], v[96:99]
	v_mfma_f32_16x16x32_bf16 v[60:63], v[164:167], v[180:183], v[60:63]
	v_mfma_f32_16x16x32_bf16 v[56:59], v[172:175], v[180:183], v[56:59]
	v_mfma_f32_16x16x32_bf16 v[52:55], v[164:167], v[190:193], v[52:55]
	v_mfma_f32_16x16x32_bf16 v[48:51], v[172:175], v[190:193], v[48:51]
	v_mfma_f32_16x16x32_bf16 v[44:47], v[164:167], v[198:201], v[44:47]
	v_mfma_f32_16x16x32_bf16 v[40:43], v[172:175], v[198:201], v[40:43]
	v_mfma_f32_16x16x32_bf16 v[36:39], v[164:167], v[206:209], v[36:39]
	v_mfma_f32_16x16x32_bf16 v[32:35], v[172:175], v[206:209], v[32:35]
	v_mfma_f32_16x16x32_bf16 v[60:63], v[168:171], v[184:187], v[60:63]
	v_mfma_f32_16x16x32_bf16 v[56:59], v[176:179], v[184:187], v[56:59]
	v_mfma_f32_16x16x32_bf16 v[52:55], v[168:171], v[194:197], v[52:55]
	v_mfma_f32_16x16x32_bf16 v[48:51], v[176:179], v[194:197], v[48:51]
	v_mfma_f32_16x16x32_bf16 v[44:47], v[168:171], v[202:205], v[44:47]
	v_mfma_f32_16x16x32_bf16 v[40:43], v[176:179], v[202:205], v[40:43]
	v_mfma_f32_16x16x32_bf16 v[36:39], v[168:171], v[210:213], v[36:39]
	v_mfma_f32_16x16x32_bf16 v[32:35], v[176:179], v[210:213], v[32:35]
	s_barrier
	s_mov_b32 m0, s56
	v_lshl_add_u64 v[214:215], s[18:19], 0, v[108:109]
	s_add_u32 s28, s18, 0x28000
	ds_read_b128 v[180:183], v137 offset:16384
	ds_read_b128 v[184:187], v137 offset:17408
	ds_read_b128 v[190:193], v137 offset:18432
	ds_read_b128 v[194:197], v137 offset:19456
	ds_read_b128 v[198:201], v137 offset:20480
	ds_read_b128 v[202:205], v137 offset:21504
	ds_read_b128 v[206:209], v137 offset:22528
	ds_read_b128 v[210:213], v137 offset:23552
	global_load_lds_dwordx4 v[214:215], off
	v_lshl_add_u64 v[216:217], s[18:19], 0, v[104:105]
	s_mov_b32 m0, s57
	s_addc_u32 s29, s19, 0
	global_load_lds_dwordx4 v[216:217], off
	v_lshl_add_u64 v[218:219], s[28:29], 0, v[108:109]
	s_mov_b32 m0, s58
	v_lshl_add_u64 v[220:221], s[40:41], 0, v[106:107]
	global_load_lds_dwordx4 v[218:219], off
	v_lshl_add_u64 v[218:219], s[28:29], 0, v[104:105]
	s_mov_b32 m0, s59
	s_nop 0
	global_load_lds_dwordx4 v[218:219], off
	v_lshl_add_u64 v[218:219], s[40:41], 0, v[110:111]
	s_mov_b32 m0, s34
	s_nop 0
	global_load_lds_dwordx4 v[218:219], off
	s_mov_b32 m0, s35
	s_nop 0
	global_load_lds_dwordx4 v[220:221], off
	s_waitcnt vmcnt(8)
	s_waitcnt lgkmcnt(0)
	s_nop 0
	s_barrier
	s_waitcnt lgkmcnt(0)
	v_mfma_f32_16x16x32_bf16 v[92:95], v[148:151], v[180:183], v[92:95]
	v_mfma_f32_16x16x32_bf16 v[88:91], v[156:159], v[180:183], v[88:91]
	v_mfma_f32_16x16x32_bf16 v[84:87], v[148:151], v[190:193], v[84:87]
	v_mfma_f32_16x16x32_bf16 v[80:83], v[156:159], v[190:193], v[80:83]
	v_mfma_f32_16x16x32_bf16 v[76:79], v[148:151], v[198:201], v[76:79]
	v_mfma_f32_16x16x32_bf16 v[72:75], v[156:159], v[198:201], v[72:75]
	v_mfma_f32_16x16x32_bf16 v[68:71], v[148:151], v[206:209], v[68:71]
	v_mfma_f32_16x16x32_bf16 v[64:67], v[156:159], v[206:209], v[64:67]
	v_mfma_f32_16x16x32_bf16 v[92:95], v[152:155], v[184:187], v[92:95]
	v_mfma_f32_16x16x32_bf16 v[88:91], v[160:163], v[184:187], v[88:91]
	v_mfma_f32_16x16x32_bf16 v[84:87], v[152:155], v[194:197], v[84:87]
	v_mfma_f32_16x16x32_bf16 v[80:83], v[160:163], v[194:197], v[80:83]
	v_mfma_f32_16x16x32_bf16 v[76:79], v[152:155], v[202:205], v[76:79]
	v_mfma_f32_16x16x32_bf16 v[72:75], v[160:163], v[202:205], v[72:75]
	v_mfma_f32_16x16x32_bf16 v[68:71], v[152:155], v[210:213], v[68:71]
	v_mfma_f32_16x16x32_bf16 v[64:67], v[160:163], v[210:213], v[64:67]
	v_mfma_f32_16x16x32_bf16 v[28:31], v[164:167], v[180:183], v[28:31]
	v_mfma_f32_16x16x32_bf16 v[24:27], v[172:175], v[180:183], v[24:27]
	v_mfma_f32_16x16x32_bf16 v[20:23], v[164:167], v[190:193], v[20:23]
	v_mfma_f32_16x16x32_bf16 v[16:19], v[172:175], v[190:193], v[16:19]
	v_mfma_f32_16x16x32_bf16 v[12:15], v[164:167], v[198:201], v[12:15]
	v_mfma_f32_16x16x32_bf16 v[8:11], v[172:175], v[198:201], v[8:11]
	v_mfma_f32_16x16x32_bf16 v[4:7], v[164:167], v[206:209], v[4:7]
	v_mfma_f32_16x16x32_bf16 v[0:3], v[172:175], v[206:209], v[0:3]
	v_mfma_f32_16x16x32_bf16 v[28:31], v[168:171], v[184:187], v[28:31]
	v_mfma_f32_16x16x32_bf16 v[24:27], v[176:179], v[184:187], v[24:27]
	v_mfma_f32_16x16x32_bf16 v[20:23], v[168:171], v[194:197], v[20:23]
	v_mfma_f32_16x16x32_bf16 v[16:19], v[176:179], v[194:197], v[16:19]
	v_mfma_f32_16x16x32_bf16 v[12:15], v[168:171], v[202:205], v[12:15]
	v_mfma_f32_16x16x32_bf16 v[8:11], v[176:179], v[202:205], v[8:11]
	v_mfma_f32_16x16x32_bf16 v[4:7], v[168:171], v[210:213], v[4:7]
	v_mfma_f32_16x16x32_bf16 v[0:3], v[176:179], v[210:213], v[0:3]
	s_barrier
	ds_read_b128 v[148:151], v138
	ds_read_b128 v[152:155], v138 offset:1024
	ds_read_b128 v[156:159], v138 offset:2048
	ds_read_b128 v[160:163], v138 offset:3072
	ds_read_b128 v[164:167], v139
	ds_read_b128 v[168:171], v139 offset:1024
	ds_read_b128 v[172:175], v139 offset:2048
	ds_read_b128 v[176:179], v139 offset:3072
	s_add_u32 s28, s40, 0x28000
	s_addc_u32 s29, s41, 0
	s_mov_b32 m0, s42
	v_lshl_add_u64 v[222:223], s[28:29], 0, v[110:111]
	ds_read_b128 v[180:183], v137 offset:32768
	ds_read_b128 v[184:187], v137 offset:33792
	ds_read_b128 v[190:193], v137 offset:34816
	ds_read_b128 v[194:197], v137 offset:35840
	ds_read_b128 v[198:201], v137 offset:36864
	ds_read_b128 v[202:205], v137 offset:37888
	ds_read_b128 v[206:209], v137 offset:38912
	ds_read_b128 v[210:213], v137 offset:39936
	global_load_lds_dwordx4 v[222:223], off
	v_lshl_add_u64 v[222:223], s[28:29], 0, v[106:107]
	s_mov_b32 m0, s43
	s_nop 0
	global_load_lds_dwordx4 v[222:223], off
	s_waitcnt vmcnt(8)
	s_waitcnt lgkmcnt(0)
	s_nop 0
	s_barrier
	s_waitcnt lgkmcnt(0)
	v_mfma_f32_16x16x32_bf16 v[144:147], v[148:151], v[180:183], v[144:147]
	v_mfma_f32_16x16x32_bf16 v[140:143], v[156:159], v[180:183], v[140:143]
	v_mfma_f32_16x16x32_bf16 v[132:135], v[148:151], v[190:193], v[132:135]
	v_mfma_f32_16x16x32_bf16 v[124:127], v[156:159], v[190:193], v[124:127]
	v_mfma_f32_16x16x32_bf16 v[116:119], v[148:151], v[198:201], v[116:119]
	v_mfma_f32_16x16x32_bf16 v[112:115], v[156:159], v[198:201], v[112:115]
	v_mfma_f32_16x16x32_bf16 v[100:103], v[148:151], v[206:209], v[100:103]
	v_mfma_f32_16x16x32_bf16 v[96:99], v[156:159], v[206:209], v[96:99]
	v_mfma_f32_16x16x32_bf16 v[144:147], v[152:155], v[184:187], v[144:147]
	v_mfma_f32_16x16x32_bf16 v[140:143], v[160:163], v[184:187], v[140:143]
	v_mfma_f32_16x16x32_bf16 v[132:135], v[152:155], v[194:197], v[132:135]
	v_mfma_f32_16x16x32_bf16 v[124:127], v[160:163], v[194:197], v[124:127]
	v_mfma_f32_16x16x32_bf16 v[116:119], v[152:155], v[202:205], v[116:119]
	v_mfma_f32_16x16x32_bf16 v[112:115], v[160:163], v[202:205], v[112:115]
	v_mfma_f32_16x16x32_bf16 v[100:103], v[152:155], v[210:213], v[100:103]
	v_mfma_f32_16x16x32_bf16 v[96:99], v[160:163], v[210:213], v[96:99]
	v_mfma_f32_16x16x32_bf16 v[60:63], v[164:167], v[180:183], v[60:63]
	v_mfma_f32_16x16x32_bf16 v[56:59], v[172:175], v[180:183], v[56:59]
	v_mfma_f32_16x16x32_bf16 v[52:55], v[164:167], v[190:193], v[52:55]
	v_mfma_f32_16x16x32_bf16 v[48:51], v[172:175], v[190:193], v[48:51]
	v_mfma_f32_16x16x32_bf16 v[44:47], v[164:167], v[198:201], v[44:47]
	v_mfma_f32_16x16x32_bf16 v[40:43], v[172:175], v[198:201], v[40:43]
	v_mfma_f32_16x16x32_bf16 v[36:39], v[164:167], v[206:209], v[36:39]
	v_mfma_f32_16x16x32_bf16 v[32:35], v[172:175], v[206:209], v[32:35]
	v_mfma_f32_16x16x32_bf16 v[60:63], v[168:171], v[184:187], v[60:63]
	v_mfma_f32_16x16x32_bf16 v[56:59], v[176:179], v[184:187], v[56:59]
	v_mfma_f32_16x16x32_bf16 v[52:55], v[168:171], v[194:197], v[52:55]
	v_mfma_f32_16x16x32_bf16 v[48:51], v[176:179], v[194:197], v[48:51]
	v_mfma_f32_16x16x32_bf16 v[44:47], v[168:171], v[202:205], v[44:47]
	v_mfma_f32_16x16x32_bf16 v[40:43], v[176:179], v[202:205], v[40:43]
	v_mfma_f32_16x16x32_bf16 v[36:39], v[168:171], v[210:213], v[36:39]
	v_mfma_f32_16x16x32_bf16 v[32:35], v[176:179], v[210:213], v[32:35]
	s_barrier
	s_mov_b32 m0, s60
	v_lshl_add_u64 v[214:215], v[214:215], 0, s[10:11]
	s_add_u32 s18, s18, 0x28080
	ds_read_b128 v[180:183], v137 offset:49152
	ds_read_b128 v[184:187], v137 offset:50176
	ds_read_b128 v[190:193], v137 offset:51200
	ds_read_b128 v[194:197], v137 offset:52224
	ds_read_b128 v[198:201], v137 offset:53248
	ds_read_b128 v[202:205], v137 offset:54272
	ds_read_b128 v[206:209], v137 offset:55296
	ds_read_b128 v[210:213], v137 offset:56320
	global_load_lds_dwordx4 v[214:215], off
	v_lshl_add_u64 v[214:215], v[216:217], 0, s[10:11]
	s_mov_b32 m0, s61
	s_addc_u32 s19, s19, 0
	global_load_lds_dwordx4 v[214:215], off
	v_lshl_add_u64 v[214:215], s[18:19], 0, v[108:109]
	s_mov_b32 m0, s62
	s_nop 0
	global_load_lds_dwordx4 v[214:215], off
	v_lshl_add_u64 v[214:215], s[18:19], 0, v[104:105]
	s_mov_b32 m0, s63
	s_nop 0
	global_load_lds_dwordx4 v[214:215], off
	v_lshl_add_u64 v[214:215], v[218:219], 0, s[10:11]
	s_mov_b32 m0, s50
	s_nop 0
	global_load_lds_dwordx4 v[214:215], off
	v_lshl_add_u64 v[214:215], v[220:221], 0, s[10:11]
	s_mov_b32 m0, s51
	s_nop 0
	global_load_lds_dwordx4 v[214:215], off
	s_waitcnt vmcnt(8)
	s_waitcnt lgkmcnt(0)
	s_barrier
	s_waitcnt lgkmcnt(0)
	v_mfma_f32_16x16x32_bf16 v[92:95], v[148:151], v[180:183], v[92:95]
	v_mfma_f32_16x16x32_bf16 v[88:91], v[156:159], v[180:183], v[88:91]
	v_mfma_f32_16x16x32_bf16 v[84:87], v[148:151], v[190:193], v[84:87]
	v_mfma_f32_16x16x32_bf16 v[80:83], v[156:159], v[190:193], v[80:83]
	v_mfma_f32_16x16x32_bf16 v[76:79], v[148:151], v[198:201], v[76:79]
	v_mfma_f32_16x16x32_bf16 v[72:75], v[156:159], v[198:201], v[72:75]
	v_mfma_f32_16x16x32_bf16 v[68:71], v[148:151], v[206:209], v[68:71]
	v_mfma_f32_16x16x32_bf16 v[64:67], v[156:159], v[206:209], v[64:67]
	v_mfma_f32_16x16x32_bf16 v[92:95], v[152:155], v[184:187], v[92:95]
	v_mfma_f32_16x16x32_bf16 v[88:91], v[160:163], v[184:187], v[88:91]
	v_mfma_f32_16x16x32_bf16 v[84:87], v[152:155], v[194:197], v[84:87]
	v_mfma_f32_16x16x32_bf16 v[80:83], v[160:163], v[194:197], v[80:83]
	v_mfma_f32_16x16x32_bf16 v[76:79], v[152:155], v[202:205], v[76:79]
	v_mfma_f32_16x16x32_bf16 v[72:75], v[160:163], v[202:205], v[72:75]
	v_mfma_f32_16x16x32_bf16 v[68:71], v[152:155], v[210:213], v[68:71]
	v_mfma_f32_16x16x32_bf16 v[64:67], v[160:163], v[210:213], v[64:67]
	v_mfma_f32_16x16x32_bf16 v[28:31], v[164:167], v[180:183], v[28:31]
	v_mfma_f32_16x16x32_bf16 v[24:27], v[172:175], v[180:183], v[24:27]
	v_mfma_f32_16x16x32_bf16 v[20:23], v[164:167], v[190:193], v[20:23]
	v_mfma_f32_16x16x32_bf16 v[16:19], v[172:175], v[190:193], v[16:19]
	v_mfma_f32_16x16x32_bf16 v[12:15], v[164:167], v[198:201], v[12:15]
	v_mfma_f32_16x16x32_bf16 v[8:11], v[172:175], v[198:201], v[8:11]
	v_mfma_f32_16x16x32_bf16 v[4:7], v[164:167], v[206:209], v[4:7]
	v_mfma_f32_16x16x32_bf16 v[0:3], v[172:175], v[206:209], v[0:3]
	v_mfma_f32_16x16x32_bf16 v[28:31], v[168:171], v[184:187], v[28:31]
	v_mfma_f32_16x16x32_bf16 v[24:27], v[176:179], v[184:187], v[24:27]
	v_mfma_f32_16x16x32_bf16 v[20:23], v[168:171], v[194:197], v[20:23]
	v_mfma_f32_16x16x32_bf16 v[16:19], v[176:179], v[194:197], v[16:19]
	v_mfma_f32_16x16x32_bf16 v[12:15], v[168:171], v[202:205], v[12:15]
	v_mfma_f32_16x16x32_bf16 v[8:11], v[176:179], v[202:205], v[8:11]
	v_mfma_f32_16x16x32_bf16 v[4:7], v[168:171], v[210:213], v[4:7]
	v_mfma_f32_16x16x32_bf16 v[0:3], v[176:179], v[210:213], v[0:3]
	s_barrier
	s_add_i32 s53, s53, 2
	s_add_u32 s16, s16, 0x100
	s_addc_u32 s17, s17, 0
	s_cmp_gt_u32 s53, 7
	s_cbranch_scc0 .LBB0_932
	v_lshl_or_b32 v104, s13, 8, v129
	v_or_b32_e32 v167, s47, v104
	v_lshlrev_b32_e32 v160, 1, v167
	v_mov_b32_e32 v161, 0
	v_lshl_add_u32 v166, s12, 8, v128
	v_lshl_add_u64 v[120:121], s[38:39], 0, v[160:161]
	s_movk_i32 s1, 0x500
	s_lshl_b32 s40, s3, 4
	v_readlane_b32 s48, v242, 40
	v_mad_i64_i32 v[104:105], s[6:7], v166, s1, v[120:121]
	s_ashr_i32 s41, s40, 31
	v_readlane_b32 s56, v242, 48
	v_readlane_b32 s57, v242, 49
	s_lshl_b32 s3, s3, 15
	s_lshl_b64 s[6:7], s[40:41], 2
	s_mov_b64 s[12:13], s[56:57]
	v_and_b32_e32 v177, 8, v130
	global_load_dwordx4 v[178:181], v[104:105], off
	s_add_u32 s42, s12, s6
	s_addc_u32 s43, s13, s7
	v_lshlrev_b32_e32 v168, 2, v177
	global_load_dwordx4 v[108:111], v168, s[42:43]
	global_load_dwordx4 v[104:107], v168, s[42:43] offset:16
	v_lshlrev_b32_e32 v122, 5, v166
	s_mov_b32 s12, 0xbf3a00e3
	v_or_b32_e32 v176, 16, v166
	v_or_b32_e32 v175, 32, v166
	v_or_b32_e32 v174, 48, v166
	v_add_u32_e32 v173, 0x80, v166
	v_add_u32_e32 v172, 0x90, v166
	v_add_u32_e32 v171, 0xa0, v166
	v_add_u32_e32 v170, 0xb0, v166
	v_subrev_u32_e32 v169, s3, v122
	v_lshrrev_b32_e32 v122, 4, v167
	v_mov_b64_e32 v[162:163], s[12:13]
	v_or_b32_e32 v164, v169, v122
	v_mad_i64_i32 v[122:123], s[12:13], v176, s1, v[120:121]
	v_mad_i64_i32 v[128:129], s[12:13], v175, s1, v[120:121]
	v_mad_i64_i32 v[130:131], s[12:13], v174, s1, v[120:121]
	v_mad_i64_i32 v[136:137], s[12:13], v173, s1, v[120:121]
	v_mad_i64_i32 v[138:139], s[12:13], v172, s1, v[120:121]
	v_mad_i64_i32 v[186:187], s[12:13], v171, s1, v[120:121]
	v_mad_i64_i32 v[120:121], s[12:13], v170, s1, v[120:121]
	global_load_dwordx4 v[182:185], v[122:123], off
	global_load_dwordx4 v[156:159], v[128:129], off
	global_load_dwordx4 v[152:155], v[130:131], off
	global_load_dwordx4 v[148:151], v[136:137], off
	s_nop 0
	global_load_dwordx4 v[136:139], v[138:139], off
	s_nop 0
	global_load_dwordx4 v[128:131], v[186:187], off
	s_nop 0
	global_load_dwordx4 v[120:123], v[120:121], off
	s_mov_b32 s10, 0x3e6d3388
	v_readlane_b32 s60, v242, 52
	v_readlane_b32 s61, v242, 53
	s_mov_b64 s[16:17], s[60:61]
	s_mov_b32 s0, 0x3f07dc22
	s_mov_b32 s18, 0xbf38aa3b
	s_mov_b32 s16, 0x3f35f0e3
	s_mov_b32 s6, 0xbe11a98e
	s_mov_b32 s14, 0x3e027906
	s_lshl_b64 s[40:41], s[40:41], 1
	s_cmpk_lt_u32 s46, 0x100
	v_readlane_b32 s49, v242, 41
	v_readlane_b32 s50, v242, 42
	v_readlane_b32 s51, v242, 43
	v_readlane_b32 s52, v242, 44
	v_readlane_b32 s53, v242, 45
	v_readlane_b32 s54, v242, 46
	v_readlane_b32 s55, v242, 47
	v_readlane_b32 s58, v242, 50
	v_readlane_b32 s59, v242, 51
	v_readlane_b32 s62, v242, 54
	v_readlane_b32 s63, v242, 55
	s_waitcnt vmcnt(0)
	v_lshlrev_b32_e32 v186, 16, v178
	v_and_b32_e32 v187, 0xffff0000, v178
	v_lshlrev_b32_e32 v178, 16, v179
	v_and_b32_e32 v179, 0xffff0000, v179
	v_pk_fma_f32 v[144:145], v[108:109], v[186:187], v[144:145]
	v_pk_fma_f32 v[146:147], v[110:111], v[178:179], v[146:147]
	v_and_b32_e32 v179, 0x7fffffff, v145
	v_and_b32_e32 v178, 0x7fffffff, v144
	v_pk_fma_f32 v[178:179], v[178:179], s[10:11], 1.0 op_sel_hi:[1,0,0]
	v_pk_mul_f32 v[186:187], v[144:145], v[144:145]
	v_rcp_f32_e32 v178, v178
	v_rcp_f32_e32 v179, v179
	v_lshlrev_b32_e32 v190, 16, v180
	v_and_b32_e32 v191, 0xffff0000, v180
	v_pk_mul_f32 v[186:187], v[186:187], s[18:19] op_sel_hi:[1,0]
	v_pk_fma_f32 v[192:193], v[178:179], s[0:1], v[162:163] op_sel_hi:[1,0,0]
	v_pk_fma_f32 v[140:141], v[104:105], v[190:191], v[140:141]
	v_and_b32_e32 v191, 0x7fffffff, v147
	v_and_b32_e32 v190, 0x7fffffff, v146
	v_exp_f32_e32 v186, v186
	v_exp_f32_e32 v187, v187
	v_pk_fma_f32 v[192:193], v[178:179], v[192:193], s[16:17] op_sel_hi:[1,1,0]
	v_pk_fma_f32 v[190:191], v[190:191], s[10:11], 1.0 op_sel_hi:[1,0,0]
	v_pk_fma_f32 v[192:193], v[178:179], v[192:193], s[6:7] op_sel_hi:[1,1,0]
	v_rcp_f32_e32 v190, v190
	v_rcp_f32_e32 v191, v191
	v_pk_fma_f32 v[192:193], v[178:179], v[192:193], s[14:15] op_sel_hi:[1,1,0]
	v_lshlrev_b32_e32 v180, 16, v181
	v_pk_mul_f32 v[178:179], v[178:179], v[192:193]
	v_and_b32_e32 v181, 0xffff0000, v181
	v_pk_mul_f32 v[178:179], v[186:187], v[178:179]
	v_pk_fma_f32 v[142:143], v[106:107], v[180:181], v[142:143]
	v_pk_mul_f32 v[180:181], v[146:147], v[146:147]
	v_pk_mul_f32 v[186:187], v[144:145], v[178:179]
	v_pk_fma_f32 v[178:179], v[144:145], v[178:179], v[144:145] neg_lo:[1,0,0] neg_hi:[1,0,0]
	v_cmp_gt_f32_e32 vcc, 0, v144
	v_pk_fma_f32 v[194:195], v[190:191], s[0:1], v[162:163] op_sel_hi:[1,0,0]
	s_nop 0
	v_cndmask_b32_e32 v160, v178, v186, vcc
	v_cmp_gt_f32_e32 vcc, 0, v145
	v_pk_mul_f32 v[144:145], v[180:181], s[18:19] op_sel_hi:[1,0]
	v_pk_fma_f32 v[194:195], v[190:191], v[194:195], s[16:17] op_sel_hi:[1,1,0]
	v_exp_f32_e32 v144, v144
	v_exp_f32_e32 v145, v145
	v_cndmask_b32_e32 v165, v179, v187, vcc
	v_pk_fma_f32 v[178:179], v[190:191], v[194:195], s[6:7] op_sel_hi:[1,1,0]
	v_and_b32_e32 v181, 0x7fffffff, v141
	v_and_b32_e32 v180, 0x7fffffff, v140
	v_pk_fma_f32 v[178:179], v[190:191], v[178:179], s[14:15] op_sel_hi:[1,1,0]
	v_pk_fma_f32 v[180:181], v[180:181], s[10:11], 1.0 op_sel_hi:[1,0,0]
	v_pk_mul_f32 v[178:179], v[190:191], v[178:179]
	v_rcp_f32_e32 v180, v180
	v_rcp_f32_e32 v181, v181
	v_pk_mul_f32 v[144:145], v[144:145], v[178:179]
	v_cmp_gt_f32_e32 vcc, 0, v146
	v_pk_mul_f32 v[178:179], v[146:147], v[144:145]
	v_pk_fma_f32 v[144:145], v[146:147], v[144:145], v[146:147] neg_lo:[1,0,0] neg_hi:[1,0,0]
	s_nop 0
	v_cndmask_b32_e32 v186, v144, v178, vcc
	v_cmp_gt_f32_e32 vcc, 0, v147
	v_pk_mul_f32 v[146:147], v[140:141], v[140:141]
	s_nop 0
	v_cndmask_b32_e32 v187, v145, v179, vcc
	v_pk_fma_f32 v[144:145], v[180:181], s[0:1], v[162:163] op_sel_hi:[1,0,0]
	v_pk_mul_f32 v[146:147], v[146:147], s[18:19] op_sel_hi:[1,0]
	v_pk_fma_f32 v[144:145], v[180:181], v[144:145], s[16:17] op_sel_hi:[1,1,0]
	v_exp_f32_e32 v146, v146
	v_pk_fma_f32 v[144:145], v[180:181], v[144:145], s[6:7] op_sel_hi:[1,1,0]
	v_exp_f32_e32 v147, v147
	v_pk_fma_f32 v[144:145], v[180:181], v[144:145], s[14:15] op_sel_hi:[1,1,0]
	v_cmp_gt_f32_e32 vcc, 0, v140
	v_pk_mul_f32 v[144:145], v[180:181], v[144:145]
	v_and_b32_e32 v181, 0x7fffffff, v143
	v_and_b32_e32 v180, 0x7fffffff, v142
	v_pk_fma_f32 v[180:181], v[180:181], s[10:11], 1.0 op_sel_hi:[1,0,0]
	v_pk_mul_f32 v[144:145], v[146:147], v[144:145]
	v_rcp_f32_e32 v180, v180
	v_rcp_f32_e32 v181, v181
	v_pk_mul_f32 v[146:147], v[140:141], v[144:145]
	v_pk_fma_f32 v[144:145], v[140:141], v[144:145], v[140:141] neg_lo:[1,0,0] neg_hi:[1,0,0]
	v_pk_mul_f32 v[178:179], v[142:143], v[142:143]
	v_cndmask_b32_e32 v146, v144, v146, vcc
	v_cmp_gt_f32_e32 vcc, 0, v141
	v_pk_fma_f32 v[140:141], v[180:181], s[0:1], v[162:163] op_sel_hi:[1,0,0]
	s_nop 0
	v_cndmask_b32_e32 v147, v145, v147, vcc
	v_pk_mul_f32 v[144:145], v[178:179], s[18:19] op_sel_hi:[1,0]
	v_pk_fma_f32 v[140:141], v[180:181], v[140:141], s[16:17] op_sel_hi:[1,1,0]
	v_exp_f32_e32 v144, v144
	v_exp_f32_e32 v145, v145
	v_pk_fma_f32 v[140:141], v[180:181], v[140:141], s[6:7] op_sel_hi:[1,1,0]
	v_cmp_gt_f32_e32 vcc, 0, v142
	v_pk_fma_f32 v[140:141], v[180:181], v[140:141], s[14:15] op_sel_hi:[1,1,0]
	s_nop 0
	v_pk_mul_f32 v[140:141], v[180:181], v[140:141]
	s_nop 0
	v_pk_mul_f32 v[140:141], v[144:145], v[140:141]
	s_nop 0
	v_pk_mul_f32 v[144:145], v[142:143], v[140:141]
	v_pk_fma_f32 v[140:141], v[142:143], v[140:141], v[142:143] neg_lo:[1,0,0] neg_hi:[1,0,0]
	s_nop 0
	v_cndmask_b32_e32 v144, v140, v144, vcc
	v_cmp_gt_f32_e32 vcc, 0, v143
	v_cvt_pk_bf16_f32 v140, v160, v165
	v_ashrrev_i32_e32 v165, 31, v164
	v_lshlrev_b32_e32 v160, 1, v177
	v_cndmask_b32_e32 v143, v141, v145, vcc
	v_cvt_pk_bf16_f32 v141, v186, v187
	v_cvt_pk_bf16_f32 v142, v146, v147
	v_cvt_pk_bf16_f32 v143, v144, v143
	v_lshlrev_b64 v[144:145], 10, v[164:165]
	v_lshl_add_u64 v[144:145], s[20:21], 0, v[144:145]
	v_lshl_add_u64 v[144:145], v[144:145], 0, s[40:41]
	v_lshl_add_u64 v[144:145], v[144:145], 0, v[160:161]
	global_store_dwordx4 v[144:145], v[140:143], off
	v_lshlrev_b32_e32 v144, 16, v184
	v_and_b32_e32 v145, 0xffff0000, v184
	v_lshlrev_b32_e32 v140, 16, v182
	v_and_b32_e32 v141, 0xffff0000, v182
	v_pk_fma_f32 v[132:133], v[108:109], v[140:141], v[132:133]
	v_lshlrev_b32_e32 v142, 16, v183
	v_and_b32_e32 v141, 0x7fffffff, v133
	v_and_b32_e32 v140, 0x7fffffff, v132
	v_pk_fma_f32 v[140:141], v[140:141], s[10:11], 1.0 op_sel_hi:[1,0,0]
	v_and_b32_e32 v143, 0xffff0000, v183
	v_rcp_f32_e32 v140, v140
	v_rcp_f32_e32 v141, v141
	v_pk_fma_f32 v[124:125], v[104:105], v[144:145], v[124:125]
	v_pk_mul_f32 v[144:145], v[132:133], v[132:133]
	v_pk_fma_f32 v[134:135], v[110:111], v[142:143], v[134:135]
	v_pk_fma_f32 v[142:143], v[140:141], s[0:1], v[162:163] op_sel_hi:[1,0,0]
	v_pk_mul_f32 v[144:145], v[144:145], s[18:19] op_sel_hi:[1,0]
	v_lshlrev_b32_e32 v146, 16, v185
	v_and_b32_e32 v147, 0xffff0000, v185
	v_pk_fma_f32 v[142:143], v[140:141], v[142:143], s[16:17] op_sel_hi:[1,1,0]
	v_exp_f32_e32 v144, v144
	v_exp_f32_e32 v145, v145
	v_pk_fma_f32 v[126:127], v[106:107], v[146:147], v[126:127]
	v_pk_fma_f32 v[142:143], v[140:141], v[142:143], s[6:7] op_sel_hi:[1,1,0]
	v_and_b32_e32 v147, 0x7fffffff, v135
	v_and_b32_e32 v146, 0x7fffffff, v134
	v_pk_fma_f32 v[142:143], v[140:141], v[142:143], s[14:15] op_sel_hi:[1,1,0]
	v_pk_fma_f32 v[146:147], v[146:147], s[10:11], 1.0 op_sel_hi:[1,0,0]
	v_pk_mul_f32 v[140:141], v[140:141], v[142:143]
	v_rcp_f32_e32 v146, v146
	v_rcp_f32_e32 v147, v147
	v_pk_mul_f32 v[140:141], v[144:145], v[140:141]
	v_cmp_gt_f32_e32 vcc, 0, v132
	v_pk_mul_f32 v[144:145], v[132:133], v[140:141]
	v_pk_fma_f32 v[140:141], v[132:133], v[140:141], v[132:133] neg_lo:[1,0,0] neg_hi:[1,0,0]
	v_pk_mul_f32 v[142:143], v[134:135], v[134:135]
	v_cndmask_b32_e32 v144, v140, v144, vcc
	v_cmp_gt_f32_e32 vcc, 0, v133
	v_pk_fma_f32 v[132:133], v[146:147], s[0:1], v[162:163] op_sel_hi:[1,0,0]
	s_nop 0
	v_cndmask_b32_e32 v145, v141, v145, vcc
	v_pk_mul_f32 v[140:141], v[142:143], s[18:19] op_sel_hi:[1,0]
	v_pk_fma_f32 v[132:133], v[146:147], v[132:133], s[16:17] op_sel_hi:[1,1,0]
	v_exp_f32_e32 v140, v140
	v_exp_f32_e32 v141, v141
	v_pk_fma_f32 v[132:133], v[146:147], v[132:133], s[6:7] op_sel_hi:[1,1,0]
	v_and_b32_e32 v143, 0x7fffffff, v125
	v_and_b32_e32 v142, 0x7fffffff, v124
	v_pk_fma_f32 v[132:133], v[146:147], v[132:133], s[14:15] op_sel_hi:[1,1,0]
	v_pk_fma_f32 v[142:143], v[142:143], s[10:11], 1.0 op_sel_hi:[1,0,0]
	v_pk_mul_f32 v[132:133], v[146:147], v[132:133]
	v_rcp_f32_e32 v142, v142
	v_rcp_f32_e32 v143, v143
	v_pk_mul_f32 v[132:133], v[140:141], v[132:133]
	v_cmp_gt_f32_e32 vcc, 0, v134
	v_pk_mul_f32 v[140:141], v[134:135], v[132:133]
	v_pk_fma_f32 v[132:133], v[134:135], v[132:133], v[134:135] neg_lo:[1,0,0] neg_hi:[1,0,0]
	s_nop 0
	v_cndmask_b32_e32 v146, v132, v140, vcc
	v_cmp_gt_f32_e32 vcc, 0, v135
	v_pk_mul_f32 v[134:135], v[124:125], v[124:125]
	s_nop 0
	v_cndmask_b32_e32 v147, v133, v141, vcc
	v_pk_fma_f32 v[132:133], v[142:143], s[0:1], v[162:163] op_sel_hi:[1,0,0]
	v_pk_mul_f32 v[134:135], v[134:135], s[18:19] op_sel_hi:[1,0]
	v_pk_fma_f32 v[132:133], v[142:143], v[132:133], s[16:17] op_sel_hi:[1,1,0]
	v_exp_f32_e32 v134, v134
	v_pk_fma_f32 v[132:133], v[142:143], v[132:133], s[6:7] op_sel_hi:[1,1,0]
	v_exp_f32_e32 v135, v135
	v_pk_fma_f32 v[132:133], v[142:143], v[132:133], s[14:15] op_sel_hi:[1,1,0]
	v_cmp_gt_f32_e32 vcc, 0, v124
	v_pk_mul_f32 v[132:133], v[142:143], v[132:133]
	v_and_b32_e32 v143, 0x7fffffff, v127
	v_and_b32_e32 v142, 0x7fffffff, v126
	v_pk_fma_f32 v[142:143], v[142:143], s[10:11], 1.0 op_sel_hi:[1,0,0]
	v_pk_mul_f32 v[132:133], v[134:135], v[132:133]
	v_rcp_f32_e32 v142, v142
	v_rcp_f32_e32 v143, v143
	v_pk_mul_f32 v[134:135], v[124:125], v[132:133]
	v_pk_fma_f32 v[132:133], v[124:125], v[132:133], v[124:125] neg_lo:[1,0,0] neg_hi:[1,0,0]
	v_pk_mul_f32 v[140:141], v[126:127], v[126:127]
	v_cndmask_b32_e32 v134, v132, v134, vcc
	v_cmp_gt_f32_e32 vcc, 0, v125
	v_pk_fma_f32 v[124:125], v[142:143], s[0:1], v[162:163] op_sel_hi:[1,0,0]
	s_nop 0
	v_cndmask_b32_e32 v135, v133, v135, vcc
	v_pk_mul_f32 v[132:133], v[140:141], s[18:19] op_sel_hi:[1,0]
	v_pk_fma_f32 v[124:125], v[142:143], v[124:125], s[16:17] op_sel_hi:[1,1,0]
	v_exp_f32_e32 v132, v132
	v_exp_f32_e32 v133, v133
	v_pk_fma_f32 v[124:125], v[142:143], v[124:125], s[6:7] op_sel_hi:[1,1,0]
	v_cmp_gt_f32_e32 vcc, 0, v126
	v_pk_fma_f32 v[124:125], v[142:143], v[124:125], s[14:15] op_sel_hi:[1,1,0]
	s_nop 0
	v_pk_mul_f32 v[124:125], v[142:143], v[124:125]
	s_nop 0
	v_pk_mul_f32 v[124:125], v[132:133], v[124:125]
	s_nop 0
	v_pk_mul_f32 v[132:133], v[126:127], v[124:125]
	v_pk_fma_f32 v[124:125], v[126:127], v[124:125], v[126:127] neg_lo:[1,0,0] neg_hi:[1,0,0]
	s_nop 0
	v_cndmask_b32_e32 v132, v124, v132, vcc
	v_cmp_gt_f32_e32 vcc, 0, v127
	v_cvt_pk_bf16_f32 v124, v144, v145
	s_nop 1
	v_cndmask_b32_e32 v127, v125, v133, vcc
	v_cvt_pk_bf16_f32 v125, v146, v147
	v_cvt_pk_bf16_f32 v126, v134, v135
	v_cvt_pk_bf16_f32 v127, v132, v127
	v_or_b32_e32 v132, 0x200, v164
	v_ashrrev_i32_e32 v133, 31, v132
	v_lshlrev_b64 v[132:133], 10, v[132:133]
	v_lshl_add_u64 v[132:133], s[20:21], 0, v[132:133]
	v_lshl_add_u64 v[132:133], v[132:133], 0, s[40:41]
	v_lshl_add_u64 v[132:133], v[132:133], 0, v[160:161]
	global_store_dwordx4 v[132:133], v[124:127], off
	v_lshlrev_b32_e32 v132, 16, v158
	v_and_b32_e32 v133, 0xffff0000, v158
	v_lshlrev_b32_e32 v124, 16, v156
	v_and_b32_e32 v125, 0xffff0000, v156
	v_pk_fma_f32 v[116:117], v[108:109], v[124:125], v[116:117]
	v_lshlrev_b32_e32 v126, 16, v157
	v_and_b32_e32 v125, 0x7fffffff, v117
	v_and_b32_e32 v124, 0x7fffffff, v116
	v_pk_fma_f32 v[124:125], v[124:125], s[10:11], 1.0 op_sel_hi:[1,0,0]
	v_and_b32_e32 v127, 0xffff0000, v157
	v_rcp_f32_e32 v124, v124
	v_rcp_f32_e32 v125, v125
	v_pk_fma_f32 v[112:113], v[104:105], v[132:133], v[112:113]
	v_pk_mul_f32 v[132:133], v[116:117], v[116:117]
	v_pk_fma_f32 v[118:119], v[110:111], v[126:127], v[118:119]
	v_pk_fma_f32 v[126:127], v[124:125], s[0:1], v[162:163] op_sel_hi:[1,0,0]
	v_pk_mul_f32 v[132:133], v[132:133], s[18:19] op_sel_hi:[1,0]
	v_lshlrev_b32_e32 v134, 16, v159
	v_and_b32_e32 v135, 0xffff0000, v159
	v_pk_fma_f32 v[126:127], v[124:125], v[126:127], s[16:17] op_sel_hi:[1,1,0]
	v_exp_f32_e32 v132, v132
	v_exp_f32_e32 v133, v133
	v_pk_fma_f32 v[114:115], v[106:107], v[134:135], v[114:115]
	v_pk_fma_f32 v[126:127], v[124:125], v[126:127], s[6:7] op_sel_hi:[1,1,0]
	v_and_b32_e32 v135, 0x7fffffff, v119
	v_and_b32_e32 v134, 0x7fffffff, v118
	v_pk_fma_f32 v[126:127], v[124:125], v[126:127], s[14:15] op_sel_hi:[1,1,0]
	v_pk_fma_f32 v[134:135], v[134:135], s[10:11], 1.0 op_sel_hi:[1,0,0]
	v_pk_mul_f32 v[124:125], v[124:125], v[126:127]
	v_rcp_f32_e32 v134, v134
	v_rcp_f32_e32 v135, v135
	v_pk_mul_f32 v[124:125], v[132:133], v[124:125]
	v_cmp_gt_f32_e32 vcc, 0, v116
	v_pk_mul_f32 v[132:133], v[116:117], v[124:125]
	v_pk_fma_f32 v[124:125], v[116:117], v[124:125], v[116:117] neg_lo:[1,0,0] neg_hi:[1,0,0]
	v_pk_mul_f32 v[126:127], v[118:119], v[118:119]
	v_cndmask_b32_e32 v132, v124, v132, vcc
	v_cmp_gt_f32_e32 vcc, 0, v117
	v_pk_fma_f32 v[116:117], v[134:135], s[0:1], v[162:163] op_sel_hi:[1,0,0]
	s_nop 0
	v_cndmask_b32_e32 v133, v125, v133, vcc
	v_pk_mul_f32 v[124:125], v[126:127], s[18:19] op_sel_hi:[1,0]
	v_pk_fma_f32 v[116:117], v[134:135], v[116:117], s[16:17] op_sel_hi:[1,1,0]
	v_exp_f32_e32 v124, v124
	v_exp_f32_e32 v125, v125
	v_pk_fma_f32 v[116:117], v[134:135], v[116:117], s[6:7] op_sel_hi:[1,1,0]
	v_and_b32_e32 v127, 0x7fffffff, v113
	v_and_b32_e32 v126, 0x7fffffff, v112
	v_pk_fma_f32 v[116:117], v[134:135], v[116:117], s[14:15] op_sel_hi:[1,1,0]
	v_pk_fma_f32 v[126:127], v[126:127], s[10:11], 1.0 op_sel_hi:[1,0,0]
	v_pk_mul_f32 v[116:117], v[134:135], v[116:117]
	v_rcp_f32_e32 v126, v126
	v_rcp_f32_e32 v127, v127
	v_pk_mul_f32 v[116:117], v[124:125], v[116:117]
	v_cmp_gt_f32_e32 vcc, 0, v118
	v_pk_mul_f32 v[124:125], v[118:119], v[116:117]
	v_pk_fma_f32 v[116:117], v[118:119], v[116:117], v[118:119] neg_lo:[1,0,0] neg_hi:[1,0,0]
	s_nop 0
	v_cndmask_b32_e32 v134, v116, v124, vcc
	v_cmp_gt_f32_e32 vcc, 0, v119
	v_pk_mul_f32 v[118:119], v[112:113], v[112:113]
	s_nop 0
	v_cndmask_b32_e32 v135, v117, v125, vcc
	v_pk_fma_f32 v[116:117], v[126:127], s[0:1], v[162:163] op_sel_hi:[1,0,0]
	v_pk_mul_f32 v[118:119], v[118:119], s[18:19] op_sel_hi:[1,0]
	v_pk_fma_f32 v[116:117], v[126:127], v[116:117], s[16:17] op_sel_hi:[1,1,0]
	v_exp_f32_e32 v118, v118
	v_pk_fma_f32 v[116:117], v[126:127], v[116:117], s[6:7] op_sel_hi:[1,1,0]
	v_exp_f32_e32 v119, v119
	v_pk_fma_f32 v[116:117], v[126:127], v[116:117], s[14:15] op_sel_hi:[1,1,0]
	v_cmp_gt_f32_e32 vcc, 0, v112
	v_pk_mul_f32 v[116:117], v[126:127], v[116:117]
	v_and_b32_e32 v127, 0x7fffffff, v115
	v_and_b32_e32 v126, 0x7fffffff, v114
	v_pk_fma_f32 v[126:127], v[126:127], s[10:11], 1.0 op_sel_hi:[1,0,0]
	v_pk_mul_f32 v[116:117], v[118:119], v[116:117]
	v_rcp_f32_e32 v126, v126
	v_rcp_f32_e32 v127, v127
	v_pk_mul_f32 v[118:119], v[112:113], v[116:117]
	v_pk_fma_f32 v[116:117], v[112:113], v[116:117], v[112:113] neg_lo:[1,0,0] neg_hi:[1,0,0]
	v_pk_mul_f32 v[124:125], v[114:115], v[114:115]
	v_cndmask_b32_e32 v118, v116, v118, vcc
	v_cmp_gt_f32_e32 vcc, 0, v113
	v_pk_fma_f32 v[112:113], v[126:127], s[0:1], v[162:163] op_sel_hi:[1,0,0]
	s_nop 0
	v_cndmask_b32_e32 v119, v117, v119, vcc
	v_pk_mul_f32 v[116:117], v[124:125], s[18:19] op_sel_hi:[1,0]
	v_pk_fma_f32 v[112:113], v[126:127], v[112:113], s[16:17] op_sel_hi:[1,1,0]
	v_exp_f32_e32 v116, v116
	v_exp_f32_e32 v117, v117
	v_pk_fma_f32 v[112:113], v[126:127], v[112:113], s[6:7] op_sel_hi:[1,1,0]
	v_cmp_gt_f32_e32 vcc, 0, v114
	v_pk_fma_f32 v[112:113], v[126:127], v[112:113], s[14:15] op_sel_hi:[1,1,0]
	s_nop 0
	v_pk_mul_f32 v[112:113], v[126:127], v[112:113]
	s_nop 0
	v_pk_mul_f32 v[112:113], v[116:117], v[112:113]
	s_nop 0
	v_pk_mul_f32 v[116:117], v[114:115], v[112:113]
	v_pk_fma_f32 v[112:113], v[114:115], v[112:113], v[114:115] neg_lo:[1,0,0] neg_hi:[1,0,0]
	s_nop 0
	v_cndmask_b32_e32 v116, v112, v116, vcc
	v_cmp_gt_f32_e32 vcc, 0, v115
	v_cvt_pk_bf16_f32 v112, v132, v133
	s_nop 1
	v_cndmask_b32_e32 v115, v113, v117, vcc
	v_cvt_pk_bf16_f32 v113, v134, v135
	v_cvt_pk_bf16_f32 v114, v118, v119
	v_cvt_pk_bf16_f32 v115, v116, v115
	v_or_b32_e32 v116, 0x400, v164
	v_ashrrev_i32_e32 v117, 31, v116
	v_lshlrev_b64 v[116:117], 10, v[116:117]
	v_lshl_add_u64 v[116:117], s[20:21], 0, v[116:117]
	v_lshl_add_u64 v[116:117], v[116:117], 0, s[40:41]
	v_lshl_add_u64 v[116:117], v[116:117], 0, v[160:161]
	global_store_dwordx4 v[116:117], v[112:115], off
	v_lshlrev_b32_e32 v116, 16, v154
	v_and_b32_e32 v117, 0xffff0000, v154
	v_lshlrev_b32_e32 v112, 16, v152
	v_and_b32_e32 v113, 0xffff0000, v152
	v_pk_fma_f32 v[100:101], v[108:109], v[112:113], v[100:101]
	v_lshlrev_b32_e32 v114, 16, v153
	v_and_b32_e32 v113, 0x7fffffff, v101
	v_and_b32_e32 v112, 0x7fffffff, v100
	v_pk_fma_f32 v[112:113], v[112:113], s[10:11], 1.0 op_sel_hi:[1,0,0]
	v_and_b32_e32 v115, 0xffff0000, v153
	v_rcp_f32_e32 v112, v112
	v_rcp_f32_e32 v113, v113
	v_pk_fma_f32 v[96:97], v[104:105], v[116:117], v[96:97]
	v_pk_mul_f32 v[116:117], v[100:101], v[100:101]
	v_pk_fma_f32 v[102:103], v[110:111], v[114:115], v[102:103]
	v_pk_fma_f32 v[114:115], v[112:113], s[0:1], v[162:163] op_sel_hi:[1,0,0]
	v_pk_mul_f32 v[116:117], v[116:117], s[18:19] op_sel_hi:[1,0]
	v_lshlrev_b32_e32 v118, 16, v155
	v_and_b32_e32 v119, 0xffff0000, v155
	v_pk_fma_f32 v[114:115], v[112:113], v[114:115], s[16:17] op_sel_hi:[1,1,0]
	v_exp_f32_e32 v116, v116
	v_exp_f32_e32 v117, v117
	v_pk_fma_f32 v[98:99], v[106:107], v[118:119], v[98:99]
	v_pk_fma_f32 v[114:115], v[112:113], v[114:115], s[6:7] op_sel_hi:[1,1,0]
	v_and_b32_e32 v119, 0x7fffffff, v103
	v_and_b32_e32 v118, 0x7fffffff, v102
	v_pk_fma_f32 v[114:115], v[112:113], v[114:115], s[14:15] op_sel_hi:[1,1,0]
	v_pk_fma_f32 v[118:119], v[118:119], s[10:11], 1.0 op_sel_hi:[1,0,0]
	v_pk_mul_f32 v[112:113], v[112:113], v[114:115]
	v_rcp_f32_e32 v118, v118
	v_rcp_f32_e32 v119, v119
	v_pk_mul_f32 v[112:113], v[116:117], v[112:113]
	v_cmp_gt_f32_e32 vcc, 0, v100
	v_pk_mul_f32 v[116:117], v[100:101], v[112:113]
	v_pk_fma_f32 v[112:113], v[100:101], v[112:113], v[100:101] neg_lo:[1,0,0] neg_hi:[1,0,0]
	v_pk_mul_f32 v[114:115], v[102:103], v[102:103]
	v_cndmask_b32_e32 v116, v112, v116, vcc
	v_cmp_gt_f32_e32 vcc, 0, v101
	v_pk_fma_f32 v[100:101], v[118:119], s[0:1], v[162:163] op_sel_hi:[1,0,0]
	s_nop 0
	v_cndmask_b32_e32 v117, v113, v117, vcc
	v_pk_mul_f32 v[112:113], v[114:115], s[18:19] op_sel_hi:[1,0]
	v_pk_fma_f32 v[100:101], v[118:119], v[100:101], s[16:17] op_sel_hi:[1,1,0]
	v_exp_f32_e32 v112, v112
	v_exp_f32_e32 v113, v113
	v_pk_fma_f32 v[100:101], v[118:119], v[100:101], s[6:7] op_sel_hi:[1,1,0]
	v_and_b32_e32 v115, 0x7fffffff, v97
	v_and_b32_e32 v114, 0x7fffffff, v96
	v_pk_fma_f32 v[100:101], v[118:119], v[100:101], s[14:15] op_sel_hi:[1,1,0]
	v_pk_fma_f32 v[114:115], v[114:115], s[10:11], 1.0 op_sel_hi:[1,0,0]
	v_pk_mul_f32 v[100:101], v[118:119], v[100:101]
	v_rcp_f32_e32 v114, v114
	v_rcp_f32_e32 v115, v115
	v_pk_mul_f32 v[100:101], v[112:113], v[100:101]
	v_cmp_gt_f32_e32 vcc, 0, v102
	v_pk_mul_f32 v[112:113], v[102:103], v[100:101]
	v_pk_fma_f32 v[100:101], v[102:103], v[100:101], v[102:103] neg_lo:[1,0,0] neg_hi:[1,0,0]
	s_nop 0
	v_cndmask_b32_e32 v118, v100, v112, vcc
	v_cmp_gt_f32_e32 vcc, 0, v103
	v_pk_mul_f32 v[102:103], v[96:97], v[96:97]
	s_nop 0
	v_cndmask_b32_e32 v119, v101, v113, vcc
	v_pk_fma_f32 v[100:101], v[114:115], s[0:1], v[162:163] op_sel_hi:[1,0,0]
	v_pk_mul_f32 v[102:103], v[102:103], s[18:19] op_sel_hi:[1,0]
	v_pk_fma_f32 v[100:101], v[114:115], v[100:101], s[16:17] op_sel_hi:[1,1,0]
	v_exp_f32_e32 v102, v102
	v_pk_fma_f32 v[100:101], v[114:115], v[100:101], s[6:7] op_sel_hi:[1,1,0]
	v_exp_f32_e32 v103, v103
	v_pk_fma_f32 v[100:101], v[114:115], v[100:101], s[14:15] op_sel_hi:[1,1,0]
	v_cmp_gt_f32_e32 vcc, 0, v96
	v_pk_mul_f32 v[100:101], v[114:115], v[100:101]
	v_and_b32_e32 v115, 0x7fffffff, v99
	v_and_b32_e32 v114, 0x7fffffff, v98
	v_pk_fma_f32 v[114:115], v[114:115], s[10:11], 1.0 op_sel_hi:[1,0,0]
	v_pk_mul_f32 v[100:101], v[102:103], v[100:101]
	v_rcp_f32_e32 v114, v114
	v_rcp_f32_e32 v115, v115
	v_pk_mul_f32 v[102:103], v[96:97], v[100:101]
	v_pk_fma_f32 v[100:101], v[96:97], v[100:101], v[96:97] neg_lo:[1,0,0] neg_hi:[1,0,0]
	v_pk_mul_f32 v[112:113], v[98:99], v[98:99]
	v_cndmask_b32_e32 v102, v100, v102, vcc
	v_cmp_gt_f32_e32 vcc, 0, v97
	v_pk_fma_f32 v[96:97], v[114:115], s[0:1], v[162:163] op_sel_hi:[1,0,0]
	s_nop 0
	v_cndmask_b32_e32 v103, v101, v103, vcc
	v_pk_mul_f32 v[100:101], v[112:113], s[18:19] op_sel_hi:[1,0]
	v_pk_fma_f32 v[96:97], v[114:115], v[96:97], s[16:17] op_sel_hi:[1,1,0]
	v_exp_f32_e32 v100, v100
	v_exp_f32_e32 v101, v101
	v_pk_fma_f32 v[96:97], v[114:115], v[96:97], s[6:7] op_sel_hi:[1,1,0]
	v_cmp_gt_f32_e32 vcc, 0, v98
	v_pk_fma_f32 v[96:97], v[114:115], v[96:97], s[14:15] op_sel_hi:[1,1,0]
	v_lshlrev_b32_e32 v112, 16, v151
	v_pk_mul_f32 v[96:97], v[114:115], v[96:97]
	v_and_b32_e32 v113, 0xffff0000, v151
	v_pk_mul_f32 v[96:97], v[100:101], v[96:97]
	v_pk_fma_f32 v[90:91], v[106:107], v[112:113], v[90:91]
	v_pk_mul_f32 v[100:101], v[98:99], v[96:97]
	v_pk_fma_f32 v[96:97], v[98:99], v[96:97], v[98:99] neg_lo:[1,0,0] neg_hi:[1,0,0]
	s_nop 0
	v_cndmask_b32_e32 v100, v96, v100, vcc
	v_cmp_gt_f32_e32 vcc, 0, v99
	v_cvt_pk_bf16_f32 v96, v116, v117
	s_nop 1
	v_cndmask_b32_e32 v99, v97, v101, vcc
	v_cvt_pk_bf16_f32 v97, v118, v119
	v_cvt_pk_bf16_f32 v98, v102, v103
	v_cvt_pk_bf16_f32 v99, v100, v99
	v_or_b32_e32 v100, 0x600, v164
	v_ashrrev_i32_e32 v101, 31, v100
	v_lshlrev_b64 v[100:101], 10, v[100:101]
	v_lshl_add_u64 v[100:101], s[20:21], 0, v[100:101]
	v_lshl_add_u64 v[100:101], v[100:101], 0, s[40:41]
	v_lshl_add_u64 v[100:101], v[100:101], 0, v[160:161]
	global_store_dwordx4 v[100:101], v[96:99], off
	v_lshlrev_b32_e32 v102, 16, v150
	v_and_b32_e32 v103, 0xffff0000, v150
	v_lshlrev_b32_e32 v98, 16, v148
	v_and_b32_e32 v99, 0xffff0000, v148
	v_pk_fma_f32 v[92:93], v[108:109], v[98:99], v[92:93]
	v_lshlrev_b32_e32 v100, 16, v149
	v_and_b32_e32 v99, 0x7fffffff, v93
	v_and_b32_e32 v98, 0x7fffffff, v92
	v_pk_fma_f32 v[98:99], v[98:99], s[10:11], 1.0 op_sel_hi:[1,0,0]
	v_and_b32_e32 v101, 0xffff0000, v149
	v_rcp_f32_e32 v98, v98
	v_rcp_f32_e32 v99, v99
	v_pk_fma_f32 v[88:89], v[104:105], v[102:103], v[88:89]
	v_pk_mul_f32 v[102:103], v[92:93], v[92:93]
	v_pk_fma_f32 v[94:95], v[110:111], v[100:101], v[94:95]
	v_pk_fma_f32 v[100:101], v[98:99], s[0:1], v[162:163] op_sel_hi:[1,0,0]
	v_pk_mul_f32 v[102:103], v[102:103], s[18:19] op_sel_hi:[1,0]
	v_pk_fma_f32 v[100:101], v[98:99], v[100:101], s[16:17] op_sel_hi:[1,1,0]
	v_exp_f32_e32 v102, v102
	v_exp_f32_e32 v103, v103
	v_pk_fma_f32 v[100:101], v[98:99], v[100:101], s[6:7] op_sel_hi:[1,1,0]
	v_and_b32_e32 v113, 0x7fffffff, v95
	v_and_b32_e32 v112, 0x7fffffff, v94
	v_pk_fma_f32 v[100:101], v[98:99], v[100:101], s[14:15] op_sel_hi:[1,1,0]
	v_pk_fma_f32 v[112:113], v[112:113], s[10:11], 1.0 op_sel_hi:[1,0,0]
	v_pk_mul_f32 v[98:99], v[98:99], v[100:101]
	v_rcp_f32_e32 v112, v112
	v_rcp_f32_e32 v113, v113
	v_pk_mul_f32 v[98:99], v[102:103], v[98:99]
	v_cmp_gt_f32_e32 vcc, 0, v92
	v_pk_mul_f32 v[102:103], v[92:93], v[98:99]
	v_pk_fma_f32 v[98:99], v[92:93], v[98:99], v[92:93] neg_lo:[1,0,0] neg_hi:[1,0,0]
	v_pk_mul_f32 v[100:101], v[94:95], v[94:95]
	v_cndmask_b32_e32 v97, v98, v102, vcc
	v_cmp_gt_f32_e32 vcc, 0, v93
	v_pk_fma_f32 v[92:93], v[112:113], s[0:1], v[162:163] op_sel_hi:[1,0,0]
	v_add_u32_e32 v96, 0x1000, v164
	v_cndmask_b32_e32 v102, v99, v103, vcc
	v_pk_mul_f32 v[98:99], v[100:101], s[18:19] op_sel_hi:[1,0]
	v_pk_fma_f32 v[92:93], v[112:113], v[92:93], s[16:17] op_sel_hi:[1,1,0]
	v_exp_f32_e32 v98, v98
	v_exp_f32_e32 v99, v99
	v_pk_fma_f32 v[92:93], v[112:113], v[92:93], s[6:7] op_sel_hi:[1,1,0]
	v_and_b32_e32 v101, 0x7fffffff, v89
	v_and_b32_e32 v100, 0x7fffffff, v88
	v_pk_fma_f32 v[92:93], v[112:113], v[92:93], s[14:15] op_sel_hi:[1,1,0]
	v_pk_fma_f32 v[100:101], v[100:101], s[10:11], 1.0 op_sel_hi:[1,0,0]
	v_pk_mul_f32 v[92:93], v[112:113], v[92:93]
	v_rcp_f32_e32 v100, v100
	v_rcp_f32_e32 v101, v101
	v_pk_mul_f32 v[92:93], v[98:99], v[92:93]
	v_cmp_gt_f32_e32 vcc, 0, v94
	v_pk_mul_f32 v[98:99], v[94:95], v[92:93]
	v_pk_fma_f32 v[92:93], v[94:95], v[92:93], v[94:95] neg_lo:[1,0,0] neg_hi:[1,0,0]
	s_nop 0
	v_cndmask_b32_e32 v103, v92, v98, vcc
	v_cmp_gt_f32_e32 vcc, 0, v95
	v_pk_mul_f32 v[94:95], v[88:89], v[88:89]
	s_nop 0
	v_cndmask_b32_e32 v112, v93, v99, vcc
	v_pk_fma_f32 v[92:93], v[100:101], s[0:1], v[162:163] op_sel_hi:[1,0,0]
	v_pk_mul_f32 v[94:95], v[94:95], s[18:19] op_sel_hi:[1,0]
	v_pk_fma_f32 v[92:93], v[100:101], v[92:93], s[16:17] op_sel_hi:[1,1,0]
	v_exp_f32_e32 v94, v94
	v_pk_fma_f32 v[92:93], v[100:101], v[92:93], s[6:7] op_sel_hi:[1,1,0]
	v_exp_f32_e32 v95, v95
	v_pk_fma_f32 v[92:93], v[100:101], v[92:93], s[14:15] op_sel_hi:[1,1,0]
	v_cmp_gt_f32_e32 vcc, 0, v88
	v_pk_mul_f32 v[92:93], v[100:101], v[92:93]
	v_and_b32_e32 v101, 0x7fffffff, v91
	v_and_b32_e32 v100, 0x7fffffff, v90
	v_pk_fma_f32 v[100:101], v[100:101], s[10:11], 1.0 op_sel_hi:[1,0,0]
	v_pk_mul_f32 v[92:93], v[94:95], v[92:93]
	v_rcp_f32_e32 v100, v100
	v_rcp_f32_e32 v101, v101
	v_pk_mul_f32 v[94:95], v[88:89], v[92:93]
	v_pk_fma_f32 v[92:93], v[88:89], v[92:93], v[88:89] neg_lo:[1,0,0] neg_hi:[1,0,0]
	v_pk_mul_f32 v[98:99], v[90:91], v[90:91]
	v_cndmask_b32_e32 v94, v92, v94, vcc
	v_cmp_gt_f32_e32 vcc, 0, v89
	v_pk_fma_f32 v[88:89], v[100:101], s[0:1], v[162:163] op_sel_hi:[1,0,0]
	s_nop 0
	v_cndmask_b32_e32 v95, v93, v95, vcc
	v_pk_mul_f32 v[92:93], v[98:99], s[18:19] op_sel_hi:[1,0]
	v_pk_fma_f32 v[88:89], v[100:101], v[88:89], s[16:17] op_sel_hi:[1,1,0]
	v_exp_f32_e32 v92, v92
	v_exp_f32_e32 v93, v93
	v_pk_fma_f32 v[88:89], v[100:101], v[88:89], s[6:7] op_sel_hi:[1,1,0]
	v_cmp_gt_f32_e32 vcc, 0, v90
	v_pk_fma_f32 v[88:89], v[100:101], v[88:89], s[14:15] op_sel_hi:[1,1,0]
	s_nop 0
	v_pk_mul_f32 v[88:89], v[100:101], v[88:89]
	s_nop 0
	v_pk_mul_f32 v[88:89], v[92:93], v[88:89]
	s_nop 0
	v_pk_mul_f32 v[92:93], v[90:91], v[88:89]
	v_pk_fma_f32 v[88:89], v[90:91], v[88:89], v[90:91] neg_lo:[1,0,0] neg_hi:[1,0,0]
	s_nop 0
	v_cndmask_b32_e32 v92, v88, v92, vcc
	v_cmp_gt_f32_e32 vcc, 0, v91
	v_cvt_pk_bf16_f32 v88, v97, v102
	v_ashrrev_i32_e32 v97, 31, v96
	s_nop 0
	v_cndmask_b32_e32 v91, v89, v93, vcc
	v_cvt_pk_bf16_f32 v89, v103, v112
	v_cvt_pk_bf16_f32 v90, v94, v95
	v_cvt_pk_bf16_f32 v91, v92, v91
	v_lshlrev_b64 v[92:93], 10, v[96:97]
	v_lshl_add_u64 v[92:93], s[20:21], 0, v[92:93]
	v_lshl_add_u64 v[92:93], v[92:93], 0, s[40:41]
	v_lshl_add_u64 v[92:93], v[92:93], 0, v[160:161]
	global_store_dwordx4 v[92:93], v[88:91], off
	v_lshlrev_b32_e32 v92, 16, v138
	v_and_b32_e32 v93, 0xffff0000, v138
	v_lshlrev_b32_e32 v88, 16, v136
	v_and_b32_e32 v89, 0xffff0000, v136
	v_pk_fma_f32 v[84:85], v[108:109], v[88:89], v[84:85]
	v_lshlrev_b32_e32 v90, 16, v137
	v_and_b32_e32 v89, 0x7fffffff, v85
	v_and_b32_e32 v88, 0x7fffffff, v84
	v_pk_fma_f32 v[88:89], v[88:89], s[10:11], 1.0 op_sel_hi:[1,0,0]
	v_and_b32_e32 v91, 0xffff0000, v137
	v_rcp_f32_e32 v88, v88
	v_rcp_f32_e32 v89, v89
	v_pk_fma_f32 v[80:81], v[104:105], v[92:93], v[80:81]
	v_pk_mul_f32 v[92:93], v[84:85], v[84:85]
	v_pk_fma_f32 v[86:87], v[110:111], v[90:91], v[86:87]
	v_pk_fma_f32 v[90:91], v[88:89], s[0:1], v[162:163] op_sel_hi:[1,0,0]
	v_pk_mul_f32 v[92:93], v[92:93], s[18:19] op_sel_hi:[1,0]
	v_lshlrev_b32_e32 v94, 16, v139
	v_and_b32_e32 v95, 0xffff0000, v139
	v_pk_fma_f32 v[90:91], v[88:89], v[90:91], s[16:17] op_sel_hi:[1,1,0]
	v_exp_f32_e32 v92, v92
	v_exp_f32_e32 v93, v93
	v_pk_fma_f32 v[82:83], v[106:107], v[94:95], v[82:83]
	v_pk_fma_f32 v[90:91], v[88:89], v[90:91], s[6:7] op_sel_hi:[1,1,0]
	v_and_b32_e32 v95, 0x7fffffff, v87
	v_and_b32_e32 v94, 0x7fffffff, v86
	v_pk_fma_f32 v[90:91], v[88:89], v[90:91], s[14:15] op_sel_hi:[1,1,0]
	v_pk_fma_f32 v[94:95], v[94:95], s[10:11], 1.0 op_sel_hi:[1,0,0]
	v_pk_mul_f32 v[88:89], v[88:89], v[90:91]
	v_rcp_f32_e32 v94, v94
	v_rcp_f32_e32 v95, v95
	v_pk_mul_f32 v[88:89], v[92:93], v[88:89]
	v_cmp_gt_f32_e32 vcc, 0, v84
	v_pk_mul_f32 v[92:93], v[84:85], v[88:89]
	v_pk_fma_f32 v[88:89], v[84:85], v[88:89], v[84:85] neg_lo:[1,0,0] neg_hi:[1,0,0]
	v_pk_mul_f32 v[90:91], v[86:87], v[86:87]
	v_cndmask_b32_e32 v92, v88, v92, vcc
	v_cmp_gt_f32_e32 vcc, 0, v85
	v_pk_fma_f32 v[84:85], v[94:95], s[0:1], v[162:163] op_sel_hi:[1,0,0]
	v_or_b32_e32 v96, 0x80, v167
	v_cndmask_b32_e32 v93, v89, v93, vcc
	v_pk_mul_f32 v[88:89], v[90:91], s[18:19] op_sel_hi:[1,0]
	v_pk_fma_f32 v[84:85], v[94:95], v[84:85], s[16:17] op_sel_hi:[1,1,0]
	v_exp_f32_e32 v88, v88
	v_exp_f32_e32 v89, v89
	v_pk_fma_f32 v[84:85], v[94:95], v[84:85], s[6:7] op_sel_hi:[1,1,0]
	v_and_b32_e32 v91, 0x7fffffff, v81
	v_and_b32_e32 v90, 0x7fffffff, v80
	v_pk_fma_f32 v[84:85], v[94:95], v[84:85], s[14:15] op_sel_hi:[1,1,0]
	v_pk_fma_f32 v[90:91], v[90:91], s[10:11], 1.0 op_sel_hi:[1,0,0]
	v_pk_mul_f32 v[84:85], v[94:95], v[84:85]
	v_rcp_f32_e32 v90, v90
	v_rcp_f32_e32 v91, v91
	v_pk_mul_f32 v[84:85], v[88:89], v[84:85]
	v_cmp_gt_f32_e32 vcc, 0, v86
	v_pk_mul_f32 v[88:89], v[86:87], v[84:85]
	v_pk_fma_f32 v[84:85], v[86:87], v[84:85], v[86:87] neg_lo:[1,0,0] neg_hi:[1,0,0]
	s_nop 0
	v_cndmask_b32_e32 v94, v84, v88, vcc
	v_cmp_gt_f32_e32 vcc, 0, v87
	v_pk_mul_f32 v[86:87], v[80:81], v[80:81]
	s_nop 0
	v_cndmask_b32_e32 v95, v85, v89, vcc
	v_pk_fma_f32 v[84:85], v[90:91], s[0:1], v[162:163] op_sel_hi:[1,0,0]
	v_pk_mul_f32 v[86:87], v[86:87], s[18:19] op_sel_hi:[1,0]
	v_pk_fma_f32 v[84:85], v[90:91], v[84:85], s[16:17] op_sel_hi:[1,1,0]
	v_exp_f32_e32 v86, v86
	v_pk_fma_f32 v[84:85], v[90:91], v[84:85], s[6:7] op_sel_hi:[1,1,0]
	v_exp_f32_e32 v87, v87
	v_pk_fma_f32 v[84:85], v[90:91], v[84:85], s[14:15] op_sel_hi:[1,1,0]
	v_cmp_gt_f32_e32 vcc, 0, v80
	v_pk_mul_f32 v[84:85], v[90:91], v[84:85]
	v_and_b32_e32 v91, 0x7fffffff, v83
	v_and_b32_e32 v90, 0x7fffffff, v82
	v_pk_fma_f32 v[90:91], v[90:91], s[10:11], 1.0 op_sel_hi:[1,0,0]
	v_pk_mul_f32 v[84:85], v[86:87], v[84:85]
	v_rcp_f32_e32 v90, v90
	v_rcp_f32_e32 v91, v91
	v_pk_mul_f32 v[86:87], v[80:81], v[84:85]
	v_pk_fma_f32 v[84:85], v[80:81], v[84:85], v[80:81] neg_lo:[1,0,0] neg_hi:[1,0,0]
	v_pk_mul_f32 v[88:89], v[82:83], v[82:83]
	v_cndmask_b32_e32 v86, v84, v86, vcc
	v_cmp_gt_f32_e32 vcc, 0, v81
	v_pk_fma_f32 v[80:81], v[90:91], s[0:1], v[162:163] op_sel_hi:[1,0,0]
	s_nop 0
	v_cndmask_b32_e32 v87, v85, v87, vcc
	v_pk_mul_f32 v[84:85], v[88:89], s[18:19] op_sel_hi:[1,0]
	v_pk_fma_f32 v[80:81], v[90:91], v[80:81], s[16:17] op_sel_hi:[1,1,0]
	v_exp_f32_e32 v84, v84
	v_exp_f32_e32 v85, v85
	v_pk_fma_f32 v[80:81], v[90:91], v[80:81], s[6:7] op_sel_hi:[1,1,0]
	v_cmp_gt_f32_e32 vcc, 0, v82
	v_pk_fma_f32 v[80:81], v[90:91], v[80:81], s[14:15] op_sel_hi:[1,1,0]
	s_nop 0
	v_pk_mul_f32 v[80:81], v[90:91], v[80:81]
	s_nop 0
	v_pk_mul_f32 v[80:81], v[84:85], v[80:81]
	s_nop 0
	v_pk_mul_f32 v[84:85], v[82:83], v[80:81]
	v_pk_fma_f32 v[80:81], v[82:83], v[80:81], v[82:83] neg_lo:[1,0,0] neg_hi:[1,0,0]
	s_nop 0
	v_cndmask_b32_e32 v84, v80, v84, vcc
	v_cmp_gt_f32_e32 vcc, 0, v83
	v_cvt_pk_bf16_f32 v80, v92, v93
	s_nop 1
	v_cndmask_b32_e32 v83, v81, v85, vcc
	v_cvt_pk_bf16_f32 v81, v94, v95
	v_cvt_pk_bf16_f32 v82, v86, v87
	v_cvt_pk_bf16_f32 v83, v84, v83
	v_add_u32_e32 v84, 0x1200, v164
	v_ashrrev_i32_e32 v85, 31, v84
	v_lshlrev_b64 v[84:85], 10, v[84:85]
	v_lshl_add_u64 v[84:85], s[20:21], 0, v[84:85]
	v_lshl_add_u64 v[84:85], v[84:85], 0, s[40:41]
	v_lshl_add_u64 v[84:85], v[84:85], 0, v[160:161]
	global_store_dwordx4 v[84:85], v[80:83], off
	v_lshlrev_b32_e32 v84, 16, v130
	v_and_b32_e32 v85, 0xffff0000, v130
	v_lshlrev_b32_e32 v80, 16, v128
	v_and_b32_e32 v81, 0xffff0000, v128
	v_pk_fma_f32 v[76:77], v[108:109], v[80:81], v[76:77]
	v_lshlrev_b32_e32 v82, 16, v129
	v_and_b32_e32 v81, 0x7fffffff, v77
	v_and_b32_e32 v80, 0x7fffffff, v76
	v_pk_fma_f32 v[80:81], v[80:81], s[10:11], 1.0 op_sel_hi:[1,0,0]
	v_and_b32_e32 v83, 0xffff0000, v129
	v_rcp_f32_e32 v80, v80
	v_rcp_f32_e32 v81, v81
	v_pk_fma_f32 v[72:73], v[104:105], v[84:85], v[72:73]
	v_pk_mul_f32 v[84:85], v[76:77], v[76:77]
	v_pk_fma_f32 v[78:79], v[110:111], v[82:83], v[78:79]
	v_pk_fma_f32 v[82:83], v[80:81], s[0:1], v[162:163] op_sel_hi:[1,0,0]
	v_pk_mul_f32 v[84:85], v[84:85], s[18:19] op_sel_hi:[1,0]
	v_lshlrev_b32_e32 v86, 16, v131
	v_and_b32_e32 v87, 0xffff0000, v131
	v_pk_fma_f32 v[82:83], v[80:81], v[82:83], s[16:17] op_sel_hi:[1,1,0]
	v_exp_f32_e32 v84, v84
	v_exp_f32_e32 v85, v85
	v_pk_fma_f32 v[74:75], v[106:107], v[86:87], v[74:75]
	v_pk_fma_f32 v[82:83], v[80:81], v[82:83], s[6:7] op_sel_hi:[1,1,0]
	v_and_b32_e32 v87, 0x7fffffff, v79
	v_and_b32_e32 v86, 0x7fffffff, v78
	v_pk_fma_f32 v[82:83], v[80:81], v[82:83], s[14:15] op_sel_hi:[1,1,0]
	v_pk_fma_f32 v[86:87], v[86:87], s[10:11], 1.0 op_sel_hi:[1,0,0]
	v_pk_mul_f32 v[80:81], v[80:81], v[82:83]
	v_rcp_f32_e32 v86, v86
	v_rcp_f32_e32 v87, v87
	v_pk_mul_f32 v[80:81], v[84:85], v[80:81]
	v_cmp_gt_f32_e32 vcc, 0, v76
	v_pk_mul_f32 v[84:85], v[76:77], v[80:81]
	v_pk_fma_f32 v[80:81], v[76:77], v[80:81], v[76:77] neg_lo:[1,0,0] neg_hi:[1,0,0]
	v_pk_mul_f32 v[82:83], v[78:79], v[78:79]
	v_cndmask_b32_e32 v84, v80, v84, vcc
	v_cmp_gt_f32_e32 vcc, 0, v77
	v_pk_fma_f32 v[76:77], v[86:87], s[0:1], v[162:163] op_sel_hi:[1,0,0]
	s_nop 0
	v_cndmask_b32_e32 v85, v81, v85, vcc
	v_pk_mul_f32 v[80:81], v[82:83], s[18:19] op_sel_hi:[1,0]
	v_pk_fma_f32 v[76:77], v[86:87], v[76:77], s[16:17] op_sel_hi:[1,1,0]
	v_exp_f32_e32 v80, v80
	v_exp_f32_e32 v81, v81
	v_pk_fma_f32 v[76:77], v[86:87], v[76:77], s[6:7] op_sel_hi:[1,1,0]
	v_and_b32_e32 v83, 0x7fffffff, v73
	v_and_b32_e32 v82, 0x7fffffff, v72
	v_pk_fma_f32 v[76:77], v[86:87], v[76:77], s[14:15] op_sel_hi:[1,1,0]
	v_pk_fma_f32 v[82:83], v[82:83], s[10:11], 1.0 op_sel_hi:[1,0,0]
	v_pk_mul_f32 v[76:77], v[86:87], v[76:77]
	v_rcp_f32_e32 v82, v82
	v_rcp_f32_e32 v83, v83
	v_pk_mul_f32 v[76:77], v[80:81], v[76:77]
	v_cmp_gt_f32_e32 vcc, 0, v78
	v_pk_mul_f32 v[80:81], v[78:79], v[76:77]
	v_pk_fma_f32 v[76:77], v[78:79], v[76:77], v[78:79] neg_lo:[1,0,0] neg_hi:[1,0,0]
	s_nop 0
	v_cndmask_b32_e32 v86, v76, v80, vcc
	v_cmp_gt_f32_e32 vcc, 0, v79
	v_pk_mul_f32 v[78:79], v[72:73], v[72:73]
	s_nop 0
	v_cndmask_b32_e32 v87, v77, v81, vcc
	v_pk_fma_f32 v[76:77], v[82:83], s[0:1], v[162:163] op_sel_hi:[1,0,0]
	v_pk_mul_f32 v[78:79], v[78:79], s[18:19] op_sel_hi:[1,0]
	v_pk_fma_f32 v[76:77], v[82:83], v[76:77], s[16:17] op_sel_hi:[1,1,0]
	v_exp_f32_e32 v78, v78
	v_pk_fma_f32 v[76:77], v[82:83], v[76:77], s[6:7] op_sel_hi:[1,1,0]
	v_exp_f32_e32 v79, v79
	v_pk_fma_f32 v[76:77], v[82:83], v[76:77], s[14:15] op_sel_hi:[1,1,0]
	v_cmp_gt_f32_e32 vcc, 0, v72
	v_pk_mul_f32 v[76:77], v[82:83], v[76:77]
	v_and_b32_e32 v83, 0x7fffffff, v75
	v_and_b32_e32 v82, 0x7fffffff, v74
	v_pk_fma_f32 v[82:83], v[82:83], s[10:11], 1.0 op_sel_hi:[1,0,0]
	v_pk_mul_f32 v[76:77], v[78:79], v[76:77]
	v_rcp_f32_e32 v82, v82
	v_rcp_f32_e32 v83, v83
	v_pk_mul_f32 v[78:79], v[72:73], v[76:77]
	v_pk_fma_f32 v[76:77], v[72:73], v[76:77], v[72:73] neg_lo:[1,0,0] neg_hi:[1,0,0]
	v_pk_mul_f32 v[80:81], v[74:75], v[74:75]
	v_cndmask_b32_e32 v78, v76, v78, vcc
	v_cmp_gt_f32_e32 vcc, 0, v73
	v_pk_fma_f32 v[72:73], v[82:83], s[0:1], v[162:163] op_sel_hi:[1,0,0]
	s_nop 0
	v_cndmask_b32_e32 v79, v77, v79, vcc
	v_pk_mul_f32 v[76:77], v[80:81], s[18:19] op_sel_hi:[1,0]
	v_pk_fma_f32 v[72:73], v[82:83], v[72:73], s[16:17] op_sel_hi:[1,1,0]
	v_exp_f32_e32 v76, v76
	v_exp_f32_e32 v77, v77
	v_pk_fma_f32 v[72:73], v[82:83], v[72:73], s[6:7] op_sel_hi:[1,1,0]
	v_cmp_gt_f32_e32 vcc, 0, v74
	v_pk_fma_f32 v[72:73], v[82:83], v[72:73], s[14:15] op_sel_hi:[1,1,0]
	s_nop 0
	v_pk_mul_f32 v[72:73], v[82:83], v[72:73]
	s_nop 0
	v_pk_mul_f32 v[72:73], v[76:77], v[72:73]
	s_nop 0
	v_pk_mul_f32 v[76:77], v[74:75], v[72:73]
	v_pk_fma_f32 v[72:73], v[74:75], v[72:73], v[74:75] neg_lo:[1,0,0] neg_hi:[1,0,0]
	s_nop 0
	v_cndmask_b32_e32 v76, v72, v76, vcc
	v_cmp_gt_f32_e32 vcc, 0, v75
	v_cvt_pk_bf16_f32 v72, v84, v85
	s_nop 1
	v_cndmask_b32_e32 v75, v73, v77, vcc
	v_cvt_pk_bf16_f32 v73, v86, v87
	v_cvt_pk_bf16_f32 v74, v78, v79
	v_cvt_pk_bf16_f32 v75, v76, v75
	v_add_u32_e32 v76, 0x1400, v164
	v_ashrrev_i32_e32 v77, 31, v76
	v_lshlrev_b64 v[76:77], 10, v[76:77]
	v_lshl_add_u64 v[76:77], s[20:21], 0, v[76:77]
	v_lshl_add_u64 v[76:77], v[76:77], 0, s[40:41]
	v_lshl_add_u64 v[76:77], v[76:77], 0, v[160:161]
	global_store_dwordx4 v[76:77], v[72:75], off
	v_lshlrev_b32_e32 v76, 16, v122
	v_and_b32_e32 v77, 0xffff0000, v122
	v_lshlrev_b32_e32 v72, 16, v120
	v_and_b32_e32 v73, 0xffff0000, v120
	v_pk_fma_f32 v[68:69], v[108:109], v[72:73], v[68:69]
	v_lshlrev_b32_e32 v74, 16, v121
	v_and_b32_e32 v73, 0x7fffffff, v69
	v_and_b32_e32 v72, 0x7fffffff, v68
	v_pk_fma_f32 v[72:73], v[72:73], s[10:11], 1.0 op_sel_hi:[1,0,0]
	v_and_b32_e32 v75, 0xffff0000, v121
	v_rcp_f32_e32 v72, v72
	v_rcp_f32_e32 v73, v73
	v_pk_fma_f32 v[64:65], v[104:105], v[76:77], v[64:65]
	v_pk_mul_f32 v[76:77], v[68:69], v[68:69]
	v_pk_fma_f32 v[70:71], v[110:111], v[74:75], v[70:71]
	v_pk_fma_f32 v[74:75], v[72:73], s[0:1], v[162:163] op_sel_hi:[1,0,0]
	v_pk_mul_f32 v[76:77], v[76:77], s[18:19] op_sel_hi:[1,0]
	v_lshlrev_b32_e32 v78, 16, v123
	v_and_b32_e32 v79, 0xffff0000, v123
	v_pk_fma_f32 v[74:75], v[72:73], v[74:75], s[16:17] op_sel_hi:[1,1,0]
	v_exp_f32_e32 v76, v76
	v_exp_f32_e32 v77, v77
	v_pk_fma_f32 v[66:67], v[106:107], v[78:79], v[66:67]
	v_pk_fma_f32 v[74:75], v[72:73], v[74:75], s[6:7] op_sel_hi:[1,1,0]
	v_and_b32_e32 v79, 0x7fffffff, v71
	v_and_b32_e32 v78, 0x7fffffff, v70
	v_pk_fma_f32 v[74:75], v[72:73], v[74:75], s[14:15] op_sel_hi:[1,1,0]
	v_pk_fma_f32 v[78:79], v[78:79], s[10:11], 1.0 op_sel_hi:[1,0,0]
	v_pk_mul_f32 v[72:73], v[72:73], v[74:75]
	v_rcp_f32_e32 v78, v78
	v_rcp_f32_e32 v79, v79
	v_pk_mul_f32 v[72:73], v[76:77], v[72:73]
	v_cmp_gt_f32_e32 vcc, 0, v68
	v_pk_mul_f32 v[76:77], v[68:69], v[72:73]
	v_pk_fma_f32 v[72:73], v[68:69], v[72:73], v[68:69] neg_lo:[1,0,0] neg_hi:[1,0,0]
	v_pk_mul_f32 v[74:75], v[70:71], v[70:71]
	v_cndmask_b32_e32 v76, v72, v76, vcc
	v_cmp_gt_f32_e32 vcc, 0, v69
	v_pk_fma_f32 v[68:69], v[78:79], s[0:1], v[162:163] op_sel_hi:[1,0,0]
	s_nop 0
	v_cndmask_b32_e32 v77, v73, v77, vcc
	v_pk_mul_f32 v[72:73], v[74:75], s[18:19] op_sel_hi:[1,0]
	v_pk_fma_f32 v[68:69], v[78:79], v[68:69], s[16:17] op_sel_hi:[1,1,0]
	v_exp_f32_e32 v72, v72
	v_exp_f32_e32 v73, v73
	v_pk_fma_f32 v[68:69], v[78:79], v[68:69], s[6:7] op_sel_hi:[1,1,0]
	v_and_b32_e32 v75, 0x7fffffff, v65
	v_and_b32_e32 v74, 0x7fffffff, v64
	v_pk_fma_f32 v[68:69], v[78:79], v[68:69], s[14:15] op_sel_hi:[1,1,0]
	v_pk_fma_f32 v[74:75], v[74:75], s[10:11], 1.0 op_sel_hi:[1,0,0]
	v_pk_mul_f32 v[68:69], v[78:79], v[68:69]
	v_rcp_f32_e32 v74, v74
	v_rcp_f32_e32 v75, v75
	v_pk_mul_f32 v[68:69], v[72:73], v[68:69]
	v_cmp_gt_f32_e32 vcc, 0, v70
	v_pk_mul_f32 v[72:73], v[70:71], v[68:69]
	v_pk_fma_f32 v[68:69], v[70:71], v[68:69], v[70:71] neg_lo:[1,0,0] neg_hi:[1,0,0]
	s_nop 0
	v_cndmask_b32_e32 v78, v68, v72, vcc
	v_cmp_gt_f32_e32 vcc, 0, v71
	v_pk_mul_f32 v[70:71], v[64:65], v[64:65]
	s_nop 0
	v_cndmask_b32_e32 v79, v69, v73, vcc
	v_pk_fma_f32 v[68:69], v[74:75], s[0:1], v[162:163] op_sel_hi:[1,0,0]
	v_pk_mul_f32 v[70:71], v[70:71], s[18:19] op_sel_hi:[1,0]
	v_pk_fma_f32 v[68:69], v[74:75], v[68:69], s[16:17] op_sel_hi:[1,1,0]
	v_exp_f32_e32 v70, v70
	v_pk_fma_f32 v[68:69], v[74:75], v[68:69], s[6:7] op_sel_hi:[1,1,0]
	v_exp_f32_e32 v71, v71
	v_pk_fma_f32 v[68:69], v[74:75], v[68:69], s[14:15] op_sel_hi:[1,1,0]
	v_cmp_gt_f32_e32 vcc, 0, v64
	v_pk_mul_f32 v[68:69], v[74:75], v[68:69]
	v_and_b32_e32 v75, 0x7fffffff, v67
	v_and_b32_e32 v74, 0x7fffffff, v66
	v_pk_fma_f32 v[74:75], v[74:75], s[10:11], 1.0 op_sel_hi:[1,0,0]
	v_pk_mul_f32 v[68:69], v[70:71], v[68:69]
	v_rcp_f32_e32 v74, v74
	v_rcp_f32_e32 v75, v75
	v_pk_mul_f32 v[70:71], v[64:65], v[68:69]
	v_pk_fma_f32 v[68:69], v[64:65], v[68:69], v[64:65] neg_lo:[1,0,0] neg_hi:[1,0,0]
	v_pk_mul_f32 v[72:73], v[66:67], v[66:67]
	v_cndmask_b32_e32 v70, v68, v70, vcc
	v_cmp_gt_f32_e32 vcc, 0, v65
	v_pk_fma_f32 v[64:65], v[74:75], s[0:1], v[162:163] op_sel_hi:[1,0,0]
	s_nop 0
	v_cndmask_b32_e32 v71, v69, v71, vcc
	v_pk_mul_f32 v[68:69], v[72:73], s[18:19] op_sel_hi:[1,0]
	v_pk_fma_f32 v[64:65], v[74:75], v[64:65], s[16:17] op_sel_hi:[1,1,0]
	v_exp_f32_e32 v68, v68
	v_exp_f32_e32 v69, v69
	v_pk_fma_f32 v[64:65], v[74:75], v[64:65], s[6:7] op_sel_hi:[1,1,0]
	v_cmp_gt_f32_e32 vcc, 0, v66
	v_pk_fma_f32 v[64:65], v[74:75], v[64:65], s[14:15] op_sel_hi:[1,1,0]
	v_mov_b64_e32 v[72:73], s[38:39]
	v_pk_mul_f32 v[64:65], v[74:75], v[64:65]
	v_lshlrev_b32_e32 v74, 1, v96
	v_pk_mul_f32 v[64:65], v[68:69], v[64:65]
	v_mov_b32_e32 v75, v161
	v_pk_mul_f32 v[68:69], v[66:67], v[64:65]
	v_pk_fma_f32 v[64:65], v[66:67], v[64:65], v[66:67] neg_lo:[1,0,0] neg_hi:[1,0,0]
	v_lshrrev_b32_e32 v96, 4, v96
	v_cndmask_b32_e32 v68, v64, v68, vcc
	v_cmp_gt_f32_e32 vcc, 0, v67
	v_cvt_pk_bf16_f32 v64, v76, v77
	v_mad_i64_i32 v[76:77], s[12:13], v176, s1, v[72:73]
	s_nop 0
	v_cndmask_b32_e32 v67, v65, v69, vcc
	v_cvt_pk_bf16_f32 v65, v78, v79
	v_cvt_pk_bf16_f32 v66, v70, v71
	v_cvt_pk_bf16_f32 v67, v68, v67
	v_add_u32_e32 v68, 0x1600, v164
	v_ashrrev_i32_e32 v69, 31, v68
	v_lshlrev_b64 v[68:69], 10, v[68:69]
	v_lshl_add_u64 v[68:69], s[20:21], 0, v[68:69]
	v_lshl_add_u64 v[68:69], v[68:69], 0, s[40:41]
	v_lshl_add_u64 v[68:69], v[68:69], 0, v[160:161]
	global_store_dwordx4 v[68:69], v[64:67], off
	v_lshl_add_u64 v[76:77], v[76:77], 0, v[74:75]
	v_mad_i64_i32 v[78:79], s[12:13], v174, s1, v[72:73]
	v_mad_i64_i32 v[64:65], s[12:13], v166, s1, v[72:73]
	v_lshl_add_u64 v[64:65], v[64:65], 0, v[74:75]
	global_load_dwordx4 v[98:101], v[64:65], off
	global_load_dwordx4 v[68:71], v168, s[42:43]
	s_nop 0
	global_load_dwordx4 v[64:67], v168, s[42:43] offset:16
	global_load_dwordx4 v[102:105], v[76:77], off
	v_mad_i64_i32 v[76:77], s[12:13], v175, s1, v[72:73]
	v_lshl_add_u64 v[76:77], v[76:77], 0, v[74:75]
	v_lshl_add_u64 v[78:79], v[78:79], 0, v[74:75]
	global_load_dwordx4 v[92:95], v[76:77], off
	global_load_dwordx4 v[88:91], v[78:79], off
	v_mad_i64_i32 v[76:77], s[12:13], v173, s1, v[72:73]
	v_lshl_add_u64 v[76:77], v[76:77], 0, v[74:75]
	v_mad_i64_i32 v[78:79], s[12:13], v172, s1, v[72:73]
	v_lshl_add_u64 v[78:79], v[78:79], 0, v[74:75]
	global_load_dwordx4 v[84:87], v[76:77], off
	global_load_dwordx4 v[80:83], v[78:79], off
	v_mad_i64_i32 v[76:77], s[12:13], v171, s1, v[72:73]
	v_mad_i64_i32 v[72:73], s[12:13], v170, s1, v[72:73]
	v_lshl_add_u64 v[76:77], v[76:77], 0, v[74:75]
	v_lshl_add_u64 v[72:73], v[72:73], 0, v[74:75]
	v_or_b32_e32 v96, v169, v96
	global_load_dwordx4 v[76:79], v[76:77], off
	s_nop 0
	global_load_dwordx4 v[72:75], v[72:73], off
	s_waitcnt vmcnt(9)
	v_lshlrev_b32_e32 v106, 16, v98
	v_and_b32_e32 v107, 0xffff0000, v98
	s_waitcnt vmcnt(8)
	v_pk_fma_f32 v[60:61], v[68:69], v[106:107], v[60:61]
	v_lshlrev_b32_e32 v108, 16, v100
	v_and_b32_e32 v107, 0x7fffffff, v61
	v_and_b32_e32 v106, 0x7fffffff, v60
	v_pk_fma_f32 v[106:107], v[106:107], s[10:11], 1.0 op_sel_hi:[1,0,0]
	v_and_b32_e32 v109, 0xffff0000, v100
	v_rcp_f32_e32 v106, v106
	v_rcp_f32_e32 v107, v107
	v_lshlrev_b32_e32 v100, 16, v101
	v_and_b32_e32 v101, 0xffff0000, v101
	v_lshlrev_b32_e32 v98, 16, v99
	v_and_b32_e32 v99, 0xffff0000, v99
	s_waitcnt vmcnt(7)
	v_pk_fma_f32 v[58:59], v[66:67], v[100:101], v[58:59]
	v_pk_mul_f32 v[100:101], v[60:61], v[60:61]
	v_pk_fma_f32 v[62:63], v[70:71], v[98:99], v[62:63]
	v_pk_fma_f32 v[98:99], v[106:107], s[0:1], v[162:163] op_sel_hi:[1,0,0]
	v_pk_mul_f32 v[100:101], v[100:101], s[18:19] op_sel_hi:[1,0]
	v_pk_fma_f32 v[98:99], v[106:107], v[98:99], s[16:17] op_sel_hi:[1,1,0]
	v_exp_f32_e32 v100, v100
	v_exp_f32_e32 v101, v101
	v_pk_fma_f32 v[56:57], v[64:65], v[108:109], v[56:57]
	v_pk_fma_f32 v[98:99], v[106:107], v[98:99], s[6:7] op_sel_hi:[1,1,0]
	v_and_b32_e32 v109, 0x7fffffff, v63
	v_and_b32_e32 v108, 0x7fffffff, v62
	v_pk_fma_f32 v[98:99], v[106:107], v[98:99], s[14:15] op_sel_hi:[1,1,0]
	v_pk_fma_f32 v[108:109], v[108:109], s[10:11], 1.0 op_sel_hi:[1,0,0]
	v_pk_mul_f32 v[98:99], v[106:107], v[98:99]
	v_rcp_f32_e32 v108, v108
	v_rcp_f32_e32 v109, v109
	v_pk_mul_f32 v[98:99], v[100:101], v[98:99]
	v_cmp_gt_f32_e32 vcc, 0, v60
	v_pk_mul_f32 v[100:101], v[60:61], v[98:99]
	v_pk_fma_f32 v[98:99], v[60:61], v[98:99], v[60:61] neg_lo:[1,0,0] neg_hi:[1,0,0]
	v_pk_mul_f32 v[106:107], v[62:63], v[62:63]
	v_cndmask_b32_e32 v97, v98, v100, vcc
	v_cmp_gt_f32_e32 vcc, 0, v61
	v_pk_fma_f32 v[60:61], v[108:109], s[0:1], v[162:163] op_sel_hi:[1,0,0]
	v_and_b32_e32 v100, 0x7fffffff, v56
	v_cndmask_b32_e32 v110, v99, v101, vcc
	v_pk_mul_f32 v[98:99], v[106:107], s[18:19] op_sel_hi:[1,0]
	v_pk_fma_f32 v[60:61], v[108:109], v[60:61], s[16:17] op_sel_hi:[1,1,0]
	v_exp_f32_e32 v98, v98
	v_exp_f32_e32 v99, v99
	v_pk_fma_f32 v[60:61], v[108:109], v[60:61], s[6:7] op_sel_hi:[1,1,0]
	v_and_b32_e32 v101, 0x7fffffff, v57
	v_pk_fma_f32 v[60:61], v[108:109], v[60:61], s[14:15] op_sel_hi:[1,1,0]
	v_pk_fma_f32 v[100:101], v[100:101], s[10:11], 1.0 op_sel_hi:[1,0,0]
	v_pk_mul_f32 v[60:61], v[108:109], v[60:61]
	v_rcp_f32_e32 v100, v100
	v_rcp_f32_e32 v101, v101
	v_pk_mul_f32 v[60:61], v[98:99], v[60:61]
	v_cmp_gt_f32_e32 vcc, 0, v62
	v_pk_mul_f32 v[98:99], v[62:63], v[60:61]
	v_pk_fma_f32 v[60:61], v[62:63], v[60:61], v[62:63] neg_lo:[1,0,0] neg_hi:[1,0,0]
	s_nop 0
	v_cndmask_b32_e32 v106, v60, v98, vcc
	v_cmp_gt_f32_e32 vcc, 0, v63
	v_pk_mul_f32 v[62:63], v[56:57], v[56:57]
	s_nop 0
	v_cndmask_b32_e32 v107, v61, v99, vcc
	v_pk_fma_f32 v[60:61], v[100:101], s[0:1], v[162:163] op_sel_hi:[1,0,0]
	v_pk_mul_f32 v[62:63], v[62:63], s[18:19] op_sel_hi:[1,0]
	v_pk_fma_f32 v[60:61], v[100:101], v[60:61], s[16:17] op_sel_hi:[1,1,0]
	v_exp_f32_e32 v62, v62
	v_pk_fma_f32 v[60:61], v[100:101], v[60:61], s[6:7] op_sel_hi:[1,1,0]
	v_exp_f32_e32 v63, v63
	v_pk_fma_f32 v[60:61], v[100:101], v[60:61], s[14:15] op_sel_hi:[1,1,0]
	v_cmp_gt_f32_e32 vcc, 0, v56
	v_pk_mul_f32 v[60:61], v[100:101], v[60:61]
	v_and_b32_e32 v101, 0x7fffffff, v59
	v_and_b32_e32 v100, 0x7fffffff, v58
	v_pk_fma_f32 v[100:101], v[100:101], s[10:11], 1.0 op_sel_hi:[1,0,0]
	v_pk_mul_f32 v[60:61], v[62:63], v[60:61]
	v_rcp_f32_e32 v100, v100
	v_rcp_f32_e32 v101, v101
	v_pk_mul_f32 v[62:63], v[56:57], v[60:61]
	v_pk_fma_f32 v[60:61], v[56:57], v[60:61], v[56:57] neg_lo:[1,0,0] neg_hi:[1,0,0]
	v_pk_mul_f32 v[98:99], v[58:59], v[58:59]
	v_cndmask_b32_e32 v62, v60, v62, vcc
	v_cmp_gt_f32_e32 vcc, 0, v57
	v_pk_fma_f32 v[56:57], v[100:101], s[0:1], v[162:163] op_sel_hi:[1,0,0]
	s_nop 0
	v_cndmask_b32_e32 v63, v61, v63, vcc
	v_pk_mul_f32 v[60:61], v[98:99], s[18:19] op_sel_hi:[1,0]
	v_pk_fma_f32 v[56:57], v[100:101], v[56:57], s[16:17] op_sel_hi:[1,1,0]
	v_exp_f32_e32 v60, v60
	v_exp_f32_e32 v61, v61
	v_pk_fma_f32 v[56:57], v[100:101], v[56:57], s[6:7] op_sel_hi:[1,1,0]
	v_cmp_gt_f32_e32 vcc, 0, v58
	v_pk_fma_f32 v[56:57], v[100:101], v[56:57], s[14:15] op_sel_hi:[1,1,0]
	s_nop 0
	v_pk_mul_f32 v[56:57], v[100:101], v[56:57]
	s_nop 0
	v_pk_mul_f32 v[56:57], v[60:61], v[56:57]
	s_nop 0
	v_pk_mul_f32 v[60:61], v[58:59], v[56:57]
	v_pk_fma_f32 v[56:57], v[58:59], v[56:57], v[58:59] neg_lo:[1,0,0] neg_hi:[1,0,0]
	s_nop 0
	v_cndmask_b32_e32 v60, v56, v60, vcc
	v_cmp_gt_f32_e32 vcc, 0, v59
	v_cvt_pk_bf16_f32 v56, v97, v110
	v_ashrrev_i32_e32 v97, 31, v96
	s_nop 0
	v_cndmask_b32_e32 v59, v57, v61, vcc
	v_cvt_pk_bf16_f32 v57, v106, v107
	v_cvt_pk_bf16_f32 v58, v62, v63
	v_cvt_pk_bf16_f32 v59, v60, v59
	v_lshlrev_b64 v[60:61], 10, v[96:97]
	v_lshl_add_u64 v[60:61], s[20:21], 0, v[60:61]
	v_lshl_add_u64 v[60:61], v[60:61], 0, s[40:41]
	v_lshl_add_u64 v[60:61], v[60:61], 0, v[160:161]
	global_store_dwordx4 v[60:61], v[56:59], off
	s_waitcnt vmcnt(7)
	v_lshlrev_b32_e32 v60, 16, v104
	v_and_b32_e32 v61, 0xffff0000, v104
	v_lshlrev_b32_e32 v56, 16, v102
	v_and_b32_e32 v57, 0xffff0000, v102
	v_pk_fma_f32 v[52:53], v[68:69], v[56:57], v[52:53]
	v_lshlrev_b32_e32 v58, 16, v103
	v_and_b32_e32 v57, 0x7fffffff, v53
	v_and_b32_e32 v56, 0x7fffffff, v52
	v_pk_fma_f32 v[56:57], v[56:57], s[10:11], 1.0 op_sel_hi:[1,0,0]
	v_and_b32_e32 v59, 0xffff0000, v103
	v_rcp_f32_e32 v56, v56
	v_rcp_f32_e32 v57, v57
	v_pk_fma_f32 v[48:49], v[64:65], v[60:61], v[48:49]
	v_pk_mul_f32 v[60:61], v[52:53], v[52:53]
	v_pk_fma_f32 v[54:55], v[70:71], v[58:59], v[54:55]
	v_pk_fma_f32 v[58:59], v[56:57], s[0:1], v[162:163] op_sel_hi:[1,0,0]
	v_pk_mul_f32 v[60:61], v[60:61], s[18:19] op_sel_hi:[1,0]
	v_lshlrev_b32_e32 v62, 16, v105
	v_and_b32_e32 v63, 0xffff0000, v105
	v_pk_fma_f32 v[58:59], v[56:57], v[58:59], s[16:17] op_sel_hi:[1,1,0]
	v_exp_f32_e32 v60, v60
	v_exp_f32_e32 v61, v61
	v_pk_fma_f32 v[50:51], v[66:67], v[62:63], v[50:51]
	v_pk_fma_f32 v[58:59], v[56:57], v[58:59], s[6:7] op_sel_hi:[1,1,0]
	v_and_b32_e32 v63, 0x7fffffff, v55
	v_and_b32_e32 v62, 0x7fffffff, v54
	v_pk_fma_f32 v[58:59], v[56:57], v[58:59], s[14:15] op_sel_hi:[1,1,0]
	v_pk_fma_f32 v[62:63], v[62:63], s[10:11], 1.0 op_sel_hi:[1,0,0]
	v_pk_mul_f32 v[56:57], v[56:57], v[58:59]
	v_rcp_f32_e32 v62, v62
	v_rcp_f32_e32 v63, v63
	v_pk_mul_f32 v[56:57], v[60:61], v[56:57]
	v_cmp_gt_f32_e32 vcc, 0, v52
	v_pk_mul_f32 v[60:61], v[52:53], v[56:57]
	v_pk_fma_f32 v[56:57], v[52:53], v[56:57], v[52:53] neg_lo:[1,0,0] neg_hi:[1,0,0]
	v_pk_mul_f32 v[58:59], v[54:55], v[54:55]
	v_cndmask_b32_e32 v60, v56, v60, vcc
	v_cmp_gt_f32_e32 vcc, 0, v53
	v_pk_fma_f32 v[52:53], v[62:63], s[0:1], v[162:163] op_sel_hi:[1,0,0]
	s_nop 0
	v_cndmask_b32_e32 v61, v57, v61, vcc
	v_pk_mul_f32 v[56:57], v[58:59], s[18:19] op_sel_hi:[1,0]
	v_pk_fma_f32 v[52:53], v[62:63], v[52:53], s[16:17] op_sel_hi:[1,1,0]
	v_exp_f32_e32 v56, v56
	v_exp_f32_e32 v57, v57
	v_pk_fma_f32 v[52:53], v[62:63], v[52:53], s[6:7] op_sel_hi:[1,1,0]
	v_and_b32_e32 v59, 0x7fffffff, v49
	v_and_b32_e32 v58, 0x7fffffff, v48
	v_pk_fma_f32 v[52:53], v[62:63], v[52:53], s[14:15] op_sel_hi:[1,1,0]
	v_pk_fma_f32 v[58:59], v[58:59], s[10:11], 1.0 op_sel_hi:[1,0,0]
	v_pk_mul_f32 v[52:53], v[62:63], v[52:53]
	v_rcp_f32_e32 v58, v58
	v_rcp_f32_e32 v59, v59
	v_pk_mul_f32 v[52:53], v[56:57], v[52:53]
	v_cmp_gt_f32_e32 vcc, 0, v54
	v_pk_mul_f32 v[56:57], v[54:55], v[52:53]
	v_pk_fma_f32 v[52:53], v[54:55], v[52:53], v[54:55] neg_lo:[1,0,0] neg_hi:[1,0,0]
	s_nop 0
	v_cndmask_b32_e32 v62, v52, v56, vcc
	v_cmp_gt_f32_e32 vcc, 0, v55
	v_pk_mul_f32 v[54:55], v[48:49], v[48:49]
	s_nop 0
	v_cndmask_b32_e32 v63, v53, v57, vcc
	v_pk_fma_f32 v[52:53], v[58:59], s[0:1], v[162:163] op_sel_hi:[1,0,0]
	v_pk_mul_f32 v[54:55], v[54:55], s[18:19] op_sel_hi:[1,0]
	v_pk_fma_f32 v[52:53], v[58:59], v[52:53], s[16:17] op_sel_hi:[1,1,0]
	v_exp_f32_e32 v54, v54
	v_pk_fma_f32 v[52:53], v[58:59], v[52:53], s[6:7] op_sel_hi:[1,1,0]
	v_exp_f32_e32 v55, v55
	v_pk_fma_f32 v[52:53], v[58:59], v[52:53], s[14:15] op_sel_hi:[1,1,0]
	v_cmp_gt_f32_e32 vcc, 0, v48
	v_pk_mul_f32 v[52:53], v[58:59], v[52:53]
	v_and_b32_e32 v59, 0x7fffffff, v51
	v_and_b32_e32 v58, 0x7fffffff, v50
	v_pk_fma_f32 v[58:59], v[58:59], s[10:11], 1.0 op_sel_hi:[1,0,0]
	v_pk_mul_f32 v[52:53], v[54:55], v[52:53]
	v_rcp_f32_e32 v58, v58
	v_rcp_f32_e32 v59, v59
	v_pk_mul_f32 v[54:55], v[48:49], v[52:53]
	v_pk_fma_f32 v[52:53], v[48:49], v[52:53], v[48:49] neg_lo:[1,0,0] neg_hi:[1,0,0]
	v_pk_mul_f32 v[56:57], v[50:51], v[50:51]
	v_cndmask_b32_e32 v54, v52, v54, vcc
	v_cmp_gt_f32_e32 vcc, 0, v49
	v_pk_fma_f32 v[48:49], v[58:59], s[0:1], v[162:163] op_sel_hi:[1,0,0]
	s_nop 0
	v_cndmask_b32_e32 v55, v53, v55, vcc
	v_pk_mul_f32 v[52:53], v[56:57], s[18:19] op_sel_hi:[1,0]
	v_pk_fma_f32 v[48:49], v[58:59], v[48:49], s[16:17] op_sel_hi:[1,1,0]
	v_exp_f32_e32 v52, v52
	v_exp_f32_e32 v53, v53
	v_pk_fma_f32 v[48:49], v[58:59], v[48:49], s[6:7] op_sel_hi:[1,1,0]
	v_cmp_gt_f32_e32 vcc, 0, v50
	v_pk_fma_f32 v[48:49], v[58:59], v[48:49], s[14:15] op_sel_hi:[1,1,0]
	s_nop 0
	v_pk_mul_f32 v[48:49], v[58:59], v[48:49]
	s_nop 0
	v_pk_mul_f32 v[48:49], v[52:53], v[48:49]
	s_nop 0
	v_pk_mul_f32 v[52:53], v[50:51], v[48:49]
	v_pk_fma_f32 v[48:49], v[50:51], v[48:49], v[50:51] neg_lo:[1,0,0] neg_hi:[1,0,0]
	s_nop 0
	v_cndmask_b32_e32 v52, v48, v52, vcc
	v_cmp_gt_f32_e32 vcc, 0, v51
	v_cvt_pk_bf16_f32 v48, v60, v61
	s_nop 1
	v_cndmask_b32_e32 v51, v49, v53, vcc
	v_cvt_pk_bf16_f32 v49, v62, v63
	v_cvt_pk_bf16_f32 v50, v54, v55
	v_cvt_pk_bf16_f32 v51, v52, v51
	v_or_b32_e32 v52, 0x200, v96
	v_ashrrev_i32_e32 v53, 31, v52
	v_lshlrev_b64 v[52:53], 10, v[52:53]
	v_lshl_add_u64 v[52:53], s[20:21], 0, v[52:53]
	v_lshl_add_u64 v[52:53], v[52:53], 0, s[40:41]
	v_lshl_add_u64 v[52:53], v[52:53], 0, v[160:161]
	global_store_dwordx4 v[52:53], v[48:51], off
	s_waitcnt vmcnt(7)
	v_lshlrev_b32_e32 v52, 16, v94
	v_and_b32_e32 v53, 0xffff0000, v94
	v_lshlrev_b32_e32 v48, 16, v92
	v_and_b32_e32 v49, 0xffff0000, v92
	v_pk_fma_f32 v[44:45], v[68:69], v[48:49], v[44:45]
	v_lshlrev_b32_e32 v50, 16, v93
	v_and_b32_e32 v49, 0x7fffffff, v45
	v_and_b32_e32 v48, 0x7fffffff, v44
	v_pk_fma_f32 v[48:49], v[48:49], s[10:11], 1.0 op_sel_hi:[1,0,0]
	v_and_b32_e32 v51, 0xffff0000, v93
	v_rcp_f32_e32 v48, v48
	v_rcp_f32_e32 v49, v49
	v_pk_fma_f32 v[40:41], v[64:65], v[52:53], v[40:41]
	v_pk_mul_f32 v[52:53], v[44:45], v[44:45]
	v_pk_fma_f32 v[46:47], v[70:71], v[50:51], v[46:47]
	v_pk_fma_f32 v[50:51], v[48:49], s[0:1], v[162:163] op_sel_hi:[1,0,0]
	v_pk_mul_f32 v[52:53], v[52:53], s[18:19] op_sel_hi:[1,0]
	v_lshlrev_b32_e32 v54, 16, v95
	v_and_b32_e32 v55, 0xffff0000, v95
	v_pk_fma_f32 v[50:51], v[48:49], v[50:51], s[16:17] op_sel_hi:[1,1,0]
	v_exp_f32_e32 v52, v52
	v_exp_f32_e32 v53, v53
	v_pk_fma_f32 v[42:43], v[66:67], v[54:55], v[42:43]
	v_pk_fma_f32 v[50:51], v[48:49], v[50:51], s[6:7] op_sel_hi:[1,1,0]
	v_and_b32_e32 v55, 0x7fffffff, v47
	v_and_b32_e32 v54, 0x7fffffff, v46
	v_pk_fma_f32 v[50:51], v[48:49], v[50:51], s[14:15] op_sel_hi:[1,1,0]
	v_pk_fma_f32 v[54:55], v[54:55], s[10:11], 1.0 op_sel_hi:[1,0,0]
	v_pk_mul_f32 v[48:49], v[48:49], v[50:51]
	v_rcp_f32_e32 v54, v54
	v_rcp_f32_e32 v55, v55
	v_pk_mul_f32 v[48:49], v[52:53], v[48:49]
	v_cmp_gt_f32_e32 vcc, 0, v44
	v_pk_mul_f32 v[52:53], v[44:45], v[48:49]
	v_pk_fma_f32 v[48:49], v[44:45], v[48:49], v[44:45] neg_lo:[1,0,0] neg_hi:[1,0,0]
	v_pk_mul_f32 v[50:51], v[46:47], v[46:47]
	v_cndmask_b32_e32 v52, v48, v52, vcc
	v_cmp_gt_f32_e32 vcc, 0, v45
	v_pk_fma_f32 v[44:45], v[54:55], s[0:1], v[162:163] op_sel_hi:[1,0,0]
	s_nop 0
	v_cndmask_b32_e32 v53, v49, v53, vcc
	v_pk_mul_f32 v[48:49], v[50:51], s[18:19] op_sel_hi:[1,0]
	v_pk_fma_f32 v[44:45], v[54:55], v[44:45], s[16:17] op_sel_hi:[1,1,0]
	v_exp_f32_e32 v48, v48
	v_exp_f32_e32 v49, v49
	v_pk_fma_f32 v[44:45], v[54:55], v[44:45], s[6:7] op_sel_hi:[1,1,0]
	v_and_b32_e32 v51, 0x7fffffff, v41
	v_and_b32_e32 v50, 0x7fffffff, v40
	v_pk_fma_f32 v[44:45], v[54:55], v[44:45], s[14:15] op_sel_hi:[1,1,0]
	v_pk_fma_f32 v[50:51], v[50:51], s[10:11], 1.0 op_sel_hi:[1,0,0]
	v_pk_mul_f32 v[44:45], v[54:55], v[44:45]
	v_rcp_f32_e32 v50, v50
	v_rcp_f32_e32 v51, v51
	v_pk_mul_f32 v[44:45], v[48:49], v[44:45]
	v_cmp_gt_f32_e32 vcc, 0, v46
	v_pk_mul_f32 v[48:49], v[46:47], v[44:45]
	v_pk_fma_f32 v[44:45], v[46:47], v[44:45], v[46:47] neg_lo:[1,0,0] neg_hi:[1,0,0]
	s_nop 0
	v_cndmask_b32_e32 v54, v44, v48, vcc
	v_cmp_gt_f32_e32 vcc, 0, v47
	v_pk_mul_f32 v[46:47], v[40:41], v[40:41]
	s_nop 0
	v_cndmask_b32_e32 v55, v45, v49, vcc
	v_pk_fma_f32 v[44:45], v[50:51], s[0:1], v[162:163] op_sel_hi:[1,0,0]
	v_pk_mul_f32 v[46:47], v[46:47], s[18:19] op_sel_hi:[1,0]
	v_pk_fma_f32 v[44:45], v[50:51], v[44:45], s[16:17] op_sel_hi:[1,1,0]
	v_exp_f32_e32 v46, v46
	v_pk_fma_f32 v[44:45], v[50:51], v[44:45], s[6:7] op_sel_hi:[1,1,0]
	v_exp_f32_e32 v47, v47
	v_pk_fma_f32 v[44:45], v[50:51], v[44:45], s[14:15] op_sel_hi:[1,1,0]
	v_cmp_gt_f32_e32 vcc, 0, v40
	v_pk_mul_f32 v[44:45], v[50:51], v[44:45]
	v_and_b32_e32 v51, 0x7fffffff, v43
	v_and_b32_e32 v50, 0x7fffffff, v42
	v_pk_fma_f32 v[50:51], v[50:51], s[10:11], 1.0 op_sel_hi:[1,0,0]
	v_pk_mul_f32 v[44:45], v[46:47], v[44:45]
	v_rcp_f32_e32 v50, v50
	v_rcp_f32_e32 v51, v51
	v_pk_mul_f32 v[46:47], v[40:41], v[44:45]
	v_pk_fma_f32 v[44:45], v[40:41], v[44:45], v[40:41] neg_lo:[1,0,0] neg_hi:[1,0,0]
	v_pk_mul_f32 v[48:49], v[42:43], v[42:43]
	v_cndmask_b32_e32 v46, v44, v46, vcc
	v_cmp_gt_f32_e32 vcc, 0, v41
	v_pk_fma_f32 v[40:41], v[50:51], s[0:1], v[162:163] op_sel_hi:[1,0,0]
	s_nop 0
	v_cndmask_b32_e32 v47, v45, v47, vcc
	v_pk_mul_f32 v[44:45], v[48:49], s[18:19] op_sel_hi:[1,0]
	v_pk_fma_f32 v[40:41], v[50:51], v[40:41], s[16:17] op_sel_hi:[1,1,0]
	v_exp_f32_e32 v44, v44
	v_exp_f32_e32 v45, v45
	v_pk_fma_f32 v[40:41], v[50:51], v[40:41], s[6:7] op_sel_hi:[1,1,0]
	v_cmp_gt_f32_e32 vcc, 0, v42
	v_pk_fma_f32 v[40:41], v[50:51], v[40:41], s[14:15] op_sel_hi:[1,1,0]
	s_nop 0
	v_pk_mul_f32 v[40:41], v[50:51], v[40:41]
	s_nop 0
	v_pk_mul_f32 v[40:41], v[44:45], v[40:41]
	s_nop 0
	v_pk_mul_f32 v[44:45], v[42:43], v[40:41]
	v_pk_fma_f32 v[40:41], v[42:43], v[40:41], v[42:43] neg_lo:[1,0,0] neg_hi:[1,0,0]
	s_nop 0
	v_cndmask_b32_e32 v44, v40, v44, vcc
	v_cmp_gt_f32_e32 vcc, 0, v43
	v_cvt_pk_bf16_f32 v40, v52, v53
	s_nop 1
	v_cndmask_b32_e32 v43, v41, v45, vcc
	v_cvt_pk_bf16_f32 v41, v54, v55
	v_cvt_pk_bf16_f32 v42, v46, v47
	v_cvt_pk_bf16_f32 v43, v44, v43
	v_or_b32_e32 v44, 0x400, v96
	v_ashrrev_i32_e32 v45, 31, v44
	v_lshlrev_b64 v[44:45], 10, v[44:45]
	v_lshl_add_u64 v[44:45], s[20:21], 0, v[44:45]
	v_lshl_add_u64 v[44:45], v[44:45], 0, s[40:41]
	v_lshl_add_u64 v[44:45], v[44:45], 0, v[160:161]
	global_store_dwordx4 v[44:45], v[40:43], off
	s_waitcnt vmcnt(7)
	v_lshlrev_b32_e32 v44, 16, v90
	v_and_b32_e32 v45, 0xffff0000, v90
	v_lshlrev_b32_e32 v40, 16, v88
	v_and_b32_e32 v41, 0xffff0000, v88
	v_pk_fma_f32 v[36:37], v[68:69], v[40:41], v[36:37]
	v_lshlrev_b32_e32 v42, 16, v89
	v_and_b32_e32 v41, 0x7fffffff, v37
	v_and_b32_e32 v40, 0x7fffffff, v36
	v_pk_fma_f32 v[40:41], v[40:41], s[10:11], 1.0 op_sel_hi:[1,0,0]
	v_and_b32_e32 v43, 0xffff0000, v89
	v_rcp_f32_e32 v40, v40
	v_rcp_f32_e32 v41, v41
	v_pk_fma_f32 v[32:33], v[64:65], v[44:45], v[32:33]
	v_pk_mul_f32 v[44:45], v[36:37], v[36:37]
	v_pk_fma_f32 v[38:39], v[70:71], v[42:43], v[38:39]
	v_pk_fma_f32 v[42:43], v[40:41], s[0:1], v[162:163] op_sel_hi:[1,0,0]
	v_pk_mul_f32 v[44:45], v[44:45], s[18:19] op_sel_hi:[1,0]
	v_lshlrev_b32_e32 v46, 16, v91
	v_and_b32_e32 v47, 0xffff0000, v91
	v_pk_fma_f32 v[42:43], v[40:41], v[42:43], s[16:17] op_sel_hi:[1,1,0]
	v_exp_f32_e32 v44, v44
	v_exp_f32_e32 v45, v45
	v_pk_fma_f32 v[34:35], v[66:67], v[46:47], v[34:35]
	v_pk_fma_f32 v[42:43], v[40:41], v[42:43], s[6:7] op_sel_hi:[1,1,0]
	v_and_b32_e32 v47, 0x7fffffff, v39
	v_and_b32_e32 v46, 0x7fffffff, v38
	v_pk_fma_f32 v[42:43], v[40:41], v[42:43], s[14:15] op_sel_hi:[1,1,0]
	v_pk_fma_f32 v[46:47], v[46:47], s[10:11], 1.0 op_sel_hi:[1,0,0]
	v_pk_mul_f32 v[40:41], v[40:41], v[42:43]
	v_rcp_f32_e32 v46, v46
	v_rcp_f32_e32 v47, v47
	v_pk_mul_f32 v[40:41], v[44:45], v[40:41]
	v_cmp_gt_f32_e32 vcc, 0, v36
	v_pk_mul_f32 v[44:45], v[36:37], v[40:41]
	v_pk_fma_f32 v[40:41], v[36:37], v[40:41], v[36:37] neg_lo:[1,0,0] neg_hi:[1,0,0]
	v_pk_mul_f32 v[42:43], v[38:39], v[38:39]
	v_cndmask_b32_e32 v44, v40, v44, vcc
	v_cmp_gt_f32_e32 vcc, 0, v37
	v_pk_fma_f32 v[36:37], v[46:47], s[0:1], v[162:163] op_sel_hi:[1,0,0]
	s_nop 0
	v_cndmask_b32_e32 v45, v41, v45, vcc
	v_pk_mul_f32 v[40:41], v[42:43], s[18:19] op_sel_hi:[1,0]
	v_pk_fma_f32 v[36:37], v[46:47], v[36:37], s[16:17] op_sel_hi:[1,1,0]
	v_exp_f32_e32 v40, v40
	v_exp_f32_e32 v41, v41
	v_pk_fma_f32 v[36:37], v[46:47], v[36:37], s[6:7] op_sel_hi:[1,1,0]
	v_and_b32_e32 v43, 0x7fffffff, v33
	v_and_b32_e32 v42, 0x7fffffff, v32
	v_pk_fma_f32 v[36:37], v[46:47], v[36:37], s[14:15] op_sel_hi:[1,1,0]
	v_pk_fma_f32 v[42:43], v[42:43], s[10:11], 1.0 op_sel_hi:[1,0,0]
	v_pk_mul_f32 v[36:37], v[46:47], v[36:37]
	v_rcp_f32_e32 v42, v42
	v_rcp_f32_e32 v43, v43
	v_pk_mul_f32 v[36:37], v[40:41], v[36:37]
	v_cmp_gt_f32_e32 vcc, 0, v38
	v_pk_mul_f32 v[40:41], v[38:39], v[36:37]
	v_pk_fma_f32 v[36:37], v[38:39], v[36:37], v[38:39] neg_lo:[1,0,0] neg_hi:[1,0,0]
	s_nop 0
	v_cndmask_b32_e32 v46, v36, v40, vcc
	v_cmp_gt_f32_e32 vcc, 0, v39
	v_pk_mul_f32 v[38:39], v[32:33], v[32:33]
	s_nop 0
	v_cndmask_b32_e32 v47, v37, v41, vcc
	v_pk_fma_f32 v[36:37], v[42:43], s[0:1], v[162:163] op_sel_hi:[1,0,0]
	v_pk_mul_f32 v[38:39], v[38:39], s[18:19] op_sel_hi:[1,0]
	v_pk_fma_f32 v[36:37], v[42:43], v[36:37], s[16:17] op_sel_hi:[1,1,0]
	v_exp_f32_e32 v38, v38
	v_pk_fma_f32 v[36:37], v[42:43], v[36:37], s[6:7] op_sel_hi:[1,1,0]
	v_exp_f32_e32 v39, v39
	v_pk_fma_f32 v[36:37], v[42:43], v[36:37], s[14:15] op_sel_hi:[1,1,0]
	v_cmp_gt_f32_e32 vcc, 0, v32
	v_pk_mul_f32 v[36:37], v[42:43], v[36:37]
	v_and_b32_e32 v43, 0x7fffffff, v35
	v_and_b32_e32 v42, 0x7fffffff, v34
	v_pk_fma_f32 v[42:43], v[42:43], s[10:11], 1.0 op_sel_hi:[1,0,0]
	v_pk_mul_f32 v[36:37], v[38:39], v[36:37]
	v_rcp_f32_e32 v42, v42
	v_rcp_f32_e32 v43, v43
	v_pk_mul_f32 v[38:39], v[32:33], v[36:37]
	v_pk_fma_f32 v[36:37], v[32:33], v[36:37], v[32:33] neg_lo:[1,0,0] neg_hi:[1,0,0]
	v_pk_mul_f32 v[40:41], v[34:35], v[34:35]
	v_cndmask_b32_e32 v38, v36, v38, vcc
	v_cmp_gt_f32_e32 vcc, 0, v33
	v_pk_fma_f32 v[32:33], v[42:43], s[0:1], v[162:163] op_sel_hi:[1,0,0]
	s_nop 0
	v_cndmask_b32_e32 v39, v37, v39, vcc
	v_pk_mul_f32 v[36:37], v[40:41], s[18:19] op_sel_hi:[1,0]
	v_pk_fma_f32 v[32:33], v[42:43], v[32:33], s[16:17] op_sel_hi:[1,1,0]
	v_exp_f32_e32 v36, v36
	v_exp_f32_e32 v37, v37
	v_pk_fma_f32 v[32:33], v[42:43], v[32:33], s[6:7] op_sel_hi:[1,1,0]
	v_cmp_gt_f32_e32 vcc, 0, v34
	v_pk_fma_f32 v[32:33], v[42:43], v[32:33], s[14:15] op_sel_hi:[1,1,0]
	s_waitcnt vmcnt(6)
	v_lshlrev_b32_e32 v40, 16, v87
	v_pk_mul_f32 v[32:33], v[42:43], v[32:33]
	v_and_b32_e32 v41, 0xffff0000, v87
	v_pk_mul_f32 v[32:33], v[36:37], v[32:33]
	v_pk_fma_f32 v[26:27], v[66:67], v[40:41], v[26:27]
	v_pk_mul_f32 v[36:37], v[34:35], v[32:33]
	v_pk_fma_f32 v[32:33], v[34:35], v[32:33], v[34:35] neg_lo:[1,0,0] neg_hi:[1,0,0]
	s_nop 0
	v_cndmask_b32_e32 v36, v32, v36, vcc
	v_cmp_gt_f32_e32 vcc, 0, v35
	v_cvt_pk_bf16_f32 v32, v44, v45
	s_nop 1
	v_cndmask_b32_e32 v35, v33, v37, vcc
	v_cvt_pk_bf16_f32 v33, v46, v47
	v_cvt_pk_bf16_f32 v34, v38, v39
	v_cvt_pk_bf16_f32 v35, v36, v35
	v_or_b32_e32 v36, 0x600, v96
	v_ashrrev_i32_e32 v37, 31, v36
	v_lshlrev_b64 v[36:37], 10, v[36:37]
	v_lshl_add_u64 v[36:37], s[20:21], 0, v[36:37]
	v_lshl_add_u64 v[36:37], v[36:37], 0, s[40:41]
	v_lshl_add_u64 v[36:37], v[36:37], 0, v[160:161]
	global_store_dwordx4 v[36:37], v[32:35], off
	v_lshlrev_b32_e32 v38, 16, v86
	v_and_b32_e32 v39, 0xffff0000, v86
	v_lshlrev_b32_e32 v34, 16, v84
	v_and_b32_e32 v35, 0xffff0000, v84
	v_pk_fma_f32 v[28:29], v[68:69], v[34:35], v[28:29]
	v_lshlrev_b32_e32 v36, 16, v85
	v_and_b32_e32 v35, 0x7fffffff, v29
	v_and_b32_e32 v34, 0x7fffffff, v28
	v_pk_fma_f32 v[34:35], v[34:35], s[10:11], 1.0 op_sel_hi:[1,0,0]
	v_and_b32_e32 v37, 0xffff0000, v85
	v_rcp_f32_e32 v34, v34
	v_rcp_f32_e32 v35, v35
	v_pk_fma_f32 v[24:25], v[64:65], v[38:39], v[24:25]
	v_pk_mul_f32 v[38:39], v[28:29], v[28:29]
	v_pk_fma_f32 v[30:31], v[70:71], v[36:37], v[30:31]
	v_pk_fma_f32 v[36:37], v[34:35], s[0:1], v[162:163] op_sel_hi:[1,0,0]
	v_pk_mul_f32 v[38:39], v[38:39], s[18:19] op_sel_hi:[1,0]
	v_pk_fma_f32 v[36:37], v[34:35], v[36:37], s[16:17] op_sel_hi:[1,1,0]
	v_exp_f32_e32 v38, v38
	v_exp_f32_e32 v39, v39
	v_pk_fma_f32 v[36:37], v[34:35], v[36:37], s[6:7] op_sel_hi:[1,1,0]
	v_and_b32_e32 v41, 0x7fffffff, v31
	v_and_b32_e32 v40, 0x7fffffff, v30
	v_pk_fma_f32 v[36:37], v[34:35], v[36:37], s[14:15] op_sel_hi:[1,1,0]
	v_pk_fma_f32 v[40:41], v[40:41], s[10:11], 1.0 op_sel_hi:[1,0,0]
	v_pk_mul_f32 v[34:35], v[34:35], v[36:37]
	v_rcp_f32_e32 v40, v40
	v_rcp_f32_e32 v41, v41
	v_pk_mul_f32 v[34:35], v[38:39], v[34:35]
	v_cmp_gt_f32_e32 vcc, 0, v28
	v_pk_mul_f32 v[38:39], v[28:29], v[34:35]
	v_pk_fma_f32 v[34:35], v[28:29], v[34:35], v[28:29] neg_lo:[1,0,0] neg_hi:[1,0,0]
	v_pk_mul_f32 v[36:37], v[30:31], v[30:31]
	v_cndmask_b32_e32 v33, v34, v38, vcc
	v_cmp_gt_f32_e32 vcc, 0, v29
	v_pk_fma_f32 v[28:29], v[40:41], s[0:1], v[162:163] op_sel_hi:[1,0,0]
	v_add_u32_e32 v32, 0x1000, v96
	v_cndmask_b32_e32 v38, v35, v39, vcc
	v_pk_mul_f32 v[34:35], v[36:37], s[18:19] op_sel_hi:[1,0]
	v_pk_fma_f32 v[28:29], v[40:41], v[28:29], s[16:17] op_sel_hi:[1,1,0]
	v_exp_f32_e32 v34, v34
	v_exp_f32_e32 v35, v35
	v_pk_fma_f32 v[28:29], v[40:41], v[28:29], s[6:7] op_sel_hi:[1,1,0]
	v_and_b32_e32 v37, 0x7fffffff, v25
	v_and_b32_e32 v36, 0x7fffffff, v24
	v_pk_fma_f32 v[28:29], v[40:41], v[28:29], s[14:15] op_sel_hi:[1,1,0]
	v_pk_fma_f32 v[36:37], v[36:37], s[10:11], 1.0 op_sel_hi:[1,0,0]
	v_pk_mul_f32 v[28:29], v[40:41], v[28:29]
	v_rcp_f32_e32 v36, v36
	v_rcp_f32_e32 v37, v37
	v_pk_mul_f32 v[28:29], v[34:35], v[28:29]
	v_cmp_gt_f32_e32 vcc, 0, v30
	v_pk_mul_f32 v[34:35], v[30:31], v[28:29]
	v_pk_fma_f32 v[28:29], v[30:31], v[28:29], v[30:31] neg_lo:[1,0,0] neg_hi:[1,0,0]
	s_nop 0
	v_cndmask_b32_e32 v39, v28, v34, vcc
	v_cmp_gt_f32_e32 vcc, 0, v31
	v_pk_mul_f32 v[30:31], v[24:25], v[24:25]
	s_nop 0
	v_cndmask_b32_e32 v40, v29, v35, vcc
	v_pk_fma_f32 v[28:29], v[36:37], s[0:1], v[162:163] op_sel_hi:[1,0,0]
	v_pk_mul_f32 v[30:31], v[30:31], s[18:19] op_sel_hi:[1,0]
	v_pk_fma_f32 v[28:29], v[36:37], v[28:29], s[16:17] op_sel_hi:[1,1,0]
	v_exp_f32_e32 v30, v30
	v_pk_fma_f32 v[28:29], v[36:37], v[28:29], s[6:7] op_sel_hi:[1,1,0]
	v_exp_f32_e32 v31, v31
	v_pk_fma_f32 v[28:29], v[36:37], v[28:29], s[14:15] op_sel_hi:[1,1,0]
	v_cmp_gt_f32_e32 vcc, 0, v24
	v_pk_mul_f32 v[28:29], v[36:37], v[28:29]
	v_and_b32_e32 v37, 0x7fffffff, v27
	v_and_b32_e32 v36, 0x7fffffff, v26
	v_pk_fma_f32 v[36:37], v[36:37], s[10:11], 1.0 op_sel_hi:[1,0,0]
	v_pk_mul_f32 v[28:29], v[30:31], v[28:29]
	v_rcp_f32_e32 v36, v36
	v_rcp_f32_e32 v37, v37
	v_pk_mul_f32 v[30:31], v[24:25], v[28:29]
	v_pk_fma_f32 v[28:29], v[24:25], v[28:29], v[24:25] neg_lo:[1,0,0] neg_hi:[1,0,0]
	v_pk_mul_f32 v[34:35], v[26:27], v[26:27]
	v_cndmask_b32_e32 v30, v28, v30, vcc
	v_cmp_gt_f32_e32 vcc, 0, v25
	v_pk_fma_f32 v[24:25], v[36:37], s[0:1], v[162:163] op_sel_hi:[1,0,0]
	s_nop 0
	v_cndmask_b32_e32 v31, v29, v31, vcc
	v_pk_mul_f32 v[28:29], v[34:35], s[18:19] op_sel_hi:[1,0]
	v_pk_fma_f32 v[24:25], v[36:37], v[24:25], s[16:17] op_sel_hi:[1,1,0]
	v_exp_f32_e32 v28, v28
	v_exp_f32_e32 v29, v29
	v_pk_fma_f32 v[24:25], v[36:37], v[24:25], s[6:7] op_sel_hi:[1,1,0]
	v_cmp_gt_f32_e32 vcc, 0, v26
	v_pk_fma_f32 v[24:25], v[36:37], v[24:25], s[14:15] op_sel_hi:[1,1,0]
	s_nop 0
	v_pk_mul_f32 v[24:25], v[36:37], v[24:25]
	s_nop 0
	v_pk_mul_f32 v[24:25], v[28:29], v[24:25]
	s_nop 0
	v_pk_mul_f32 v[28:29], v[26:27], v[24:25]
	v_pk_fma_f32 v[24:25], v[26:27], v[24:25], v[26:27] neg_lo:[1,0,0] neg_hi:[1,0,0]
	s_nop 0
	v_cndmask_b32_e32 v28, v24, v28, vcc
	v_cmp_gt_f32_e32 vcc, 0, v27
	v_cvt_pk_bf16_f32 v24, v33, v38
	v_ashrrev_i32_e32 v33, 31, v32
	s_nop 0
	v_cndmask_b32_e32 v27, v25, v29, vcc
	v_cvt_pk_bf16_f32 v25, v39, v40
	v_cvt_pk_bf16_f32 v26, v30, v31
	v_cvt_pk_bf16_f32 v27, v28, v27
	v_lshlrev_b64 v[28:29], 10, v[32:33]
	v_lshl_add_u64 v[28:29], s[20:21], 0, v[28:29]
	v_lshl_add_u64 v[28:29], v[28:29], 0, s[40:41]
	v_lshl_add_u64 v[28:29], v[28:29], 0, v[160:161]
	global_store_dwordx4 v[28:29], v[24:27], off
	s_waitcnt vmcnt(7)
	v_lshlrev_b32_e32 v28, 16, v82
	v_and_b32_e32 v29, 0xffff0000, v82
	v_lshlrev_b32_e32 v24, 16, v80
	v_and_b32_e32 v25, 0xffff0000, v80
	v_pk_fma_f32 v[20:21], v[68:69], v[24:25], v[20:21]
	v_lshlrev_b32_e32 v26, 16, v81
	v_and_b32_e32 v25, 0x7fffffff, v21
	v_and_b32_e32 v24, 0x7fffffff, v20
	v_pk_fma_f32 v[24:25], v[24:25], s[10:11], 1.0 op_sel_hi:[1,0,0]
	v_and_b32_e32 v27, 0xffff0000, v81
	v_rcp_f32_e32 v24, v24
	v_rcp_f32_e32 v25, v25
	v_pk_fma_f32 v[16:17], v[64:65], v[28:29], v[16:17]
	v_pk_mul_f32 v[28:29], v[20:21], v[20:21]
	v_pk_fma_f32 v[22:23], v[70:71], v[26:27], v[22:23]
	v_pk_fma_f32 v[26:27], v[24:25], s[0:1], v[162:163] op_sel_hi:[1,0,0]
	v_pk_mul_f32 v[28:29], v[28:29], s[18:19] op_sel_hi:[1,0]
	v_lshlrev_b32_e32 v30, 16, v83
	v_and_b32_e32 v31, 0xffff0000, v83
	v_pk_fma_f32 v[26:27], v[24:25], v[26:27], s[16:17] op_sel_hi:[1,1,0]
	v_exp_f32_e32 v28, v28
	v_exp_f32_e32 v29, v29
	v_pk_fma_f32 v[18:19], v[66:67], v[30:31], v[18:19]
	v_pk_fma_f32 v[26:27], v[24:25], v[26:27], s[6:7] op_sel_hi:[1,1,0]
	v_and_b32_e32 v31, 0x7fffffff, v23
	v_and_b32_e32 v30, 0x7fffffff, v22
	v_pk_fma_f32 v[26:27], v[24:25], v[26:27], s[14:15] op_sel_hi:[1,1,0]
	v_pk_fma_f32 v[30:31], v[30:31], s[10:11], 1.0 op_sel_hi:[1,0,0]
	v_pk_mul_f32 v[24:25], v[24:25], v[26:27]
	v_rcp_f32_e32 v30, v30
	v_rcp_f32_e32 v31, v31
	v_pk_mul_f32 v[24:25], v[28:29], v[24:25]
	v_cmp_gt_f32_e32 vcc, 0, v20
	v_pk_mul_f32 v[28:29], v[20:21], v[24:25]
	v_pk_fma_f32 v[24:25], v[20:21], v[24:25], v[20:21] neg_lo:[1,0,0] neg_hi:[1,0,0]
	v_pk_mul_f32 v[26:27], v[22:23], v[22:23]
	v_cndmask_b32_e32 v28, v24, v28, vcc
	v_cmp_gt_f32_e32 vcc, 0, v21
	v_pk_fma_f32 v[20:21], v[30:31], s[0:1], v[162:163] op_sel_hi:[1,0,0]
	s_nop 0
	v_cndmask_b32_e32 v29, v25, v29, vcc
	v_pk_mul_f32 v[24:25], v[26:27], s[18:19] op_sel_hi:[1,0]
	v_pk_fma_f32 v[20:21], v[30:31], v[20:21], s[16:17] op_sel_hi:[1,1,0]
	v_exp_f32_e32 v24, v24
	v_exp_f32_e32 v25, v25
	v_pk_fma_f32 v[20:21], v[30:31], v[20:21], s[6:7] op_sel_hi:[1,1,0]
	v_and_b32_e32 v27, 0x7fffffff, v17
	v_and_b32_e32 v26, 0x7fffffff, v16
	v_pk_fma_f32 v[20:21], v[30:31], v[20:21], s[14:15] op_sel_hi:[1,1,0]
	v_pk_fma_f32 v[26:27], v[26:27], s[10:11], 1.0 op_sel_hi:[1,0,0]
	v_pk_mul_f32 v[20:21], v[30:31], v[20:21]
	v_rcp_f32_e32 v26, v26
	v_rcp_f32_e32 v27, v27
	v_pk_mul_f32 v[20:21], v[24:25], v[20:21]
	v_cmp_gt_f32_e32 vcc, 0, v22
	v_pk_mul_f32 v[24:25], v[22:23], v[20:21]
	v_pk_fma_f32 v[20:21], v[22:23], v[20:21], v[22:23] neg_lo:[1,0,0] neg_hi:[1,0,0]
	s_nop 0
	v_cndmask_b32_e32 v30, v20, v24, vcc
	v_cmp_gt_f32_e32 vcc, 0, v23
	v_pk_mul_f32 v[22:23], v[16:17], v[16:17]
	s_nop 0
	v_cndmask_b32_e32 v31, v21, v25, vcc
	v_pk_fma_f32 v[20:21], v[26:27], s[0:1], v[162:163] op_sel_hi:[1,0,0]
	v_pk_mul_f32 v[22:23], v[22:23], s[18:19] op_sel_hi:[1,0]
	v_pk_fma_f32 v[20:21], v[26:27], v[20:21], s[16:17] op_sel_hi:[1,1,0]
	v_exp_f32_e32 v22, v22
	v_pk_fma_f32 v[20:21], v[26:27], v[20:21], s[6:7] op_sel_hi:[1,1,0]
	v_exp_f32_e32 v23, v23
	v_pk_fma_f32 v[20:21], v[26:27], v[20:21], s[14:15] op_sel_hi:[1,1,0]
	v_cmp_gt_f32_e32 vcc, 0, v16
	v_pk_mul_f32 v[20:21], v[26:27], v[20:21]
	v_and_b32_e32 v27, 0x7fffffff, v19
	v_and_b32_e32 v26, 0x7fffffff, v18
	v_pk_fma_f32 v[26:27], v[26:27], s[10:11], 1.0 op_sel_hi:[1,0,0]
	v_pk_mul_f32 v[20:21], v[22:23], v[20:21]
	v_rcp_f32_e32 v26, v26
	v_rcp_f32_e32 v27, v27
	v_pk_mul_f32 v[22:23], v[16:17], v[20:21]
	v_pk_fma_f32 v[20:21], v[16:17], v[20:21], v[16:17] neg_lo:[1,0,0] neg_hi:[1,0,0]
	v_pk_mul_f32 v[24:25], v[18:19], v[18:19]
	v_cndmask_b32_e32 v22, v20, v22, vcc
	v_cmp_gt_f32_e32 vcc, 0, v17
	v_pk_fma_f32 v[16:17], v[26:27], s[0:1], v[162:163] op_sel_hi:[1,0,0]
	s_nop 0
	v_cndmask_b32_e32 v23, v21, v23, vcc
	v_pk_mul_f32 v[20:21], v[24:25], s[18:19] op_sel_hi:[1,0]
	v_pk_fma_f32 v[16:17], v[26:27], v[16:17], s[16:17] op_sel_hi:[1,1,0]
	v_exp_f32_e32 v20, v20
	v_exp_f32_e32 v21, v21
	v_pk_fma_f32 v[16:17], v[26:27], v[16:17], s[6:7] op_sel_hi:[1,1,0]
	v_cmp_gt_f32_e32 vcc, 0, v18
	v_pk_fma_f32 v[16:17], v[26:27], v[16:17], s[14:15] op_sel_hi:[1,1,0]
	s_nop 0
	v_pk_mul_f32 v[16:17], v[26:27], v[16:17]
	s_nop 0
	v_pk_mul_f32 v[16:17], v[20:21], v[16:17]
	s_nop 0
	v_pk_mul_f32 v[20:21], v[18:19], v[16:17]
	v_pk_fma_f32 v[16:17], v[18:19], v[16:17], v[18:19] neg_lo:[1,0,0] neg_hi:[1,0,0]
	s_nop 0
	v_cndmask_b32_e32 v20, v16, v20, vcc
	v_cmp_gt_f32_e32 vcc, 0, v19
	v_cvt_pk_bf16_f32 v16, v28, v29
	s_nop 1
	v_cndmask_b32_e32 v19, v17, v21, vcc
	v_cvt_pk_bf16_f32 v17, v30, v31
	v_cvt_pk_bf16_f32 v18, v22, v23
	v_cvt_pk_bf16_f32 v19, v20, v19
	v_add_u32_e32 v20, 0x1200, v96
	v_ashrrev_i32_e32 v21, 31, v20
	v_lshlrev_b64 v[20:21], 10, v[20:21]
	v_lshl_add_u64 v[20:21], s[20:21], 0, v[20:21]
	v_lshl_add_u64 v[20:21], v[20:21], 0, s[40:41]
	v_lshl_add_u64 v[20:21], v[20:21], 0, v[160:161]
	global_store_dwordx4 v[20:21], v[16:19], off
	s_waitcnt vmcnt(7)
	v_lshlrev_b32_e32 v20, 16, v78
	v_and_b32_e32 v21, 0xffff0000, v78
	v_lshlrev_b32_e32 v16, 16, v76
	v_and_b32_e32 v17, 0xffff0000, v76
	v_pk_fma_f32 v[12:13], v[68:69], v[16:17], v[12:13]
	v_lshlrev_b32_e32 v18, 16, v77
	v_and_b32_e32 v17, 0x7fffffff, v13
	v_and_b32_e32 v16, 0x7fffffff, v12
	v_pk_fma_f32 v[16:17], v[16:17], s[10:11], 1.0 op_sel_hi:[1,0,0]
	v_and_b32_e32 v19, 0xffff0000, v77
	v_rcp_f32_e32 v16, v16
	v_rcp_f32_e32 v17, v17
	v_pk_fma_f32 v[8:9], v[64:65], v[20:21], v[8:9]
	v_pk_mul_f32 v[20:21], v[12:13], v[12:13]
	v_pk_fma_f32 v[14:15], v[70:71], v[18:19], v[14:15]
	v_pk_fma_f32 v[18:19], v[16:17], s[0:1], v[162:163] op_sel_hi:[1,0,0]
	v_pk_mul_f32 v[20:21], v[20:21], s[18:19] op_sel_hi:[1,0]
	v_lshlrev_b32_e32 v22, 16, v79
	v_and_b32_e32 v23, 0xffff0000, v79
	v_pk_fma_f32 v[18:19], v[16:17], v[18:19], s[16:17] op_sel_hi:[1,1,0]
	v_exp_f32_e32 v20, v20
	v_exp_f32_e32 v21, v21
	v_pk_fma_f32 v[10:11], v[66:67], v[22:23], v[10:11]
	v_pk_fma_f32 v[18:19], v[16:17], v[18:19], s[6:7] op_sel_hi:[1,1,0]
	v_and_b32_e32 v23, 0x7fffffff, v15
	v_and_b32_e32 v22, 0x7fffffff, v14
	v_pk_fma_f32 v[18:19], v[16:17], v[18:19], s[14:15] op_sel_hi:[1,1,0]
	v_pk_fma_f32 v[22:23], v[22:23], s[10:11], 1.0 op_sel_hi:[1,0,0]
	v_pk_mul_f32 v[16:17], v[16:17], v[18:19]
	v_rcp_f32_e32 v22, v22
	v_rcp_f32_e32 v23, v23
	v_pk_mul_f32 v[16:17], v[20:21], v[16:17]
	v_cmp_gt_f32_e32 vcc, 0, v12
	v_pk_mul_f32 v[20:21], v[12:13], v[16:17]
	v_pk_fma_f32 v[16:17], v[12:13], v[16:17], v[12:13] neg_lo:[1,0,0] neg_hi:[1,0,0]
	v_pk_mul_f32 v[18:19], v[14:15], v[14:15]
	v_cndmask_b32_e32 v20, v16, v20, vcc
	v_cmp_gt_f32_e32 vcc, 0, v13
	v_pk_fma_f32 v[12:13], v[22:23], s[0:1], v[162:163] op_sel_hi:[1,0,0]
	s_nop 0
	v_cndmask_b32_e32 v21, v17, v21, vcc
	v_pk_mul_f32 v[16:17], v[18:19], s[18:19] op_sel_hi:[1,0]
	v_pk_fma_f32 v[12:13], v[22:23], v[12:13], s[16:17] op_sel_hi:[1,1,0]
	v_exp_f32_e32 v16, v16
	v_exp_f32_e32 v17, v17
	v_pk_fma_f32 v[12:13], v[22:23], v[12:13], s[6:7] op_sel_hi:[1,1,0]
	v_and_b32_e32 v19, 0x7fffffff, v9
	v_and_b32_e32 v18, 0x7fffffff, v8
	v_pk_fma_f32 v[12:13], v[22:23], v[12:13], s[14:15] op_sel_hi:[1,1,0]
	v_pk_fma_f32 v[18:19], v[18:19], s[10:11], 1.0 op_sel_hi:[1,0,0]
	v_pk_mul_f32 v[12:13], v[22:23], v[12:13]
	v_rcp_f32_e32 v18, v18
	v_rcp_f32_e32 v19, v19
	v_pk_mul_f32 v[12:13], v[16:17], v[12:13]
	v_cmp_gt_f32_e32 vcc, 0, v14
	v_pk_mul_f32 v[16:17], v[14:15], v[12:13]
	v_pk_fma_f32 v[12:13], v[14:15], v[12:13], v[14:15] neg_lo:[1,0,0] neg_hi:[1,0,0]
	s_nop 0
	v_cndmask_b32_e32 v22, v12, v16, vcc
	v_cmp_gt_f32_e32 vcc, 0, v15
	v_pk_mul_f32 v[14:15], v[8:9], v[8:9]
	s_nop 0
	v_cndmask_b32_e32 v23, v13, v17, vcc
	v_pk_fma_f32 v[12:13], v[18:19], s[0:1], v[162:163] op_sel_hi:[1,0,0]
	v_pk_mul_f32 v[14:15], v[14:15], s[18:19] op_sel_hi:[1,0]
	v_pk_fma_f32 v[12:13], v[18:19], v[12:13], s[16:17] op_sel_hi:[1,1,0]
	v_exp_f32_e32 v14, v14
	v_pk_fma_f32 v[12:13], v[18:19], v[12:13], s[6:7] op_sel_hi:[1,1,0]
	v_exp_f32_e32 v15, v15
	v_pk_fma_f32 v[12:13], v[18:19], v[12:13], s[14:15] op_sel_hi:[1,1,0]
	v_cmp_gt_f32_e32 vcc, 0, v8
	v_pk_mul_f32 v[12:13], v[18:19], v[12:13]
	v_and_b32_e32 v19, 0x7fffffff, v11
	v_and_b32_e32 v18, 0x7fffffff, v10
	v_pk_fma_f32 v[18:19], v[18:19], s[10:11], 1.0 op_sel_hi:[1,0,0]
	v_pk_mul_f32 v[12:13], v[14:15], v[12:13]
	v_rcp_f32_e32 v18, v18
	v_rcp_f32_e32 v19, v19
	v_pk_mul_f32 v[14:15], v[8:9], v[12:13]
	v_pk_fma_f32 v[12:13], v[8:9], v[12:13], v[8:9] neg_lo:[1,0,0] neg_hi:[1,0,0]
	v_pk_mul_f32 v[16:17], v[10:11], v[10:11]
	v_cndmask_b32_e32 v14, v12, v14, vcc
	v_cmp_gt_f32_e32 vcc, 0, v9
	v_pk_fma_f32 v[8:9], v[18:19], s[0:1], v[162:163] op_sel_hi:[1,0,0]
	s_nop 0
	v_cndmask_b32_e32 v15, v13, v15, vcc
	v_pk_mul_f32 v[12:13], v[16:17], s[18:19] op_sel_hi:[1,0]
	v_pk_fma_f32 v[8:9], v[18:19], v[8:9], s[16:17] op_sel_hi:[1,1,0]
	v_exp_f32_e32 v12, v12
	v_exp_f32_e32 v13, v13
	v_pk_fma_f32 v[8:9], v[18:19], v[8:9], s[6:7] op_sel_hi:[1,1,0]
	v_cmp_gt_f32_e32 vcc, 0, v10
	v_pk_fma_f32 v[8:9], v[18:19], v[8:9], s[14:15] op_sel_hi:[1,1,0]
	s_nop 0
	v_pk_mul_f32 v[8:9], v[18:19], v[8:9]
	s_nop 0
	v_pk_mul_f32 v[8:9], v[12:13], v[8:9]
	s_nop 0
	v_pk_mul_f32 v[12:13], v[10:11], v[8:9]
	v_pk_fma_f32 v[8:9], v[10:11], v[8:9], v[10:11] neg_lo:[1,0,0] neg_hi:[1,0,0]
	s_nop 0
	v_cndmask_b32_e32 v12, v8, v12, vcc
	v_cmp_gt_f32_e32 vcc, 0, v11
	v_cvt_pk_bf16_f32 v8, v20, v21
	s_nop 1
	v_cndmask_b32_e32 v11, v9, v13, vcc
	v_cvt_pk_bf16_f32 v9, v22, v23
	v_cvt_pk_bf16_f32 v10, v14, v15
	v_cvt_pk_bf16_f32 v11, v12, v11
	v_add_u32_e32 v12, 0x1400, v96
	v_ashrrev_i32_e32 v13, 31, v12
	v_lshlrev_b64 v[12:13], 10, v[12:13]
	v_lshl_add_u64 v[12:13], s[20:21], 0, v[12:13]
	v_lshl_add_u64 v[12:13], v[12:13], 0, s[40:41]
	v_lshl_add_u64 v[12:13], v[12:13], 0, v[160:161]
	global_store_dwordx4 v[12:13], v[8:11], off
	s_waitcnt vmcnt(7)
	v_lshlrev_b32_e32 v12, 16, v74
	v_and_b32_e32 v13, 0xffff0000, v74
	v_lshlrev_b32_e32 v8, 16, v72
	v_and_b32_e32 v9, 0xffff0000, v72
	v_pk_fma_f32 v[4:5], v[68:69], v[8:9], v[4:5]
	v_lshlrev_b32_e32 v10, 16, v73
	v_and_b32_e32 v9, 0x7fffffff, v5
	v_and_b32_e32 v8, 0x7fffffff, v4
	v_pk_fma_f32 v[8:9], v[8:9], s[10:11], 1.0 op_sel_hi:[1,0,0]
	v_and_b32_e32 v11, 0xffff0000, v73
	v_rcp_f32_e32 v8, v8
	v_rcp_f32_e32 v9, v9
	v_pk_fma_f32 v[0:1], v[64:65], v[12:13], v[0:1]
	v_pk_mul_f32 v[12:13], v[4:5], v[4:5]
	v_pk_fma_f32 v[6:7], v[70:71], v[10:11], v[6:7]
	v_pk_fma_f32 v[10:11], v[8:9], s[0:1], v[162:163] op_sel_hi:[1,0,0]
	v_pk_mul_f32 v[12:13], v[12:13], s[18:19] op_sel_hi:[1,0]
	v_lshlrev_b32_e32 v14, 16, v75
	v_and_b32_e32 v15, 0xffff0000, v75
	v_pk_fma_f32 v[10:11], v[8:9], v[10:11], s[16:17] op_sel_hi:[1,1,0]
	v_exp_f32_e32 v12, v12
	v_exp_f32_e32 v13, v13
	v_pk_fma_f32 v[2:3], v[66:67], v[14:15], v[2:3]
	v_pk_fma_f32 v[10:11], v[8:9], v[10:11], s[6:7] op_sel_hi:[1,1,0]
	v_and_b32_e32 v15, 0x7fffffff, v7
	v_and_b32_e32 v14, 0x7fffffff, v6
	v_pk_fma_f32 v[10:11], v[8:9], v[10:11], s[14:15] op_sel_hi:[1,1,0]
	v_pk_fma_f32 v[14:15], v[14:15], s[10:11], 1.0 op_sel_hi:[1,0,0]
	v_pk_mul_f32 v[8:9], v[8:9], v[10:11]
	v_rcp_f32_e32 v14, v14
	v_rcp_f32_e32 v15, v15
	v_pk_mul_f32 v[8:9], v[12:13], v[8:9]
	v_cmp_gt_f32_e32 vcc, 0, v4
	v_pk_mul_f32 v[12:13], v[4:5], v[8:9]
	v_pk_fma_f32 v[8:9], v[4:5], v[8:9], v[4:5] neg_lo:[1,0,0] neg_hi:[1,0,0]
	v_pk_mul_f32 v[10:11], v[6:7], v[6:7]
	v_cndmask_b32_e32 v12, v8, v12, vcc
	v_cmp_gt_f32_e32 vcc, 0, v5
	v_pk_fma_f32 v[4:5], v[14:15], s[0:1], v[162:163] op_sel_hi:[1,0,0]
	s_nop 0
	v_cndmask_b32_e32 v13, v9, v13, vcc
	v_pk_mul_f32 v[8:9], v[10:11], s[18:19] op_sel_hi:[1,0]
	v_pk_fma_f32 v[4:5], v[14:15], v[4:5], s[16:17] op_sel_hi:[1,1,0]
	v_exp_f32_e32 v8, v8
	v_exp_f32_e32 v9, v9
	v_pk_fma_f32 v[4:5], v[14:15], v[4:5], s[6:7] op_sel_hi:[1,1,0]
	v_and_b32_e32 v11, 0x7fffffff, v1
	v_and_b32_e32 v10, 0x7fffffff, v0
	v_pk_fma_f32 v[4:5], v[14:15], v[4:5], s[14:15] op_sel_hi:[1,1,0]
	v_pk_fma_f32 v[10:11], v[10:11], s[10:11], 1.0 op_sel_hi:[1,0,0]
	v_pk_mul_f32 v[4:5], v[14:15], v[4:5]
	v_rcp_f32_e32 v10, v10
	v_rcp_f32_e32 v11, v11
	v_pk_mul_f32 v[4:5], v[8:9], v[4:5]
	v_cmp_gt_f32_e32 vcc, 0, v6
	v_pk_mul_f32 v[8:9], v[6:7], v[4:5]
	v_pk_fma_f32 v[4:5], v[6:7], v[4:5], v[6:7] neg_lo:[1,0,0] neg_hi:[1,0,0]
	s_nop 0
	v_cndmask_b32_e32 v14, v4, v8, vcc
	v_cmp_gt_f32_e32 vcc, 0, v7
	v_pk_mul_f32 v[6:7], v[0:1], v[0:1]
	s_nop 0
	v_cndmask_b32_e32 v15, v5, v9, vcc
	v_pk_fma_f32 v[4:5], v[10:11], s[0:1], v[162:163] op_sel_hi:[1,0,0]
	v_pk_mul_f32 v[6:7], v[6:7], s[18:19] op_sel_hi:[1,0]
	v_pk_fma_f32 v[4:5], v[10:11], v[4:5], s[16:17] op_sel_hi:[1,1,0]
	v_exp_f32_e32 v6, v6
	v_pk_fma_f32 v[4:5], v[10:11], v[4:5], s[6:7] op_sel_hi:[1,1,0]
	v_exp_f32_e32 v7, v7
	v_pk_fma_f32 v[4:5], v[10:11], v[4:5], s[14:15] op_sel_hi:[1,1,0]
	v_cmp_gt_f32_e32 vcc, 0, v0
	v_pk_mul_f32 v[4:5], v[10:11], v[4:5]
	v_and_b32_e32 v11, 0x7fffffff, v3
	v_and_b32_e32 v10, 0x7fffffff, v2
	v_pk_fma_f32 v[10:11], v[10:11], s[10:11], 1.0 op_sel_hi:[1,0,0]
	v_pk_mul_f32 v[4:5], v[6:7], v[4:5]
	v_rcp_f32_e32 v10, v10
	v_rcp_f32_e32 v11, v11
	v_pk_mul_f32 v[6:7], v[0:1], v[4:5]
	v_pk_fma_f32 v[4:5], v[0:1], v[4:5], v[0:1] neg_lo:[1,0,0] neg_hi:[1,0,0]
	v_pk_mul_f32 v[8:9], v[2:3], v[2:3]
	v_cndmask_b32_e32 v6, v4, v6, vcc
	v_cmp_gt_f32_e32 vcc, 0, v1
	v_pk_fma_f32 v[0:1], v[10:11], s[0:1], v[162:163] op_sel_hi:[1,0,0]
	s_nop 0
	v_cndmask_b32_e32 v7, v5, v7, vcc
	v_pk_mul_f32 v[4:5], v[8:9], s[18:19] op_sel_hi:[1,0]
	v_pk_fma_f32 v[0:1], v[10:11], v[0:1], s[16:17] op_sel_hi:[1,1,0]
	v_exp_f32_e32 v4, v4
	v_exp_f32_e32 v5, v5
	v_pk_fma_f32 v[0:1], v[10:11], v[0:1], s[6:7] op_sel_hi:[1,1,0]
	v_cmp_gt_f32_e32 vcc, 0, v2
	v_pk_fma_f32 v[0:1], v[10:11], v[0:1], s[14:15] op_sel_hi:[1,1,0]
	s_nop 0
	v_pk_mul_f32 v[0:1], v[10:11], v[0:1]
	s_nop 0
	v_pk_mul_f32 v[0:1], v[4:5], v[0:1]
	s_nop 0
	v_pk_mul_f32 v[4:5], v[2:3], v[0:1]
	v_pk_fma_f32 v[0:1], v[2:3], v[0:1], v[2:3] neg_lo:[1,0,0] neg_hi:[1,0,0]
	s_nop 0
	v_cndmask_b32_e32 v4, v0, v4, vcc
	v_cmp_gt_f32_e32 vcc, 0, v3
	v_cvt_pk_bf16_f32 v0, v12, v13
	s_nop 1
	v_cndmask_b32_e32 v3, v1, v5, vcc
	v_cvt_pk_bf16_f32 v1, v14, v15
	v_cvt_pk_bf16_f32 v2, v6, v7
	v_cvt_pk_bf16_f32 v3, v4, v3
	v_add_u32_e32 v4, 0x1600, v96
	v_ashrrev_i32_e32 v5, 31, v4
	v_lshlrev_b64 v[4:5], 10, v[4:5]
	v_lshl_add_u64 v[4:5], s[20:21], 0, v[4:5]
	v_lshl_add_u64 v[4:5], v[4:5], 0, s[40:41]
	v_lshl_add_u64 v[4:5], v[4:5], 0, v[160:161]
	global_store_dwordx4 v[4:5], v[0:3], off
	s_waitcnt vmcnt(0)
	s_cbranch_scc0 .LBB0_935
	s_barrier

.LBB0_953:
	ds_read_b128 v[144:147], v157
	ds_read_b128 v[148:151], v157 offset:1024
	ds_read_b128 v[160:163], v157 offset:2048
	ds_read_b128 v[164:167], v157 offset:3072
	ds_read_b128 v[168:171], v158
	ds_read_b128 v[172:175], v158 offset:1024
	ds_read_b128 v[176:179], v158 offset:2048
	ds_read_b128 v[180:183], v158 offset:3072
	s_add_u32 s28, s54, 0xfffe0080
	s_addc_u32 s29, s55, -1
	s_cmp_eq_u32 s78, 4
	s_cselect_b32 s59, s45, s29
	s_cselect_b32 s58, s66, s28
	s_cselect_b32 s57, s43, s77
	s_cselect_b32 s56, s67, s76
	v_lshl_add_u64 v[152:153], s[54:55], 0, v[136:137]
	s_add_i32 m0, s27, 0xc000
	ds_read_b128 v[184:187], v159
	ds_read_b128 v[190:193], v159 offset:1024
	ds_read_b128 v[194:197], v159 offset:2048
	ds_read_b128 v[198:201], v159 offset:3072
	ds_read_b128 v[202:205], v159 offset:4096
	ds_read_b128 v[206:209], v159 offset:5120
	ds_read_b128 v[210:213], v159 offset:6144
	ds_read_b128 v[214:217], v159 offset:7168
	global_load_lds_dwordx4 v[152:153], off
	v_lshl_add_u64 v[152:153], s[54:55], 0, v[138:139]
	s_add_i32 m0, s27, 0xe000
	s_nop 0
	global_load_lds_dwordx4 v[152:153], off
	s_waitcnt vmcnt(8)
	s_waitcnt lgkmcnt(0)
	s_nop 0
	s_barrier
	s_waitcnt lgkmcnt(0)
	v_mfma_f32_16x16x32_bf16 v[124:127], v[144:147], v[184:187], v[124:127]
	v_mfma_f32_16x16x32_bf16 v[120:123], v[160:163], v[184:187], v[120:123]
	v_mfma_f32_16x16x32_bf16 v[116:119], v[144:147], v[194:197], v[116:119]
	v_mfma_f32_16x16x32_bf16 v[112:115], v[160:163], v[194:197], v[112:115]
	v_mfma_f32_16x16x32_bf16 v[92:95], v[144:147], v[202:205], v[92:95]
	v_mfma_f32_16x16x32_bf16 v[88:91], v[160:163], v[202:205], v[88:91]
	v_mfma_f32_16x16x32_bf16 v[76:79], v[144:147], v[210:213], v[76:79]
	v_mfma_f32_16x16x32_bf16 v[72:75], v[160:163], v[210:213], v[72:75]
	v_mfma_f32_16x16x32_bf16 v[124:127], v[148:151], v[190:193], v[124:127]
	v_mfma_f32_16x16x32_bf16 v[120:123], v[164:167], v[190:193], v[120:123]
	v_mfma_f32_16x16x32_bf16 v[116:119], v[148:151], v[198:201], v[116:119]
	v_mfma_f32_16x16x32_bf16 v[112:115], v[164:167], v[198:201], v[112:115]
	v_mfma_f32_16x16x32_bf16 v[92:95], v[148:151], v[206:209], v[92:95]
	v_mfma_f32_16x16x32_bf16 v[88:91], v[164:167], v[206:209], v[88:91]
	v_mfma_f32_16x16x32_bf16 v[76:79], v[148:151], v[214:217], v[76:79]
	v_mfma_f32_16x16x32_bf16 v[72:75], v[164:167], v[214:217], v[72:75]
	v_mfma_f32_16x16x32_bf16 v[108:111], v[168:171], v[184:187], v[108:111]
	v_mfma_f32_16x16x32_bf16 v[104:107], v[176:179], v[184:187], v[104:107]
	v_mfma_f32_16x16x32_bf16 v[100:103], v[168:171], v[194:197], v[100:103]
	v_mfma_f32_16x16x32_bf16 v[96:99], v[176:179], v[194:197], v[96:99]
	v_mfma_f32_16x16x32_bf16 v[84:87], v[168:171], v[202:205], v[84:87]
	v_mfma_f32_16x16x32_bf16 v[80:83], v[176:179], v[202:205], v[80:83]
	v_mfma_f32_16x16x32_bf16 v[68:71], v[168:171], v[210:213], v[68:71]
	v_mfma_f32_16x16x32_bf16 v[64:67], v[176:179], v[210:213], v[64:67]
	v_mfma_f32_16x16x32_bf16 v[108:111], v[172:175], v[190:193], v[108:111]
	v_mfma_f32_16x16x32_bf16 v[104:107], v[180:183], v[190:193], v[104:107]
	v_mfma_f32_16x16x32_bf16 v[100:103], v[172:175], v[198:201], v[100:103]
	v_mfma_f32_16x16x32_bf16 v[96:99], v[180:183], v[198:201], v[96:99]
	v_mfma_f32_16x16x32_bf16 v[84:87], v[172:175], v[206:209], v[84:87]
	v_mfma_f32_16x16x32_bf16 v[80:83], v[180:183], v[206:209], v[80:83]
	v_mfma_f32_16x16x32_bf16 v[68:71], v[172:175], v[214:217], v[68:71]
	v_mfma_f32_16x16x32_bf16 v[64:67], v[180:183], v[214:217], v[64:67]
	s_barrier
	s_add_i32 s28, s63, s13
	v_lshl_add_u64 v[152:153], s[56:57], 0, v[130:131]
	s_mov_b32 m0, s28
	ds_read_b128 v[184:187], v159 offset:16384
	ds_read_b128 v[190:193], v159 offset:17408
	ds_read_b128 v[194:197], v159 offset:18432
	ds_read_b128 v[198:201], v159 offset:19456
	ds_read_b128 v[202:205], v159 offset:20480
	ds_read_b128 v[206:209], v159 offset:21504
	ds_read_b128 v[210:213], v159 offset:22528
	ds_read_b128 v[214:217], v159 offset:23552
	global_load_lds_dwordx4 v[152:153], off
	s_add_i32 m0, s28, 0x2000
	s_add_u32 s28, s56, 0x20000
	v_lshl_add_u64 v[218:219], s[56:57], 0, v[134:135]
	s_addc_u32 s29, s57, 0
	s_add_i32 s33, s64, s13
	global_load_lds_dwordx4 v[218:219], off
	v_lshl_add_u64 v[220:221], s[28:29], 0, v[130:131]
	s_mov_b32 m0, s33
	v_lshl_add_u64 v[222:223], s[58:59], 0, v[132:133]
	global_load_lds_dwordx4 v[220:221], off
	v_lshl_add_u64 v[220:221], s[28:29], 0, v[134:135]
	s_add_i32 m0, s33, 0x2000
	s_nop 0
	global_load_lds_dwordx4 v[220:221], off
	v_lshl_add_u64 v[220:221], s[58:59], 0, v[128:129]
	s_mov_b32 m0, s27
	s_nop 0
	global_load_lds_dwordx4 v[220:221], off
	s_mov_b32 m0, s34
	s_nop 0
	global_load_lds_dwordx4 v[222:223], off
	s_waitcnt vmcnt(8)
	s_waitcnt lgkmcnt(0)
	s_nop 0
	s_barrier
	s_waitcnt lgkmcnt(0)
	v_mfma_f32_16x16x32_bf16 v[60:63], v[144:147], v[184:187], v[60:63]
	v_mfma_f32_16x16x32_bf16 v[56:59], v[160:163], v[184:187], v[56:59]
	v_mfma_f32_16x16x32_bf16 v[44:47], v[144:147], v[194:197], v[44:47]
	v_mfma_f32_16x16x32_bf16 v[40:43], v[160:163], v[194:197], v[40:43]
	v_mfma_f32_16x16x32_bf16 v[28:31], v[144:147], v[202:205], v[28:31]
	v_mfma_f32_16x16x32_bf16 v[24:27], v[160:163], v[202:205], v[24:27]
	v_mfma_f32_16x16x32_bf16 v[12:15], v[144:147], v[210:213], v[12:15]
	v_mfma_f32_16x16x32_bf16 v[8:11], v[160:163], v[210:213], v[8:11]
	v_mfma_f32_16x16x32_bf16 v[60:63], v[148:151], v[190:193], v[60:63]
	v_mfma_f32_16x16x32_bf16 v[56:59], v[164:167], v[190:193], v[56:59]
	v_mfma_f32_16x16x32_bf16 v[44:47], v[148:151], v[198:201], v[44:47]
	v_mfma_f32_16x16x32_bf16 v[40:43], v[164:167], v[198:201], v[40:43]
	v_mfma_f32_16x16x32_bf16 v[28:31], v[148:151], v[206:209], v[28:31]
	v_mfma_f32_16x16x32_bf16 v[24:27], v[164:167], v[206:209], v[24:27]
	v_mfma_f32_16x16x32_bf16 v[12:15], v[148:151], v[214:217], v[12:15]
	v_mfma_f32_16x16x32_bf16 v[8:11], v[164:167], v[214:217], v[8:11]
	v_mfma_f32_16x16x32_bf16 v[52:55], v[168:171], v[184:187], v[52:55]
	v_mfma_f32_16x16x32_bf16 v[48:51], v[176:179], v[184:187], v[48:51]
	v_mfma_f32_16x16x32_bf16 v[36:39], v[168:171], v[194:197], v[36:39]
	v_mfma_f32_16x16x32_bf16 v[32:35], v[176:179], v[194:197], v[32:35]
	v_mfma_f32_16x16x32_bf16 v[20:23], v[168:171], v[202:205], v[20:23]
	v_mfma_f32_16x16x32_bf16 v[16:19], v[176:179], v[202:205], v[16:19]
	v_mfma_f32_16x16x32_bf16 v[4:7], v[168:171], v[210:213], v[4:7]
	v_mfma_f32_16x16x32_bf16 v[0:3], v[176:179], v[210:213], v[0:3]
	v_mfma_f32_16x16x32_bf16 v[52:55], v[172:175], v[190:193], v[52:55]
	v_mfma_f32_16x16x32_bf16 v[48:51], v[180:183], v[190:193], v[48:51]
	v_mfma_f32_16x16x32_bf16 v[36:39], v[172:175], v[198:201], v[36:39]
	v_mfma_f32_16x16x32_bf16 v[32:35], v[180:183], v[198:201], v[32:35]
	v_mfma_f32_16x16x32_bf16 v[20:23], v[172:175], v[206:209], v[20:23]
	v_mfma_f32_16x16x32_bf16 v[16:19], v[180:183], v[206:209], v[16:19]
	v_mfma_f32_16x16x32_bf16 v[4:7], v[172:175], v[214:217], v[4:7]
	v_mfma_f32_16x16x32_bf16 v[0:3], v[180:183], v[214:217], v[0:3]
	s_barrier
	s_add_i32 s33, 0, 0x18000
	s_add_i32 s79, 0, 0x1c000
	v_add_u32_e32 v164, s33, v155
	v_add_u32_e32 v180, s79, v155
	ds_read_b128 v[144:147], v164
	ds_read_b128 v[148:151], v164 offset:1024
	ds_read_b128 v[160:163], v164 offset:2048
	ds_read_b128 v[164:167], v164 offset:3072
	ds_read_b128 v[168:171], v180
	ds_read_b128 v[172:175], v180 offset:1024
	ds_read_b128 v[176:179], v180 offset:2048
	ds_read_b128 v[180:183], v180 offset:3072
	s_add_u32 s28, s58, 0x20000
	s_addc_u32 s29, s59, 0
	s_mov_b32 m0, s35
	v_lshl_add_u64 v[224:225], s[28:29], 0, v[128:129]
	ds_read_b128 v[184:187], v159 offset:32768
	ds_read_b128 v[190:193], v159 offset:33792
	ds_read_b128 v[194:197], v159 offset:34816
	ds_read_b128 v[198:201], v159 offset:35840
	ds_read_b128 v[202:205], v159 offset:36864
	ds_read_b128 v[206:209], v159 offset:37888
	ds_read_b128 v[210:213], v159 offset:38912
	ds_read_b128 v[214:217], v159 offset:39936
	global_load_lds_dwordx4 v[224:225], off
	v_lshl_add_u64 v[224:225], s[28:29], 0, v[132:133]
	s_mov_b32 m0, s53
	s_nop 0
	global_load_lds_dwordx4 v[224:225], off
	s_waitcnt vmcnt(8)
	s_waitcnt lgkmcnt(0)
	s_nop 0
	s_barrier
	s_waitcnt lgkmcnt(0)
	v_mfma_f32_16x16x32_bf16 v[124:127], v[144:147], v[184:187], v[124:127]
	v_mfma_f32_16x16x32_bf16 v[120:123], v[160:163], v[184:187], v[120:123]
	v_mfma_f32_16x16x32_bf16 v[116:119], v[144:147], v[194:197], v[116:119]
	v_mfma_f32_16x16x32_bf16 v[112:115], v[160:163], v[194:197], v[112:115]
	v_mfma_f32_16x16x32_bf16 v[92:95], v[144:147], v[202:205], v[92:95]
	v_mfma_f32_16x16x32_bf16 v[88:91], v[160:163], v[202:205], v[88:91]
	v_mfma_f32_16x16x32_bf16 v[76:79], v[144:147], v[210:213], v[76:79]
	v_mfma_f32_16x16x32_bf16 v[72:75], v[160:163], v[210:213], v[72:75]
	v_mfma_f32_16x16x32_bf16 v[124:127], v[148:151], v[190:193], v[124:127]
	v_mfma_f32_16x16x32_bf16 v[120:123], v[164:167], v[190:193], v[120:123]
	v_mfma_f32_16x16x32_bf16 v[116:119], v[148:151], v[198:201], v[116:119]
	v_mfma_f32_16x16x32_bf16 v[112:115], v[164:167], v[198:201], v[112:115]
	v_mfma_f32_16x16x32_bf16 v[92:95], v[148:151], v[206:209], v[92:95]
	v_mfma_f32_16x16x32_bf16 v[88:91], v[164:167], v[206:209], v[88:91]
	v_mfma_f32_16x16x32_bf16 v[76:79], v[148:151], v[214:217], v[76:79]
	v_mfma_f32_16x16x32_bf16 v[72:75], v[164:167], v[214:217], v[72:75]
	v_mfma_f32_16x16x32_bf16 v[108:111], v[168:171], v[184:187], v[108:111]
	v_mfma_f32_16x16x32_bf16 v[104:107], v[176:179], v[184:187], v[104:107]
	v_mfma_f32_16x16x32_bf16 v[100:103], v[168:171], v[194:197], v[100:103]
	v_mfma_f32_16x16x32_bf16 v[96:99], v[176:179], v[194:197], v[96:99]
	v_mfma_f32_16x16x32_bf16 v[84:87], v[168:171], v[202:205], v[84:87]
	v_mfma_f32_16x16x32_bf16 v[80:83], v[176:179], v[202:205], v[80:83]
	v_mfma_f32_16x16x32_bf16 v[68:71], v[168:171], v[210:213], v[68:71]
	v_mfma_f32_16x16x32_bf16 v[64:67], v[176:179], v[210:213], v[64:67]
	v_mfma_f32_16x16x32_bf16 v[108:111], v[172:175], v[190:193], v[108:111]
	v_mfma_f32_16x16x32_bf16 v[104:107], v[180:183], v[190:193], v[104:107]
	v_mfma_f32_16x16x32_bf16 v[100:103], v[172:175], v[198:201], v[100:103]
	v_mfma_f32_16x16x32_bf16 v[96:99], v[180:183], v[198:201], v[96:99]
	v_mfma_f32_16x16x32_bf16 v[84:87], v[172:175], v[206:209], v[84:87]
	v_mfma_f32_16x16x32_bf16 v[80:83], v[180:183], v[206:209], v[80:83]
	v_mfma_f32_16x16x32_bf16 v[68:71], v[172:175], v[214:217], v[68:71]
	v_mfma_f32_16x16x32_bf16 v[64:67], v[180:183], v[214:217], v[64:67]
	s_barrier
	s_add_i32 s28, s33, s13
	v_lshl_add_u64 v[152:153], v[152:153], 0, s[14:15]
	s_mov_b32 m0, s28
	ds_read_b128 v[184:187], v159 offset:49152
	ds_read_b128 v[190:193], v159 offset:50176
	ds_read_b128 v[194:197], v159 offset:51200
	ds_read_b128 v[198:201], v159 offset:52224
	ds_read_b128 v[202:205], v159 offset:53248
	ds_read_b128 v[206:209], v159 offset:54272
	ds_read_b128 v[210:213], v159 offset:55296
	ds_read_b128 v[214:217], v159 offset:56320
	global_load_lds_dwordx4 v[152:153], off
	s_add_i32 m0, s28, 0x2000
	s_add_u32 s28, s56, 0x20080
	v_lshl_add_u64 v[152:153], v[218:219], 0, s[14:15]
	s_addc_u32 s29, s57, 0
	s_add_i32 s33, s79, s13
	global_load_lds_dwordx4 v[152:153], off
	v_lshl_add_u64 v[152:153], s[28:29], 0, v[130:131]
	s_mov_b32 m0, s33
	s_nop 0
	global_load_lds_dwordx4 v[152:153], off
	v_lshl_add_u64 v[152:153], s[28:29], 0, v[134:135]
	s_add_i32 m0, s33, 0x2000
	s_nop 0
	global_load_lds_dwordx4 v[152:153], off
	v_lshl_add_u64 v[152:153], v[220:221], 0, s[14:15]
	s_mov_b32 m0, s61
	s_nop 0
	global_load_lds_dwordx4 v[152:153], off
	v_lshl_add_u64 v[152:153], v[222:223], 0, s[14:15]
	s_mov_b32 m0, s62
	s_nop 0
	global_load_lds_dwordx4 v[152:153], off
	s_waitcnt vmcnt(8)
	s_waitcnt lgkmcnt(0)
	s_barrier
	s_waitcnt lgkmcnt(0)
	v_mfma_f32_16x16x32_bf16 v[60:63], v[144:147], v[184:187], v[60:63]
	v_mfma_f32_16x16x32_bf16 v[56:59], v[160:163], v[184:187], v[56:59]
	v_mfma_f32_16x16x32_bf16 v[44:47], v[144:147], v[194:197], v[44:47]
	v_mfma_f32_16x16x32_bf16 v[40:43], v[160:163], v[194:197], v[40:43]
	v_mfma_f32_16x16x32_bf16 v[28:31], v[144:147], v[202:205], v[28:31]
	v_mfma_f32_16x16x32_bf16 v[24:27], v[160:163], v[202:205], v[24:27]
	v_mfma_f32_16x16x32_bf16 v[12:15], v[144:147], v[210:213], v[12:15]
	v_mfma_f32_16x16x32_bf16 v[8:11], v[160:163], v[210:213], v[8:11]
	v_mfma_f32_16x16x32_bf16 v[60:63], v[148:151], v[190:193], v[60:63]
	v_mfma_f32_16x16x32_bf16 v[56:59], v[164:167], v[190:193], v[56:59]
	v_mfma_f32_16x16x32_bf16 v[44:47], v[148:151], v[198:201], v[44:47]
	v_mfma_f32_16x16x32_bf16 v[40:43], v[164:167], v[198:201], v[40:43]
	v_mfma_f32_16x16x32_bf16 v[28:31], v[148:151], v[206:209], v[28:31]
	v_mfma_f32_16x16x32_bf16 v[24:27], v[164:167], v[206:209], v[24:27]
	v_mfma_f32_16x16x32_bf16 v[12:15], v[148:151], v[214:217], v[12:15]
	v_mfma_f32_16x16x32_bf16 v[8:11], v[164:167], v[214:217], v[8:11]
	v_mfma_f32_16x16x32_bf16 v[52:55], v[168:171], v[184:187], v[52:55]
	v_mfma_f32_16x16x32_bf16 v[48:51], v[176:179], v[184:187], v[48:51]
	v_mfma_f32_16x16x32_bf16 v[36:39], v[168:171], v[194:197], v[36:39]
	v_mfma_f32_16x16x32_bf16 v[32:35], v[176:179], v[194:197], v[32:35]
	v_mfma_f32_16x16x32_bf16 v[20:23], v[168:171], v[202:205], v[20:23]
	v_mfma_f32_16x16x32_bf16 v[16:19], v[176:179], v[202:205], v[16:19]
	v_mfma_f32_16x16x32_bf16 v[4:7], v[168:171], v[210:213], v[4:7]
	v_mfma_f32_16x16x32_bf16 v[0:3], v[176:179], v[210:213], v[0:3]
	v_mfma_f32_16x16x32_bf16 v[52:55], v[172:175], v[190:193], v[52:55]
	v_mfma_f32_16x16x32_bf16 v[48:51], v[180:183], v[190:193], v[48:51]
	v_mfma_f32_16x16x32_bf16 v[36:39], v[172:175], v[198:201], v[36:39]
	v_mfma_f32_16x16x32_bf16 v[32:35], v[180:183], v[198:201], v[32:35]
	v_mfma_f32_16x16x32_bf16 v[20:23], v[172:175], v[206:209], v[20:23]
	v_mfma_f32_16x16x32_bf16 v[16:19], v[180:183], v[206:209], v[16:19]
	v_mfma_f32_16x16x32_bf16 v[4:7], v[172:175], v[214:217], v[4:7]
	v_mfma_f32_16x16x32_bf16 v[0:3], v[180:183], v[214:217], v[0:3]
	s_barrier
	s_add_i32 s78, s78, 2
	s_add_u32 s54, s54, 0x100
	s_addc_u32 s55, s55, 0
	s_add_u32 s76, s76, 0x100
	s_addc_u32 s77, s77, 0
	s_cmp_gt_u32 s78, 5
	s_cbranch_scc0 .LBB0_953
	s_and_b64 vcc, exec, s[16:17]
	s_cbranch_vccz .LBB0_956
	s_barrier

.LBB0_1029:
	ds_read_b128 v[128:131], v169
	ds_read_b128 v[132:135], v169 offset:1024
	ds_read_b128 v[136:139], v169 offset:2048
	ds_read_b128 v[140:143], v169 offset:3072
	ds_read_b128 v[160:163], v170
	ds_read_b128 v[172:175], v170 offset:1024
	ds_read_b128 v[176:179], v170 offset:2048
	ds_read_b128 v[180:183], v170 offset:3072
	s_add_u32 s28, s44, 0xfffe0080
	s_addc_u32 s29, s45, -1
	s_cmp_eq_u32 s64, 4
	s_cselect_b32 s51, s37, s29
	s_cselect_b32 s50, s60, s28
	s_cselect_b32 s47, s19, s63
	s_cselect_b32 s46, s61, s62
	v_lshl_add_u64 v[164:165], s[44:45], 0, v[152:153]
	s_add_i32 m0, s17, 0xc000
	ds_read_b128 v[184:187], v171
	ds_read_b128 v[190:193], v171 offset:1024
	ds_read_b128 v[194:197], v171 offset:2048
	ds_read_b128 v[198:201], v171 offset:3072
	ds_read_b128 v[202:205], v171 offset:4096
	ds_read_b128 v[206:209], v171 offset:5120
	ds_read_b128 v[210:213], v171 offset:6144
	ds_read_b128 v[214:217], v171 offset:7168
	global_load_lds_dwordx4 v[164:165], off
	v_lshl_add_u64 v[164:165], s[44:45], 0, v[154:155]
	s_add_i32 m0, s17, 0xe000
	s_nop 0
	global_load_lds_dwordx4 v[164:165], off
	s_waitcnt vmcnt(8)
	s_waitcnt lgkmcnt(0)
	s_barrier
	s_waitcnt lgkmcnt(0)
	v_mfma_f32_16x16x32_bf16 v[124:127], v[128:131], v[184:187], v[124:127]
	v_mfma_f32_16x16x32_bf16 v[120:123], v[136:139], v[184:187], v[120:123]
	v_mfma_f32_16x16x32_bf16 v[116:119], v[128:131], v[194:197], v[116:119]
	v_mfma_f32_16x16x32_bf16 v[112:115], v[136:139], v[194:197], v[112:115]
	v_mfma_f32_16x16x32_bf16 v[92:95], v[128:131], v[202:205], v[92:95]
	v_mfma_f32_16x16x32_bf16 v[84:87], v[136:139], v[202:205], v[84:87]
	v_mfma_f32_16x16x32_bf16 v[76:79], v[128:131], v[210:213], v[76:79]
	v_mfma_f32_16x16x32_bf16 v[68:71], v[136:139], v[210:213], v[68:71]
	v_mfma_f32_16x16x32_bf16 v[124:127], v[132:135], v[190:193], v[124:127]
	v_mfma_f32_16x16x32_bf16 v[120:123], v[140:143], v[190:193], v[120:123]
	v_mfma_f32_16x16x32_bf16 v[116:119], v[132:135], v[198:201], v[116:119]
	v_mfma_f32_16x16x32_bf16 v[112:115], v[140:143], v[198:201], v[112:115]
	v_mfma_f32_16x16x32_bf16 v[92:95], v[132:135], v[206:209], v[92:95]
	v_mfma_f32_16x16x32_bf16 v[84:87], v[140:143], v[206:209], v[84:87]
	v_mfma_f32_16x16x32_bf16 v[76:79], v[132:135], v[214:217], v[76:79]
	v_mfma_f32_16x16x32_bf16 v[68:71], v[140:143], v[214:217], v[68:71]
	v_mfma_f32_16x16x32_bf16 v[108:111], v[160:163], v[184:187], v[108:111]
	v_mfma_f32_16x16x32_bf16 v[104:107], v[176:179], v[184:187], v[104:107]
	v_mfma_f32_16x16x32_bf16 v[100:103], v[160:163], v[194:197], v[100:103]
	v_mfma_f32_16x16x32_bf16 v[96:99], v[176:179], v[194:197], v[96:99]
	v_mfma_f32_16x16x32_bf16 v[88:91], v[160:163], v[202:205], v[88:91]
	v_mfma_f32_16x16x32_bf16 v[80:83], v[176:179], v[202:205], v[80:83]
	v_mfma_f32_16x16x32_bf16 v[72:75], v[160:163], v[210:213], v[72:75]
	v_mfma_f32_16x16x32_bf16 v[64:67], v[176:179], v[210:213], v[64:67]
	v_mfma_f32_16x16x32_bf16 v[108:111], v[172:175], v[190:193], v[108:111]
	v_mfma_f32_16x16x32_bf16 v[104:107], v[180:183], v[190:193], v[104:107]
	v_mfma_f32_16x16x32_bf16 v[100:103], v[172:175], v[198:201], v[100:103]
	v_mfma_f32_16x16x32_bf16 v[96:99], v[180:183], v[198:201], v[96:99]
	v_mfma_f32_16x16x32_bf16 v[88:91], v[172:175], v[206:209], v[88:91]
	v_mfma_f32_16x16x32_bf16 v[80:83], v[180:183], v[206:209], v[80:83]
	v_mfma_f32_16x16x32_bf16 v[72:75], v[172:175], v[214:217], v[72:75]
	v_mfma_f32_16x16x32_bf16 v[64:67], v[180:183], v[214:217], v[64:67]
	s_barrier
	s_add_i32 s28, s54, s13
	v_lshl_add_u64 v[164:165], s[46:47], 0, v[146:147]
	s_mov_b32 m0, s28
	ds_read_b128 v[184:187], v171 offset:16384
	ds_read_b128 v[190:193], v171 offset:17408
	ds_read_b128 v[194:197], v171 offset:18432
	ds_read_b128 v[198:201], v171 offset:19456
	ds_read_b128 v[202:205], v171 offset:20480
	ds_read_b128 v[206:209], v171 offset:21504
	ds_read_b128 v[210:213], v171 offset:22528
	ds_read_b128 v[214:217], v171 offset:23552
	global_load_lds_dwordx4 v[164:165], off
	s_add_i32 m0, s28, 0x2000
	s_add_u32 s28, s46, 0x20000
	v_lshl_add_u64 v[218:219], s[46:47], 0, v[150:151]
	s_addc_u32 s29, s47, 0
	s_add_i32 s33, s55, s13
	global_load_lds_dwordx4 v[218:219], off
	v_lshl_add_u64 v[220:221], s[28:29], 0, v[146:147]
	s_mov_b32 m0, s33
	v_lshl_add_u64 v[222:223], s[50:51], 0, v[148:149]
	global_load_lds_dwordx4 v[220:221], off
	v_lshl_add_u64 v[220:221], s[28:29], 0, v[150:151]
	s_add_i32 m0, s33, 0x2000
	s_nop 0
	global_load_lds_dwordx4 v[220:221], off
	v_lshl_add_u64 v[220:221], s[50:51], 0, v[144:145]
	s_mov_b32 m0, s17
	s_nop 0
	global_load_lds_dwordx4 v[220:221], off
	s_mov_b32 m0, s27
	s_nop 0
	global_load_lds_dwordx4 v[222:223], off
	s_waitcnt vmcnt(8)
	s_waitcnt lgkmcnt(0)
	s_nop 0
	s_barrier
	s_waitcnt lgkmcnt(0)
	v_mfma_f32_16x16x32_bf16 v[60:63], v[128:131], v[184:187], v[60:63]
	v_mfma_f32_16x16x32_bf16 v[52:55], v[136:139], v[184:187], v[52:55]
	v_mfma_f32_16x16x32_bf16 v[44:47], v[128:131], v[194:197], v[44:47]
	v_mfma_f32_16x16x32_bf16 v[36:39], v[136:139], v[194:197], v[36:39]
	v_mfma_f32_16x16x32_bf16 v[28:31], v[128:131], v[202:205], v[28:31]
	v_mfma_f32_16x16x32_bf16 v[20:23], v[136:139], v[202:205], v[20:23]
	v_mfma_f32_16x16x32_bf16 v[12:15], v[128:131], v[210:213], v[12:15]
	v_mfma_f32_16x16x32_bf16 v[4:7], v[136:139], v[210:213], v[4:7]
	v_mfma_f32_16x16x32_bf16 v[60:63], v[132:135], v[190:193], v[60:63]
	v_mfma_f32_16x16x32_bf16 v[52:55], v[140:143], v[190:193], v[52:55]
	v_mfma_f32_16x16x32_bf16 v[44:47], v[132:135], v[198:201], v[44:47]
	v_mfma_f32_16x16x32_bf16 v[36:39], v[140:143], v[198:201], v[36:39]
	v_mfma_f32_16x16x32_bf16 v[28:31], v[132:135], v[206:209], v[28:31]
	v_mfma_f32_16x16x32_bf16 v[20:23], v[140:143], v[206:209], v[20:23]
	v_mfma_f32_16x16x32_bf16 v[12:15], v[132:135], v[214:217], v[12:15]
	v_mfma_f32_16x16x32_bf16 v[4:7], v[140:143], v[214:217], v[4:7]
	v_mfma_f32_16x16x32_bf16 v[56:59], v[160:163], v[184:187], v[56:59]
	v_mfma_f32_16x16x32_bf16 v[48:51], v[176:179], v[184:187], v[48:51]
	v_mfma_f32_16x16x32_bf16 v[40:43], v[160:163], v[194:197], v[40:43]
	v_mfma_f32_16x16x32_bf16 v[32:35], v[176:179], v[194:197], v[32:35]
	v_mfma_f32_16x16x32_bf16 v[24:27], v[160:163], v[202:205], v[24:27]
	v_mfma_f32_16x16x32_bf16 v[16:19], v[176:179], v[202:205], v[16:19]
	v_mfma_f32_16x16x32_bf16 v[8:11], v[160:163], v[210:213], v[8:11]
	v_mfma_f32_16x16x32_bf16 v[0:3], v[176:179], v[210:213], v[0:3]
	v_mfma_f32_16x16x32_bf16 v[56:59], v[172:175], v[190:193], v[56:59]
	v_mfma_f32_16x16x32_bf16 v[48:51], v[180:183], v[190:193], v[48:51]
	v_mfma_f32_16x16x32_bf16 v[40:43], v[172:175], v[198:201], v[40:43]
	v_mfma_f32_16x16x32_bf16 v[32:35], v[180:183], v[198:201], v[32:35]
	v_mfma_f32_16x16x32_bf16 v[24:27], v[172:175], v[206:209], v[24:27]
	v_mfma_f32_16x16x32_bf16 v[16:19], v[180:183], v[206:209], v[16:19]
	v_mfma_f32_16x16x32_bf16 v[8:11], v[172:175], v[214:217], v[8:11]
	v_mfma_f32_16x16x32_bf16 v[0:3], v[180:183], v[214:217], v[0:3]
	s_barrier
	s_add_i32 s33, 0, 0x18000
	s_add_i32 s65, 0, 0x1c000
	v_add_u32_e32 v140, s33, v167
	v_add_u32_e32 v180, s65, v167
	ds_read_b128 v[128:131], v140
	ds_read_b128 v[132:135], v140 offset:1024
	ds_read_b128 v[136:139], v140 offset:2048
	ds_read_b128 v[140:143], v140 offset:3072
	ds_read_b128 v[160:163], v180
	ds_read_b128 v[172:175], v180 offset:1024
	ds_read_b128 v[176:179], v180 offset:2048
	ds_read_b128 v[180:183], v180 offset:3072
	s_add_u32 s28, s50, 0x20000
	s_addc_u32 s29, s51, 0
	s_mov_b32 m0, s34
	v_lshl_add_u64 v[224:225], s[28:29], 0, v[144:145]
	ds_read_b128 v[184:187], v171 offset:32768
	ds_read_b128 v[190:193], v171 offset:33792
	ds_read_b128 v[194:197], v171 offset:34816
	ds_read_b128 v[198:201], v171 offset:35840
	ds_read_b128 v[202:205], v171 offset:36864
	ds_read_b128 v[206:209], v171 offset:37888
	ds_read_b128 v[210:213], v171 offset:38912
	ds_read_b128 v[214:217], v171 offset:39936
	global_load_lds_dwordx4 v[224:225], off
	v_lshl_add_u64 v[224:225], s[28:29], 0, v[148:149]
	s_mov_b32 m0, s35
	s_nop 0
	global_load_lds_dwordx4 v[224:225], off
	s_waitcnt vmcnt(8)
	s_waitcnt lgkmcnt(0)
	s_nop 0
	s_barrier
	s_waitcnt lgkmcnt(0)
	v_mfma_f32_16x16x32_bf16 v[124:127], v[128:131], v[184:187], v[124:127]
	v_mfma_f32_16x16x32_bf16 v[120:123], v[136:139], v[184:187], v[120:123]
	v_mfma_f32_16x16x32_bf16 v[116:119], v[128:131], v[194:197], v[116:119]
	v_mfma_f32_16x16x32_bf16 v[112:115], v[136:139], v[194:197], v[112:115]
	v_mfma_f32_16x16x32_bf16 v[92:95], v[128:131], v[202:205], v[92:95]
	v_mfma_f32_16x16x32_bf16 v[84:87], v[136:139], v[202:205], v[84:87]
	v_mfma_f32_16x16x32_bf16 v[76:79], v[128:131], v[210:213], v[76:79]
	v_mfma_f32_16x16x32_bf16 v[68:71], v[136:139], v[210:213], v[68:71]
	v_mfma_f32_16x16x32_bf16 v[124:127], v[132:135], v[190:193], v[124:127]
	v_mfma_f32_16x16x32_bf16 v[120:123], v[140:143], v[190:193], v[120:123]
	v_mfma_f32_16x16x32_bf16 v[116:119], v[132:135], v[198:201], v[116:119]
	v_mfma_f32_16x16x32_bf16 v[112:115], v[140:143], v[198:201], v[112:115]
	v_mfma_f32_16x16x32_bf16 v[92:95], v[132:135], v[206:209], v[92:95]
	v_mfma_f32_16x16x32_bf16 v[84:87], v[140:143], v[206:209], v[84:87]
	v_mfma_f32_16x16x32_bf16 v[76:79], v[132:135], v[214:217], v[76:79]
	v_mfma_f32_16x16x32_bf16 v[68:71], v[140:143], v[214:217], v[68:71]
	v_mfma_f32_16x16x32_bf16 v[108:111], v[160:163], v[184:187], v[108:111]
	v_mfma_f32_16x16x32_bf16 v[104:107], v[176:179], v[184:187], v[104:107]
	v_mfma_f32_16x16x32_bf16 v[100:103], v[160:163], v[194:197], v[100:103]
	v_mfma_f32_16x16x32_bf16 v[96:99], v[176:179], v[194:197], v[96:99]
	v_mfma_f32_16x16x32_bf16 v[88:91], v[160:163], v[202:205], v[88:91]
	v_mfma_f32_16x16x32_bf16 v[80:83], v[176:179], v[202:205], v[80:83]
	v_mfma_f32_16x16x32_bf16 v[72:75], v[160:163], v[210:213], v[72:75]
	v_mfma_f32_16x16x32_bf16 v[64:67], v[176:179], v[210:213], v[64:67]
	v_mfma_f32_16x16x32_bf16 v[108:111], v[172:175], v[190:193], v[108:111]
	v_mfma_f32_16x16x32_bf16 v[104:107], v[180:183], v[190:193], v[104:107]
	v_mfma_f32_16x16x32_bf16 v[100:103], v[172:175], v[198:201], v[100:103]
	v_mfma_f32_16x16x32_bf16 v[96:99], v[180:183], v[198:201], v[96:99]
	v_mfma_f32_16x16x32_bf16 v[88:91], v[172:175], v[206:209], v[88:91]
	v_mfma_f32_16x16x32_bf16 v[80:83], v[180:183], v[206:209], v[80:83]
	v_mfma_f32_16x16x32_bf16 v[72:75], v[172:175], v[214:217], v[72:75]
	v_mfma_f32_16x16x32_bf16 v[64:67], v[180:183], v[214:217], v[64:67]
	s_barrier
	s_add_i32 s28, s33, s13
	v_lshl_add_u64 v[164:165], v[164:165], 0, s[10:11]
	s_mov_b32 m0, s28
	ds_read_b128 v[184:187], v171 offset:49152
	ds_read_b128 v[190:193], v171 offset:50176
	ds_read_b128 v[194:197], v171 offset:51200
	ds_read_b128 v[198:201], v171 offset:52224
	ds_read_b128 v[202:205], v171 offset:53248
	ds_read_b128 v[206:209], v171 offset:54272
	ds_read_b128 v[210:213], v171 offset:55296
	ds_read_b128 v[214:217], v171 offset:56320
	global_load_lds_dwordx4 v[164:165], off
	s_add_i32 m0, s28, 0x2000
	s_add_u32 s28, s46, 0x20080
	v_lshl_add_u64 v[164:165], v[218:219], 0, s[10:11]
	s_addc_u32 s29, s47, 0
	s_add_i32 s33, s65, s13
	global_load_lds_dwordx4 v[164:165], off
	v_lshl_add_u64 v[164:165], s[28:29], 0, v[146:147]
	s_mov_b32 m0, s33
	s_nop 0
	global_load_lds_dwordx4 v[164:165], off
	v_lshl_add_u64 v[164:165], s[28:29], 0, v[150:151]
	s_add_i32 m0, s33, 0x2000
	s_nop 0
	global_load_lds_dwordx4 v[164:165], off
	v_lshl_add_u64 v[164:165], v[220:221], 0, s[10:11]
	s_mov_b32 m0, s52
	s_nop 0
	global_load_lds_dwordx4 v[164:165], off
	v_lshl_add_u64 v[164:165], v[222:223], 0, s[10:11]
	s_mov_b32 m0, s53
	s_nop 0
	global_load_lds_dwordx4 v[164:165], off
	s_waitcnt vmcnt(8)
	s_waitcnt lgkmcnt(0)
	s_barrier
	s_waitcnt lgkmcnt(0)
	v_mfma_f32_16x16x32_bf16 v[60:63], v[128:131], v[184:187], v[60:63]
	v_mfma_f32_16x16x32_bf16 v[52:55], v[136:139], v[184:187], v[52:55]
	v_mfma_f32_16x16x32_bf16 v[44:47], v[128:131], v[194:197], v[44:47]
	v_mfma_f32_16x16x32_bf16 v[36:39], v[136:139], v[194:197], v[36:39]
	v_mfma_f32_16x16x32_bf16 v[28:31], v[128:131], v[202:205], v[28:31]
	v_mfma_f32_16x16x32_bf16 v[20:23], v[136:139], v[202:205], v[20:23]
	v_mfma_f32_16x16x32_bf16 v[12:15], v[128:131], v[210:213], v[12:15]
	v_mfma_f32_16x16x32_bf16 v[4:7], v[136:139], v[210:213], v[4:7]
	v_mfma_f32_16x16x32_bf16 v[60:63], v[132:135], v[190:193], v[60:63]
	v_mfma_f32_16x16x32_bf16 v[52:55], v[140:143], v[190:193], v[52:55]
	v_mfma_f32_16x16x32_bf16 v[44:47], v[132:135], v[198:201], v[44:47]
	v_mfma_f32_16x16x32_bf16 v[36:39], v[140:143], v[198:201], v[36:39]
	v_mfma_f32_16x16x32_bf16 v[28:31], v[132:135], v[206:209], v[28:31]
	v_mfma_f32_16x16x32_bf16 v[20:23], v[140:143], v[206:209], v[20:23]
	v_mfma_f32_16x16x32_bf16 v[12:15], v[132:135], v[214:217], v[12:15]
	v_mfma_f32_16x16x32_bf16 v[4:7], v[140:143], v[214:217], v[4:7]
	v_mfma_f32_16x16x32_bf16 v[56:59], v[160:163], v[184:187], v[56:59]
	v_mfma_f32_16x16x32_bf16 v[48:51], v[176:179], v[184:187], v[48:51]
	v_mfma_f32_16x16x32_bf16 v[40:43], v[160:163], v[194:197], v[40:43]
	v_mfma_f32_16x16x32_bf16 v[32:35], v[176:179], v[194:197], v[32:35]
	v_mfma_f32_16x16x32_bf16 v[24:27], v[160:163], v[202:205], v[24:27]
	v_mfma_f32_16x16x32_bf16 v[16:19], v[176:179], v[202:205], v[16:19]
	v_mfma_f32_16x16x32_bf16 v[8:11], v[160:163], v[210:213], v[8:11]
	v_mfma_f32_16x16x32_bf16 v[0:3], v[176:179], v[210:213], v[0:3]
	v_mfma_f32_16x16x32_bf16 v[56:59], v[172:175], v[190:193], v[56:59]
	v_mfma_f32_16x16x32_bf16 v[48:51], v[180:183], v[190:193], v[48:51]
	v_mfma_f32_16x16x32_bf16 v[40:43], v[172:175], v[198:201], v[40:43]
	v_mfma_f32_16x16x32_bf16 v[32:35], v[180:183], v[198:201], v[32:35]
	v_mfma_f32_16x16x32_bf16 v[24:27], v[172:175], v[206:209], v[24:27]
	v_mfma_f32_16x16x32_bf16 v[16:19], v[180:183], v[206:209], v[16:19]
	v_mfma_f32_16x16x32_bf16 v[8:11], v[172:175], v[214:217], v[8:11]
	v_mfma_f32_16x16x32_bf16 v[0:3], v[180:183], v[214:217], v[0:3]
	s_barrier
	s_add_i32 s64, s64, 2
	s_add_u32 s44, s44, 0x100
	s_addc_u32 s45, s45, 0
	s_add_u32 s62, s62, 0x100
	s_addc_u32 s63, s63, 0
	s_cmp_gt_u32 s64, 5
	s_cbranch_scc0 .LBB0_1029
	s_and_b64 vcc, exec, s[14:15]
	s_cbranch_vccz .LBB0_1032
	s_barrier

.LBB0_1105:
	ds_read_b128 v[128:131], v181
	ds_read_b128 v[132:135], v181 offset:1024
	ds_read_b128 v[136:139], v181 offset:2048
	ds_read_b128 v[140:143], v181 offset:3072
	ds_read_b128 v[144:147], v182
	ds_read_b128 v[148:151], v182 offset:1024
	ds_read_b128 v[168:171], v182 offset:2048
	ds_read_b128 v[172:175], v182 offset:3072
	s_add_u32 s28, s42, 0xfffe0080
	s_addc_u32 s29, s43, -1
	s_cmp_eq_u32 s58, 4
	s_cselect_b32 s47, s19, s29
	s_cselect_b32 s46, s54, s28
	s_cselect_b32 s45, s17, s57
	s_cselect_b32 s44, s55, s56
	v_lshl_add_u64 v[176:177], s[42:43], 0, v[160:161]
	s_add_i32 m0, s27, 0xc000
	ds_read_b128 v[184:187], v183
	ds_read_b128 v[190:193], v183 offset:1024
	ds_read_b128 v[194:197], v183 offset:2048
	ds_read_b128 v[198:201], v183 offset:3072
	ds_read_b128 v[202:205], v183 offset:4096
	ds_read_b128 v[206:209], v183 offset:5120
	ds_read_b128 v[210:213], v183 offset:6144
	ds_read_b128 v[214:217], v183 offset:7168
	global_load_lds_dwordx4 v[176:177], off
	v_lshl_add_u64 v[176:177], s[42:43], 0, v[162:163]
	s_add_i32 m0, s27, 0xe000
	s_nop 0
	global_load_lds_dwordx4 v[176:177], off
	s_waitcnt vmcnt(8)
	s_waitcnt lgkmcnt(0)
	s_barrier
	s_waitcnt lgkmcnt(0)
	v_mfma_f32_16x16x32_bf16 v[124:127], v[128:131], v[184:187], v[124:127]
	v_mfma_f32_16x16x32_bf16 v[120:123], v[136:139], v[184:187], v[120:123]
	v_mfma_f32_16x16x32_bf16 v[108:111], v[128:131], v[194:197], v[108:111]
	v_mfma_f32_16x16x32_bf16 v[104:107], v[136:139], v[194:197], v[104:107]
	v_mfma_f32_16x16x32_bf16 v[92:95], v[128:131], v[202:205], v[92:95]
	v_mfma_f32_16x16x32_bf16 v[88:91], v[136:139], v[202:205], v[88:91]
	v_mfma_f32_16x16x32_bf16 v[76:79], v[128:131], v[210:213], v[76:79]
	v_mfma_f32_16x16x32_bf16 v[72:75], v[136:139], v[210:213], v[72:75]
	v_mfma_f32_16x16x32_bf16 v[124:127], v[132:135], v[190:193], v[124:127]
	v_mfma_f32_16x16x32_bf16 v[120:123], v[140:143], v[190:193], v[120:123]
	v_mfma_f32_16x16x32_bf16 v[108:111], v[132:135], v[198:201], v[108:111]
	v_mfma_f32_16x16x32_bf16 v[104:107], v[140:143], v[198:201], v[104:107]
	v_mfma_f32_16x16x32_bf16 v[92:95], v[132:135], v[206:209], v[92:95]
	v_mfma_f32_16x16x32_bf16 v[88:91], v[140:143], v[206:209], v[88:91]
	v_mfma_f32_16x16x32_bf16 v[76:79], v[132:135], v[214:217], v[76:79]
	v_mfma_f32_16x16x32_bf16 v[72:75], v[140:143], v[214:217], v[72:75]
	v_mfma_f32_16x16x32_bf16 v[116:119], v[144:147], v[184:187], v[116:119]
	v_mfma_f32_16x16x32_bf16 v[112:115], v[168:171], v[184:187], v[112:115]
	v_mfma_f32_16x16x32_bf16 v[100:103], v[144:147], v[194:197], v[100:103]
	v_mfma_f32_16x16x32_bf16 v[96:99], v[168:171], v[194:197], v[96:99]
	v_mfma_f32_16x16x32_bf16 v[84:87], v[144:147], v[202:205], v[84:87]
	v_mfma_f32_16x16x32_bf16 v[80:83], v[168:171], v[202:205], v[80:83]
	v_mfma_f32_16x16x32_bf16 v[68:71], v[144:147], v[210:213], v[68:71]
	v_mfma_f32_16x16x32_bf16 v[64:67], v[168:171], v[210:213], v[64:67]
	v_mfma_f32_16x16x32_bf16 v[116:119], v[148:151], v[190:193], v[116:119]
	v_mfma_f32_16x16x32_bf16 v[112:115], v[172:175], v[190:193], v[112:115]
	v_mfma_f32_16x16x32_bf16 v[100:103], v[148:151], v[198:201], v[100:103]
	v_mfma_f32_16x16x32_bf16 v[96:99], v[172:175], v[198:201], v[96:99]
	v_mfma_f32_16x16x32_bf16 v[84:87], v[148:151], v[206:209], v[84:87]
	v_mfma_f32_16x16x32_bf16 v[80:83], v[172:175], v[206:209], v[80:83]
	v_mfma_f32_16x16x32_bf16 v[68:71], v[148:151], v[214:217], v[68:71]
	v_mfma_f32_16x16x32_bf16 v[64:67], v[172:175], v[214:217], v[64:67]
	s_barrier
	s_add_i32 s28, s51, s13
	v_lshl_add_u64 v[176:177], s[44:45], 0, v[154:155]
	s_mov_b32 m0, s28
	ds_read_b128 v[184:187], v183 offset:16384
	ds_read_b128 v[190:193], v183 offset:17408
	ds_read_b128 v[194:197], v183 offset:18432
	ds_read_b128 v[198:201], v183 offset:19456
	ds_read_b128 v[202:205], v183 offset:20480
	ds_read_b128 v[206:209], v183 offset:21504
	ds_read_b128 v[210:213], v183 offset:22528
	ds_read_b128 v[214:217], v183 offset:23552
	global_load_lds_dwordx4 v[176:177], off
	s_add_i32 m0, s28, 0x2000
	s_add_u32 s28, s44, 0x20000
	v_lshl_add_u64 v[218:219], s[44:45], 0, v[158:159]
	s_addc_u32 s29, s45, 0
	s_add_i32 s33, s52, s13
	global_load_lds_dwordx4 v[218:219], off
	v_lshl_add_u64 v[220:221], s[28:29], 0, v[154:155]
	s_mov_b32 m0, s33
	v_lshl_add_u64 v[222:223], s[46:47], 0, v[156:157]
	global_load_lds_dwordx4 v[220:221], off
	v_lshl_add_u64 v[220:221], s[28:29], 0, v[158:159]
	s_add_i32 m0, s33, 0x2000
	s_nop 0
	global_load_lds_dwordx4 v[220:221], off
	v_lshl_add_u64 v[220:221], s[46:47], 0, v[152:153]
	s_mov_b32 m0, s27
	s_nop 0
	global_load_lds_dwordx4 v[220:221], off
	s_mov_b32 m0, s34
	s_nop 0
	global_load_lds_dwordx4 v[222:223], off
	s_waitcnt vmcnt(8)
	s_waitcnt lgkmcnt(0)
	s_nop 0
	s_barrier
	s_waitcnt lgkmcnt(0)
	v_mfma_f32_16x16x32_bf16 v[60:63], v[128:131], v[184:187], v[60:63]
	v_mfma_f32_16x16x32_bf16 v[56:59], v[136:139], v[184:187], v[56:59]
	v_mfma_f32_16x16x32_bf16 v[44:47], v[128:131], v[194:197], v[44:47]
	v_mfma_f32_16x16x32_bf16 v[40:43], v[136:139], v[194:197], v[40:43]
	v_mfma_f32_16x16x32_bf16 v[28:31], v[128:131], v[202:205], v[28:31]
	v_mfma_f32_16x16x32_bf16 v[24:27], v[136:139], v[202:205], v[24:27]
	v_mfma_f32_16x16x32_bf16 v[12:15], v[128:131], v[210:213], v[12:15]
	v_mfma_f32_16x16x32_bf16 v[8:11], v[136:139], v[210:213], v[8:11]
	v_mfma_f32_16x16x32_bf16 v[60:63], v[132:135], v[190:193], v[60:63]
	v_mfma_f32_16x16x32_bf16 v[56:59], v[140:143], v[190:193], v[56:59]
	v_mfma_f32_16x16x32_bf16 v[44:47], v[132:135], v[198:201], v[44:47]
	v_mfma_f32_16x16x32_bf16 v[40:43], v[140:143], v[198:201], v[40:43]
	v_mfma_f32_16x16x32_bf16 v[28:31], v[132:135], v[206:209], v[28:31]
	v_mfma_f32_16x16x32_bf16 v[24:27], v[140:143], v[206:209], v[24:27]
	v_mfma_f32_16x16x32_bf16 v[12:15], v[132:135], v[214:217], v[12:15]
	v_mfma_f32_16x16x32_bf16 v[8:11], v[140:143], v[214:217], v[8:11]
	v_mfma_f32_16x16x32_bf16 v[52:55], v[144:147], v[184:187], v[52:55]
	v_mfma_f32_16x16x32_bf16 v[48:51], v[168:171], v[184:187], v[48:51]
	v_mfma_f32_16x16x32_bf16 v[36:39], v[144:147], v[194:197], v[36:39]
	v_mfma_f32_16x16x32_bf16 v[32:35], v[168:171], v[194:197], v[32:35]
	v_mfma_f32_16x16x32_bf16 v[20:23], v[144:147], v[202:205], v[20:23]
	v_mfma_f32_16x16x32_bf16 v[16:19], v[168:171], v[202:205], v[16:19]
	v_mfma_f32_16x16x32_bf16 v[4:7], v[144:147], v[210:213], v[4:7]
	v_mfma_f32_16x16x32_bf16 v[0:3], v[168:171], v[210:213], v[0:3]
	v_mfma_f32_16x16x32_bf16 v[52:55], v[148:151], v[190:193], v[52:55]
	v_mfma_f32_16x16x32_bf16 v[48:51], v[172:175], v[190:193], v[48:51]
	v_mfma_f32_16x16x32_bf16 v[36:39], v[148:151], v[198:201], v[36:39]
	v_mfma_f32_16x16x32_bf16 v[32:35], v[172:175], v[198:201], v[32:35]
	v_mfma_f32_16x16x32_bf16 v[20:23], v[148:151], v[206:209], v[20:23]
	v_mfma_f32_16x16x32_bf16 v[16:19], v[172:175], v[206:209], v[16:19]
	v_mfma_f32_16x16x32_bf16 v[4:7], v[148:151], v[214:217], v[4:7]
	v_mfma_f32_16x16x32_bf16 v[0:3], v[172:175], v[214:217], v[0:3]
	s_barrier
	s_add_i32 s33, 0, 0x18000
	s_add_i32 s59, 0, 0x1c000
	v_add_u32_e32 v140, s33, v179
	v_add_u32_e32 v172, s59, v179
	ds_read_b128 v[128:131], v140
	ds_read_b128 v[132:135], v140 offset:1024
	ds_read_b128 v[136:139], v140 offset:2048
	ds_read_b128 v[140:143], v140 offset:3072
	ds_read_b128 v[144:147], v172
	ds_read_b128 v[148:151], v172 offset:1024
	ds_read_b128 v[168:171], v172 offset:2048
	ds_read_b128 v[172:175], v172 offset:3072
	s_add_u32 s28, s46, 0x20000
	s_addc_u32 s29, s47, 0
	s_mov_b32 m0, s35
	v_lshl_add_u64 v[224:225], s[28:29], 0, v[152:153]
	ds_read_b128 v[184:187], v183 offset:32768
	ds_read_b128 v[190:193], v183 offset:33792
	ds_read_b128 v[194:197], v183 offset:34816
	ds_read_b128 v[198:201], v183 offset:35840
	ds_read_b128 v[202:205], v183 offset:36864
	ds_read_b128 v[206:209], v183 offset:37888
	ds_read_b128 v[210:213], v183 offset:38912
	ds_read_b128 v[214:217], v183 offset:39936
	global_load_lds_dwordx4 v[224:225], off
	v_lshl_add_u64 v[224:225], s[28:29], 0, v[156:157]
	s_mov_b32 m0, s41
	s_nop 0
	global_load_lds_dwordx4 v[224:225], off
	s_waitcnt vmcnt(8)
	s_waitcnt lgkmcnt(0)
	s_nop 0
	s_barrier
	s_waitcnt lgkmcnt(0)
	v_mfma_f32_16x16x32_bf16 v[124:127], v[128:131], v[184:187], v[124:127]
	v_mfma_f32_16x16x32_bf16 v[120:123], v[136:139], v[184:187], v[120:123]
	v_mfma_f32_16x16x32_bf16 v[108:111], v[128:131], v[194:197], v[108:111]
	v_mfma_f32_16x16x32_bf16 v[104:107], v[136:139], v[194:197], v[104:107]
	v_mfma_f32_16x16x32_bf16 v[92:95], v[128:131], v[202:205], v[92:95]
	v_mfma_f32_16x16x32_bf16 v[88:91], v[136:139], v[202:205], v[88:91]
	v_mfma_f32_16x16x32_bf16 v[76:79], v[128:131], v[210:213], v[76:79]
	v_mfma_f32_16x16x32_bf16 v[72:75], v[136:139], v[210:213], v[72:75]
	v_mfma_f32_16x16x32_bf16 v[124:127], v[132:135], v[190:193], v[124:127]
	v_mfma_f32_16x16x32_bf16 v[120:123], v[140:143], v[190:193], v[120:123]
	v_mfma_f32_16x16x32_bf16 v[108:111], v[132:135], v[198:201], v[108:111]
	v_mfma_f32_16x16x32_bf16 v[104:107], v[140:143], v[198:201], v[104:107]
	v_mfma_f32_16x16x32_bf16 v[92:95], v[132:135], v[206:209], v[92:95]
	v_mfma_f32_16x16x32_bf16 v[88:91], v[140:143], v[206:209], v[88:91]
	v_mfma_f32_16x16x32_bf16 v[76:79], v[132:135], v[214:217], v[76:79]
	v_mfma_f32_16x16x32_bf16 v[72:75], v[140:143], v[214:217], v[72:75]
	v_mfma_f32_16x16x32_bf16 v[116:119], v[144:147], v[184:187], v[116:119]
	v_mfma_f32_16x16x32_bf16 v[112:115], v[168:171], v[184:187], v[112:115]
	v_mfma_f32_16x16x32_bf16 v[100:103], v[144:147], v[194:197], v[100:103]
	v_mfma_f32_16x16x32_bf16 v[96:99], v[168:171], v[194:197], v[96:99]
	v_mfma_f32_16x16x32_bf16 v[84:87], v[144:147], v[202:205], v[84:87]
	v_mfma_f32_16x16x32_bf16 v[80:83], v[168:171], v[202:205], v[80:83]
	v_mfma_f32_16x16x32_bf16 v[68:71], v[144:147], v[210:213], v[68:71]
	v_mfma_f32_16x16x32_bf16 v[64:67], v[168:171], v[210:213], v[64:67]
	v_mfma_f32_16x16x32_bf16 v[116:119], v[148:151], v[190:193], v[116:119]
	v_mfma_f32_16x16x32_bf16 v[112:115], v[172:175], v[190:193], v[112:115]
	v_mfma_f32_16x16x32_bf16 v[100:103], v[148:151], v[198:201], v[100:103]
	v_mfma_f32_16x16x32_bf16 v[96:99], v[172:175], v[198:201], v[96:99]
	v_mfma_f32_16x16x32_bf16 v[84:87], v[148:151], v[206:209], v[84:87]
	v_mfma_f32_16x16x32_bf16 v[80:83], v[172:175], v[206:209], v[80:83]
	v_mfma_f32_16x16x32_bf16 v[68:71], v[148:151], v[214:217], v[68:71]
	v_mfma_f32_16x16x32_bf16 v[64:67], v[172:175], v[214:217], v[64:67]
	s_barrier
	s_add_i32 s28, s33, s13
	v_lshl_add_u64 v[176:177], v[176:177], 0, s[10:11]
	s_mov_b32 m0, s28
	ds_read_b128 v[184:187], v183 offset:49152
	ds_read_b128 v[190:193], v183 offset:50176
	ds_read_b128 v[194:197], v183 offset:51200
	ds_read_b128 v[198:201], v183 offset:52224
	ds_read_b128 v[202:205], v183 offset:53248
	ds_read_b128 v[206:209], v183 offset:54272
	ds_read_b128 v[210:213], v183 offset:55296
	ds_read_b128 v[214:217], v183 offset:56320
	global_load_lds_dwordx4 v[176:177], off
	s_add_i32 m0, s28, 0x2000
	s_add_u32 s28, s44, 0x20080
	v_lshl_add_u64 v[176:177], v[218:219], 0, s[10:11]
	s_addc_u32 s29, s45, 0
	s_add_i32 s33, s59, s13
	global_load_lds_dwordx4 v[176:177], off
	v_lshl_add_u64 v[176:177], s[28:29], 0, v[154:155]
	s_mov_b32 m0, s33
	s_nop 0
	global_load_lds_dwordx4 v[176:177], off
	v_lshl_add_u64 v[176:177], s[28:29], 0, v[158:159]
	s_add_i32 m0, s33, 0x2000
	s_nop 0
	global_load_lds_dwordx4 v[176:177], off
	v_lshl_add_u64 v[176:177], v[220:221], 0, s[10:11]
	s_mov_b32 m0, s49
	s_nop 0
	global_load_lds_dwordx4 v[176:177], off
	v_lshl_add_u64 v[176:177], v[222:223], 0, s[10:11]
	s_mov_b32 m0, s50
	s_nop 0
	global_load_lds_dwordx4 v[176:177], off
	s_waitcnt vmcnt(8)
	s_waitcnt lgkmcnt(0)
	s_barrier
	s_waitcnt lgkmcnt(0)
	v_mfma_f32_16x16x32_bf16 v[60:63], v[128:131], v[184:187], v[60:63]
	v_mfma_f32_16x16x32_bf16 v[56:59], v[136:139], v[184:187], v[56:59]
	v_mfma_f32_16x16x32_bf16 v[44:47], v[128:131], v[194:197], v[44:47]
	v_mfma_f32_16x16x32_bf16 v[40:43], v[136:139], v[194:197], v[40:43]
	v_mfma_f32_16x16x32_bf16 v[28:31], v[128:131], v[202:205], v[28:31]
	v_mfma_f32_16x16x32_bf16 v[24:27], v[136:139], v[202:205], v[24:27]
	v_mfma_f32_16x16x32_bf16 v[12:15], v[128:131], v[210:213], v[12:15]
	v_mfma_f32_16x16x32_bf16 v[8:11], v[136:139], v[210:213], v[8:11]
	v_mfma_f32_16x16x32_bf16 v[60:63], v[132:135], v[190:193], v[60:63]
	v_mfma_f32_16x16x32_bf16 v[56:59], v[140:143], v[190:193], v[56:59]
	v_mfma_f32_16x16x32_bf16 v[44:47], v[132:135], v[198:201], v[44:47]
	v_mfma_f32_16x16x32_bf16 v[40:43], v[140:143], v[198:201], v[40:43]
	v_mfma_f32_16x16x32_bf16 v[28:31], v[132:135], v[206:209], v[28:31]
	v_mfma_f32_16x16x32_bf16 v[24:27], v[140:143], v[206:209], v[24:27]
	v_mfma_f32_16x16x32_bf16 v[12:15], v[132:135], v[214:217], v[12:15]
	v_mfma_f32_16x16x32_bf16 v[8:11], v[140:143], v[214:217], v[8:11]
	v_mfma_f32_16x16x32_bf16 v[52:55], v[144:147], v[184:187], v[52:55]
	v_mfma_f32_16x16x32_bf16 v[48:51], v[168:171], v[184:187], v[48:51]
	v_mfma_f32_16x16x32_bf16 v[36:39], v[144:147], v[194:197], v[36:39]
	v_mfma_f32_16x16x32_bf16 v[32:35], v[168:171], v[194:197], v[32:35]
	v_mfma_f32_16x16x32_bf16 v[20:23], v[144:147], v[202:205], v[20:23]
	v_mfma_f32_16x16x32_bf16 v[16:19], v[168:171], v[202:205], v[16:19]
	v_mfma_f32_16x16x32_bf16 v[4:7], v[144:147], v[210:213], v[4:7]
	v_mfma_f32_16x16x32_bf16 v[0:3], v[168:171], v[210:213], v[0:3]
	v_mfma_f32_16x16x32_bf16 v[52:55], v[148:151], v[190:193], v[52:55]
	v_mfma_f32_16x16x32_bf16 v[48:51], v[172:175], v[190:193], v[48:51]
	v_mfma_f32_16x16x32_bf16 v[36:39], v[148:151], v[198:201], v[36:39]
	v_mfma_f32_16x16x32_bf16 v[32:35], v[172:175], v[198:201], v[32:35]
	v_mfma_f32_16x16x32_bf16 v[20:23], v[148:151], v[206:209], v[20:23]
	v_mfma_f32_16x16x32_bf16 v[16:19], v[172:175], v[206:209], v[16:19]
	v_mfma_f32_16x16x32_bf16 v[4:7], v[148:151], v[214:217], v[4:7]
	v_mfma_f32_16x16x32_bf16 v[0:3], v[172:175], v[214:217], v[0:3]
	s_barrier
	s_add_i32 s58, s58, 2
	s_add_u32 s42, s42, 0x100
	s_addc_u32 s43, s43, 0
	s_add_u32 s56, s56, 0x100
	s_addc_u32 s57, s57, 0
	s_cmp_gt_u32 s58, 5
	s_cbranch_scc0 .LBB0_1105
	s_and_b64 vcc, exec, s[14:15]
	s_cbranch_vccz .LBB0_1108
	s_barrier

.LBB0_1181:
	ds_read_b128 v[152:155], v149
	ds_read_b128 v[156:159], v149 offset:1024
	ds_read_b128 v[160:163], v149 offset:2048
	ds_read_b128 v[164:167], v149 offset:3072
	ds_read_b128 v[168:171], v150
	ds_read_b128 v[172:175], v150 offset:1024
	ds_read_b128 v[176:179], v150 offset:2048
	ds_read_b128 v[180:183], v150 offset:3072
	s_add_u32 s28, s48, 0xfffc0080
	s_addc_u32 s29, s49, -1
	s_cmp_eq_u32 s76, 12
	s_cselect_b32 s53, s41, s29
	s_cselect_b32 s52, s64, s28
	s_cselect_b32 s51, s39, s67
	s_cselect_b32 s50, s65, s66
	v_lshl_add_u64 v[144:145], s[48:49], 0, v[136:137]
	s_add_i32 m0, s27, 0xc000
	ds_read_b128 v[184:187], v151
	ds_read_b128 v[190:193], v151 offset:1024
	ds_read_b128 v[194:197], v151 offset:2048
	ds_read_b128 v[198:201], v151 offset:3072
	ds_read_b128 v[202:205], v151 offset:4096
	ds_read_b128 v[206:209], v151 offset:5120
	ds_read_b128 v[210:213], v151 offset:6144
	ds_read_b128 v[214:217], v151 offset:7168
	global_load_lds_dwordx4 v[144:145], off
	v_lshl_add_u64 v[144:145], s[48:49], 0, v[138:139]
	s_add_i32 m0, s27, 0xe000
	s_nop 0
	global_load_lds_dwordx4 v[144:145], off
	s_waitcnt vmcnt(8)
	s_waitcnt lgkmcnt(0)
	s_barrier
	s_waitcnt lgkmcnt(0)
	v_mfma_f32_16x16x32_bf16 v[124:127], v[152:155], v[184:187], v[124:127]
	v_mfma_f32_16x16x32_bf16 v[120:123], v[160:163], v[184:187], v[120:123]
	v_mfma_f32_16x16x32_bf16 v[116:119], v[152:155], v[194:197], v[116:119]
	v_mfma_f32_16x16x32_bf16 v[108:111], v[160:163], v[194:197], v[108:111]
	v_mfma_f32_16x16x32_bf16 v[100:103], v[152:155], v[202:205], v[100:103]
	v_mfma_f32_16x16x32_bf16 v[92:95], v[160:163], v[202:205], v[92:95]
	v_mfma_f32_16x16x32_bf16 v[84:87], v[152:155], v[210:213], v[84:87]
	v_mfma_f32_16x16x32_bf16 v[76:79], v[160:163], v[210:213], v[76:79]
	v_mfma_f32_16x16x32_bf16 v[124:127], v[156:159], v[190:193], v[124:127]
	v_mfma_f32_16x16x32_bf16 v[120:123], v[164:167], v[190:193], v[120:123]
	v_mfma_f32_16x16x32_bf16 v[116:119], v[156:159], v[198:201], v[116:119]
	v_mfma_f32_16x16x32_bf16 v[108:111], v[164:167], v[198:201], v[108:111]
	v_mfma_f32_16x16x32_bf16 v[100:103], v[156:159], v[206:209], v[100:103]
	v_mfma_f32_16x16x32_bf16 v[92:95], v[164:167], v[206:209], v[92:95]
	v_mfma_f32_16x16x32_bf16 v[84:87], v[156:159], v[214:217], v[84:87]
	v_mfma_f32_16x16x32_bf16 v[76:79], v[164:167], v[214:217], v[76:79]
	v_mfma_f32_16x16x32_bf16 v[112:115], v[168:171], v[184:187], v[112:115]
	v_mfma_f32_16x16x32_bf16 v[104:107], v[176:179], v[184:187], v[104:107]
	v_mfma_f32_16x16x32_bf16 v[96:99], v[168:171], v[194:197], v[96:99]
	v_mfma_f32_16x16x32_bf16 v[88:91], v[176:179], v[194:197], v[88:91]
	v_mfma_f32_16x16x32_bf16 v[80:83], v[168:171], v[202:205], v[80:83]
	v_mfma_f32_16x16x32_bf16 v[72:75], v[176:179], v[202:205], v[72:75]
	v_mfma_f32_16x16x32_bf16 v[68:71], v[168:171], v[210:213], v[68:71]
	v_mfma_f32_16x16x32_bf16 v[64:67], v[176:179], v[210:213], v[64:67]
	v_mfma_f32_16x16x32_bf16 v[112:115], v[172:175], v[190:193], v[112:115]
	v_mfma_f32_16x16x32_bf16 v[104:107], v[180:183], v[190:193], v[104:107]
	v_mfma_f32_16x16x32_bf16 v[96:99], v[172:175], v[198:201], v[96:99]
	v_mfma_f32_16x16x32_bf16 v[88:91], v[180:183], v[198:201], v[88:91]
	v_mfma_f32_16x16x32_bf16 v[80:83], v[172:175], v[206:209], v[80:83]
	v_mfma_f32_16x16x32_bf16 v[72:75], v[180:183], v[206:209], v[72:75]
	v_mfma_f32_16x16x32_bf16 v[68:71], v[172:175], v[214:217], v[68:71]
	v_mfma_f32_16x16x32_bf16 v[64:67], v[180:183], v[214:217], v[64:67]
	s_barrier
	s_add_i32 s28, s57, s13
	v_lshl_add_u64 v[144:145], s[50:51], 0, v[130:131]
	s_mov_b32 m0, s28
	ds_read_b128 v[184:187], v151 offset:16384
	ds_read_b128 v[190:193], v151 offset:17408
	ds_read_b128 v[194:197], v151 offset:18432
	ds_read_b128 v[198:201], v151 offset:19456
	ds_read_b128 v[202:205], v151 offset:20480
	ds_read_b128 v[206:209], v151 offset:21504
	ds_read_b128 v[210:213], v151 offset:22528
	ds_read_b128 v[214:217], v151 offset:23552
	global_load_lds_dwordx4 v[144:145], off
	s_add_i32 m0, s28, 0x2000
	s_add_u32 s28, s50, 0x40000
	v_lshl_add_u64 v[218:219], s[50:51], 0, v[134:135]
	s_addc_u32 s29, s51, 0
	s_add_i32 s33, s58, s13
	global_load_lds_dwordx4 v[218:219], off
	v_lshl_add_u64 v[220:221], s[28:29], 0, v[130:131]
	s_mov_b32 m0, s33
	v_lshl_add_u64 v[222:223], s[52:53], 0, v[132:133]
	global_load_lds_dwordx4 v[220:221], off
	v_lshl_add_u64 v[220:221], s[28:29], 0, v[134:135]
	s_add_i32 m0, s33, 0x2000
	s_nop 0
	global_load_lds_dwordx4 v[220:221], off
	v_lshl_add_u64 v[220:221], s[52:53], 0, v[128:129]
	s_mov_b32 m0, s27
	s_nop 0
	global_load_lds_dwordx4 v[220:221], off
	s_mov_b32 m0, s34
	s_nop 0
	global_load_lds_dwordx4 v[222:223], off
	s_waitcnt vmcnt(8)
	s_waitcnt lgkmcnt(0)
	s_nop 0
	s_barrier
	s_waitcnt lgkmcnt(0)
	v_mfma_f32_16x16x32_bf16 v[60:63], v[152:155], v[184:187], v[60:63]
	v_mfma_f32_16x16x32_bf16 v[56:59], v[160:163], v[184:187], v[56:59]
	v_mfma_f32_16x16x32_bf16 v[52:55], v[152:155], v[194:197], v[52:55]
	v_mfma_f32_16x16x32_bf16 v[44:47], v[160:163], v[194:197], v[44:47]
	v_mfma_f32_16x16x32_bf16 v[36:39], v[152:155], v[202:205], v[36:39]
	v_mfma_f32_16x16x32_bf16 v[28:31], v[160:163], v[202:205], v[28:31]
	v_mfma_f32_16x16x32_bf16 v[20:23], v[152:155], v[210:213], v[20:23]
	v_mfma_f32_16x16x32_bf16 v[12:15], v[160:163], v[210:213], v[12:15]
	v_mfma_f32_16x16x32_bf16 v[60:63], v[156:159], v[190:193], v[60:63]
	v_mfma_f32_16x16x32_bf16 v[56:59], v[164:167], v[190:193], v[56:59]
	v_mfma_f32_16x16x32_bf16 v[52:55], v[156:159], v[198:201], v[52:55]
	v_mfma_f32_16x16x32_bf16 v[44:47], v[164:167], v[198:201], v[44:47]
	v_mfma_f32_16x16x32_bf16 v[36:39], v[156:159], v[206:209], v[36:39]
	v_mfma_f32_16x16x32_bf16 v[28:31], v[164:167], v[206:209], v[28:31]
	v_mfma_f32_16x16x32_bf16 v[20:23], v[156:159], v[214:217], v[20:23]
	v_mfma_f32_16x16x32_bf16 v[12:15], v[164:167], v[214:217], v[12:15]
	v_mfma_f32_16x16x32_bf16 v[48:51], v[168:171], v[184:187], v[48:51]
	v_mfma_f32_16x16x32_bf16 v[40:43], v[176:179], v[184:187], v[40:43]
	v_mfma_f32_16x16x32_bf16 v[32:35], v[168:171], v[194:197], v[32:35]
	v_mfma_f32_16x16x32_bf16 v[24:27], v[176:179], v[194:197], v[24:27]
	v_mfma_f32_16x16x32_bf16 v[16:19], v[168:171], v[202:205], v[16:19]
	v_mfma_f32_16x16x32_bf16 v[8:11], v[176:179], v[202:205], v[8:11]
	v_mfma_f32_16x16x32_bf16 v[4:7], v[168:171], v[210:213], v[4:7]
	v_mfma_f32_16x16x32_bf16 v[0:3], v[176:179], v[210:213], v[0:3]
	v_mfma_f32_16x16x32_bf16 v[48:51], v[172:175], v[190:193], v[48:51]
	v_mfma_f32_16x16x32_bf16 v[40:43], v[180:183], v[190:193], v[40:43]
	v_mfma_f32_16x16x32_bf16 v[32:35], v[172:175], v[198:201], v[32:35]
	v_mfma_f32_16x16x32_bf16 v[24:27], v[180:183], v[198:201], v[24:27]
	v_mfma_f32_16x16x32_bf16 v[16:19], v[172:175], v[206:209], v[16:19]
	v_mfma_f32_16x16x32_bf16 v[8:11], v[180:183], v[206:209], v[8:11]
	v_mfma_f32_16x16x32_bf16 v[4:7], v[172:175], v[214:217], v[4:7]
	v_mfma_f32_16x16x32_bf16 v[0:3], v[180:183], v[214:217], v[0:3]
	s_barrier
	s_add_i32 s33, 0, 0x18000
	s_add_i32 s77, 0, 0x1c000
	v_add_u32_e32 v164, s33, v147
	v_add_u32_e32 v180, s77, v147
	ds_read_b128 v[152:155], v164
	ds_read_b128 v[156:159], v164 offset:1024
	ds_read_b128 v[160:163], v164 offset:2048
	ds_read_b128 v[164:167], v164 offset:3072
	ds_read_b128 v[168:171], v180
	ds_read_b128 v[172:175], v180 offset:1024
	ds_read_b128 v[176:179], v180 offset:2048
	ds_read_b128 v[180:183], v180 offset:3072
	s_add_u32 s28, s52, 0x40000
	s_addc_u32 s29, s53, 0
	s_mov_b32 m0, s35
	v_lshl_add_u64 v[224:225], s[28:29], 0, v[128:129]
	ds_read_b128 v[184:187], v151 offset:32768
	ds_read_b128 v[190:193], v151 offset:33792
	ds_read_b128 v[194:197], v151 offset:34816
	ds_read_b128 v[198:201], v151 offset:35840
	ds_read_b128 v[202:205], v151 offset:36864
	ds_read_b128 v[206:209], v151 offset:37888
	ds_read_b128 v[210:213], v151 offset:38912
	ds_read_b128 v[214:217], v151 offset:39936
	global_load_lds_dwordx4 v[224:225], off
	v_lshl_add_u64 v[224:225], s[28:29], 0, v[132:133]
	s_mov_b32 m0, s47
	s_nop 0
	global_load_lds_dwordx4 v[224:225], off
	s_waitcnt vmcnt(8)
	s_waitcnt lgkmcnt(0)
	s_nop 0
	s_barrier
	s_waitcnt lgkmcnt(0)
	v_mfma_f32_16x16x32_bf16 v[124:127], v[152:155], v[184:187], v[124:127]
	v_mfma_f32_16x16x32_bf16 v[120:123], v[160:163], v[184:187], v[120:123]
	v_mfma_f32_16x16x32_bf16 v[116:119], v[152:155], v[194:197], v[116:119]
	v_mfma_f32_16x16x32_bf16 v[108:111], v[160:163], v[194:197], v[108:111]
	v_mfma_f32_16x16x32_bf16 v[100:103], v[152:155], v[202:205], v[100:103]
	v_mfma_f32_16x16x32_bf16 v[92:95], v[160:163], v[202:205], v[92:95]
	v_mfma_f32_16x16x32_bf16 v[84:87], v[152:155], v[210:213], v[84:87]
	v_mfma_f32_16x16x32_bf16 v[76:79], v[160:163], v[210:213], v[76:79]
	v_mfma_f32_16x16x32_bf16 v[124:127], v[156:159], v[190:193], v[124:127]
	v_mfma_f32_16x16x32_bf16 v[120:123], v[164:167], v[190:193], v[120:123]
	v_mfma_f32_16x16x32_bf16 v[116:119], v[156:159], v[198:201], v[116:119]
	v_mfma_f32_16x16x32_bf16 v[108:111], v[164:167], v[198:201], v[108:111]
	v_mfma_f32_16x16x32_bf16 v[100:103], v[156:159], v[206:209], v[100:103]
	v_mfma_f32_16x16x32_bf16 v[92:95], v[164:167], v[206:209], v[92:95]
	v_mfma_f32_16x16x32_bf16 v[84:87], v[156:159], v[214:217], v[84:87]
	v_mfma_f32_16x16x32_bf16 v[76:79], v[164:167], v[214:217], v[76:79]
	v_mfma_f32_16x16x32_bf16 v[112:115], v[168:171], v[184:187], v[112:115]
	v_mfma_f32_16x16x32_bf16 v[104:107], v[176:179], v[184:187], v[104:107]
	v_mfma_f32_16x16x32_bf16 v[96:99], v[168:171], v[194:197], v[96:99]
	v_mfma_f32_16x16x32_bf16 v[88:91], v[176:179], v[194:197], v[88:91]
	v_mfma_f32_16x16x32_bf16 v[80:83], v[168:171], v[202:205], v[80:83]
	v_mfma_f32_16x16x32_bf16 v[72:75], v[176:179], v[202:205], v[72:75]
	v_mfma_f32_16x16x32_bf16 v[68:71], v[168:171], v[210:213], v[68:71]
	v_mfma_f32_16x16x32_bf16 v[64:67], v[176:179], v[210:213], v[64:67]
	v_mfma_f32_16x16x32_bf16 v[112:115], v[172:175], v[190:193], v[112:115]
	v_mfma_f32_16x16x32_bf16 v[104:107], v[180:183], v[190:193], v[104:107]
	v_mfma_f32_16x16x32_bf16 v[96:99], v[172:175], v[198:201], v[96:99]
	v_mfma_f32_16x16x32_bf16 v[88:91], v[180:183], v[198:201], v[88:91]
	v_mfma_f32_16x16x32_bf16 v[80:83], v[172:175], v[206:209], v[80:83]
	v_mfma_f32_16x16x32_bf16 v[72:75], v[180:183], v[206:209], v[72:75]
	v_mfma_f32_16x16x32_bf16 v[68:71], v[172:175], v[214:217], v[68:71]
	v_mfma_f32_16x16x32_bf16 v[64:67], v[180:183], v[214:217], v[64:67]
	s_barrier
	s_add_i32 s28, s33, s13
	v_lshl_add_u64 v[144:145], v[144:145], 0, s[10:11]
	s_mov_b32 m0, s28
	ds_read_b128 v[184:187], v151 offset:49152
	ds_read_b128 v[190:193], v151 offset:50176
	ds_read_b128 v[194:197], v151 offset:51200
	ds_read_b128 v[198:201], v151 offset:52224
	ds_read_b128 v[202:205], v151 offset:53248
	ds_read_b128 v[206:209], v151 offset:54272
	ds_read_b128 v[210:213], v151 offset:55296
	ds_read_b128 v[214:217], v151 offset:56320
	global_load_lds_dwordx4 v[144:145], off
	s_add_i32 m0, s28, 0x2000
	s_add_u32 s28, s50, 0x40080
	v_lshl_add_u64 v[144:145], v[218:219], 0, s[10:11]
	s_addc_u32 s29, s51, 0
	s_add_i32 s33, s77, s13
	global_load_lds_dwordx4 v[144:145], off
	v_lshl_add_u64 v[144:145], s[28:29], 0, v[130:131]
	s_mov_b32 m0, s33
	s_nop 0
	global_load_lds_dwordx4 v[144:145], off
	v_lshl_add_u64 v[144:145], s[28:29], 0, v[134:135]
	s_add_i32 m0, s33, 0x2000
	s_nop 0
	global_load_lds_dwordx4 v[144:145], off
	v_lshl_add_u64 v[144:145], v[220:221], 0, s[10:11]
	s_mov_b32 m0, s55
	s_nop 0
	global_load_lds_dwordx4 v[144:145], off
	v_lshl_add_u64 v[144:145], v[222:223], 0, s[10:11]
	s_mov_b32 m0, s56
	s_nop 0
	global_load_lds_dwordx4 v[144:145], off
	s_waitcnt vmcnt(8)
	s_waitcnt lgkmcnt(0)
	s_barrier
	s_waitcnt lgkmcnt(0)
	v_mfma_f32_16x16x32_bf16 v[60:63], v[152:155], v[184:187], v[60:63]
	v_mfma_f32_16x16x32_bf16 v[56:59], v[160:163], v[184:187], v[56:59]
	v_mfma_f32_16x16x32_bf16 v[52:55], v[152:155], v[194:197], v[52:55]
	v_mfma_f32_16x16x32_bf16 v[44:47], v[160:163], v[194:197], v[44:47]
	v_mfma_f32_16x16x32_bf16 v[36:39], v[152:155], v[202:205], v[36:39]
	v_mfma_f32_16x16x32_bf16 v[28:31], v[160:163], v[202:205], v[28:31]
	v_mfma_f32_16x16x32_bf16 v[20:23], v[152:155], v[210:213], v[20:23]
	v_mfma_f32_16x16x32_bf16 v[12:15], v[160:163], v[210:213], v[12:15]
	v_mfma_f32_16x16x32_bf16 v[60:63], v[156:159], v[190:193], v[60:63]
	v_mfma_f32_16x16x32_bf16 v[56:59], v[164:167], v[190:193], v[56:59]
	v_mfma_f32_16x16x32_bf16 v[52:55], v[156:159], v[198:201], v[52:55]
	v_mfma_f32_16x16x32_bf16 v[44:47], v[164:167], v[198:201], v[44:47]
	v_mfma_f32_16x16x32_bf16 v[36:39], v[156:159], v[206:209], v[36:39]
	v_mfma_f32_16x16x32_bf16 v[28:31], v[164:167], v[206:209], v[28:31]
	v_mfma_f32_16x16x32_bf16 v[20:23], v[156:159], v[214:217], v[20:23]
	v_mfma_f32_16x16x32_bf16 v[12:15], v[164:167], v[214:217], v[12:15]
	v_mfma_f32_16x16x32_bf16 v[48:51], v[168:171], v[184:187], v[48:51]
	v_mfma_f32_16x16x32_bf16 v[40:43], v[176:179], v[184:187], v[40:43]
	v_mfma_f32_16x16x32_bf16 v[32:35], v[168:171], v[194:197], v[32:35]
	v_mfma_f32_16x16x32_bf16 v[24:27], v[176:179], v[194:197], v[24:27]
	v_mfma_f32_16x16x32_bf16 v[16:19], v[168:171], v[202:205], v[16:19]
	v_mfma_f32_16x16x32_bf16 v[8:11], v[176:179], v[202:205], v[8:11]
	v_mfma_f32_16x16x32_bf16 v[4:7], v[168:171], v[210:213], v[4:7]
	v_mfma_f32_16x16x32_bf16 v[0:3], v[176:179], v[210:213], v[0:3]
	v_mfma_f32_16x16x32_bf16 v[48:51], v[172:175], v[190:193], v[48:51]
	v_mfma_f32_16x16x32_bf16 v[40:43], v[180:183], v[190:193], v[40:43]
	v_mfma_f32_16x16x32_bf16 v[32:35], v[172:175], v[198:201], v[32:35]
	v_mfma_f32_16x16x32_bf16 v[24:27], v[180:183], v[198:201], v[24:27]
	v_mfma_f32_16x16x32_bf16 v[16:19], v[172:175], v[206:209], v[16:19]
	v_mfma_f32_16x16x32_bf16 v[8:11], v[180:183], v[206:209], v[8:11]
	v_mfma_f32_16x16x32_bf16 v[4:7], v[172:175], v[214:217], v[4:7]
	v_mfma_f32_16x16x32_bf16 v[0:3], v[180:183], v[214:217], v[0:3]
	s_barrier
	s_add_i32 s76, s76, 2
	s_add_u32 s48, s48, 0x100
	s_addc_u32 s49, s49, 0
	s_add_u32 s66, s66, 0x100
	s_addc_u32 s67, s67, 0
	s_cmp_gt_u32 s76, 13
	s_cbranch_scc0 .LBB0_1181
	s_and_b64 vcc, exec, s[14:15]
	s_cbranch_vccz .LBB0_1184
	s_barrier

.LBB0_1308:
	ds_read_b128 v[150:153], v147
	ds_read_b128 v[154:157], v147 offset:1024
	ds_read_b128 v[158:161], v147 offset:2048
	ds_read_b128 v[162:165], v147 offset:3072
	ds_read_b128 v[166:169], v148
	ds_read_b128 v[170:173], v148 offset:1024
	ds_read_b128 v[174:177], v148 offset:2048
	ds_read_b128 v[178:181], v148 offset:3072
	s_add_u32 s33, s38, 0xfffc0080
	s_addc_u32 s40, s39, -1
	s_cmp_eq_u32 s56, 12
	s_cselect_b32 s43, s19, s40
	s_cselect_b32 s42, s52, s33
	s_cselect_b32 s41, s17, s55
	s_cselect_b32 s40, s53, s54
	v_lshl_add_u64 v[186:187], s[38:39], 0, v[136:137]
	s_add_i32 m0, s34, 0xc000
	ds_read_b128 v[182:185], v149
	ds_read_b128 v[190:193], v149 offset:1024
	ds_read_b128 v[194:197], v149 offset:2048
	ds_read_b128 v[198:201], v149 offset:3072
	ds_read_b128 v[202:205], v149 offset:4096
	ds_read_b128 v[206:209], v149 offset:5120
	ds_read_b128 v[210:213], v149 offset:6144
	ds_read_b128 v[214:217], v149 offset:7168
	global_load_lds_dwordx4 v[186:187], off
	v_lshl_add_u64 v[186:187], s[38:39], 0, v[138:139]
	s_add_i32 m0, s34, 0xe000
	s_nop 0
	global_load_lds_dwordx4 v[186:187], off
	s_waitcnt vmcnt(8)
	s_waitcnt lgkmcnt(0)
	s_nop 0
	s_barrier
	s_waitcnt lgkmcnt(0)
	v_mfma_f32_16x16x32_bf16 v[124:127], v[150:153], v[182:185], v[124:127]
	v_mfma_f32_16x16x32_bf16 v[116:119], v[158:161], v[182:185], v[116:119]
	v_mfma_f32_16x16x32_bf16 v[108:111], v[150:153], v[194:197], v[108:111]
	v_mfma_f32_16x16x32_bf16 v[100:103], v[158:161], v[194:197], v[100:103]
	v_mfma_f32_16x16x32_bf16 v[92:95], v[150:153], v[202:205], v[92:95]
	v_mfma_f32_16x16x32_bf16 v[84:87], v[158:161], v[202:205], v[84:87]
	v_mfma_f32_16x16x32_bf16 v[76:79], v[150:153], v[210:213], v[76:79]
	v_mfma_f32_16x16x32_bf16 v[68:71], v[158:161], v[210:213], v[68:71]
	v_mfma_f32_16x16x32_bf16 v[124:127], v[154:157], v[190:193], v[124:127]
	v_mfma_f32_16x16x32_bf16 v[116:119], v[162:165], v[190:193], v[116:119]
	v_mfma_f32_16x16x32_bf16 v[108:111], v[154:157], v[198:201], v[108:111]
	v_mfma_f32_16x16x32_bf16 v[100:103], v[162:165], v[198:201], v[100:103]
	v_mfma_f32_16x16x32_bf16 v[92:95], v[154:157], v[206:209], v[92:95]
	v_mfma_f32_16x16x32_bf16 v[84:87], v[162:165], v[206:209], v[84:87]
	v_mfma_f32_16x16x32_bf16 v[76:79], v[154:157], v[214:217], v[76:79]
	v_mfma_f32_16x16x32_bf16 v[68:71], v[162:165], v[214:217], v[68:71]
	v_mfma_f32_16x16x32_bf16 v[120:123], v[166:169], v[182:185], v[120:123]
	v_mfma_f32_16x16x32_bf16 v[112:115], v[174:177], v[182:185], v[112:115]
	v_mfma_f32_16x16x32_bf16 v[104:107], v[166:169], v[194:197], v[104:107]
	v_mfma_f32_16x16x32_bf16 v[96:99], v[174:177], v[194:197], v[96:99]
	v_mfma_f32_16x16x32_bf16 v[88:91], v[166:169], v[202:205], v[88:91]
	v_mfma_f32_16x16x32_bf16 v[80:83], v[174:177], v[202:205], v[80:83]
	v_mfma_f32_16x16x32_bf16 v[72:75], v[166:169], v[210:213], v[72:75]
	v_mfma_f32_16x16x32_bf16 v[64:67], v[174:177], v[210:213], v[64:67]
	v_mfma_f32_16x16x32_bf16 v[120:123], v[170:173], v[190:193], v[120:123]
	v_mfma_f32_16x16x32_bf16 v[112:115], v[178:181], v[190:193], v[112:115]
	v_mfma_f32_16x16x32_bf16 v[104:107], v[170:173], v[198:201], v[104:107]
	v_mfma_f32_16x16x32_bf16 v[96:99], v[178:181], v[198:201], v[96:99]
	v_mfma_f32_16x16x32_bf16 v[88:91], v[170:173], v[206:209], v[88:91]
	v_mfma_f32_16x16x32_bf16 v[80:83], v[178:181], v[206:209], v[80:83]
	v_mfma_f32_16x16x32_bf16 v[72:75], v[170:173], v[214:217], v[72:75]
	v_mfma_f32_16x16x32_bf16 v[64:67], v[178:181], v[214:217], v[64:67]
	s_barrier
	s_add_i32 s33, s48, s13
	v_lshl_add_u64 v[186:187], s[40:41], 0, v[132:133]
	s_mov_b32 m0, s33
	ds_read_b128 v[182:185], v149 offset:16384
	ds_read_b128 v[190:193], v149 offset:17408
	ds_read_b128 v[194:197], v149 offset:18432
	ds_read_b128 v[198:201], v149 offset:19456
	ds_read_b128 v[202:205], v149 offset:20480
	ds_read_b128 v[206:209], v149 offset:21504
	ds_read_b128 v[210:213], v149 offset:22528
	ds_read_b128 v[214:217], v149 offset:23552
	global_load_lds_dwordx4 v[186:187], off
	s_add_i32 m0, s33, 0x2000
	s_add_u32 s58, s40, 0x40000
	v_lshl_add_u64 v[218:219], s[40:41], 0, v[128:129]
	s_addc_u32 s59, s41, 0
	s_add_i32 s33, s49, s13
	global_load_lds_dwordx4 v[218:219], off
	v_lshl_add_u64 v[220:221], s[58:59], 0, v[132:133]
	s_mov_b32 m0, s33
	v_lshl_add_u64 v[222:223], s[42:43], 0, v[130:131]
	global_load_lds_dwordx4 v[220:221], off
	v_lshl_add_u64 v[220:221], s[58:59], 0, v[128:129]
	s_add_i32 m0, s33, 0x2000
	s_nop 0
	global_load_lds_dwordx4 v[220:221], off
	v_lshl_add_u64 v[220:221], s[42:43], 0, v[134:135]
	s_mov_b32 m0, s34
	s_nop 0
	global_load_lds_dwordx4 v[220:221], off
	s_mov_b32 m0, s35
	s_nop 0
	global_load_lds_dwordx4 v[222:223], off
	s_waitcnt vmcnt(8)
	s_waitcnt lgkmcnt(0)
	s_nop 0
	s_barrier
	s_waitcnt lgkmcnt(0)
	v_mfma_f32_16x16x32_bf16 v[60:63], v[150:153], v[182:185], v[60:63]
	v_mfma_f32_16x16x32_bf16 v[52:55], v[158:161], v[182:185], v[52:55]
	v_mfma_f32_16x16x32_bf16 v[44:47], v[150:153], v[194:197], v[44:47]
	v_mfma_f32_16x16x32_bf16 v[36:39], v[158:161], v[194:197], v[36:39]
	v_mfma_f32_16x16x32_bf16 v[28:31], v[150:153], v[202:205], v[28:31]
	v_mfma_f32_16x16x32_bf16 v[20:23], v[158:161], v[202:205], v[20:23]
	v_mfma_f32_16x16x32_bf16 v[12:15], v[150:153], v[210:213], v[12:15]
	v_mfma_f32_16x16x32_bf16 v[4:7], v[158:161], v[210:213], v[4:7]
	v_mfma_f32_16x16x32_bf16 v[60:63], v[154:157], v[190:193], v[60:63]
	v_mfma_f32_16x16x32_bf16 v[52:55], v[162:165], v[190:193], v[52:55]
	v_mfma_f32_16x16x32_bf16 v[44:47], v[154:157], v[198:201], v[44:47]
	v_mfma_f32_16x16x32_bf16 v[36:39], v[162:165], v[198:201], v[36:39]
	v_mfma_f32_16x16x32_bf16 v[28:31], v[154:157], v[206:209], v[28:31]
	v_mfma_f32_16x16x32_bf16 v[20:23], v[162:165], v[206:209], v[20:23]
	v_mfma_f32_16x16x32_bf16 v[12:15], v[154:157], v[214:217], v[12:15]
	v_mfma_f32_16x16x32_bf16 v[4:7], v[162:165], v[214:217], v[4:7]
	v_mfma_f32_16x16x32_bf16 v[56:59], v[166:169], v[182:185], v[56:59]
	v_mfma_f32_16x16x32_bf16 v[48:51], v[174:177], v[182:185], v[48:51]
	v_mfma_f32_16x16x32_bf16 v[40:43], v[166:169], v[194:197], v[40:43]
	v_mfma_f32_16x16x32_bf16 v[32:35], v[174:177], v[194:197], v[32:35]
	v_mfma_f32_16x16x32_bf16 v[24:27], v[166:169], v[202:205], v[24:27]
	v_mfma_f32_16x16x32_bf16 v[16:19], v[174:177], v[202:205], v[16:19]
	v_mfma_f32_16x16x32_bf16 v[8:11], v[166:169], v[210:213], v[8:11]
	v_mfma_f32_16x16x32_bf16 v[0:3], v[174:177], v[210:213], v[0:3]
	v_mfma_f32_16x16x32_bf16 v[56:59], v[170:173], v[190:193], v[56:59]
	v_mfma_f32_16x16x32_bf16 v[48:51], v[178:181], v[190:193], v[48:51]
	v_mfma_f32_16x16x32_bf16 v[40:43], v[170:173], v[198:201], v[40:43]
	v_mfma_f32_16x16x32_bf16 v[32:35], v[178:181], v[198:201], v[32:35]
	v_mfma_f32_16x16x32_bf16 v[24:27], v[170:173], v[206:209], v[24:27]
	v_mfma_f32_16x16x32_bf16 v[16:19], v[178:181], v[206:209], v[16:19]
	v_mfma_f32_16x16x32_bf16 v[8:11], v[170:173], v[214:217], v[8:11]
	v_mfma_f32_16x16x32_bf16 v[0:3], v[178:181], v[214:217], v[0:3]
	s_barrier
	s_add_i32 s33, 0, 0x18000
	s_add_i32 s57, 0, 0x1c000
	v_add_u32_e32 v162, s33, v145
	v_add_u32_e32 v178, s57, v145
	ds_read_b128 v[150:153], v162
	ds_read_b128 v[154:157], v162 offset:1024
	ds_read_b128 v[158:161], v162 offset:2048
	ds_read_b128 v[162:165], v162 offset:3072
	ds_read_b128 v[166:169], v178
	ds_read_b128 v[170:173], v178 offset:1024
	ds_read_b128 v[174:177], v178 offset:2048
	ds_read_b128 v[178:181], v178 offset:3072
	s_add_u32 s42, s42, 0x40000
	s_addc_u32 s43, s43, 0
	s_mov_b32 m0, s37
	v_lshl_add_u64 v[224:225], s[42:43], 0, v[134:135]
	ds_read_b128 v[182:185], v149 offset:32768
	ds_read_b128 v[190:193], v149 offset:33792
	ds_read_b128 v[194:197], v149 offset:34816
	ds_read_b128 v[198:201], v149 offset:35840
	ds_read_b128 v[202:205], v149 offset:36864
	ds_read_b128 v[206:209], v149 offset:37888
	ds_read_b128 v[210:213], v149 offset:38912
	ds_read_b128 v[214:217], v149 offset:39936
	global_load_lds_dwordx4 v[224:225], off
	v_lshl_add_u64 v[224:225], s[42:43], 0, v[130:131]
	s_mov_b32 m0, s44
	s_nop 0
	global_load_lds_dwordx4 v[224:225], off
	s_waitcnt vmcnt(8)
	s_waitcnt lgkmcnt(0)
	s_nop 0
	s_barrier
	s_waitcnt lgkmcnt(0)
	v_mfma_f32_16x16x32_bf16 v[124:127], v[150:153], v[182:185], v[124:127]
	v_mfma_f32_16x16x32_bf16 v[116:119], v[158:161], v[182:185], v[116:119]
	v_mfma_f32_16x16x32_bf16 v[108:111], v[150:153], v[194:197], v[108:111]
	v_mfma_f32_16x16x32_bf16 v[100:103], v[158:161], v[194:197], v[100:103]
	v_mfma_f32_16x16x32_bf16 v[92:95], v[150:153], v[202:205], v[92:95]
	v_mfma_f32_16x16x32_bf16 v[84:87], v[158:161], v[202:205], v[84:87]
	v_mfma_f32_16x16x32_bf16 v[76:79], v[150:153], v[210:213], v[76:79]
	v_mfma_f32_16x16x32_bf16 v[68:71], v[158:161], v[210:213], v[68:71]
	v_mfma_f32_16x16x32_bf16 v[124:127], v[154:157], v[190:193], v[124:127]
	v_mfma_f32_16x16x32_bf16 v[116:119], v[162:165], v[190:193], v[116:119]
	v_mfma_f32_16x16x32_bf16 v[108:111], v[154:157], v[198:201], v[108:111]
	v_mfma_f32_16x16x32_bf16 v[100:103], v[162:165], v[198:201], v[100:103]
	v_mfma_f32_16x16x32_bf16 v[92:95], v[154:157], v[206:209], v[92:95]
	v_mfma_f32_16x16x32_bf16 v[84:87], v[162:165], v[206:209], v[84:87]
	v_mfma_f32_16x16x32_bf16 v[76:79], v[154:157], v[214:217], v[76:79]
	v_mfma_f32_16x16x32_bf16 v[68:71], v[162:165], v[214:217], v[68:71]
	v_mfma_f32_16x16x32_bf16 v[120:123], v[166:169], v[182:185], v[120:123]
	v_mfma_f32_16x16x32_bf16 v[112:115], v[174:177], v[182:185], v[112:115]
	v_mfma_f32_16x16x32_bf16 v[104:107], v[166:169], v[194:197], v[104:107]
	v_mfma_f32_16x16x32_bf16 v[96:99], v[174:177], v[194:197], v[96:99]
	v_mfma_f32_16x16x32_bf16 v[88:91], v[166:169], v[202:205], v[88:91]
	v_mfma_f32_16x16x32_bf16 v[80:83], v[174:177], v[202:205], v[80:83]
	v_mfma_f32_16x16x32_bf16 v[72:75], v[166:169], v[210:213], v[72:75]
	v_mfma_f32_16x16x32_bf16 v[64:67], v[174:177], v[210:213], v[64:67]
	v_mfma_f32_16x16x32_bf16 v[120:123], v[170:173], v[190:193], v[120:123]
	v_mfma_f32_16x16x32_bf16 v[112:115], v[178:181], v[190:193], v[112:115]
	v_mfma_f32_16x16x32_bf16 v[104:107], v[170:173], v[198:201], v[104:107]
	v_mfma_f32_16x16x32_bf16 v[96:99], v[178:181], v[198:201], v[96:99]
	v_mfma_f32_16x16x32_bf16 v[88:91], v[170:173], v[206:209], v[88:91]
	v_mfma_f32_16x16x32_bf16 v[80:83], v[178:181], v[206:209], v[80:83]
	v_mfma_f32_16x16x32_bf16 v[72:75], v[170:173], v[214:217], v[72:75]
	v_mfma_f32_16x16x32_bf16 v[64:67], v[178:181], v[214:217], v[64:67]
	s_barrier
	s_add_i32 s33, s33, s13
	v_lshl_add_u64 v[186:187], v[186:187], 0, s[8:9]
	s_mov_b32 m0, s33
	ds_read_b128 v[182:185], v149 offset:49152
	ds_read_b128 v[190:193], v149 offset:50176
	ds_read_b128 v[194:197], v149 offset:51200
	ds_read_b128 v[198:201], v149 offset:52224
	ds_read_b128 v[202:205], v149 offset:53248
	ds_read_b128 v[206:209], v149 offset:54272
	ds_read_b128 v[210:213], v149 offset:55296
	ds_read_b128 v[214:217], v149 offset:56320
	global_load_lds_dwordx4 v[186:187], off
	s_add_i32 m0, s33, 0x2000
	s_add_u32 s40, s40, 0x40080
	v_lshl_add_u64 v[186:187], v[218:219], 0, s[8:9]
	s_addc_u32 s41, s41, 0
	s_add_i32 s33, s57, s13
	global_load_lds_dwordx4 v[186:187], off
	v_lshl_add_u64 v[186:187], s[40:41], 0, v[132:133]
	s_mov_b32 m0, s33
	s_nop 0
	global_load_lds_dwordx4 v[186:187], off
	v_lshl_add_u64 v[186:187], s[40:41], 0, v[128:129]
	s_add_i32 m0, s33, 0x2000
	s_nop 0
	global_load_lds_dwordx4 v[186:187], off
	v_lshl_add_u64 v[186:187], v[220:221], 0, s[8:9]
	s_mov_b32 m0, s46
	s_nop 0
	global_load_lds_dwordx4 v[186:187], off
	v_lshl_add_u64 v[186:187], v[222:223], 0, s[8:9]
	s_mov_b32 m0, s47
	s_nop 0
	global_load_lds_dwordx4 v[186:187], off
	s_waitcnt vmcnt(8)
	s_waitcnt lgkmcnt(0)
	s_barrier
	s_waitcnt lgkmcnt(0)
	v_mfma_f32_16x16x32_bf16 v[60:63], v[150:153], v[182:185], v[60:63]
	v_mfma_f32_16x16x32_bf16 v[52:55], v[158:161], v[182:185], v[52:55]
	v_mfma_f32_16x16x32_bf16 v[44:47], v[150:153], v[194:197], v[44:47]
	v_mfma_f32_16x16x32_bf16 v[36:39], v[158:161], v[194:197], v[36:39]
	v_mfma_f32_16x16x32_bf16 v[28:31], v[150:153], v[202:205], v[28:31]
	v_mfma_f32_16x16x32_bf16 v[20:23], v[158:161], v[202:205], v[20:23]
	v_mfma_f32_16x16x32_bf16 v[12:15], v[150:153], v[210:213], v[12:15]
	v_mfma_f32_16x16x32_bf16 v[4:7], v[158:161], v[210:213], v[4:7]
	v_mfma_f32_16x16x32_bf16 v[60:63], v[154:157], v[190:193], v[60:63]
	v_mfma_f32_16x16x32_bf16 v[52:55], v[162:165], v[190:193], v[52:55]
	v_mfma_f32_16x16x32_bf16 v[44:47], v[154:157], v[198:201], v[44:47]
	v_mfma_f32_16x16x32_bf16 v[36:39], v[162:165], v[198:201], v[36:39]
	v_mfma_f32_16x16x32_bf16 v[28:31], v[154:157], v[206:209], v[28:31]
	v_mfma_f32_16x16x32_bf16 v[20:23], v[162:165], v[206:209], v[20:23]
	v_mfma_f32_16x16x32_bf16 v[12:15], v[154:157], v[214:217], v[12:15]
	v_mfma_f32_16x16x32_bf16 v[4:7], v[162:165], v[214:217], v[4:7]
	v_mfma_f32_16x16x32_bf16 v[56:59], v[166:169], v[182:185], v[56:59]
	v_mfma_f32_16x16x32_bf16 v[48:51], v[174:177], v[182:185], v[48:51]
	v_mfma_f32_16x16x32_bf16 v[40:43], v[166:169], v[194:197], v[40:43]
	v_mfma_f32_16x16x32_bf16 v[32:35], v[174:177], v[194:197], v[32:35]
	v_mfma_f32_16x16x32_bf16 v[24:27], v[166:169], v[202:205], v[24:27]
	v_mfma_f32_16x16x32_bf16 v[16:19], v[174:177], v[202:205], v[16:19]
	v_mfma_f32_16x16x32_bf16 v[8:11], v[166:169], v[210:213], v[8:11]
	v_mfma_f32_16x16x32_bf16 v[0:3], v[174:177], v[210:213], v[0:3]
	v_mfma_f32_16x16x32_bf16 v[56:59], v[170:173], v[190:193], v[56:59]
	v_mfma_f32_16x16x32_bf16 v[48:51], v[178:181], v[190:193], v[48:51]
	v_mfma_f32_16x16x32_bf16 v[40:43], v[170:173], v[198:201], v[40:43]
	v_mfma_f32_16x16x32_bf16 v[32:35], v[178:181], v[198:201], v[32:35]
	v_mfma_f32_16x16x32_bf16 v[24:27], v[170:173], v[206:209], v[24:27]
	v_mfma_f32_16x16x32_bf16 v[16:19], v[178:181], v[206:209], v[16:19]
	v_mfma_f32_16x16x32_bf16 v[8:11], v[170:173], v[214:217], v[8:11]
	v_mfma_f32_16x16x32_bf16 v[0:3], v[178:181], v[214:217], v[0:3]
	s_barrier
	s_add_i32 s56, s56, 2
	s_add_u32 s38, s38, 0x100
	s_addc_u32 s39, s39, 0
	s_add_u32 s54, s54, 0x100
	s_addc_u32 s55, s55, 0
	s_cmp_gt_u32 s56, 13
	s_cbranch_scc0 .LBB0_1308
	s_and_b64 vcc, exec, s[10:11]
	s_cbranch_vccz .LBB0_1311
	s_barrier

.LBB0_1388:
	ds_read_b128 v[152:155], v149
	ds_read_b128 v[156:159], v149 offset:1024
	ds_read_b128 v[160:163], v149 offset:2048
	ds_read_b128 v[164:167], v149 offset:3072
	ds_read_b128 v[168:171], v150
	ds_read_b128 v[172:175], v150 offset:1024
	ds_read_b128 v[176:179], v150 offset:2048
	ds_read_b128 v[180:183], v150 offset:3072
	s_add_u32 s36, s28, 0x10000
	s_addc_u32 s37, s29, 0
	s_cmp_eq_u32 s59, 40
	s_cselect_b32 s41, s5, s37
	s_cselect_b32 s40, s4, s36
	s_cselect_b32 s39, s27, s58
	s_cselect_b32 s38, s26, s57
	v_lshl_add_u64 v[144:145], s[28:29], 0, v[136:137]
	s_add_i32 m0, s34, 0xc000
	ds_read_b128 v[184:187], v151
	ds_read_b128 v[190:193], v151 offset:1024
	ds_read_b128 v[194:197], v151 offset:2048
	ds_read_b128 v[198:201], v151 offset:3072
	ds_read_b128 v[202:205], v151 offset:4096
	ds_read_b128 v[206:209], v151 offset:5120
	ds_read_b128 v[210:213], v151 offset:6144
	ds_read_b128 v[214:217], v151 offset:7168
	global_load_lds_dwordx4 v[144:145], off
	v_lshl_add_u64 v[144:145], s[28:29], 0, v[138:139]
	s_add_i32 m0, s34, 0xe000
	s_nop 0
	global_load_lds_dwordx4 v[144:145], off
	s_waitcnt vmcnt(8)
	s_waitcnt lgkmcnt(0)
	s_barrier
	s_waitcnt lgkmcnt(0)
	v_mfma_f32_16x16x32_bf16 v[124:127], v[152:155], v[184:187], v[124:127]
	v_mfma_f32_16x16x32_bf16 v[120:123], v[160:163], v[184:187], v[120:123]
	v_mfma_f32_16x16x32_bf16 v[116:119], v[152:155], v[194:197], v[116:119]
	v_mfma_f32_16x16x32_bf16 v[108:111], v[160:163], v[194:197], v[108:111]
	v_mfma_f32_16x16x32_bf16 v[100:103], v[152:155], v[202:205], v[100:103]
	v_mfma_f32_16x16x32_bf16 v[92:95], v[160:163], v[202:205], v[92:95]
	v_mfma_f32_16x16x32_bf16 v[84:87], v[152:155], v[210:213], v[84:87]
	v_mfma_f32_16x16x32_bf16 v[76:79], v[160:163], v[210:213], v[76:79]
	v_mfma_f32_16x16x32_bf16 v[124:127], v[156:159], v[190:193], v[124:127]
	v_mfma_f32_16x16x32_bf16 v[120:123], v[164:167], v[190:193], v[120:123]
	v_mfma_f32_16x16x32_bf16 v[116:119], v[156:159], v[198:201], v[116:119]
	v_mfma_f32_16x16x32_bf16 v[108:111], v[164:167], v[198:201], v[108:111]
	v_mfma_f32_16x16x32_bf16 v[100:103], v[156:159], v[206:209], v[100:103]
	v_mfma_f32_16x16x32_bf16 v[92:95], v[164:167], v[206:209], v[92:95]
	v_mfma_f32_16x16x32_bf16 v[84:87], v[156:159], v[214:217], v[84:87]
	v_mfma_f32_16x16x32_bf16 v[76:79], v[164:167], v[214:217], v[76:79]
	v_mfma_f32_16x16x32_bf16 v[112:115], v[168:171], v[184:187], v[112:115]
	v_mfma_f32_16x16x32_bf16 v[104:107], v[176:179], v[184:187], v[104:107]
	v_mfma_f32_16x16x32_bf16 v[96:99], v[168:171], v[194:197], v[96:99]
	v_mfma_f32_16x16x32_bf16 v[88:91], v[176:179], v[194:197], v[88:91]
	v_mfma_f32_16x16x32_bf16 v[80:83], v[168:171], v[202:205], v[80:83]
	v_mfma_f32_16x16x32_bf16 v[72:75], v[176:179], v[202:205], v[72:75]
	v_mfma_f32_16x16x32_bf16 v[68:71], v[168:171], v[210:213], v[68:71]
	v_mfma_f32_16x16x32_bf16 v[64:67], v[176:179], v[210:213], v[64:67]
	v_mfma_f32_16x16x32_bf16 v[112:115], v[172:175], v[190:193], v[112:115]
	v_mfma_f32_16x16x32_bf16 v[104:107], v[180:183], v[190:193], v[104:107]
	v_mfma_f32_16x16x32_bf16 v[96:99], v[172:175], v[198:201], v[96:99]
	v_mfma_f32_16x16x32_bf16 v[88:91], v[180:183], v[198:201], v[88:91]
	v_mfma_f32_16x16x32_bf16 v[80:83], v[172:175], v[206:209], v[80:83]
	v_mfma_f32_16x16x32_bf16 v[72:75], v[180:183], v[206:209], v[72:75]
	v_mfma_f32_16x16x32_bf16 v[68:71], v[172:175], v[214:217], v[68:71]
	v_mfma_f32_16x16x32_bf16 v[64:67], v[180:183], v[214:217], v[64:67]
	s_barrier
	s_add_i32 s28, s47, s13
	v_lshl_add_u64 v[144:145], s[38:39], 0, v[130:131]
	s_mov_b32 m0, s28
	ds_read_b128 v[184:187], v151 offset:16384
	ds_read_b128 v[190:193], v151 offset:17408
	ds_read_b128 v[194:197], v151 offset:18432
	ds_read_b128 v[198:201], v151 offset:19456
	ds_read_b128 v[202:205], v151 offset:20480
	ds_read_b128 v[206:209], v151 offset:21504
	ds_read_b128 v[210:213], v151 offset:22528
	ds_read_b128 v[214:217], v151 offset:23552
	global_load_lds_dwordx4 v[144:145], off
	s_add_i32 m0, s28, 0x2000
	s_add_u32 s28, s38, 0xb0000
	v_lshl_add_u64 v[218:219], s[38:39], 0, v[134:135]
	s_addc_u32 s29, s39, 0
	s_add_i32 s33, s48, s13
	global_load_lds_dwordx4 v[218:219], off
	v_lshl_add_u64 v[220:221], s[28:29], 0, v[130:131]
	s_mov_b32 m0, s33
	v_lshl_add_u64 v[222:223], s[40:41], 0, v[132:133]
	global_load_lds_dwordx4 v[220:221], off
	v_lshl_add_u64 v[220:221], s[28:29], 0, v[134:135]
	s_add_i32 m0, s33, 0x2000
	s_nop 0
	global_load_lds_dwordx4 v[220:221], off
	v_lshl_add_u64 v[220:221], s[40:41], 0, v[128:129]
	s_mov_b32 m0, s34
	s_nop 0
	global_load_lds_dwordx4 v[220:221], off
	s_mov_b32 m0, s35
	s_nop 0
	global_load_lds_dwordx4 v[222:223], off
	s_waitcnt vmcnt(8)
	s_waitcnt lgkmcnt(0)
	s_nop 0
	s_barrier
	s_waitcnt lgkmcnt(0)
	v_mfma_f32_16x16x32_bf16 v[60:63], v[152:155], v[184:187], v[60:63]
	v_mfma_f32_16x16x32_bf16 v[56:59], v[160:163], v[184:187], v[56:59]
	v_mfma_f32_16x16x32_bf16 v[52:55], v[152:155], v[194:197], v[52:55]
	v_mfma_f32_16x16x32_bf16 v[44:47], v[160:163], v[194:197], v[44:47]
	v_mfma_f32_16x16x32_bf16 v[36:39], v[152:155], v[202:205], v[36:39]
	v_mfma_f32_16x16x32_bf16 v[28:31], v[160:163], v[202:205], v[28:31]
	v_mfma_f32_16x16x32_bf16 v[20:23], v[152:155], v[210:213], v[20:23]
	v_mfma_f32_16x16x32_bf16 v[12:15], v[160:163], v[210:213], v[12:15]
	v_mfma_f32_16x16x32_bf16 v[60:63], v[156:159], v[190:193], v[60:63]
	v_mfma_f32_16x16x32_bf16 v[56:59], v[164:167], v[190:193], v[56:59]
	v_mfma_f32_16x16x32_bf16 v[52:55], v[156:159], v[198:201], v[52:55]
	v_mfma_f32_16x16x32_bf16 v[44:47], v[164:167], v[198:201], v[44:47]
	v_mfma_f32_16x16x32_bf16 v[36:39], v[156:159], v[206:209], v[36:39]
	v_mfma_f32_16x16x32_bf16 v[28:31], v[164:167], v[206:209], v[28:31]
	v_mfma_f32_16x16x32_bf16 v[20:23], v[156:159], v[214:217], v[20:23]
	v_mfma_f32_16x16x32_bf16 v[12:15], v[164:167], v[214:217], v[12:15]
	v_mfma_f32_16x16x32_bf16 v[48:51], v[168:171], v[184:187], v[48:51]
	v_mfma_f32_16x16x32_bf16 v[40:43], v[176:179], v[184:187], v[40:43]
	v_mfma_f32_16x16x32_bf16 v[32:35], v[168:171], v[194:197], v[32:35]
	v_mfma_f32_16x16x32_bf16 v[24:27], v[176:179], v[194:197], v[24:27]
	v_mfma_f32_16x16x32_bf16 v[16:19], v[168:171], v[202:205], v[16:19]
	v_mfma_f32_16x16x32_bf16 v[8:11], v[176:179], v[202:205], v[8:11]
	v_mfma_f32_16x16x32_bf16 v[4:7], v[168:171], v[210:213], v[4:7]
	v_mfma_f32_16x16x32_bf16 v[0:3], v[176:179], v[210:213], v[0:3]
	v_mfma_f32_16x16x32_bf16 v[48:51], v[172:175], v[190:193], v[48:51]
	v_mfma_f32_16x16x32_bf16 v[40:43], v[180:183], v[190:193], v[40:43]
	v_mfma_f32_16x16x32_bf16 v[32:35], v[172:175], v[198:201], v[32:35]
	v_mfma_f32_16x16x32_bf16 v[24:27], v[180:183], v[198:201], v[24:27]
	v_mfma_f32_16x16x32_bf16 v[16:19], v[172:175], v[206:209], v[16:19]
	v_mfma_f32_16x16x32_bf16 v[8:11], v[180:183], v[206:209], v[8:11]
	v_mfma_f32_16x16x32_bf16 v[4:7], v[172:175], v[214:217], v[4:7]
	v_mfma_f32_16x16x32_bf16 v[0:3], v[180:183], v[214:217], v[0:3]
	s_barrier
	s_add_i32 s33, 0, 0x18000
	s_add_i32 s60, 0, 0x1c000
	v_add_u32_e32 v164, s33, v147
	v_add_u32_e32 v180, s60, v147
	ds_read_b128 v[152:155], v164
	ds_read_b128 v[156:159], v164 offset:1024
	ds_read_b128 v[160:163], v164 offset:2048
	ds_read_b128 v[164:167], v164 offset:3072
	ds_read_b128 v[168:171], v180
	ds_read_b128 v[172:175], v180 offset:1024
	ds_read_b128 v[176:179], v180 offset:2048
	ds_read_b128 v[180:183], v180 offset:3072
	s_add_u32 s28, s40, 0x4000
	s_addc_u32 s29, s41, 0
	s_mov_b32 m0, s42
	v_lshl_add_u64 v[224:225], s[28:29], 0, v[128:129]
	ds_read_b128 v[184:187], v151 offset:32768
	ds_read_b128 v[190:193], v151 offset:33792
	ds_read_b128 v[194:197], v151 offset:34816
	ds_read_b128 v[198:201], v151 offset:35840
	ds_read_b128 v[202:205], v151 offset:36864
	ds_read_b128 v[206:209], v151 offset:37888
	ds_read_b128 v[210:213], v151 offset:38912
	ds_read_b128 v[214:217], v151 offset:39936
	global_load_lds_dwordx4 v[224:225], off
	v_lshl_add_u64 v[224:225], s[28:29], 0, v[132:133]
	s_mov_b32 m0, s43
	s_nop 0
	global_load_lds_dwordx4 v[224:225], off
	s_waitcnt vmcnt(8)
	s_waitcnt lgkmcnt(0)
	s_nop 0
	s_barrier
	s_waitcnt lgkmcnt(0)
	v_mfma_f32_16x16x32_bf16 v[124:127], v[152:155], v[184:187], v[124:127]
	v_mfma_f32_16x16x32_bf16 v[120:123], v[160:163], v[184:187], v[120:123]
	v_mfma_f32_16x16x32_bf16 v[116:119], v[152:155], v[194:197], v[116:119]
	v_mfma_f32_16x16x32_bf16 v[108:111], v[160:163], v[194:197], v[108:111]
	v_mfma_f32_16x16x32_bf16 v[100:103], v[152:155], v[202:205], v[100:103]
	v_mfma_f32_16x16x32_bf16 v[92:95], v[160:163], v[202:205], v[92:95]
	v_mfma_f32_16x16x32_bf16 v[84:87], v[152:155], v[210:213], v[84:87]
	v_mfma_f32_16x16x32_bf16 v[76:79], v[160:163], v[210:213], v[76:79]
	v_mfma_f32_16x16x32_bf16 v[124:127], v[156:159], v[190:193], v[124:127]
	v_mfma_f32_16x16x32_bf16 v[120:123], v[164:167], v[190:193], v[120:123]
	v_mfma_f32_16x16x32_bf16 v[116:119], v[156:159], v[198:201], v[116:119]
	v_mfma_f32_16x16x32_bf16 v[108:111], v[164:167], v[198:201], v[108:111]
	v_mfma_f32_16x16x32_bf16 v[100:103], v[156:159], v[206:209], v[100:103]
	v_mfma_f32_16x16x32_bf16 v[92:95], v[164:167], v[206:209], v[92:95]
	v_mfma_f32_16x16x32_bf16 v[84:87], v[156:159], v[214:217], v[84:87]
	v_mfma_f32_16x16x32_bf16 v[76:79], v[164:167], v[214:217], v[76:79]
	v_mfma_f32_16x16x32_bf16 v[112:115], v[168:171], v[184:187], v[112:115]
	v_mfma_f32_16x16x32_bf16 v[104:107], v[176:179], v[184:187], v[104:107]
	v_mfma_f32_16x16x32_bf16 v[96:99], v[168:171], v[194:197], v[96:99]
	v_mfma_f32_16x16x32_bf16 v[88:91], v[176:179], v[194:197], v[88:91]
	v_mfma_f32_16x16x32_bf16 v[80:83], v[168:171], v[202:205], v[80:83]
	v_mfma_f32_16x16x32_bf16 v[72:75], v[176:179], v[202:205], v[72:75]
	v_mfma_f32_16x16x32_bf16 v[68:71], v[168:171], v[210:213], v[68:71]
	v_mfma_f32_16x16x32_bf16 v[64:67], v[176:179], v[210:213], v[64:67]
	v_mfma_f32_16x16x32_bf16 v[112:115], v[172:175], v[190:193], v[112:115]
	v_mfma_f32_16x16x32_bf16 v[104:107], v[180:183], v[190:193], v[104:107]
	v_mfma_f32_16x16x32_bf16 v[96:99], v[172:175], v[198:201], v[96:99]
	v_mfma_f32_16x16x32_bf16 v[88:91], v[180:183], v[198:201], v[88:91]
	v_mfma_f32_16x16x32_bf16 v[80:83], v[172:175], v[206:209], v[80:83]
	v_mfma_f32_16x16x32_bf16 v[72:75], v[180:183], v[206:209], v[72:75]
	v_mfma_f32_16x16x32_bf16 v[68:71], v[172:175], v[214:217], v[68:71]
	v_mfma_f32_16x16x32_bf16 v[64:67], v[180:183], v[214:217], v[64:67]
	s_barrier
	s_add_i32 s28, s33, s13
	v_lshl_add_u64 v[144:145], v[144:145], 0, s[8:9]
	s_mov_b32 m0, s28
	ds_read_b128 v[184:187], v151 offset:49152
	ds_read_b128 v[190:193], v151 offset:50176
	ds_read_b128 v[194:197], v151 offset:51200
	ds_read_b128 v[198:201], v151 offset:52224
	ds_read_b128 v[202:205], v151 offset:53248
	ds_read_b128 v[206:209], v151 offset:54272
	ds_read_b128 v[210:213], v151 offset:55296
	ds_read_b128 v[214:217], v151 offset:56320
	global_load_lds_dwordx4 v[144:145], off
	s_add_i32 m0, s28, 0x2000
	s_add_u32 s28, s38, 0xb0080
	v_lshl_add_u64 v[144:145], v[218:219], 0, s[8:9]
	s_addc_u32 s29, s39, 0
	s_add_i32 s33, s60, s13
	global_load_lds_dwordx4 v[144:145], off
	v_lshl_add_u64 v[144:145], s[28:29], 0, v[130:131]
	s_mov_b32 m0, s33
	s_nop 0
	global_load_lds_dwordx4 v[144:145], off
	v_lshl_add_u64 v[144:145], s[28:29], 0, v[134:135]
	s_add_i32 m0, s33, 0x2000
	s_nop 0
	global_load_lds_dwordx4 v[144:145], off
	v_lshl_add_u64 v[144:145], v[220:221], 0, s[92:93]
	s_mov_b32 m0, s45
	s_nop 0
	global_load_lds_dwordx4 v[144:145], off
	v_lshl_add_u64 v[144:145], v[222:223], 0, s[92:93]
	s_mov_b32 m0, s46
	s_nop 0
	global_load_lds_dwordx4 v[144:145], off
	s_waitcnt vmcnt(8)
	s_waitcnt lgkmcnt(0)
	s_barrier
	s_waitcnt lgkmcnt(0)
	v_mfma_f32_16x16x32_bf16 v[60:63], v[152:155], v[184:187], v[60:63]
	v_mfma_f32_16x16x32_bf16 v[56:59], v[160:163], v[184:187], v[56:59]
	v_mfma_f32_16x16x32_bf16 v[52:55], v[152:155], v[194:197], v[52:55]
	v_mfma_f32_16x16x32_bf16 v[44:47], v[160:163], v[194:197], v[44:47]
	v_mfma_f32_16x16x32_bf16 v[36:39], v[152:155], v[202:205], v[36:39]
	v_mfma_f32_16x16x32_bf16 v[28:31], v[160:163], v[202:205], v[28:31]
	v_mfma_f32_16x16x32_bf16 v[20:23], v[152:155], v[210:213], v[20:23]
	v_mfma_f32_16x16x32_bf16 v[12:15], v[160:163], v[210:213], v[12:15]
	v_mfma_f32_16x16x32_bf16 v[60:63], v[156:159], v[190:193], v[60:63]
	v_mfma_f32_16x16x32_bf16 v[56:59], v[164:167], v[190:193], v[56:59]
	v_mfma_f32_16x16x32_bf16 v[52:55], v[156:159], v[198:201], v[52:55]
	v_mfma_f32_16x16x32_bf16 v[44:47], v[164:167], v[198:201], v[44:47]
	v_mfma_f32_16x16x32_bf16 v[36:39], v[156:159], v[206:209], v[36:39]
	v_mfma_f32_16x16x32_bf16 v[28:31], v[164:167], v[206:209], v[28:31]
	v_mfma_f32_16x16x32_bf16 v[20:23], v[156:159], v[214:217], v[20:23]
	v_mfma_f32_16x16x32_bf16 v[12:15], v[164:167], v[214:217], v[12:15]
	v_mfma_f32_16x16x32_bf16 v[48:51], v[168:171], v[184:187], v[48:51]
	v_mfma_f32_16x16x32_bf16 v[40:43], v[176:179], v[184:187], v[40:43]
	v_mfma_f32_16x16x32_bf16 v[32:35], v[168:171], v[194:197], v[32:35]
	v_mfma_f32_16x16x32_bf16 v[24:27], v[176:179], v[194:197], v[24:27]
	v_mfma_f32_16x16x32_bf16 v[16:19], v[168:171], v[202:205], v[16:19]
	v_mfma_f32_16x16x32_bf16 v[8:11], v[176:179], v[202:205], v[8:11]
	v_mfma_f32_16x16x32_bf16 v[4:7], v[168:171], v[210:213], v[4:7]
	v_mfma_f32_16x16x32_bf16 v[0:3], v[176:179], v[210:213], v[0:3]
	v_mfma_f32_16x16x32_bf16 v[48:51], v[172:175], v[190:193], v[48:51]
	v_mfma_f32_16x16x32_bf16 v[40:43], v[180:183], v[190:193], v[40:43]
	v_mfma_f32_16x16x32_bf16 v[32:35], v[172:175], v[198:201], v[32:35]
	v_mfma_f32_16x16x32_bf16 v[24:27], v[180:183], v[198:201], v[24:27]
	v_mfma_f32_16x16x32_bf16 v[16:19], v[172:175], v[206:209], v[16:19]
	v_mfma_f32_16x16x32_bf16 v[8:11], v[180:183], v[206:209], v[8:11]
	v_mfma_f32_16x16x32_bf16 v[4:7], v[172:175], v[214:217], v[4:7]
	v_mfma_f32_16x16x32_bf16 v[0:3], v[180:183], v[214:217], v[0:3]
	s_barrier
	s_add_i32 s59, s59, 2
	s_add_u32 s57, s57, 0x100
	s_addc_u32 s58, s58, 0
	s_cmp_gt_u32 s59, 41
	s_mov_b64 s[28:29], s[36:37]
	s_cbranch_scc0 .LBB0_1388
	s_and_b64 vcc, exec, s[10:11]
	s_cbranch_vccz .LBB0_1391
	s_barrier
